# K-loop LDS-DMA split 3/5 instead of 4/4 (one piece moved per segment pair), waits 8/7/8/7; group barriers kept
# speedup vs baseline: 1.0017x; 1.0017x over previous
.LBB0_410:
	ds_read_b128 v[154:157], v149
	ds_read_b128 v[158:161], v149 offset:1024
	ds_read_b128 v[162:165], v149 offset:2048
	ds_read_b128 v[166:169], v149 offset:3072
	ds_read_b128 v[170:173], v150
	ds_read_b128 v[174:177], v150 offset:1024
	ds_read_b128 v[178:181], v150 offset:2048
	ds_read_b128 v[182:185], v150 offset:3072
	s_add_u32 s30, s28, 0xfffc0080
	s_addc_u32 s31, s29, -1
	s_cmp_eq_u32 s71, 12
	s_cselect_b32 s35, s21, s31
	s_cselect_b32 s34, s61, s30
	s_cselect_b32 s31, s19, s70
	s_cselect_b32 s30, s62, s63
	v_lshl_add_u64 v[144:145], s[28:29], 0, v[136:137]
	s_add_i32 m0, s27, 0xc000
	ds_read_b128 v[186:189], v151
	ds_read_b128 v[190:193], v151 offset:1024
	ds_read_b128 v[196:199], v151 offset:2048
	ds_read_b128 v[200:203], v151 offset:3072
	ds_read_b128 v[204:207], v151 offset:4096
	ds_read_b128 v[208:211], v151 offset:5120
	ds_read_b128 v[212:215], v151 offset:6144
	ds_read_b128 v[216:219], v151 offset:7168
	global_load_lds_dwordx4 v[144:145], off
	v_lshl_add_u64 v[144:145], s[28:29], 0, v[138:139]
	s_add_i32 m0, s27, 0xe000
	s_nop 0
	global_load_lds_dwordx4 v[144:145], off
	s_waitcnt vmcnt(8)
	s_waitcnt lgkmcnt(0)
	s_barrier
	s_setprio 1
	s_waitcnt lgkmcnt(0)
	v_mfma_f32_16x16x32_bf16 v[116:119], v[154:157], v[186:189], v[116:119]
	v_mfma_f32_16x16x32_bf16 v[112:115], v[162:165], v[186:189], v[112:115]
	v_mfma_f32_16x16x32_bf16 v[100:103], v[154:157], v[196:199], v[100:103]
	v_mfma_f32_16x16x32_bf16 v[96:99], v[162:165], v[196:199], v[96:99]
	v_mfma_f32_16x16x32_bf16 v[84:87], v[154:157], v[204:207], v[84:87]
	v_mfma_f32_16x16x32_bf16 v[80:83], v[162:165], v[204:207], v[80:83]
	v_mfma_f32_16x16x32_bf16 v[68:71], v[154:157], v[212:215], v[68:71]
	v_mfma_f32_16x16x32_bf16 v[64:67], v[162:165], v[212:215], v[64:67]
	v_mfma_f32_16x16x32_bf16 v[116:119], v[158:161], v[190:193], v[116:119]
	v_mfma_f32_16x16x32_bf16 v[112:115], v[166:169], v[190:193], v[112:115]
	v_mfma_f32_16x16x32_bf16 v[100:103], v[158:161], v[200:203], v[100:103]
	v_mfma_f32_16x16x32_bf16 v[96:99], v[166:169], v[200:203], v[96:99]
	v_mfma_f32_16x16x32_bf16 v[84:87], v[158:161], v[208:211], v[84:87]
	v_mfma_f32_16x16x32_bf16 v[80:83], v[166:169], v[208:211], v[80:83]
	v_mfma_f32_16x16x32_bf16 v[68:71], v[158:161], v[216:219], v[68:71]
	v_mfma_f32_16x16x32_bf16 v[64:67], v[166:169], v[216:219], v[64:67]
	s_setprio 0
	s_setprio 1
	v_mfma_f32_16x16x32_bf16 v[124:127], v[170:173], v[186:189], v[124:127]
	v_mfma_f32_16x16x32_bf16 v[120:123], v[178:181], v[186:189], v[120:123]
	v_mfma_f32_16x16x32_bf16 v[108:111], v[170:173], v[196:199], v[108:111]
	v_mfma_f32_16x16x32_bf16 v[104:107], v[178:181], v[196:199], v[104:107]
	v_mfma_f32_16x16x32_bf16 v[92:95], v[170:173], v[204:207], v[92:95]
	v_mfma_f32_16x16x32_bf16 v[88:91], v[178:181], v[204:207], v[88:91]
	v_mfma_f32_16x16x32_bf16 v[76:79], v[170:173], v[212:215], v[76:79]
	v_mfma_f32_16x16x32_bf16 v[72:75], v[178:181], v[212:215], v[72:75]
	v_mfma_f32_16x16x32_bf16 v[124:127], v[174:177], v[190:193], v[124:127]
	v_mfma_f32_16x16x32_bf16 v[120:123], v[182:185], v[190:193], v[120:123]
	v_mfma_f32_16x16x32_bf16 v[108:111], v[174:177], v[200:203], v[108:111]
	v_mfma_f32_16x16x32_bf16 v[104:107], v[182:185], v[200:203], v[104:107]
	v_mfma_f32_16x16x32_bf16 v[92:95], v[174:177], v[208:211], v[92:95]
	v_mfma_f32_16x16x32_bf16 v[88:91], v[182:185], v[208:211], v[88:91]
	v_mfma_f32_16x16x32_bf16 v[76:79], v[174:177], v[216:219], v[76:79]
	v_mfma_f32_16x16x32_bf16 v[72:75], v[182:185], v[216:219], v[72:75]
	s_setprio 0
	s_barrier
	s_add_i32 s72, s54, s41
	v_lshl_add_u64 v[144:145], s[30:31], 0, v[132:133]
	s_mov_b32 m0, s72
	ds_read_b128 v[186:189], v151 offset:16384
	ds_read_b128 v[190:193], v151 offset:17408
	ds_read_b128 v[196:199], v151 offset:18432
	ds_read_b128 v[200:203], v151 offset:19456
	ds_read_b128 v[204:207], v151 offset:20480
	ds_read_b128 v[208:211], v151 offset:21504
	ds_read_b128 v[212:215], v151 offset:22528
	ds_read_b128 v[216:219], v151 offset:23552
	global_load_lds_dwordx4 v[144:145], off
	s_add_i32 m0, s72, 0x2000
	s_add_u32 s72, s30, 0x40000
	v_lshl_add_u64 v[220:221], s[30:31], 0, v[128:129]
	s_addc_u32 s73, s31, 0
	s_add_i32 s77, s55, s41
	global_load_lds_dwordx4 v[220:221], off
	v_lshl_add_u64 v[222:223], s[72:73], 0, v[132:133]
	s_mov_b32 m0, s77
	v_lshl_add_u64 v[224:225], s[34:35], 0, v[130:131]
	global_load_lds_dwordx4 v[222:223], off
	v_lshl_add_u64 v[222:223], s[72:73], 0, v[128:129]
	s_add_i32 m0, s77, 0x2000
	s_nop 0
	global_load_lds_dwordx4 v[222:223], off
	v_lshl_add_u64 v[222:223], s[34:35], 0, v[134:135]
	s_mov_b32 m0, s27
	s_nop 0
	global_load_lds_dwordx4 v[222:223], off
	s_waitcnt vmcnt(7)
	s_waitcnt lgkmcnt(0)
	s_barrier
	s_setprio 1
	s_waitcnt lgkmcnt(0)
	v_mfma_f32_16x16x32_bf16 v[52:55], v[154:157], v[186:189], v[52:55]
	v_mfma_f32_16x16x32_bf16 v[48:51], v[162:165], v[186:189], v[48:51]
	v_mfma_f32_16x16x32_bf16 v[36:39], v[154:157], v[196:199], v[36:39]
	v_mfma_f32_16x16x32_bf16 v[32:35], v[162:165], v[196:199], v[32:35]
	v_mfma_f32_16x16x32_bf16 v[20:23], v[154:157], v[204:207], v[20:23]
	v_mfma_f32_16x16x32_bf16 v[16:19], v[162:165], v[204:207], v[16:19]
	v_mfma_f32_16x16x32_bf16 v[4:7], v[154:157], v[212:215], v[4:7]
	v_mfma_f32_16x16x32_bf16 v[0:3], v[162:165], v[212:215], v[0:3]
	v_mfma_f32_16x16x32_bf16 v[52:55], v[158:161], v[190:193], v[52:55]
	v_mfma_f32_16x16x32_bf16 v[48:51], v[166:169], v[190:193], v[48:51]
	v_mfma_f32_16x16x32_bf16 v[36:39], v[158:161], v[200:203], v[36:39]
	v_mfma_f32_16x16x32_bf16 v[32:35], v[166:169], v[200:203], v[32:35]
	v_mfma_f32_16x16x32_bf16 v[20:23], v[158:161], v[208:211], v[20:23]
	v_mfma_f32_16x16x32_bf16 v[16:19], v[166:169], v[208:211], v[16:19]
	v_mfma_f32_16x16x32_bf16 v[4:7], v[158:161], v[216:219], v[4:7]
	v_mfma_f32_16x16x32_bf16 v[0:3], v[166:169], v[216:219], v[0:3]
	s_setprio 0
	s_setprio 1
	v_mfma_f32_16x16x32_bf16 v[60:63], v[170:173], v[186:189], v[60:63]
	v_mfma_f32_16x16x32_bf16 v[56:59], v[178:181], v[186:189], v[56:59]
	v_mfma_f32_16x16x32_bf16 v[44:47], v[170:173], v[196:199], v[44:47]
	v_mfma_f32_16x16x32_bf16 v[40:43], v[178:181], v[196:199], v[40:43]
	v_mfma_f32_16x16x32_bf16 v[28:31], v[170:173], v[204:207], v[28:31]
	v_mfma_f32_16x16x32_bf16 v[24:27], v[178:181], v[204:207], v[24:27]
	v_mfma_f32_16x16x32_bf16 v[12:15], v[170:173], v[212:215], v[12:15]
	v_mfma_f32_16x16x32_bf16 v[8:11], v[178:181], v[212:215], v[8:11]
	v_mfma_f32_16x16x32_bf16 v[60:63], v[174:177], v[190:193], v[60:63]
	v_mfma_f32_16x16x32_bf16 v[56:59], v[182:185], v[190:193], v[56:59]
	v_mfma_f32_16x16x32_bf16 v[44:47], v[174:177], v[200:203], v[44:47]
	v_mfma_f32_16x16x32_bf16 v[40:43], v[182:185], v[200:203], v[40:43]
	v_mfma_f32_16x16x32_bf16 v[28:31], v[174:177], v[208:211], v[28:31]
	v_mfma_f32_16x16x32_bf16 v[24:27], v[182:185], v[208:211], v[24:27]
	v_mfma_f32_16x16x32_bf16 v[12:15], v[174:177], v[216:219], v[12:15]
	v_mfma_f32_16x16x32_bf16 v[8:11], v[182:185], v[216:219], v[8:11]
	s_setprio 0
	s_barrier
	s_add_i32 s72, 0, 0x18000
	v_add_u32_e32 v153, s72, v147
	s_add_i32 s73, 0, 0x1c000
	ds_read_b128 v[154:157], v153
	ds_read_b128 v[158:161], v153 offset:1024
	ds_read_b128 v[162:165], v153 offset:2048
	ds_read_b128 v[166:169], v153 offset:3072
	v_add_u32_e32 v153, s73, v147
	ds_read_b128 v[170:173], v153
	ds_read_b128 v[174:177], v153 offset:1024
	ds_read_b128 v[178:181], v153 offset:2048
	ds_read_b128 v[182:185], v153 offset:3072
	s_add_u32 s34, s34, 0x40000
	s_addc_u32 s35, s35, 0
	v_lshl_add_u64 v[226:227], s[34:35], 0, v[134:135]
	ds_read_b128 v[186:189], v151 offset:32768
	ds_read_b128 v[190:193], v151 offset:33792
	ds_read_b128 v[196:199], v151 offset:34816
	ds_read_b128 v[200:203], v151 offset:35840
	ds_read_b128 v[204:207], v151 offset:36864
	ds_read_b128 v[208:211], v151 offset:37888
	ds_read_b128 v[212:215], v151 offset:38912
	ds_read_b128 v[216:219], v151 offset:39936
	s_mov_b32 m0, s43
	s_nop 0
	global_load_lds_dwordx4 v[224:225], off
	s_mov_b32 m0, s44
	s_nop 0
	global_load_lds_dwordx4 v[226:227], off
	v_lshl_add_u64 v[226:227], s[34:35], 0, v[130:131]
	s_mov_b32 m0, s45
	s_nop 0
	global_load_lds_dwordx4 v[226:227], off
	s_waitcnt vmcnt(8)
	s_waitcnt lgkmcnt(0)
	s_barrier
	s_setprio 1
	s_waitcnt lgkmcnt(0)
	v_mfma_f32_16x16x32_bf16 v[116:119], v[154:157], v[186:189], v[116:119]
	v_mfma_f32_16x16x32_bf16 v[112:115], v[162:165], v[186:189], v[112:115]
	v_mfma_f32_16x16x32_bf16 v[100:103], v[154:157], v[196:199], v[100:103]
	v_mfma_f32_16x16x32_bf16 v[96:99], v[162:165], v[196:199], v[96:99]
	v_mfma_f32_16x16x32_bf16 v[84:87], v[154:157], v[204:207], v[84:87]
	v_mfma_f32_16x16x32_bf16 v[80:83], v[162:165], v[204:207], v[80:83]
	v_mfma_f32_16x16x32_bf16 v[68:71], v[154:157], v[212:215], v[68:71]
	v_mfma_f32_16x16x32_bf16 v[64:67], v[162:165], v[212:215], v[64:67]
	v_mfma_f32_16x16x32_bf16 v[116:119], v[158:161], v[190:193], v[116:119]
	v_mfma_f32_16x16x32_bf16 v[112:115], v[166:169], v[190:193], v[112:115]
	v_mfma_f32_16x16x32_bf16 v[100:103], v[158:161], v[200:203], v[100:103]
	v_mfma_f32_16x16x32_bf16 v[96:99], v[166:169], v[200:203], v[96:99]
	v_mfma_f32_16x16x32_bf16 v[84:87], v[158:161], v[208:211], v[84:87]
	v_mfma_f32_16x16x32_bf16 v[80:83], v[166:169], v[208:211], v[80:83]
	v_mfma_f32_16x16x32_bf16 v[68:71], v[158:161], v[216:219], v[68:71]
	v_mfma_f32_16x16x32_bf16 v[64:67], v[166:169], v[216:219], v[64:67]
	s_setprio 0
	s_setprio 1
	v_mfma_f32_16x16x32_bf16 v[124:127], v[170:173], v[186:189], v[124:127]
	v_mfma_f32_16x16x32_bf16 v[120:123], v[178:181], v[186:189], v[120:123]
	v_mfma_f32_16x16x32_bf16 v[108:111], v[170:173], v[196:199], v[108:111]
	v_mfma_f32_16x16x32_bf16 v[104:107], v[178:181], v[196:199], v[104:107]
	v_mfma_f32_16x16x32_bf16 v[92:95], v[170:173], v[204:207], v[92:95]
	v_mfma_f32_16x16x32_bf16 v[88:91], v[178:181], v[204:207], v[88:91]
	v_mfma_f32_16x16x32_bf16 v[76:79], v[170:173], v[212:215], v[76:79]
	v_mfma_f32_16x16x32_bf16 v[72:75], v[178:181], v[212:215], v[72:75]
	v_mfma_f32_16x16x32_bf16 v[124:127], v[174:177], v[190:193], v[124:127]
	v_mfma_f32_16x16x32_bf16 v[120:123], v[182:185], v[190:193], v[120:123]
	v_mfma_f32_16x16x32_bf16 v[108:111], v[174:177], v[200:203], v[108:111]
	v_mfma_f32_16x16x32_bf16 v[104:107], v[182:185], v[200:203], v[104:107]
	v_mfma_f32_16x16x32_bf16 v[92:95], v[174:177], v[208:211], v[92:95]
	v_mfma_f32_16x16x32_bf16 v[88:91], v[182:185], v[208:211], v[88:91]
	v_mfma_f32_16x16x32_bf16 v[76:79], v[174:177], v[216:219], v[76:79]
	v_mfma_f32_16x16x32_bf16 v[72:75], v[182:185], v[216:219], v[72:75]
	s_setprio 0
	s_barrier
	s_add_i32 s34, s72, s41
	v_lshl_add_u64 v[144:145], v[144:145], 0, s[12:13]
	s_mov_b32 m0, s34
	ds_read_b128 v[186:189], v151 offset:49152
	ds_read_b128 v[190:193], v151 offset:50176
	ds_read_b128 v[196:199], v151 offset:51200
	ds_read_b128 v[200:203], v151 offset:52224
	ds_read_b128 v[204:207], v151 offset:53248
	ds_read_b128 v[208:211], v151 offset:54272
	ds_read_b128 v[212:215], v151 offset:55296
	ds_read_b128 v[216:219], v151 offset:56320
	global_load_lds_dwordx4 v[144:145], off
	s_add_i32 m0, s34, 0x2000
	s_add_u32 s30, s30, 0x40080
	v_lshl_add_u64 v[144:145], v[220:221], 0, s[12:13]
	s_addc_u32 s31, s31, 0
	s_add_i32 s34, s73, s41
	global_load_lds_dwordx4 v[144:145], off
	v_lshl_add_u64 v[144:145], s[30:31], 0, v[132:133]
	s_mov_b32 m0, s34
	s_nop 0
	global_load_lds_dwordx4 v[144:145], off
	v_lshl_add_u64 v[144:145], s[30:31], 0, v[128:129]
	s_add_i32 m0, s34, 0x2000
	s_nop 0
	global_load_lds_dwordx4 v[144:145], off
	v_lshl_add_u64 v[144:145], v[222:223], 0, s[12:13]
	s_mov_b32 m0, s51
	s_nop 0
	global_load_lds_dwordx4 v[144:145], off
	s_waitcnt vmcnt(7)
	s_waitcnt lgkmcnt(0)
	s_barrier
	s_setprio 1
	s_waitcnt lgkmcnt(0)
	v_mfma_f32_16x16x32_bf16 v[52:55], v[154:157], v[186:189], v[52:55]
	v_mfma_f32_16x16x32_bf16 v[48:51], v[162:165], v[186:189], v[48:51]
	v_mfma_f32_16x16x32_bf16 v[36:39], v[154:157], v[196:199], v[36:39]
	v_mfma_f32_16x16x32_bf16 v[32:35], v[162:165], v[196:199], v[32:35]
	v_mfma_f32_16x16x32_bf16 v[20:23], v[154:157], v[204:207], v[20:23]
	v_mfma_f32_16x16x32_bf16 v[16:19], v[162:165], v[204:207], v[16:19]
	v_mfma_f32_16x16x32_bf16 v[4:7], v[154:157], v[212:215], v[4:7]
	v_mfma_f32_16x16x32_bf16 v[0:3], v[162:165], v[212:215], v[0:3]
	v_mfma_f32_16x16x32_bf16 v[52:55], v[158:161], v[190:193], v[52:55]
	v_mfma_f32_16x16x32_bf16 v[48:51], v[166:169], v[190:193], v[48:51]
	v_mfma_f32_16x16x32_bf16 v[36:39], v[158:161], v[200:203], v[36:39]
	v_mfma_f32_16x16x32_bf16 v[32:35], v[166:169], v[200:203], v[32:35]
	v_mfma_f32_16x16x32_bf16 v[20:23], v[158:161], v[208:211], v[20:23]
	v_mfma_f32_16x16x32_bf16 v[16:19], v[166:169], v[208:211], v[16:19]
	v_mfma_f32_16x16x32_bf16 v[4:7], v[158:161], v[216:219], v[4:7]
	v_mfma_f32_16x16x32_bf16 v[0:3], v[166:169], v[216:219], v[0:3]
	s_setprio 0
	s_setprio 1
	v_mfma_f32_16x16x32_bf16 v[60:63], v[170:173], v[186:189], v[60:63]
	v_mfma_f32_16x16x32_bf16 v[56:59], v[178:181], v[186:189], v[56:59]
	v_mfma_f32_16x16x32_bf16 v[44:47], v[170:173], v[196:199], v[44:47]
	v_mfma_f32_16x16x32_bf16 v[40:43], v[178:181], v[196:199], v[40:43]
	v_mfma_f32_16x16x32_bf16 v[28:31], v[170:173], v[204:207], v[28:31]
	v_mfma_f32_16x16x32_bf16 v[24:27], v[178:181], v[204:207], v[24:27]
	v_mfma_f32_16x16x32_bf16 v[12:15], v[170:173], v[212:215], v[12:15]
	v_mfma_f32_16x16x32_bf16 v[8:11], v[178:181], v[212:215], v[8:11]
	v_mfma_f32_16x16x32_bf16 v[60:63], v[174:177], v[190:193], v[60:63]
	v_mfma_f32_16x16x32_bf16 v[56:59], v[182:185], v[190:193], v[56:59]
	v_mfma_f32_16x16x32_bf16 v[44:47], v[174:177], v[200:203], v[44:47]
	v_mfma_f32_16x16x32_bf16 v[40:43], v[182:185], v[200:203], v[40:43]
	v_mfma_f32_16x16x32_bf16 v[28:31], v[174:177], v[208:211], v[28:31]
	v_mfma_f32_16x16x32_bf16 v[24:27], v[182:185], v[208:211], v[24:27]
	v_mfma_f32_16x16x32_bf16 v[12:15], v[174:177], v[216:219], v[12:15]
	v_mfma_f32_16x16x32_bf16 v[8:11], v[182:185], v[216:219], v[8:11]
	s_setprio 0
	s_barrier
	v_lshl_add_u64 v[224:225], v[224:225], 0, s[12:13]
	s_mov_b32 m0, s52
	s_nop 0
	global_load_lds_dwordx4 v[224:225], off
	s_add_i32 s71, s71, 2
	s_add_u32 s28, s28, 0x100
	s_addc_u32 s29, s29, 0
	s_add_u32 s63, s63, 0x100
	s_addc_u32 s70, s70, 0
	s_cmp_gt_u32 s71, 13
	s_cbranch_scc0 .LBB0_410
	s_and_b64 vcc, exec, s[16:17]
	s_cbranch_vccz .LBB0_413
	s_barrier

.LBB0_532:
	ds_read_b128 v[146:149], v155
	ds_read_b128 v[160:163], v155 offset:1024
	ds_read_b128 v[164:167], v155 offset:2048
	ds_read_b128 v[168:171], v155 offset:3072
	ds_read_b128 v[172:175], v156
	ds_read_b128 v[176:179], v156 offset:1024
	ds_read_b128 v[180:183], v156 offset:2048
	ds_read_b128 v[184:187], v156 offset:3072
	s_add_u32 s30, s28, 0x100
	s_addc_u32 s31, s29, 0
	s_cmp_eq_u32 s77, 40
	s_cselect_b32 s37, s1, s31
	s_cselect_b32 s36, s0, s30
	s_cselect_b32 s35, s27, s73
	s_cselect_b32 s34, s26, s72
	v_lshl_add_u64 v[150:151], s[28:29], 0, v[138:139]
	s_add_i32 m0, s44, 0xc000
	ds_read_b128 v[188:191], v157
	ds_read_b128 v[196:199], v157 offset:1024
	ds_read_b128 v[200:203], v157 offset:2048
	ds_read_b128 v[204:207], v157 offset:3072
	ds_read_b128 v[208:211], v157 offset:4096
	ds_read_b128 v[212:215], v157 offset:5120
	ds_read_b128 v[216:219], v157 offset:6144
	ds_read_b128 v[220:223], v157 offset:7168
	global_load_lds_dwordx4 v[150:151], off
	v_lshl_add_u64 v[150:151], s[28:29], 0, v[140:141]
	s_add_i32 m0, s44, 0xe000
	s_nop 0
	global_load_lds_dwordx4 v[150:151], off
	s_waitcnt vmcnt(8)
	s_waitcnt lgkmcnt(0)
	s_barrier
	s_setprio 1
	s_waitcnt lgkmcnt(0)
	v_mfma_f32_16x16x32_bf16 v[124:127], v[146:149], v[188:191], v[124:127]
	v_mfma_f32_16x16x32_bf16 v[120:123], v[164:167], v[188:191], v[120:123]
	v_mfma_f32_16x16x32_bf16 v[108:111], v[146:149], v[200:203], v[108:111]
	v_mfma_f32_16x16x32_bf16 v[104:107], v[164:167], v[200:203], v[104:107]
	v_mfma_f32_16x16x32_bf16 v[92:95], v[146:149], v[208:211], v[92:95]
	v_mfma_f32_16x16x32_bf16 v[88:91], v[164:167], v[208:211], v[88:91]
	v_mfma_f32_16x16x32_bf16 v[76:79], v[146:149], v[216:219], v[76:79]
	v_mfma_f32_16x16x32_bf16 v[72:75], v[164:167], v[216:219], v[72:75]
	v_mfma_f32_16x16x32_bf16 v[124:127], v[160:163], v[196:199], v[124:127]
	v_mfma_f32_16x16x32_bf16 v[120:123], v[168:171], v[196:199], v[120:123]
	v_mfma_f32_16x16x32_bf16 v[108:111], v[160:163], v[204:207], v[108:111]
	v_mfma_f32_16x16x32_bf16 v[104:107], v[168:171], v[204:207], v[104:107]
	v_mfma_f32_16x16x32_bf16 v[92:95], v[160:163], v[212:215], v[92:95]
	v_mfma_f32_16x16x32_bf16 v[88:91], v[168:171], v[212:215], v[88:91]
	v_mfma_f32_16x16x32_bf16 v[76:79], v[160:163], v[220:223], v[76:79]
	v_mfma_f32_16x16x32_bf16 v[72:75], v[168:171], v[220:223], v[72:75]
	s_setprio 0
	s_setprio 1
	v_mfma_f32_16x16x32_bf16 v[116:119], v[172:175], v[188:191], v[116:119]
	v_mfma_f32_16x16x32_bf16 v[112:115], v[180:183], v[188:191], v[112:115]
	v_mfma_f32_16x16x32_bf16 v[100:103], v[172:175], v[200:203], v[100:103]
	v_mfma_f32_16x16x32_bf16 v[96:99], v[180:183], v[200:203], v[96:99]
	v_mfma_f32_16x16x32_bf16 v[84:87], v[172:175], v[208:211], v[84:87]
	v_mfma_f32_16x16x32_bf16 v[80:83], v[180:183], v[208:211], v[80:83]
	v_mfma_f32_16x16x32_bf16 v[68:71], v[172:175], v[216:219], v[68:71]
	v_mfma_f32_16x16x32_bf16 v[64:67], v[180:183], v[216:219], v[64:67]
	v_mfma_f32_16x16x32_bf16 v[116:119], v[176:179], v[196:199], v[116:119]
	v_mfma_f32_16x16x32_bf16 v[112:115], v[184:187], v[196:199], v[112:115]
	v_mfma_f32_16x16x32_bf16 v[100:103], v[176:179], v[204:207], v[100:103]
	v_mfma_f32_16x16x32_bf16 v[96:99], v[184:187], v[204:207], v[96:99]
	v_mfma_f32_16x16x32_bf16 v[84:87], v[176:179], v[212:215], v[84:87]
	v_mfma_f32_16x16x32_bf16 v[80:83], v[184:187], v[212:215], v[80:83]
	v_mfma_f32_16x16x32_bf16 v[68:71], v[176:179], v[220:223], v[68:71]
	v_mfma_f32_16x16x32_bf16 v[64:67], v[184:187], v[220:223], v[64:67]
	s_setprio 0
	s_barrier
	s_add_i32 s28, s60, s43
	v_lshl_add_u64 v[150:151], s[34:35], 0, v[132:133]
	s_mov_b32 m0, s28
	ds_read_b128 v[188:191], v157 offset:16384
	ds_read_b128 v[196:199], v157 offset:17408
	ds_read_b128 v[200:203], v157 offset:18432
	ds_read_b128 v[204:207], v157 offset:19456
	ds_read_b128 v[208:211], v157 offset:20480
	ds_read_b128 v[212:215], v157 offset:21504
	ds_read_b128 v[216:219], v157 offset:22528
	ds_read_b128 v[220:223], v157 offset:23552
	global_load_lds_dwordx4 v[150:151], off
	s_add_i32 m0, s28, 0x2000
	s_add_u32 s28, s34, 0xb0000
	v_lshl_add_u64 v[192:193], s[34:35], 0, v[136:137]
	s_addc_u32 s29, s35, 0
	s_add_i32 s78, s61, s43
	global_load_lds_dwordx4 v[192:193], off
	v_lshl_add_u64 v[224:225], s[28:29], 0, v[132:133]
	s_mov_b32 m0, s78
	v_lshl_add_u64 v[226:227], s[36:37], 0, v[134:135]
	global_load_lds_dwordx4 v[224:225], off
	v_lshl_add_u64 v[224:225], s[28:29], 0, v[136:137]
	s_add_i32 m0, s78, 0x2000
	s_nop 0
	global_load_lds_dwordx4 v[224:225], off
	v_lshl_add_u64 v[224:225], s[36:37], 0, v[130:131]
	s_mov_b32 m0, s44
	s_nop 0
	global_load_lds_dwordx4 v[224:225], off
	s_waitcnt vmcnt(7)
	s_waitcnt lgkmcnt(0)
	s_barrier
	s_setprio 1
	s_waitcnt lgkmcnt(0)
	v_mfma_f32_16x16x32_bf16 v[60:63], v[146:149], v[188:191], v[60:63]
	v_mfma_f32_16x16x32_bf16 v[56:59], v[164:167], v[188:191], v[56:59]
	v_mfma_f32_16x16x32_bf16 v[44:47], v[146:149], v[200:203], v[44:47]
	v_mfma_f32_16x16x32_bf16 v[40:43], v[164:167], v[200:203], v[40:43]
	v_mfma_f32_16x16x32_bf16 v[28:31], v[146:149], v[208:211], v[28:31]
	v_mfma_f32_16x16x32_bf16 v[24:27], v[164:167], v[208:211], v[24:27]
	v_mfma_f32_16x16x32_bf16 v[12:15], v[146:149], v[216:219], v[12:15]
	v_mfma_f32_16x16x32_bf16 v[8:11], v[164:167], v[216:219], v[8:11]
	v_mfma_f32_16x16x32_bf16 v[60:63], v[160:163], v[196:199], v[60:63]
	v_mfma_f32_16x16x32_bf16 v[56:59], v[168:171], v[196:199], v[56:59]
	v_mfma_f32_16x16x32_bf16 v[44:47], v[160:163], v[204:207], v[44:47]
	v_mfma_f32_16x16x32_bf16 v[40:43], v[168:171], v[204:207], v[40:43]
	v_mfma_f32_16x16x32_bf16 v[28:31], v[160:163], v[212:215], v[28:31]
	v_mfma_f32_16x16x32_bf16 v[24:27], v[168:171], v[212:215], v[24:27]
	v_mfma_f32_16x16x32_bf16 v[12:15], v[160:163], v[220:223], v[12:15]
	v_mfma_f32_16x16x32_bf16 v[8:11], v[168:171], v[220:223], v[8:11]
	s_setprio 0
	s_setprio 1
	v_mfma_f32_16x16x32_bf16 v[52:55], v[172:175], v[188:191], v[52:55]
	v_mfma_f32_16x16x32_bf16 v[48:51], v[180:183], v[188:191], v[48:51]
	v_mfma_f32_16x16x32_bf16 v[36:39], v[172:175], v[200:203], v[36:39]
	v_mfma_f32_16x16x32_bf16 v[32:35], v[180:183], v[200:203], v[32:35]
	v_mfma_f32_16x16x32_bf16 v[20:23], v[172:175], v[208:211], v[20:23]
	v_mfma_f32_16x16x32_bf16 v[16:19], v[180:183], v[208:211], v[16:19]
	v_mfma_f32_16x16x32_bf16 v[4:7], v[172:175], v[216:219], v[4:7]
	v_mfma_f32_16x16x32_bf16 v[0:3], v[180:183], v[216:219], v[0:3]
	v_mfma_f32_16x16x32_bf16 v[52:55], v[176:179], v[196:199], v[52:55]
	v_mfma_f32_16x16x32_bf16 v[48:51], v[184:187], v[196:199], v[48:51]
	v_mfma_f32_16x16x32_bf16 v[36:39], v[176:179], v[204:207], v[36:39]
	v_mfma_f32_16x16x32_bf16 v[32:35], v[184:187], v[204:207], v[32:35]
	v_mfma_f32_16x16x32_bf16 v[20:23], v[176:179], v[212:215], v[20:23]
	v_mfma_f32_16x16x32_bf16 v[16:19], v[184:187], v[212:215], v[16:19]
	v_mfma_f32_16x16x32_bf16 v[4:7], v[176:179], v[220:223], v[4:7]
	v_mfma_f32_16x16x32_bf16 v[0:3], v[184:187], v[220:223], v[0:3]
	s_setprio 0
	s_barrier
	s_add_i32 s78, 0, 0x18000
	v_add_u32_e32 v159, s78, v153
	s_add_i32 s79, 0, 0x1c000
	ds_read_b128 v[146:149], v159
	ds_read_b128 v[160:163], v159 offset:1024
	ds_read_b128 v[164:167], v159 offset:2048
	ds_read_b128 v[168:171], v159 offset:3072
	v_add_u32_e32 v159, s79, v153
	ds_read_b128 v[172:175], v159
	ds_read_b128 v[176:179], v159 offset:1024
	ds_read_b128 v[180:183], v159 offset:2048
	ds_read_b128 v[184:187], v159 offset:3072
	s_add_u32 s28, s36, 0xb0000
	s_addc_u32 s29, s37, 0
	v_lshl_add_u64 v[228:229], s[28:29], 0, v[130:131]
	ds_read_b128 v[188:191], v157 offset:32768
	ds_read_b128 v[196:199], v157 offset:33792
	ds_read_b128 v[200:203], v157 offset:34816
	ds_read_b128 v[204:207], v157 offset:35840
	ds_read_b128 v[208:211], v157 offset:36864
	ds_read_b128 v[212:215], v157 offset:37888
	ds_read_b128 v[216:219], v157 offset:38912
	ds_read_b128 v[220:223], v157 offset:39936
	s_mov_b32 m0, s45
	s_nop 0
	global_load_lds_dwordx4 v[226:227], off
	s_mov_b32 m0, s50
	s_nop 0
	global_load_lds_dwordx4 v[228:229], off
	v_lshl_add_u64 v[228:229], s[28:29], 0, v[134:135]
	s_mov_b32 m0, s51
	s_nop 0
	global_load_lds_dwordx4 v[228:229], off
	s_waitcnt vmcnt(8)
	s_waitcnt lgkmcnt(0)
	s_barrier
	s_setprio 1
	s_waitcnt lgkmcnt(0)
	v_mfma_f32_16x16x32_bf16 v[124:127], v[146:149], v[188:191], v[124:127]
	v_mfma_f32_16x16x32_bf16 v[120:123], v[164:167], v[188:191], v[120:123]
	v_mfma_f32_16x16x32_bf16 v[108:111], v[146:149], v[200:203], v[108:111]
	v_mfma_f32_16x16x32_bf16 v[104:107], v[164:167], v[200:203], v[104:107]
	v_mfma_f32_16x16x32_bf16 v[92:95], v[146:149], v[208:211], v[92:95]
	v_mfma_f32_16x16x32_bf16 v[88:91], v[164:167], v[208:211], v[88:91]
	v_mfma_f32_16x16x32_bf16 v[76:79], v[146:149], v[216:219], v[76:79]
	v_mfma_f32_16x16x32_bf16 v[72:75], v[164:167], v[216:219], v[72:75]
	v_mfma_f32_16x16x32_bf16 v[124:127], v[160:163], v[196:199], v[124:127]
	v_mfma_f32_16x16x32_bf16 v[120:123], v[168:171], v[196:199], v[120:123]
	v_mfma_f32_16x16x32_bf16 v[108:111], v[160:163], v[204:207], v[108:111]
	v_mfma_f32_16x16x32_bf16 v[104:107], v[168:171], v[204:207], v[104:107]
	v_mfma_f32_16x16x32_bf16 v[92:95], v[160:163], v[212:215], v[92:95]
	v_mfma_f32_16x16x32_bf16 v[88:91], v[168:171], v[212:215], v[88:91]
	v_mfma_f32_16x16x32_bf16 v[76:79], v[160:163], v[220:223], v[76:79]
	v_mfma_f32_16x16x32_bf16 v[72:75], v[168:171], v[220:223], v[72:75]
	s_setprio 0
	s_setprio 1
	v_mfma_f32_16x16x32_bf16 v[116:119], v[172:175], v[188:191], v[116:119]
	v_mfma_f32_16x16x32_bf16 v[112:115], v[180:183], v[188:191], v[112:115]
	v_mfma_f32_16x16x32_bf16 v[100:103], v[172:175], v[200:203], v[100:103]
	v_mfma_f32_16x16x32_bf16 v[96:99], v[180:183], v[200:203], v[96:99]
	v_mfma_f32_16x16x32_bf16 v[84:87], v[172:175], v[208:211], v[84:87]
	v_mfma_f32_16x16x32_bf16 v[80:83], v[180:183], v[208:211], v[80:83]
	v_mfma_f32_16x16x32_bf16 v[68:71], v[172:175], v[216:219], v[68:71]
	v_mfma_f32_16x16x32_bf16 v[64:67], v[180:183], v[216:219], v[64:67]
	v_mfma_f32_16x16x32_bf16 v[116:119], v[176:179], v[196:199], v[116:119]
	v_mfma_f32_16x16x32_bf16 v[112:115], v[184:187], v[196:199], v[112:115]
	v_mfma_f32_16x16x32_bf16 v[100:103], v[176:179], v[204:207], v[100:103]
	v_mfma_f32_16x16x32_bf16 v[96:99], v[184:187], v[204:207], v[96:99]
	v_mfma_f32_16x16x32_bf16 v[84:87], v[176:179], v[212:215], v[84:87]
	v_mfma_f32_16x16x32_bf16 v[80:83], v[184:187], v[212:215], v[80:83]
	v_mfma_f32_16x16x32_bf16 v[68:71], v[176:179], v[220:223], v[68:71]
	v_mfma_f32_16x16x32_bf16 v[64:67], v[184:187], v[220:223], v[64:67]
	s_setprio 0
	s_barrier
	s_add_i32 s28, s78, s43
	v_lshl_add_u64 v[150:151], v[150:151], 0, s[22:23]
	s_mov_b32 m0, s28
	ds_read_b128 v[188:191], v157 offset:49152
	ds_read_b128 v[196:199], v157 offset:50176
	ds_read_b128 v[200:203], v157 offset:51200
	ds_read_b128 v[204:207], v157 offset:52224
	ds_read_b128 v[208:211], v157 offset:53248
	ds_read_b128 v[212:215], v157 offset:54272
	ds_read_b128 v[216:219], v157 offset:55296
	ds_read_b128 v[220:223], v157 offset:56320
	global_load_lds_dwordx4 v[150:151], off
	s_add_i32 m0, s28, 0x2000
	s_add_u32 s28, s34, 0xb0080
	v_lshl_add_u64 v[150:151], v[192:193], 0, s[22:23]
	s_addc_u32 s29, s35, 0
	s_add_i32 s34, s79, s43
	global_load_lds_dwordx4 v[150:151], off
	v_lshl_add_u64 v[150:151], s[28:29], 0, v[132:133]
	s_mov_b32 m0, s34
	s_nop 0
	global_load_lds_dwordx4 v[150:151], off
	v_lshl_add_u64 v[150:151], s[28:29], 0, v[136:137]
	s_add_i32 m0, s34, 0x2000
	s_nop 0
	global_load_lds_dwordx4 v[150:151], off
	v_lshl_add_u64 v[150:151], v[224:225], 0, s[22:23]
	s_mov_b32 m0, s55
	s_nop 0
	global_load_lds_dwordx4 v[150:151], off
	s_waitcnt vmcnt(7)
	s_waitcnt lgkmcnt(0)
	s_barrier
	s_setprio 1
	s_waitcnt lgkmcnt(0)
	v_mfma_f32_16x16x32_bf16 v[60:63], v[146:149], v[188:191], v[60:63]
	v_mfma_f32_16x16x32_bf16 v[56:59], v[164:167], v[188:191], v[56:59]
	v_mfma_f32_16x16x32_bf16 v[44:47], v[146:149], v[200:203], v[44:47]
	v_mfma_f32_16x16x32_bf16 v[40:43], v[164:167], v[200:203], v[40:43]
	v_mfma_f32_16x16x32_bf16 v[28:31], v[146:149], v[208:211], v[28:31]
	v_mfma_f32_16x16x32_bf16 v[24:27], v[164:167], v[208:211], v[24:27]
	v_mfma_f32_16x16x32_bf16 v[12:15], v[146:149], v[216:219], v[12:15]
	v_mfma_f32_16x16x32_bf16 v[8:11], v[164:167], v[216:219], v[8:11]
	v_mfma_f32_16x16x32_bf16 v[60:63], v[160:163], v[196:199], v[60:63]
	v_mfma_f32_16x16x32_bf16 v[56:59], v[168:171], v[196:199], v[56:59]
	v_mfma_f32_16x16x32_bf16 v[44:47], v[160:163], v[204:207], v[44:47]
	v_mfma_f32_16x16x32_bf16 v[40:43], v[168:171], v[204:207], v[40:43]
	v_mfma_f32_16x16x32_bf16 v[28:31], v[160:163], v[212:215], v[28:31]
	v_mfma_f32_16x16x32_bf16 v[24:27], v[168:171], v[212:215], v[24:27]
	v_mfma_f32_16x16x32_bf16 v[12:15], v[160:163], v[220:223], v[12:15]
	v_mfma_f32_16x16x32_bf16 v[8:11], v[168:171], v[220:223], v[8:11]
	s_setprio 0
	s_setprio 1
	v_mfma_f32_16x16x32_bf16 v[52:55], v[172:175], v[188:191], v[52:55]
	v_mfma_f32_16x16x32_bf16 v[48:51], v[180:183], v[188:191], v[48:51]
	v_mfma_f32_16x16x32_bf16 v[36:39], v[172:175], v[200:203], v[36:39]
	v_mfma_f32_16x16x32_bf16 v[32:35], v[180:183], v[200:203], v[32:35]
	v_mfma_f32_16x16x32_bf16 v[20:23], v[172:175], v[208:211], v[20:23]
	v_mfma_f32_16x16x32_bf16 v[16:19], v[180:183], v[208:211], v[16:19]
	v_mfma_f32_16x16x32_bf16 v[4:7], v[172:175], v[216:219], v[4:7]
	v_mfma_f32_16x16x32_bf16 v[0:3], v[180:183], v[216:219], v[0:3]
	v_mfma_f32_16x16x32_bf16 v[52:55], v[176:179], v[196:199], v[52:55]
	v_mfma_f32_16x16x32_bf16 v[48:51], v[184:187], v[196:199], v[48:51]
	v_mfma_f32_16x16x32_bf16 v[36:39], v[176:179], v[204:207], v[36:39]
	v_mfma_f32_16x16x32_bf16 v[32:35], v[184:187], v[204:207], v[32:35]
	v_mfma_f32_16x16x32_bf16 v[20:23], v[176:179], v[212:215], v[20:23]
	v_mfma_f32_16x16x32_bf16 v[16:19], v[184:187], v[212:215], v[16:19]
	v_mfma_f32_16x16x32_bf16 v[4:7], v[176:179], v[220:223], v[4:7]
	v_mfma_f32_16x16x32_bf16 v[0:3], v[184:187], v[220:223], v[0:3]
	s_setprio 0
	s_barrier
	v_lshl_add_u64 v[226:227], v[226:227], 0, s[22:23]
	s_mov_b32 m0, s58
	s_nop 0
	global_load_lds_dwordx4 v[226:227], off
	s_add_i32 s77, s77, 2
	s_add_u32 s72, s72, 0x100
	s_addc_u32 s73, s73, 0
	s_cmp_gt_u32 s77, 41
	s_mov_b64 s[28:29], s[30:31]
	s_cbranch_scc0 .LBB0_532
	s_and_b64 vcc, exec, s[24:25]
	s_cbranch_vccz .LBB0_535
	s_barrier

.LBB0_626:
	ds_read_b128 v[152:155], v157
	ds_read_b128 v[162:165], v157 offset:1024
	ds_read_b128 v[166:169], v157 offset:2048
	ds_read_b128 v[170:173], v157 offset:3072
	ds_read_b128 v[174:177], v158
	ds_read_b128 v[178:181], v158 offset:1024
	ds_read_b128 v[182:185], v158 offset:2048
	ds_read_b128 v[186:189], v158 offset:3072
	s_add_u32 s40, s38, 0xfffc0080
	s_addc_u32 s41, s39, -1
	s_cmp_eq_u32 s86, 12
	s_cselect_b32 s43, s1, s41
	s_cselect_b32 s42, s11, s40
	s_cselect_b32 s41, s12, s85
	s_cselect_b32 s40, s29, s31
	v_lshl_add_u64 v[224:225], s[38:39], 0, v[144:145]
	s_add_i32 m0, s58, 0xc000
	ds_read_b128 v[190:193], v159
	ds_read_b128 v[196:199], v159 offset:1024
	ds_read_b128 v[200:203], v159 offset:2048
	ds_read_b128 v[204:207], v159 offset:3072
	ds_read_b128 v[208:211], v159 offset:4096
	ds_read_b128 v[212:215], v159 offset:5120
	ds_read_b128 v[216:219], v159 offset:6144
	ds_read_b128 v[220:223], v159 offset:7168
	global_load_lds_dwordx4 v[224:225], off
	v_lshl_add_u64 v[224:225], s[38:39], 0, v[146:147]
	s_add_i32 m0, s58, 0xe000
	s_nop 0
	global_load_lds_dwordx4 v[224:225], off
	s_waitcnt vmcnt(8)
	s_waitcnt lgkmcnt(0)
	s_barrier
	s_setprio 1
	s_waitcnt lgkmcnt(0)
	v_mfma_f32_16x16x32_bf16 v[124:127], v[152:155], v[190:193], v[124:127]
	v_mfma_f32_16x16x32_bf16 v[120:123], v[166:169], v[190:193], v[120:123]
	v_mfma_f32_16x16x32_bf16 v[108:111], v[152:155], v[200:203], v[108:111]
	v_mfma_f32_16x16x32_bf16 v[104:107], v[166:169], v[200:203], v[104:107]
	v_mfma_f32_16x16x32_bf16 v[92:95], v[152:155], v[208:211], v[92:95]
	v_mfma_f32_16x16x32_bf16 v[88:91], v[166:169], v[208:211], v[88:91]
	v_mfma_f32_16x16x32_bf16 v[76:79], v[152:155], v[216:219], v[76:79]
	v_mfma_f32_16x16x32_bf16 v[72:75], v[166:169], v[216:219], v[72:75]
	v_mfma_f32_16x16x32_bf16 v[124:127], v[162:165], v[196:199], v[124:127]
	v_mfma_f32_16x16x32_bf16 v[120:123], v[170:173], v[196:199], v[120:123]
	v_mfma_f32_16x16x32_bf16 v[108:111], v[162:165], v[204:207], v[108:111]
	v_mfma_f32_16x16x32_bf16 v[104:107], v[170:173], v[204:207], v[104:107]
	v_mfma_f32_16x16x32_bf16 v[92:95], v[162:165], v[212:215], v[92:95]
	v_mfma_f32_16x16x32_bf16 v[88:91], v[170:173], v[212:215], v[88:91]
	v_mfma_f32_16x16x32_bf16 v[76:79], v[162:165], v[220:223], v[76:79]
	v_mfma_f32_16x16x32_bf16 v[72:75], v[170:173], v[220:223], v[72:75]
	s_setprio 0
	s_setprio 1
	v_mfma_f32_16x16x32_bf16 v[116:119], v[174:177], v[190:193], v[116:119]
	v_mfma_f32_16x16x32_bf16 v[112:115], v[182:185], v[190:193], v[112:115]
	v_mfma_f32_16x16x32_bf16 v[100:103], v[174:177], v[200:203], v[100:103]
	v_mfma_f32_16x16x32_bf16 v[96:99], v[182:185], v[200:203], v[96:99]
	v_mfma_f32_16x16x32_bf16 v[84:87], v[174:177], v[208:211], v[84:87]
	v_mfma_f32_16x16x32_bf16 v[80:83], v[182:185], v[208:211], v[80:83]
	v_mfma_f32_16x16x32_bf16 v[68:71], v[174:177], v[216:219], v[68:71]
	v_mfma_f32_16x16x32_bf16 v[64:67], v[182:185], v[216:219], v[64:67]
	v_mfma_f32_16x16x32_bf16 v[116:119], v[178:181], v[196:199], v[116:119]
	v_mfma_f32_16x16x32_bf16 v[112:115], v[186:189], v[196:199], v[112:115]
	v_mfma_f32_16x16x32_bf16 v[100:103], v[178:181], v[204:207], v[100:103]
	v_mfma_f32_16x16x32_bf16 v[96:99], v[186:189], v[204:207], v[96:99]
	v_mfma_f32_16x16x32_bf16 v[84:87], v[178:181], v[212:215], v[84:87]
	v_mfma_f32_16x16x32_bf16 v[80:83], v[186:189], v[212:215], v[80:83]
	v_mfma_f32_16x16x32_bf16 v[68:71], v[178:181], v[220:223], v[68:71]
	v_mfma_f32_16x16x32_bf16 v[64:67], v[186:189], v[220:223], v[64:67]
	s_setprio 0
	s_barrier
	s_add_i32 s87, s73, s55
	v_lshl_add_u64 v[224:225], s[40:41], 0, v[130:131]
	s_mov_b32 m0, s87
	ds_read_b128 v[190:193], v159 offset:16384
	ds_read_b128 v[196:199], v159 offset:17408
	ds_read_b128 v[200:203], v159 offset:18432
	ds_read_b128 v[204:207], v159 offset:19456
	ds_read_b128 v[208:211], v159 offset:20480
	ds_read_b128 v[212:215], v159 offset:21504
	ds_read_b128 v[216:219], v159 offset:22528
	ds_read_b128 v[220:223], v159 offset:23552
	global_load_lds_dwordx4 v[224:225], off
	s_add_i32 m0, s87, 0x2000
	s_add_u32 s88, s40, 0x40000
	v_lshl_add_u64 v[226:227], s[40:41], 0, v[134:135]
	s_addc_u32 s89, s41, 0
	s_add_i32 s87, s77, s55
	global_load_lds_dwordx4 v[226:227], off
	v_lshl_add_u64 v[228:229], s[88:89], 0, v[130:131]
	s_mov_b32 m0, s87
	v_lshl_add_u64 v[230:231], s[42:43], 0, v[132:133]
	global_load_lds_dwordx4 v[228:229], off
	v_lshl_add_u64 v[228:229], s[88:89], 0, v[134:135]
	s_add_i32 m0, s87, 0x2000
	s_nop 0
	global_load_lds_dwordx4 v[228:229], off
	v_lshl_add_u64 v[228:229], s[42:43], 0, v[128:129]
	s_mov_b32 m0, s58
	s_nop 0
	global_load_lds_dwordx4 v[228:229], off
	s_waitcnt vmcnt(7)
	s_waitcnt lgkmcnt(0)
	s_barrier
	s_setprio 1
	s_waitcnt lgkmcnt(0)
	v_mfma_f32_16x16x32_bf16 v[60:63], v[152:155], v[190:193], v[60:63]
	v_mfma_f32_16x16x32_bf16 v[56:59], v[166:169], v[190:193], v[56:59]
	v_mfma_f32_16x16x32_bf16 v[44:47], v[152:155], v[200:203], v[44:47]
	v_mfma_f32_16x16x32_bf16 v[40:43], v[166:169], v[200:203], v[40:43]
	v_mfma_f32_16x16x32_bf16 v[28:31], v[152:155], v[208:211], v[28:31]
	v_mfma_f32_16x16x32_bf16 v[24:27], v[166:169], v[208:211], v[24:27]
	v_mfma_f32_16x16x32_bf16 v[12:15], v[152:155], v[216:219], v[12:15]
	v_mfma_f32_16x16x32_bf16 v[8:11], v[166:169], v[216:219], v[8:11]
	v_mfma_f32_16x16x32_bf16 v[60:63], v[162:165], v[196:199], v[60:63]
	v_mfma_f32_16x16x32_bf16 v[56:59], v[170:173], v[196:199], v[56:59]
	v_mfma_f32_16x16x32_bf16 v[44:47], v[162:165], v[204:207], v[44:47]
	v_mfma_f32_16x16x32_bf16 v[40:43], v[170:173], v[204:207], v[40:43]
	v_mfma_f32_16x16x32_bf16 v[28:31], v[162:165], v[212:215], v[28:31]
	v_mfma_f32_16x16x32_bf16 v[24:27], v[170:173], v[212:215], v[24:27]
	v_mfma_f32_16x16x32_bf16 v[12:15], v[162:165], v[220:223], v[12:15]
	v_mfma_f32_16x16x32_bf16 v[8:11], v[170:173], v[220:223], v[8:11]
	s_setprio 0
	s_setprio 1
	v_mfma_f32_16x16x32_bf16 v[52:55], v[174:177], v[190:193], v[52:55]
	v_mfma_f32_16x16x32_bf16 v[48:51], v[182:185], v[190:193], v[48:51]
	v_mfma_f32_16x16x32_bf16 v[36:39], v[174:177], v[200:203], v[36:39]
	v_mfma_f32_16x16x32_bf16 v[32:35], v[182:185], v[200:203], v[32:35]
	v_mfma_f32_16x16x32_bf16 v[20:23], v[174:177], v[208:211], v[20:23]
	v_mfma_f32_16x16x32_bf16 v[16:19], v[182:185], v[208:211], v[16:19]
	v_mfma_f32_16x16x32_bf16 v[4:7], v[174:177], v[216:219], v[4:7]
	v_mfma_f32_16x16x32_bf16 v[0:3], v[182:185], v[216:219], v[0:3]
	v_mfma_f32_16x16x32_bf16 v[52:55], v[178:181], v[196:199], v[52:55]
	v_mfma_f32_16x16x32_bf16 v[48:51], v[186:189], v[196:199], v[48:51]
	v_mfma_f32_16x16x32_bf16 v[36:39], v[178:181], v[204:207], v[36:39]
	v_mfma_f32_16x16x32_bf16 v[32:35], v[186:189], v[204:207], v[32:35]
	v_mfma_f32_16x16x32_bf16 v[20:23], v[178:181], v[212:215], v[20:23]
	v_mfma_f32_16x16x32_bf16 v[16:19], v[186:189], v[212:215], v[16:19]
	v_mfma_f32_16x16x32_bf16 v[4:7], v[178:181], v[220:223], v[4:7]
	v_mfma_f32_16x16x32_bf16 v[0:3], v[186:189], v[220:223], v[0:3]
	s_setprio 0
	s_barrier
	s_add_i32 s87, 0, 0x18000
	v_add_u32_e32 v136, s87, v141
	s_add_i32 s88, 0, 0x1c000
	ds_read_b128 v[152:155], v136
	ds_read_b128 v[162:165], v136 offset:1024
	ds_read_b128 v[166:169], v136 offset:2048
	ds_read_b128 v[170:173], v136 offset:3072
	v_add_u32_e32 v136, s88, v141
	ds_read_b128 v[174:177], v136
	ds_read_b128 v[178:181], v136 offset:1024
	ds_read_b128 v[182:185], v136 offset:2048
	ds_read_b128 v[186:189], v136 offset:3072
	s_add_u32 s42, s42, 0x40000
	s_addc_u32 s43, s43, 0
	v_lshl_add_u64 v[232:233], s[42:43], 0, v[128:129]
	ds_read_b128 v[190:193], v159 offset:32768
	ds_read_b128 v[196:199], v159 offset:33792
	ds_read_b128 v[200:203], v159 offset:34816
	ds_read_b128 v[204:207], v159 offset:35840
	ds_read_b128 v[208:211], v159 offset:36864
	ds_read_b128 v[212:215], v159 offset:37888
	ds_read_b128 v[216:219], v159 offset:38912
	ds_read_b128 v[220:223], v159 offset:39936
	s_mov_b32 m0, s59
	s_nop 0
	global_load_lds_dwordx4 v[230:231], off
	s_mov_b32 m0, s60
	s_nop 0
	global_load_lds_dwordx4 v[232:233], off
	v_lshl_add_u64 v[232:233], s[42:43], 0, v[132:133]
	s_mov_b32 m0, s61
	s_nop 0
	global_load_lds_dwordx4 v[232:233], off
	s_waitcnt vmcnt(8)
	s_waitcnt lgkmcnt(0)
	s_barrier
	s_setprio 1
	s_waitcnt lgkmcnt(0)
	v_mfma_f32_16x16x32_bf16 v[124:127], v[152:155], v[190:193], v[124:127]
	v_mfma_f32_16x16x32_bf16 v[120:123], v[166:169], v[190:193], v[120:123]
	v_mfma_f32_16x16x32_bf16 v[108:111], v[152:155], v[200:203], v[108:111]
	v_mfma_f32_16x16x32_bf16 v[104:107], v[166:169], v[200:203], v[104:107]
	v_mfma_f32_16x16x32_bf16 v[92:95], v[152:155], v[208:211], v[92:95]
	v_mfma_f32_16x16x32_bf16 v[88:91], v[166:169], v[208:211], v[88:91]
	v_mfma_f32_16x16x32_bf16 v[76:79], v[152:155], v[216:219], v[76:79]
	v_mfma_f32_16x16x32_bf16 v[72:75], v[166:169], v[216:219], v[72:75]
	v_mfma_f32_16x16x32_bf16 v[124:127], v[162:165], v[196:199], v[124:127]
	v_mfma_f32_16x16x32_bf16 v[120:123], v[170:173], v[196:199], v[120:123]
	v_mfma_f32_16x16x32_bf16 v[108:111], v[162:165], v[204:207], v[108:111]
	v_mfma_f32_16x16x32_bf16 v[104:107], v[170:173], v[204:207], v[104:107]
	v_mfma_f32_16x16x32_bf16 v[92:95], v[162:165], v[212:215], v[92:95]
	v_mfma_f32_16x16x32_bf16 v[88:91], v[170:173], v[212:215], v[88:91]
	v_mfma_f32_16x16x32_bf16 v[76:79], v[162:165], v[220:223], v[76:79]
	v_mfma_f32_16x16x32_bf16 v[72:75], v[170:173], v[220:223], v[72:75]
	s_setprio 0
	s_setprio 1
	v_mfma_f32_16x16x32_bf16 v[116:119], v[174:177], v[190:193], v[116:119]
	v_mfma_f32_16x16x32_bf16 v[112:115], v[182:185], v[190:193], v[112:115]
	v_mfma_f32_16x16x32_bf16 v[100:103], v[174:177], v[200:203], v[100:103]
	v_mfma_f32_16x16x32_bf16 v[96:99], v[182:185], v[200:203], v[96:99]
	v_mfma_f32_16x16x32_bf16 v[84:87], v[174:177], v[208:211], v[84:87]
	v_mfma_f32_16x16x32_bf16 v[80:83], v[182:185], v[208:211], v[80:83]
	v_mfma_f32_16x16x32_bf16 v[68:71], v[174:177], v[216:219], v[68:71]
	v_mfma_f32_16x16x32_bf16 v[64:67], v[182:185], v[216:219], v[64:67]
	v_mfma_f32_16x16x32_bf16 v[116:119], v[178:181], v[196:199], v[116:119]
	v_mfma_f32_16x16x32_bf16 v[112:115], v[186:189], v[196:199], v[112:115]
	v_mfma_f32_16x16x32_bf16 v[100:103], v[178:181], v[204:207], v[100:103]
	v_mfma_f32_16x16x32_bf16 v[96:99], v[186:189], v[204:207], v[96:99]
	v_mfma_f32_16x16x32_bf16 v[84:87], v[178:181], v[212:215], v[84:87]
	v_mfma_f32_16x16x32_bf16 v[80:83], v[186:189], v[212:215], v[80:83]
	v_mfma_f32_16x16x32_bf16 v[68:71], v[178:181], v[220:223], v[68:71]
	v_mfma_f32_16x16x32_bf16 v[64:67], v[186:189], v[220:223], v[64:67]
	s_setprio 0
	s_barrier
	s_add_i32 s42, s87, s55
	v_lshl_add_u64 v[224:225], v[224:225], 0, s[24:25]
	s_mov_b32 m0, s42
	ds_read_b128 v[190:193], v159 offset:49152
	ds_read_b128 v[196:199], v159 offset:50176
	ds_read_b128 v[200:203], v159 offset:51200
	ds_read_b128 v[204:207], v159 offset:52224
	ds_read_b128 v[208:211], v159 offset:53248
	ds_read_b128 v[212:215], v159 offset:54272
	ds_read_b128 v[216:219], v159 offset:55296
	ds_read_b128 v[220:223], v159 offset:56320
	global_load_lds_dwordx4 v[224:225], off
	s_add_i32 m0, s42, 0x2000
	s_add_u32 s40, s40, 0x40080
	v_lshl_add_u64 v[224:225], v[226:227], 0, s[24:25]
	s_addc_u32 s41, s41, 0
	s_add_i32 s42, s88, s55
	global_load_lds_dwordx4 v[224:225], off
	v_lshl_add_u64 v[224:225], s[40:41], 0, v[130:131]
	s_mov_b32 m0, s42
	s_nop 0
	global_load_lds_dwordx4 v[224:225], off
	v_lshl_add_u64 v[224:225], s[40:41], 0, v[134:135]
	s_add_i32 m0, s42, 0x2000
	s_nop 0
	global_load_lds_dwordx4 v[224:225], off
	v_lshl_add_u64 v[224:225], v[228:229], 0, s[24:25]
	s_mov_b32 m0, s70
	s_nop 0
	global_load_lds_dwordx4 v[224:225], off
	s_waitcnt vmcnt(7)
	s_waitcnt lgkmcnt(0)
	s_barrier
	s_setprio 1
	s_waitcnt lgkmcnt(0)
	v_mfma_f32_16x16x32_bf16 v[60:63], v[152:155], v[190:193], v[60:63]
	v_mfma_f32_16x16x32_bf16 v[56:59], v[166:169], v[190:193], v[56:59]
	v_mfma_f32_16x16x32_bf16 v[44:47], v[152:155], v[200:203], v[44:47]
	v_mfma_f32_16x16x32_bf16 v[40:43], v[166:169], v[200:203], v[40:43]
	v_mfma_f32_16x16x32_bf16 v[28:31], v[152:155], v[208:211], v[28:31]
	v_mfma_f32_16x16x32_bf16 v[24:27], v[166:169], v[208:211], v[24:27]
	v_mfma_f32_16x16x32_bf16 v[12:15], v[152:155], v[216:219], v[12:15]
	v_mfma_f32_16x16x32_bf16 v[8:11], v[166:169], v[216:219], v[8:11]
	v_mfma_f32_16x16x32_bf16 v[60:63], v[162:165], v[196:199], v[60:63]
	v_mfma_f32_16x16x32_bf16 v[56:59], v[170:173], v[196:199], v[56:59]
	v_mfma_f32_16x16x32_bf16 v[44:47], v[162:165], v[204:207], v[44:47]
	v_mfma_f32_16x16x32_bf16 v[40:43], v[170:173], v[204:207], v[40:43]
	v_mfma_f32_16x16x32_bf16 v[28:31], v[162:165], v[212:215], v[28:31]
	v_mfma_f32_16x16x32_bf16 v[24:27], v[170:173], v[212:215], v[24:27]
	v_mfma_f32_16x16x32_bf16 v[12:15], v[162:165], v[220:223], v[12:15]
	v_mfma_f32_16x16x32_bf16 v[8:11], v[170:173], v[220:223], v[8:11]
	s_setprio 0
	s_setprio 1
	v_mfma_f32_16x16x32_bf16 v[52:55], v[174:177], v[190:193], v[52:55]
	v_mfma_f32_16x16x32_bf16 v[48:51], v[182:185], v[190:193], v[48:51]
	v_mfma_f32_16x16x32_bf16 v[36:39], v[174:177], v[200:203], v[36:39]
	v_mfma_f32_16x16x32_bf16 v[32:35], v[182:185], v[200:203], v[32:35]
	v_mfma_f32_16x16x32_bf16 v[20:23], v[174:177], v[208:211], v[20:23]
	v_mfma_f32_16x16x32_bf16 v[16:19], v[182:185], v[208:211], v[16:19]
	v_mfma_f32_16x16x32_bf16 v[4:7], v[174:177], v[216:219], v[4:7]
	v_mfma_f32_16x16x32_bf16 v[0:3], v[182:185], v[216:219], v[0:3]
	v_mfma_f32_16x16x32_bf16 v[52:55], v[178:181], v[196:199], v[52:55]
	v_mfma_f32_16x16x32_bf16 v[48:51], v[186:189], v[196:199], v[48:51]
	v_mfma_f32_16x16x32_bf16 v[36:39], v[178:181], v[204:207], v[36:39]
	v_mfma_f32_16x16x32_bf16 v[32:35], v[186:189], v[204:207], v[32:35]
	v_mfma_f32_16x16x32_bf16 v[20:23], v[178:181], v[212:215], v[20:23]
	v_mfma_f32_16x16x32_bf16 v[16:19], v[186:189], v[212:215], v[16:19]
	v_mfma_f32_16x16x32_bf16 v[4:7], v[178:181], v[220:223], v[4:7]
	v_mfma_f32_16x16x32_bf16 v[0:3], v[186:189], v[220:223], v[0:3]
	s_setprio 0
	s_barrier
	v_lshl_add_u64 v[230:231], v[230:231], 0, s[24:25]
	s_mov_b32 m0, s71
	s_nop 0
	global_load_lds_dwordx4 v[230:231], off
	s_add_i32 s86, s86, 2
	s_add_u32 s38, s38, 0x100
	s_addc_u32 s39, s39, 0
	s_add_u32 s31, s31, 0x100
	s_addc_u32 s85, s85, 0
	s_cmp_gt_u32 s86, 13
	s_cbranch_scc0 .LBB0_626
	s_and_b64 vcc, exec, s[26:27]
	s_cbranch_vccz .LBB0_629
	s_barrier

.LBB0_760:
	ds_read_b128 v[148:151], v144
	ds_read_b128 v[152:155], v144 offset:1024
	ds_read_b128 v[156:159], v144 offset:2048
	ds_read_b128 v[160:163], v144 offset:3072
	ds_read_b128 v[164:167], v145
	ds_read_b128 v[168:171], v145 offset:1024
	ds_read_b128 v[172:175], v145 offset:2048
	ds_read_b128 v[176:179], v145 offset:3072
	s_add_u32 s36, s34, 0x100
	s_addc_u32 s37, s35, 0
	s_cmp_eq_u32 s83, 4
	s_cselect_b32 s41, s29, s37
	s_cselect_b32 s40, s28, s36
	s_cselect_b32 s39, s31, s25
	s_cselect_b32 s38, s30, s13
	v_lshl_add_u64 v[192:193], s[34:35], 0, v[138:139]
	s_add_i32 m0, s58, 0xc000
	ds_read_b128 v[180:183], v146
	ds_read_b128 v[184:187], v146 offset:1024
	ds_read_b128 v[188:191], v146 offset:2048
	ds_read_b128 v[196:199], v146 offset:3072
	ds_read_b128 v[200:203], v146 offset:4096
	ds_read_b128 v[204:207], v146 offset:5120
	ds_read_b128 v[208:211], v146 offset:6144
	ds_read_b128 v[212:215], v146 offset:7168
	global_load_lds_dwordx4 v[192:193], off
	v_lshl_add_u64 v[192:193], s[34:35], 0, v[140:141]
	s_add_i32 m0, s58, 0xe000
	s_nop 0
	global_load_lds_dwordx4 v[192:193], off
	s_waitcnt vmcnt(8)
	s_waitcnt lgkmcnt(0)
	s_barrier
	s_setprio 1
	s_waitcnt lgkmcnt(0)
	v_mfma_f32_16x16x32_bf16 v[124:127], v[148:151], v[180:183], v[124:127]
	v_mfma_f32_16x16x32_bf16 v[120:123], v[156:159], v[180:183], v[120:123]
	v_mfma_f32_16x16x32_bf16 v[116:119], v[148:151], v[188:191], v[116:119]
	v_mfma_f32_16x16x32_bf16 v[112:115], v[156:159], v[188:191], v[112:115]
	v_mfma_f32_16x16x32_bf16 v[104:107], v[148:151], v[200:203], v[104:107]
	v_mfma_f32_16x16x32_bf16 v[96:99], v[156:159], v[200:203], v[96:99]
	v_mfma_f32_16x16x32_bf16 v[88:91], v[148:151], v[208:211], v[88:91]
	v_mfma_f32_16x16x32_bf16 v[80:83], v[156:159], v[208:211], v[80:83]
	v_mfma_f32_16x16x32_bf16 v[124:127], v[152:155], v[184:187], v[124:127]
	v_mfma_f32_16x16x32_bf16 v[120:123], v[160:163], v[184:187], v[120:123]
	v_mfma_f32_16x16x32_bf16 v[116:119], v[152:155], v[196:199], v[116:119]
	v_mfma_f32_16x16x32_bf16 v[112:115], v[160:163], v[196:199], v[112:115]
	v_mfma_f32_16x16x32_bf16 v[104:107], v[152:155], v[204:207], v[104:107]
	v_mfma_f32_16x16x32_bf16 v[96:99], v[160:163], v[204:207], v[96:99]
	v_mfma_f32_16x16x32_bf16 v[88:91], v[152:155], v[212:215], v[88:91]
	v_mfma_f32_16x16x32_bf16 v[80:83], v[160:163], v[212:215], v[80:83]
	s_setprio 0
	s_setprio 1
	v_mfma_f32_16x16x32_bf16 v[108:111], v[164:167], v[180:183], v[108:111]
	v_mfma_f32_16x16x32_bf16 v[100:103], v[172:175], v[180:183], v[100:103]
	v_mfma_f32_16x16x32_bf16 v[92:95], v[164:167], v[188:191], v[92:95]
	v_mfma_f32_16x16x32_bf16 v[84:87], v[172:175], v[188:191], v[84:87]
	v_mfma_f32_16x16x32_bf16 v[76:79], v[164:167], v[200:203], v[76:79]
	v_mfma_f32_16x16x32_bf16 v[72:75], v[172:175], v[200:203], v[72:75]
	v_mfma_f32_16x16x32_bf16 v[68:71], v[164:167], v[208:211], v[68:71]
	v_mfma_f32_16x16x32_bf16 v[64:67], v[172:175], v[208:211], v[64:67]
	v_mfma_f32_16x16x32_bf16 v[108:111], v[168:171], v[184:187], v[108:111]
	v_mfma_f32_16x16x32_bf16 v[100:103], v[176:179], v[184:187], v[100:103]
	v_mfma_f32_16x16x32_bf16 v[92:95], v[168:171], v[196:199], v[92:95]
	v_mfma_f32_16x16x32_bf16 v[84:87], v[176:179], v[196:199], v[84:87]
	v_mfma_f32_16x16x32_bf16 v[76:79], v[168:171], v[204:207], v[76:79]
	v_mfma_f32_16x16x32_bf16 v[72:75], v[176:179], v[204:207], v[72:75]
	v_mfma_f32_16x16x32_bf16 v[68:71], v[168:171], v[212:215], v[68:71]
	v_mfma_f32_16x16x32_bf16 v[64:67], v[176:179], v[212:215], v[64:67]
	s_setprio 0
	s_barrier
	s_add_i32 s34, s77, s51
	v_lshl_add_u64 v[192:193], s[38:39], 0, v[132:133]
	s_mov_b32 m0, s34
	ds_read_b128 v[180:183], v146 offset:16384
	ds_read_b128 v[184:187], v146 offset:17408
	ds_read_b128 v[188:191], v146 offset:18432
	ds_read_b128 v[196:199], v146 offset:19456
	ds_read_b128 v[200:203], v146 offset:20480
	ds_read_b128 v[204:207], v146 offset:21504
	ds_read_b128 v[208:211], v146 offset:22528
	ds_read_b128 v[212:215], v146 offset:23552
	global_load_lds_dwordx4 v[192:193], off
	s_add_i32 m0, s34, 0x2000
	s_add_u32 s34, s38, 0x20000
	v_lshl_add_u64 v[216:217], s[38:39], 0, v[128:129]
	s_addc_u32 s35, s39, 0
	s_add_i32 s84, s78, s51
	global_load_lds_dwordx4 v[216:217], off
	v_lshl_add_u64 v[218:219], s[34:35], 0, v[132:133]
	s_mov_b32 m0, s84
	v_lshl_add_u64 v[220:221], s[40:41], 0, v[130:131]
	global_load_lds_dwordx4 v[218:219], off
	v_lshl_add_u64 v[218:219], s[34:35], 0, v[128:129]
	s_add_i32 m0, s84, 0x2000
	s_nop 0
	global_load_lds_dwordx4 v[218:219], off
	v_lshl_add_u64 v[218:219], s[40:41], 0, v[134:135]
	s_mov_b32 m0, s58
	s_nop 0
	global_load_lds_dwordx4 v[218:219], off
	s_waitcnt vmcnt(7)
	s_waitcnt lgkmcnt(0)
	s_barrier
	s_setprio 1
	s_waitcnt lgkmcnt(0)
	v_mfma_f32_16x16x32_bf16 v[60:63], v[148:151], v[180:183], v[60:63]
	v_mfma_f32_16x16x32_bf16 v[56:59], v[156:159], v[180:183], v[56:59]
	v_mfma_f32_16x16x32_bf16 v[52:55], v[148:151], v[188:191], v[52:55]
	v_mfma_f32_16x16x32_bf16 v[48:51], v[156:159], v[188:191], v[48:51]
	v_mfma_f32_16x16x32_bf16 v[40:43], v[148:151], v[200:203], v[40:43]
	v_mfma_f32_16x16x32_bf16 v[32:35], v[156:159], v[200:203], v[32:35]
	v_mfma_f32_16x16x32_bf16 v[24:27], v[148:151], v[208:211], v[24:27]
	v_mfma_f32_16x16x32_bf16 v[16:19], v[156:159], v[208:211], v[16:19]
	v_mfma_f32_16x16x32_bf16 v[60:63], v[152:155], v[184:187], v[60:63]
	v_mfma_f32_16x16x32_bf16 v[56:59], v[160:163], v[184:187], v[56:59]
	v_mfma_f32_16x16x32_bf16 v[52:55], v[152:155], v[196:199], v[52:55]
	v_mfma_f32_16x16x32_bf16 v[48:51], v[160:163], v[196:199], v[48:51]
	v_mfma_f32_16x16x32_bf16 v[40:43], v[152:155], v[204:207], v[40:43]
	v_mfma_f32_16x16x32_bf16 v[32:35], v[160:163], v[204:207], v[32:35]
	v_mfma_f32_16x16x32_bf16 v[24:27], v[152:155], v[212:215], v[24:27]
	v_mfma_f32_16x16x32_bf16 v[16:19], v[160:163], v[212:215], v[16:19]
	s_setprio 0
	s_setprio 1
	v_mfma_f32_16x16x32_bf16 v[44:47], v[164:167], v[180:183], v[44:47]
	v_mfma_f32_16x16x32_bf16 v[36:39], v[172:175], v[180:183], v[36:39]
	v_mfma_f32_16x16x32_bf16 v[28:31], v[164:167], v[188:191], v[28:31]
	v_mfma_f32_16x16x32_bf16 v[20:23], v[172:175], v[188:191], v[20:23]
	v_mfma_f32_16x16x32_bf16 v[12:15], v[164:167], v[200:203], v[12:15]
	v_mfma_f32_16x16x32_bf16 v[8:11], v[172:175], v[200:203], v[8:11]
	v_mfma_f32_16x16x32_bf16 v[4:7], v[164:167], v[208:211], v[4:7]
	v_mfma_f32_16x16x32_bf16 v[0:3], v[172:175], v[208:211], v[0:3]
	v_mfma_f32_16x16x32_bf16 v[44:47], v[168:171], v[184:187], v[44:47]
	v_mfma_f32_16x16x32_bf16 v[36:39], v[176:179], v[184:187], v[36:39]
	v_mfma_f32_16x16x32_bf16 v[28:31], v[168:171], v[196:199], v[28:31]
	v_mfma_f32_16x16x32_bf16 v[20:23], v[176:179], v[196:199], v[20:23]
	v_mfma_f32_16x16x32_bf16 v[12:15], v[168:171], v[204:207], v[12:15]
	v_mfma_f32_16x16x32_bf16 v[8:11], v[176:179], v[204:207], v[8:11]
	v_mfma_f32_16x16x32_bf16 v[4:7], v[168:171], v[212:215], v[4:7]
	v_mfma_f32_16x16x32_bf16 v[0:3], v[176:179], v[212:215], v[0:3]
	s_setprio 0
	s_barrier
	s_add_i32 s84, 0, 0x18000
	v_add_u32_e32 v147, s84, v143
	s_add_i32 s85, 0, 0x1c000
	ds_read_b128 v[148:151], v147
	ds_read_b128 v[152:155], v147 offset:1024
	ds_read_b128 v[156:159], v147 offset:2048
	ds_read_b128 v[160:163], v147 offset:3072
	v_add_u32_e32 v147, s85, v143
	ds_read_b128 v[164:167], v147
	ds_read_b128 v[168:171], v147 offset:1024
	ds_read_b128 v[172:175], v147 offset:2048
	ds_read_b128 v[176:179], v147 offset:3072
	s_add_u32 s34, s40, 0x30000
	s_addc_u32 s35, s41, 0
	v_lshl_add_u64 v[222:223], s[34:35], 0, v[134:135]
	ds_read_b128 v[180:183], v146 offset:32768
	ds_read_b128 v[184:187], v146 offset:33792
	ds_read_b128 v[188:191], v146 offset:34816
	ds_read_b128 v[196:199], v146 offset:35840
	ds_read_b128 v[200:203], v146 offset:36864
	ds_read_b128 v[204:207], v146 offset:37888
	ds_read_b128 v[208:211], v146 offset:38912
	ds_read_b128 v[212:215], v146 offset:39936
	s_mov_b32 m0, s59
	s_nop 0
	global_load_lds_dwordx4 v[220:221], off
	s_mov_b32 m0, s60
	s_nop 0
	global_load_lds_dwordx4 v[222:223], off
	v_lshl_add_u64 v[222:223], s[34:35], 0, v[130:131]
	s_mov_b32 m0, s61
	s_nop 0
	global_load_lds_dwordx4 v[222:223], off
	s_waitcnt vmcnt(8)
	s_waitcnt lgkmcnt(0)
	s_barrier
	s_setprio 1
	s_waitcnt lgkmcnt(0)
	v_mfma_f32_16x16x32_bf16 v[124:127], v[148:151], v[180:183], v[124:127]
	v_mfma_f32_16x16x32_bf16 v[120:123], v[156:159], v[180:183], v[120:123]
	v_mfma_f32_16x16x32_bf16 v[116:119], v[148:151], v[188:191], v[116:119]
	v_mfma_f32_16x16x32_bf16 v[112:115], v[156:159], v[188:191], v[112:115]
	v_mfma_f32_16x16x32_bf16 v[104:107], v[148:151], v[200:203], v[104:107]
	v_mfma_f32_16x16x32_bf16 v[96:99], v[156:159], v[200:203], v[96:99]
	v_mfma_f32_16x16x32_bf16 v[88:91], v[148:151], v[208:211], v[88:91]
	v_mfma_f32_16x16x32_bf16 v[80:83], v[156:159], v[208:211], v[80:83]
	v_mfma_f32_16x16x32_bf16 v[124:127], v[152:155], v[184:187], v[124:127]
	v_mfma_f32_16x16x32_bf16 v[120:123], v[160:163], v[184:187], v[120:123]
	v_mfma_f32_16x16x32_bf16 v[116:119], v[152:155], v[196:199], v[116:119]
	v_mfma_f32_16x16x32_bf16 v[112:115], v[160:163], v[196:199], v[112:115]
	v_mfma_f32_16x16x32_bf16 v[104:107], v[152:155], v[204:207], v[104:107]
	v_mfma_f32_16x16x32_bf16 v[96:99], v[160:163], v[204:207], v[96:99]
	v_mfma_f32_16x16x32_bf16 v[88:91], v[152:155], v[212:215], v[88:91]
	v_mfma_f32_16x16x32_bf16 v[80:83], v[160:163], v[212:215], v[80:83]
	s_setprio 0
	s_setprio 1
	v_mfma_f32_16x16x32_bf16 v[108:111], v[164:167], v[180:183], v[108:111]
	v_mfma_f32_16x16x32_bf16 v[100:103], v[172:175], v[180:183], v[100:103]
	v_mfma_f32_16x16x32_bf16 v[92:95], v[164:167], v[188:191], v[92:95]
	v_mfma_f32_16x16x32_bf16 v[84:87], v[172:175], v[188:191], v[84:87]
	v_mfma_f32_16x16x32_bf16 v[76:79], v[164:167], v[200:203], v[76:79]
	v_mfma_f32_16x16x32_bf16 v[72:75], v[172:175], v[200:203], v[72:75]
	v_mfma_f32_16x16x32_bf16 v[68:71], v[164:167], v[208:211], v[68:71]
	v_mfma_f32_16x16x32_bf16 v[64:67], v[172:175], v[208:211], v[64:67]
	v_mfma_f32_16x16x32_bf16 v[108:111], v[168:171], v[184:187], v[108:111]
	v_mfma_f32_16x16x32_bf16 v[100:103], v[176:179], v[184:187], v[100:103]
	v_mfma_f32_16x16x32_bf16 v[92:95], v[168:171], v[196:199], v[92:95]
	v_mfma_f32_16x16x32_bf16 v[84:87], v[176:179], v[196:199], v[84:87]
	v_mfma_f32_16x16x32_bf16 v[76:79], v[168:171], v[204:207], v[76:79]
	v_mfma_f32_16x16x32_bf16 v[72:75], v[176:179], v[204:207], v[72:75]
	v_mfma_f32_16x16x32_bf16 v[68:71], v[168:171], v[212:215], v[68:71]
	v_mfma_f32_16x16x32_bf16 v[64:67], v[176:179], v[212:215], v[64:67]
	s_setprio 0
	s_barrier
	s_add_i32 s34, s84, s51
	v_lshl_add_u64 v[192:193], v[192:193], 0, s[10:11]
	s_mov_b32 m0, s34
	ds_read_b128 v[180:183], v146 offset:49152
	ds_read_b128 v[184:187], v146 offset:50176
	ds_read_b128 v[188:191], v146 offset:51200
	ds_read_b128 v[196:199], v146 offset:52224
	ds_read_b128 v[200:203], v146 offset:53248
	ds_read_b128 v[204:207], v146 offset:54272
	ds_read_b128 v[208:211], v146 offset:55296
	ds_read_b128 v[212:215], v146 offset:56320
	global_load_lds_dwordx4 v[192:193], off
	s_add_i32 m0, s34, 0x2000
	s_add_u32 s34, s38, 0x20080
	v_lshl_add_u64 v[192:193], v[216:217], 0, s[10:11]
	s_addc_u32 s35, s39, 0
	s_add_i32 s38, s85, s51
	global_load_lds_dwordx4 v[192:193], off
	v_lshl_add_u64 v[192:193], s[34:35], 0, v[132:133]
	s_mov_b32 m0, s38
	s_nop 0
	global_load_lds_dwordx4 v[192:193], off
	v_lshl_add_u64 v[192:193], s[34:35], 0, v[128:129]
	s_add_i32 m0, s38, 0x2000
	s_nop 0
	global_load_lds_dwordx4 v[192:193], off
	v_lshl_add_u64 v[192:193], v[218:219], 0, s[10:11]
	s_mov_b32 m0, s71
	s_nop 0
	global_load_lds_dwordx4 v[192:193], off
	s_waitcnt vmcnt(7)
	s_waitcnt lgkmcnt(0)
	s_barrier
	s_setprio 1
	s_waitcnt lgkmcnt(0)
	v_mfma_f32_16x16x32_bf16 v[60:63], v[148:151], v[180:183], v[60:63]
	v_mfma_f32_16x16x32_bf16 v[56:59], v[156:159], v[180:183], v[56:59]
	v_mfma_f32_16x16x32_bf16 v[52:55], v[148:151], v[188:191], v[52:55]
	v_mfma_f32_16x16x32_bf16 v[48:51], v[156:159], v[188:191], v[48:51]
	v_mfma_f32_16x16x32_bf16 v[40:43], v[148:151], v[200:203], v[40:43]
	v_mfma_f32_16x16x32_bf16 v[32:35], v[156:159], v[200:203], v[32:35]
	v_mfma_f32_16x16x32_bf16 v[24:27], v[148:151], v[208:211], v[24:27]
	v_mfma_f32_16x16x32_bf16 v[16:19], v[156:159], v[208:211], v[16:19]
	v_mfma_f32_16x16x32_bf16 v[60:63], v[152:155], v[184:187], v[60:63]
	v_mfma_f32_16x16x32_bf16 v[56:59], v[160:163], v[184:187], v[56:59]
	v_mfma_f32_16x16x32_bf16 v[52:55], v[152:155], v[196:199], v[52:55]
	v_mfma_f32_16x16x32_bf16 v[48:51], v[160:163], v[196:199], v[48:51]
	v_mfma_f32_16x16x32_bf16 v[40:43], v[152:155], v[204:207], v[40:43]
	v_mfma_f32_16x16x32_bf16 v[32:35], v[160:163], v[204:207], v[32:35]
	v_mfma_f32_16x16x32_bf16 v[24:27], v[152:155], v[212:215], v[24:27]
	v_mfma_f32_16x16x32_bf16 v[16:19], v[160:163], v[212:215], v[16:19]
	s_setprio 0
	s_setprio 1
	v_mfma_f32_16x16x32_bf16 v[44:47], v[164:167], v[180:183], v[44:47]
	v_mfma_f32_16x16x32_bf16 v[36:39], v[172:175], v[180:183], v[36:39]
	v_mfma_f32_16x16x32_bf16 v[28:31], v[164:167], v[188:191], v[28:31]
	v_mfma_f32_16x16x32_bf16 v[20:23], v[172:175], v[188:191], v[20:23]
	v_mfma_f32_16x16x32_bf16 v[12:15], v[164:167], v[200:203], v[12:15]
	v_mfma_f32_16x16x32_bf16 v[8:11], v[172:175], v[200:203], v[8:11]
	v_mfma_f32_16x16x32_bf16 v[4:7], v[164:167], v[208:211], v[4:7]
	v_mfma_f32_16x16x32_bf16 v[0:3], v[172:175], v[208:211], v[0:3]
	v_mfma_f32_16x16x32_bf16 v[44:47], v[168:171], v[184:187], v[44:47]
	v_mfma_f32_16x16x32_bf16 v[36:39], v[176:179], v[184:187], v[36:39]
	v_mfma_f32_16x16x32_bf16 v[28:31], v[168:171], v[196:199], v[28:31]
	v_mfma_f32_16x16x32_bf16 v[20:23], v[176:179], v[196:199], v[20:23]
	v_mfma_f32_16x16x32_bf16 v[12:15], v[168:171], v[204:207], v[12:15]
	v_mfma_f32_16x16x32_bf16 v[8:11], v[176:179], v[204:207], v[8:11]
	v_mfma_f32_16x16x32_bf16 v[4:7], v[168:171], v[212:215], v[4:7]
	v_mfma_f32_16x16x32_bf16 v[0:3], v[176:179], v[212:215], v[0:3]
	s_setprio 0
	s_barrier
	v_lshl_add_u64 v[220:221], v[220:221], 0, s[10:11]
	s_mov_b32 m0, s72
	s_nop 0
	global_load_lds_dwordx4 v[220:221], off
	s_add_i32 s83, s83, 2
	s_add_u32 s13, s13, 0x100
	s_addc_u32 s25, s25, 0
	s_cmp_gt_u32 s83, 5
	s_mov_b64 s[34:35], s[36:37]
	s_cbranch_scc0 .LBB0_760
	s_and_b64 vcc, exec, s[16:17]
	s_cbranch_vccz .LBB0_763
	s_barrier

.LBB0_786:
	ds_read_b128 v[144:147], v153
	ds_read_b128 v[158:161], v153 offset:1024
	ds_read_b128 v[162:165], v153 offset:2048
	ds_read_b128 v[166:169], v153 offset:3072
	ds_read_b128 v[170:173], v154
	ds_read_b128 v[174:177], v154 offset:1024
	ds_read_b128 v[178:181], v154 offset:2048
	ds_read_b128 v[182:185], v154 offset:3072
	s_add_u32 s34, s30, 0xfffc0080
	s_addc_u32 s35, s31, -1
	s_cmp_eq_u32 s82, 12
	s_cselect_b32 s37, s25, s35
	s_cselect_b32 s36, s78, s34
	s_cselect_b32 s35, s23, s81
	s_cselect_b32 s34, s79, s80
	v_lshl_add_u64 v[148:149], s[30:31], 0, v[136:137]
	s_add_i32 m0, s50, 0xc000
	ds_read_b128 v[186:189], v155
	ds_read_b128 v[190:193], v155 offset:1024
	ds_read_b128 v[196:199], v155 offset:2048
	ds_read_b128 v[200:203], v155 offset:3072
	ds_read_b128 v[204:207], v155 offset:4096
	ds_read_b128 v[208:211], v155 offset:5120
	ds_read_b128 v[212:215], v155 offset:6144
	ds_read_b128 v[216:219], v155 offset:7168
	global_load_lds_dwordx4 v[148:149], off
	v_lshl_add_u64 v[148:149], s[30:31], 0, v[138:139]
	s_add_i32 m0, s50, 0xe000
	s_nop 0
	global_load_lds_dwordx4 v[148:149], off
	s_waitcnt vmcnt(8)
	s_waitcnt lgkmcnt(0)
	s_barrier
	s_setprio 1
	s_waitcnt lgkmcnt(0)
	v_mfma_f32_16x16x32_bf16 v[124:127], v[144:147], v[186:189], v[124:127]
	v_mfma_f32_16x16x32_bf16 v[120:123], v[162:165], v[186:189], v[120:123]
	v_mfma_f32_16x16x32_bf16 v[108:111], v[144:147], v[196:199], v[108:111]
	v_mfma_f32_16x16x32_bf16 v[104:107], v[162:165], v[196:199], v[104:107]
	v_mfma_f32_16x16x32_bf16 v[92:95], v[144:147], v[204:207], v[92:95]
	v_mfma_f32_16x16x32_bf16 v[88:91], v[162:165], v[204:207], v[88:91]
	v_mfma_f32_16x16x32_bf16 v[76:79], v[144:147], v[212:215], v[76:79]
	v_mfma_f32_16x16x32_bf16 v[72:75], v[162:165], v[212:215], v[72:75]
	v_mfma_f32_16x16x32_bf16 v[124:127], v[158:161], v[190:193], v[124:127]
	v_mfma_f32_16x16x32_bf16 v[120:123], v[166:169], v[190:193], v[120:123]
	v_mfma_f32_16x16x32_bf16 v[108:111], v[158:161], v[200:203], v[108:111]
	v_mfma_f32_16x16x32_bf16 v[104:107], v[166:169], v[200:203], v[104:107]
	v_mfma_f32_16x16x32_bf16 v[92:95], v[158:161], v[208:211], v[92:95]
	v_mfma_f32_16x16x32_bf16 v[88:91], v[166:169], v[208:211], v[88:91]
	v_mfma_f32_16x16x32_bf16 v[76:79], v[158:161], v[216:219], v[76:79]
	v_mfma_f32_16x16x32_bf16 v[72:75], v[166:169], v[216:219], v[72:75]
	s_setprio 0
	s_setprio 1
	v_mfma_f32_16x16x32_bf16 v[116:119], v[170:173], v[186:189], v[116:119]
	v_mfma_f32_16x16x32_bf16 v[112:115], v[178:181], v[186:189], v[112:115]
	v_mfma_f32_16x16x32_bf16 v[100:103], v[170:173], v[196:199], v[100:103]
	v_mfma_f32_16x16x32_bf16 v[96:99], v[178:181], v[196:199], v[96:99]
	v_mfma_f32_16x16x32_bf16 v[84:87], v[170:173], v[204:207], v[84:87]
	v_mfma_f32_16x16x32_bf16 v[80:83], v[178:181], v[204:207], v[80:83]
	v_mfma_f32_16x16x32_bf16 v[68:71], v[170:173], v[212:215], v[68:71]
	v_mfma_f32_16x16x32_bf16 v[64:67], v[178:181], v[212:215], v[64:67]
	v_mfma_f32_16x16x32_bf16 v[116:119], v[174:177], v[190:193], v[116:119]
	v_mfma_f32_16x16x32_bf16 v[112:115], v[182:185], v[190:193], v[112:115]
	v_mfma_f32_16x16x32_bf16 v[100:103], v[174:177], v[200:203], v[100:103]
	v_mfma_f32_16x16x32_bf16 v[96:99], v[182:185], v[200:203], v[96:99]
	v_mfma_f32_16x16x32_bf16 v[84:87], v[174:177], v[208:211], v[84:87]
	v_mfma_f32_16x16x32_bf16 v[80:83], v[182:185], v[208:211], v[80:83]
	v_mfma_f32_16x16x32_bf16 v[68:71], v[174:177], v[216:219], v[68:71]
	v_mfma_f32_16x16x32_bf16 v[64:67], v[182:185], v[216:219], v[64:67]
	s_setprio 0
	s_barrier
	s_add_i32 s83, s70, s45
	v_lshl_add_u64 v[148:149], s[34:35], 0, v[130:131]
	s_mov_b32 m0, s83
	ds_read_b128 v[186:189], v155 offset:16384
	ds_read_b128 v[190:193], v155 offset:17408
	ds_read_b128 v[196:199], v155 offset:18432
	ds_read_b128 v[200:203], v155 offset:19456
	ds_read_b128 v[204:207], v155 offset:20480
	ds_read_b128 v[208:211], v155 offset:21504
	ds_read_b128 v[212:215], v155 offset:22528
	ds_read_b128 v[216:219], v155 offset:23552
	global_load_lds_dwordx4 v[148:149], off
	s_add_i32 m0, s83, 0x2000
	s_add_u32 s84, s34, 0x40000
	v_lshl_add_u64 v[220:221], s[34:35], 0, v[134:135]
	s_addc_u32 s85, s35, 0
	s_add_i32 s83, s71, s45
	global_load_lds_dwordx4 v[220:221], off
	v_lshl_add_u64 v[222:223], s[84:85], 0, v[130:131]
	s_mov_b32 m0, s83
	v_lshl_add_u64 v[224:225], s[36:37], 0, v[132:133]
	global_load_lds_dwordx4 v[222:223], off
	v_lshl_add_u64 v[222:223], s[84:85], 0, v[134:135]
	s_add_i32 m0, s83, 0x2000
	s_nop 0
	global_load_lds_dwordx4 v[222:223], off
	v_lshl_add_u64 v[222:223], s[36:37], 0, v[128:129]
	s_mov_b32 m0, s50
	s_nop 0
	global_load_lds_dwordx4 v[222:223], off
	s_waitcnt vmcnt(7)
	s_waitcnt lgkmcnt(0)
	s_barrier
	s_setprio 1
	s_waitcnt lgkmcnt(0)
	v_mfma_f32_16x16x32_bf16 v[60:63], v[144:147], v[186:189], v[60:63]
	v_mfma_f32_16x16x32_bf16 v[56:59], v[162:165], v[186:189], v[56:59]
	v_mfma_f32_16x16x32_bf16 v[44:47], v[144:147], v[196:199], v[44:47]
	v_mfma_f32_16x16x32_bf16 v[40:43], v[162:165], v[196:199], v[40:43]
	v_mfma_f32_16x16x32_bf16 v[28:31], v[144:147], v[204:207], v[28:31]
	v_mfma_f32_16x16x32_bf16 v[24:27], v[162:165], v[204:207], v[24:27]
	v_mfma_f32_16x16x32_bf16 v[12:15], v[144:147], v[212:215], v[12:15]
	v_mfma_f32_16x16x32_bf16 v[8:11], v[162:165], v[212:215], v[8:11]
	v_mfma_f32_16x16x32_bf16 v[60:63], v[158:161], v[190:193], v[60:63]
	v_mfma_f32_16x16x32_bf16 v[56:59], v[166:169], v[190:193], v[56:59]
	v_mfma_f32_16x16x32_bf16 v[44:47], v[158:161], v[200:203], v[44:47]
	v_mfma_f32_16x16x32_bf16 v[40:43], v[166:169], v[200:203], v[40:43]
	v_mfma_f32_16x16x32_bf16 v[28:31], v[158:161], v[208:211], v[28:31]
	v_mfma_f32_16x16x32_bf16 v[24:27], v[166:169], v[208:211], v[24:27]
	v_mfma_f32_16x16x32_bf16 v[12:15], v[158:161], v[216:219], v[12:15]
	v_mfma_f32_16x16x32_bf16 v[8:11], v[166:169], v[216:219], v[8:11]
	s_setprio 0
	s_setprio 1
	v_mfma_f32_16x16x32_bf16 v[52:55], v[170:173], v[186:189], v[52:55]
	v_mfma_f32_16x16x32_bf16 v[48:51], v[178:181], v[186:189], v[48:51]
	v_mfma_f32_16x16x32_bf16 v[36:39], v[170:173], v[196:199], v[36:39]
	v_mfma_f32_16x16x32_bf16 v[32:35], v[178:181], v[196:199], v[32:35]
	v_mfma_f32_16x16x32_bf16 v[20:23], v[170:173], v[204:207], v[20:23]
	v_mfma_f32_16x16x32_bf16 v[16:19], v[178:181], v[204:207], v[16:19]
	v_mfma_f32_16x16x32_bf16 v[4:7], v[170:173], v[212:215], v[4:7]
	v_mfma_f32_16x16x32_bf16 v[0:3], v[178:181], v[212:215], v[0:3]
	v_mfma_f32_16x16x32_bf16 v[52:55], v[174:177], v[190:193], v[52:55]
	v_mfma_f32_16x16x32_bf16 v[48:51], v[182:185], v[190:193], v[48:51]
	v_mfma_f32_16x16x32_bf16 v[36:39], v[174:177], v[200:203], v[36:39]
	v_mfma_f32_16x16x32_bf16 v[32:35], v[182:185], v[200:203], v[32:35]
	v_mfma_f32_16x16x32_bf16 v[20:23], v[174:177], v[208:211], v[20:23]
	v_mfma_f32_16x16x32_bf16 v[16:19], v[182:185], v[208:211], v[16:19]
	v_mfma_f32_16x16x32_bf16 v[4:7], v[174:177], v[216:219], v[4:7]
	v_mfma_f32_16x16x32_bf16 v[0:3], v[182:185], v[216:219], v[0:3]
	s_setprio 0
	s_barrier
	s_add_i32 s83, 0, 0x18000
	v_add_u32_e32 v157, s83, v151
	s_add_i32 s84, 0, 0x1c000
	ds_read_b128 v[144:147], v157
	ds_read_b128 v[158:161], v157 offset:1024
	ds_read_b128 v[162:165], v157 offset:2048
	ds_read_b128 v[166:169], v157 offset:3072
	v_add_u32_e32 v157, s84, v151
	ds_read_b128 v[170:173], v157
	ds_read_b128 v[174:177], v157 offset:1024
	ds_read_b128 v[178:181], v157 offset:2048
	ds_read_b128 v[182:185], v157 offset:3072
	s_add_u32 s36, s36, 0x40000
	s_addc_u32 s37, s37, 0
	v_lshl_add_u64 v[226:227], s[36:37], 0, v[128:129]
	ds_read_b128 v[186:189], v155 offset:32768
	ds_read_b128 v[190:193], v155 offset:33792
	ds_read_b128 v[196:199], v155 offset:34816
	ds_read_b128 v[200:203], v155 offset:35840
	ds_read_b128 v[204:207], v155 offset:36864
	ds_read_b128 v[208:211], v155 offset:37888
	ds_read_b128 v[212:215], v155 offset:38912
	ds_read_b128 v[216:219], v155 offset:39936
	s_mov_b32 m0, s51
	s_nop 0
	global_load_lds_dwordx4 v[224:225], off
	s_mov_b32 m0, s58
	s_nop 0
	global_load_lds_dwordx4 v[226:227], off
	v_lshl_add_u64 v[226:227], s[36:37], 0, v[132:133]
	s_mov_b32 m0, s59
	s_nop 0
	global_load_lds_dwordx4 v[226:227], off
	s_waitcnt vmcnt(8)
	s_waitcnt lgkmcnt(0)
	s_barrier
	s_setprio 1
	s_waitcnt lgkmcnt(0)
	v_mfma_f32_16x16x32_bf16 v[124:127], v[144:147], v[186:189], v[124:127]
	v_mfma_f32_16x16x32_bf16 v[120:123], v[162:165], v[186:189], v[120:123]
	v_mfma_f32_16x16x32_bf16 v[108:111], v[144:147], v[196:199], v[108:111]
	v_mfma_f32_16x16x32_bf16 v[104:107], v[162:165], v[196:199], v[104:107]
	v_mfma_f32_16x16x32_bf16 v[92:95], v[144:147], v[204:207], v[92:95]
	v_mfma_f32_16x16x32_bf16 v[88:91], v[162:165], v[204:207], v[88:91]
	v_mfma_f32_16x16x32_bf16 v[76:79], v[144:147], v[212:215], v[76:79]
	v_mfma_f32_16x16x32_bf16 v[72:75], v[162:165], v[212:215], v[72:75]
	v_mfma_f32_16x16x32_bf16 v[124:127], v[158:161], v[190:193], v[124:127]
	v_mfma_f32_16x16x32_bf16 v[120:123], v[166:169], v[190:193], v[120:123]
	v_mfma_f32_16x16x32_bf16 v[108:111], v[158:161], v[200:203], v[108:111]
	v_mfma_f32_16x16x32_bf16 v[104:107], v[166:169], v[200:203], v[104:107]
	v_mfma_f32_16x16x32_bf16 v[92:95], v[158:161], v[208:211], v[92:95]
	v_mfma_f32_16x16x32_bf16 v[88:91], v[166:169], v[208:211], v[88:91]
	v_mfma_f32_16x16x32_bf16 v[76:79], v[158:161], v[216:219], v[76:79]
	v_mfma_f32_16x16x32_bf16 v[72:75], v[166:169], v[216:219], v[72:75]
	s_setprio 0
	s_setprio 1
	v_mfma_f32_16x16x32_bf16 v[116:119], v[170:173], v[186:189], v[116:119]
	v_mfma_f32_16x16x32_bf16 v[112:115], v[178:181], v[186:189], v[112:115]
	v_mfma_f32_16x16x32_bf16 v[100:103], v[170:173], v[196:199], v[100:103]
	v_mfma_f32_16x16x32_bf16 v[96:99], v[178:181], v[196:199], v[96:99]
	v_mfma_f32_16x16x32_bf16 v[84:87], v[170:173], v[204:207], v[84:87]
	v_mfma_f32_16x16x32_bf16 v[80:83], v[178:181], v[204:207], v[80:83]
	v_mfma_f32_16x16x32_bf16 v[68:71], v[170:173], v[212:215], v[68:71]
	v_mfma_f32_16x16x32_bf16 v[64:67], v[178:181], v[212:215], v[64:67]
	v_mfma_f32_16x16x32_bf16 v[116:119], v[174:177], v[190:193], v[116:119]
	v_mfma_f32_16x16x32_bf16 v[112:115], v[182:185], v[190:193], v[112:115]
	v_mfma_f32_16x16x32_bf16 v[100:103], v[174:177], v[200:203], v[100:103]
	v_mfma_f32_16x16x32_bf16 v[96:99], v[182:185], v[200:203], v[96:99]
	v_mfma_f32_16x16x32_bf16 v[84:87], v[174:177], v[208:211], v[84:87]
	v_mfma_f32_16x16x32_bf16 v[80:83], v[182:185], v[208:211], v[80:83]
	v_mfma_f32_16x16x32_bf16 v[68:71], v[174:177], v[216:219], v[68:71]
	v_mfma_f32_16x16x32_bf16 v[64:67], v[182:185], v[216:219], v[64:67]
	s_setprio 0
	s_barrier
	s_add_i32 s36, s83, s45
	v_lshl_add_u64 v[148:149], v[148:149], 0, s[18:19]
	s_mov_b32 m0, s36
	ds_read_b128 v[186:189], v155 offset:49152
	ds_read_b128 v[190:193], v155 offset:50176
	ds_read_b128 v[196:199], v155 offset:51200
	ds_read_b128 v[200:203], v155 offset:52224
	ds_read_b128 v[204:207], v155 offset:53248
	ds_read_b128 v[208:211], v155 offset:54272
	ds_read_b128 v[212:215], v155 offset:55296
	ds_read_b128 v[216:219], v155 offset:56320
	global_load_lds_dwordx4 v[148:149], off
	s_add_i32 m0, s36, 0x2000
	s_add_u32 s34, s34, 0x40080
	v_lshl_add_u64 v[148:149], v[220:221], 0, s[18:19]
	s_addc_u32 s35, s35, 0
	s_add_i32 s36, s84, s45
	global_load_lds_dwordx4 v[148:149], off
	v_lshl_add_u64 v[148:149], s[34:35], 0, v[130:131]
	s_mov_b32 m0, s36
	s_nop 0
	global_load_lds_dwordx4 v[148:149], off
	v_lshl_add_u64 v[148:149], s[34:35], 0, v[134:135]
	s_add_i32 m0, s36, 0x2000
	s_nop 0
	global_load_lds_dwordx4 v[148:149], off
	v_lshl_add_u64 v[148:149], v[222:223], 0, s[18:19]
	s_mov_b32 m0, s61
	s_nop 0
	global_load_lds_dwordx4 v[148:149], off
	s_waitcnt vmcnt(7)
	s_waitcnt lgkmcnt(0)
	s_barrier
	s_setprio 1
	s_waitcnt lgkmcnt(0)
	v_mfma_f32_16x16x32_bf16 v[60:63], v[144:147], v[186:189], v[60:63]
	v_mfma_f32_16x16x32_bf16 v[56:59], v[162:165], v[186:189], v[56:59]
	v_mfma_f32_16x16x32_bf16 v[44:47], v[144:147], v[196:199], v[44:47]
	v_mfma_f32_16x16x32_bf16 v[40:43], v[162:165], v[196:199], v[40:43]
	v_mfma_f32_16x16x32_bf16 v[28:31], v[144:147], v[204:207], v[28:31]
	v_mfma_f32_16x16x32_bf16 v[24:27], v[162:165], v[204:207], v[24:27]
	v_mfma_f32_16x16x32_bf16 v[12:15], v[144:147], v[212:215], v[12:15]
	v_mfma_f32_16x16x32_bf16 v[8:11], v[162:165], v[212:215], v[8:11]
	v_mfma_f32_16x16x32_bf16 v[60:63], v[158:161], v[190:193], v[60:63]
	v_mfma_f32_16x16x32_bf16 v[56:59], v[166:169], v[190:193], v[56:59]
	v_mfma_f32_16x16x32_bf16 v[44:47], v[158:161], v[200:203], v[44:47]
	v_mfma_f32_16x16x32_bf16 v[40:43], v[166:169], v[200:203], v[40:43]
	v_mfma_f32_16x16x32_bf16 v[28:31], v[158:161], v[208:211], v[28:31]
	v_mfma_f32_16x16x32_bf16 v[24:27], v[166:169], v[208:211], v[24:27]
	v_mfma_f32_16x16x32_bf16 v[12:15], v[158:161], v[216:219], v[12:15]
	v_mfma_f32_16x16x32_bf16 v[8:11], v[166:169], v[216:219], v[8:11]
	s_setprio 0
	s_setprio 1
	v_mfma_f32_16x16x32_bf16 v[52:55], v[170:173], v[186:189], v[52:55]
	v_mfma_f32_16x16x32_bf16 v[48:51], v[178:181], v[186:189], v[48:51]
	v_mfma_f32_16x16x32_bf16 v[36:39], v[170:173], v[196:199], v[36:39]
	v_mfma_f32_16x16x32_bf16 v[32:35], v[178:181], v[196:199], v[32:35]
	v_mfma_f32_16x16x32_bf16 v[20:23], v[170:173], v[204:207], v[20:23]
	v_mfma_f32_16x16x32_bf16 v[16:19], v[178:181], v[204:207], v[16:19]
	v_mfma_f32_16x16x32_bf16 v[4:7], v[170:173], v[212:215], v[4:7]
	v_mfma_f32_16x16x32_bf16 v[0:3], v[178:181], v[212:215], v[0:3]
	v_mfma_f32_16x16x32_bf16 v[52:55], v[174:177], v[190:193], v[52:55]
	v_mfma_f32_16x16x32_bf16 v[48:51], v[182:185], v[190:193], v[48:51]
	v_mfma_f32_16x16x32_bf16 v[36:39], v[174:177], v[200:203], v[36:39]
	v_mfma_f32_16x16x32_bf16 v[32:35], v[182:185], v[200:203], v[32:35]
	v_mfma_f32_16x16x32_bf16 v[20:23], v[174:177], v[208:211], v[20:23]
	v_mfma_f32_16x16x32_bf16 v[16:19], v[182:185], v[208:211], v[16:19]
	v_mfma_f32_16x16x32_bf16 v[4:7], v[174:177], v[216:219], v[4:7]
	v_mfma_f32_16x16x32_bf16 v[0:3], v[182:185], v[216:219], v[0:3]
	s_setprio 0
	s_barrier
	v_lshl_add_u64 v[224:225], v[224:225], 0, s[18:19]
	s_mov_b32 m0, s62
	s_nop 0
	global_load_lds_dwordx4 v[224:225], off
	s_add_i32 s82, s82, 2
	s_add_u32 s30, s30, 0x100
	s_addc_u32 s31, s31, 0
	s_add_u32 s80, s80, 0x100
	s_addc_u32 s81, s81, 0
	s_cmp_gt_u32 s82, 13
	s_cbranch_scc0 .LBB0_786
	s_and_b64 vcc, exec, s[20:21]
	s_cbranch_vccz .LBB0_789
	s_barrier

.LBB0_923:
	ds_read_b128 v[152:155], v148
	ds_read_b128 v[156:159], v148 offset:1024
	ds_read_b128 v[160:163], v148 offset:2048
	ds_read_b128 v[164:167], v148 offset:3072
	ds_read_b128 v[168:171], v149
	ds_read_b128 v[172:175], v149 offset:1024
	ds_read_b128 v[176:179], v149 offset:2048
	ds_read_b128 v[180:183], v149 offset:3072
	s_add_u32 s26, s24, 0x100
	s_addc_u32 s27, s25, 0
	s_cmp_eq_u32 s79, 8
	s_cselect_b32 s31, s21, s27
	s_cselect_b32 s30, s20, s26
	s_cselect_b32 s29, s23, s78
	s_cselect_b32 s28, s22, s73
	s_mov_b32 m0, s60
	v_lshl_add_u64 v[192:193], s[24:25], 0, v[138:139]
	ds_read_b128 v[184:187], v150
	ds_read_b128 v[188:191], v150 offset:1024
	ds_read_b128 v[196:199], v150 offset:2048
	ds_read_b128 v[200:203], v150 offset:3072
	ds_read_b128 v[204:207], v150 offset:4096
	ds_read_b128 v[208:211], v150 offset:5120
	ds_read_b128 v[212:215], v150 offset:6144
	ds_read_b128 v[216:219], v150 offset:7168
	global_load_lds_dwordx4 v[192:193], off
	v_lshl_add_u64 v[192:193], s[24:25], 0, v[140:141]
	s_add_i32 m0, s40, 0xe000
	s_nop 0
	global_load_lds_dwordx4 v[192:193], off
	s_waitcnt vmcnt(8)
	s_waitcnt lgkmcnt(0)
	s_barrier
	s_setprio 1
	s_waitcnt lgkmcnt(0)
	v_mfma_f32_16x16x32_bf16 v[124:127], v[152:155], v[184:187], v[124:127]
	v_mfma_f32_16x16x32_bf16 v[120:123], v[160:163], v[184:187], v[120:123]
	v_mfma_f32_16x16x32_bf16 v[108:111], v[152:155], v[196:199], v[108:111]
	v_mfma_f32_16x16x32_bf16 v[104:107], v[160:163], v[196:199], v[104:107]
	v_mfma_f32_16x16x32_bf16 v[92:95], v[152:155], v[204:207], v[92:95]
	v_mfma_f32_16x16x32_bf16 v[88:91], v[160:163], v[204:207], v[88:91]
	v_mfma_f32_16x16x32_bf16 v[76:79], v[152:155], v[212:215], v[76:79]
	v_mfma_f32_16x16x32_bf16 v[72:75], v[160:163], v[212:215], v[72:75]
	v_mfma_f32_16x16x32_bf16 v[124:127], v[156:159], v[188:191], v[124:127]
	v_mfma_f32_16x16x32_bf16 v[120:123], v[164:167], v[188:191], v[120:123]
	v_mfma_f32_16x16x32_bf16 v[108:111], v[156:159], v[200:203], v[108:111]
	v_mfma_f32_16x16x32_bf16 v[104:107], v[164:167], v[200:203], v[104:107]
	v_mfma_f32_16x16x32_bf16 v[92:95], v[156:159], v[208:211], v[92:95]
	v_mfma_f32_16x16x32_bf16 v[88:91], v[164:167], v[208:211], v[88:91]
	v_mfma_f32_16x16x32_bf16 v[76:79], v[156:159], v[216:219], v[76:79]
	v_mfma_f32_16x16x32_bf16 v[72:75], v[164:167], v[216:219], v[72:75]
	s_setprio 0
	s_setprio 1
	v_mfma_f32_16x16x32_bf16 v[116:119], v[168:171], v[184:187], v[116:119]
	v_mfma_f32_16x16x32_bf16 v[112:115], v[176:179], v[184:187], v[112:115]
	v_mfma_f32_16x16x32_bf16 v[100:103], v[168:171], v[196:199], v[100:103]
	v_mfma_f32_16x16x32_bf16 v[96:99], v[176:179], v[196:199], v[96:99]
	v_mfma_f32_16x16x32_bf16 v[84:87], v[168:171], v[204:207], v[84:87]
	v_mfma_f32_16x16x32_bf16 v[80:83], v[176:179], v[204:207], v[80:83]
	v_mfma_f32_16x16x32_bf16 v[68:71], v[168:171], v[212:215], v[68:71]
	v_mfma_f32_16x16x32_bf16 v[64:67], v[176:179], v[212:215], v[64:67]
	v_mfma_f32_16x16x32_bf16 v[116:119], v[172:175], v[188:191], v[116:119]
	v_mfma_f32_16x16x32_bf16 v[112:115], v[180:183], v[188:191], v[112:115]
	v_mfma_f32_16x16x32_bf16 v[100:103], v[172:175], v[200:203], v[100:103]
	v_mfma_f32_16x16x32_bf16 v[96:99], v[180:183], v[200:203], v[96:99]
	v_mfma_f32_16x16x32_bf16 v[84:87], v[172:175], v[208:211], v[84:87]
	v_mfma_f32_16x16x32_bf16 v[80:83], v[180:183], v[208:211], v[80:83]
	v_mfma_f32_16x16x32_bf16 v[68:71], v[172:175], v[216:219], v[68:71]
	v_mfma_f32_16x16x32_bf16 v[64:67], v[180:183], v[216:219], v[64:67]
	s_setprio 0
	s_barrier
	s_add_i32 s24, s58, s39
	v_lshl_add_u64 v[192:193], s[28:29], 0, v[132:133]
	s_mov_b32 m0, s24
	ds_read_b128 v[184:187], v150 offset:16384
	ds_read_b128 v[188:191], v150 offset:17408
	ds_read_b128 v[196:199], v150 offset:18432
	ds_read_b128 v[200:203], v150 offset:19456
	ds_read_b128 v[204:207], v150 offset:20480
	ds_read_b128 v[208:211], v150 offset:21504
	ds_read_b128 v[212:215], v150 offset:22528
	ds_read_b128 v[216:219], v150 offset:23552
	global_load_lds_dwordx4 v[192:193], off
	s_add_i32 m0, s24, 0x2000
	s_add_u32 s24, s28, 0x30000
	v_lshl_add_u64 v[220:221], s[28:29], 0, v[128:129]
	s_addc_u32 s25, s29, 0
	s_add_i32 s80, s59, s39
	global_load_lds_dwordx4 v[220:221], off
	v_lshl_add_u64 v[222:223], s[24:25], 0, v[132:133]
	s_mov_b32 m0, s80
	v_lshl_add_u64 v[224:225], s[30:31], 0, v[130:131]
	global_load_lds_dwordx4 v[222:223], off
	v_lshl_add_u64 v[222:223], s[24:25], 0, v[128:129]
	s_add_i32 m0, s80, 0x2000
	s_nop 0
	global_load_lds_dwordx4 v[222:223], off
	v_lshl_add_u64 v[222:223], s[30:31], 0, v[134:135]
	s_mov_b32 m0, s40
	s_nop 0
	global_load_lds_dwordx4 v[222:223], off
	s_waitcnt vmcnt(7)
	s_waitcnt lgkmcnt(0)
	s_barrier
	s_setprio 1
	s_waitcnt lgkmcnt(0)
	v_mfma_f32_16x16x32_bf16 v[60:63], v[152:155], v[184:187], v[60:63]
	v_mfma_f32_16x16x32_bf16 v[56:59], v[160:163], v[184:187], v[56:59]
	v_mfma_f32_16x16x32_bf16 v[44:47], v[152:155], v[196:199], v[44:47]
	v_mfma_f32_16x16x32_bf16 v[40:43], v[160:163], v[196:199], v[40:43]
	v_mfma_f32_16x16x32_bf16 v[28:31], v[152:155], v[204:207], v[28:31]
	v_mfma_f32_16x16x32_bf16 v[24:27], v[160:163], v[204:207], v[24:27]
	v_mfma_f32_16x16x32_bf16 v[12:15], v[152:155], v[212:215], v[12:15]
	v_mfma_f32_16x16x32_bf16 v[8:11], v[160:163], v[212:215], v[8:11]
	v_mfma_f32_16x16x32_bf16 v[60:63], v[156:159], v[188:191], v[60:63]
	v_mfma_f32_16x16x32_bf16 v[56:59], v[164:167], v[188:191], v[56:59]
	v_mfma_f32_16x16x32_bf16 v[44:47], v[156:159], v[200:203], v[44:47]
	v_mfma_f32_16x16x32_bf16 v[40:43], v[164:167], v[200:203], v[40:43]
	v_mfma_f32_16x16x32_bf16 v[28:31], v[156:159], v[208:211], v[28:31]
	v_mfma_f32_16x16x32_bf16 v[24:27], v[164:167], v[208:211], v[24:27]
	v_mfma_f32_16x16x32_bf16 v[12:15], v[156:159], v[216:219], v[12:15]
	v_mfma_f32_16x16x32_bf16 v[8:11], v[164:167], v[216:219], v[8:11]
	s_setprio 0
	s_setprio 1
	v_mfma_f32_16x16x32_bf16 v[52:55], v[168:171], v[184:187], v[52:55]
	v_mfma_f32_16x16x32_bf16 v[48:51], v[176:179], v[184:187], v[48:51]
	v_mfma_f32_16x16x32_bf16 v[36:39], v[168:171], v[196:199], v[36:39]
	v_mfma_f32_16x16x32_bf16 v[32:35], v[176:179], v[196:199], v[32:35]
	v_mfma_f32_16x16x32_bf16 v[20:23], v[168:171], v[204:207], v[20:23]
	v_mfma_f32_16x16x32_bf16 v[16:19], v[176:179], v[204:207], v[16:19]
	v_mfma_f32_16x16x32_bf16 v[4:7], v[168:171], v[212:215], v[4:7]
	v_mfma_f32_16x16x32_bf16 v[0:3], v[176:179], v[212:215], v[0:3]
	v_mfma_f32_16x16x32_bf16 v[52:55], v[172:175], v[188:191], v[52:55]
	v_mfma_f32_16x16x32_bf16 v[48:51], v[180:183], v[188:191], v[48:51]
	v_mfma_f32_16x16x32_bf16 v[36:39], v[172:175], v[200:203], v[36:39]
	v_mfma_f32_16x16x32_bf16 v[32:35], v[180:183], v[200:203], v[32:35]
	v_mfma_f32_16x16x32_bf16 v[20:23], v[172:175], v[208:211], v[20:23]
	v_mfma_f32_16x16x32_bf16 v[16:19], v[180:183], v[208:211], v[16:19]
	v_mfma_f32_16x16x32_bf16 v[4:7], v[172:175], v[216:219], v[4:7]
	v_mfma_f32_16x16x32_bf16 v[0:3], v[180:183], v[216:219], v[0:3]
	s_setprio 0
	s_barrier
	s_add_i32 s80, 0, 0x18000
	v_add_u32_e32 v151, s80, v142
	s_add_i32 s81, 0, 0x1c000
	ds_read_b128 v[152:155], v151
	ds_read_b128 v[156:159], v151 offset:1024
	ds_read_b128 v[160:163], v151 offset:2048
	ds_read_b128 v[164:167], v151 offset:3072
	v_add_u32_e32 v151, s81, v142
	ds_read_b128 v[168:171], v151
	ds_read_b128 v[172:175], v151 offset:1024
	ds_read_b128 v[176:179], v151 offset:2048
	ds_read_b128 v[180:183], v151 offset:3072
	s_add_u32 s24, s30, 0x30000
	s_addc_u32 s25, s31, 0
	v_lshl_add_u64 v[226:227], s[24:25], 0, v[134:135]
	ds_read_b128 v[184:187], v150 offset:32768
	ds_read_b128 v[188:191], v150 offset:33792
	ds_read_b128 v[196:199], v150 offset:34816
	ds_read_b128 v[200:203], v150 offset:35840
	ds_read_b128 v[204:207], v150 offset:36864
	ds_read_b128 v[208:211], v150 offset:37888
	ds_read_b128 v[212:215], v150 offset:38912
	ds_read_b128 v[216:219], v150 offset:39936
	s_mov_b32 m0, s41
	s_nop 0
	global_load_lds_dwordx4 v[224:225], off
	s_mov_b32 m0, s42
	s_nop 0
	global_load_lds_dwordx4 v[226:227], off
	v_lshl_add_u64 v[226:227], s[24:25], 0, v[130:131]
	s_mov_b32 m0, s43
	s_nop 0
	global_load_lds_dwordx4 v[226:227], off
	s_waitcnt vmcnt(8)
	s_waitcnt lgkmcnt(0)
	s_barrier
	s_setprio 1
	s_waitcnt lgkmcnt(0)
	v_mfma_f32_16x16x32_bf16 v[124:127], v[152:155], v[184:187], v[124:127]
	v_mfma_f32_16x16x32_bf16 v[120:123], v[160:163], v[184:187], v[120:123]
	v_mfma_f32_16x16x32_bf16 v[108:111], v[152:155], v[196:199], v[108:111]
	v_mfma_f32_16x16x32_bf16 v[104:107], v[160:163], v[196:199], v[104:107]
	v_mfma_f32_16x16x32_bf16 v[92:95], v[152:155], v[204:207], v[92:95]
	v_mfma_f32_16x16x32_bf16 v[88:91], v[160:163], v[204:207], v[88:91]
	v_mfma_f32_16x16x32_bf16 v[76:79], v[152:155], v[212:215], v[76:79]
	v_mfma_f32_16x16x32_bf16 v[72:75], v[160:163], v[212:215], v[72:75]
	v_mfma_f32_16x16x32_bf16 v[124:127], v[156:159], v[188:191], v[124:127]
	v_mfma_f32_16x16x32_bf16 v[120:123], v[164:167], v[188:191], v[120:123]
	v_mfma_f32_16x16x32_bf16 v[108:111], v[156:159], v[200:203], v[108:111]
	v_mfma_f32_16x16x32_bf16 v[104:107], v[164:167], v[200:203], v[104:107]
	v_mfma_f32_16x16x32_bf16 v[92:95], v[156:159], v[208:211], v[92:95]
	v_mfma_f32_16x16x32_bf16 v[88:91], v[164:167], v[208:211], v[88:91]
	v_mfma_f32_16x16x32_bf16 v[76:79], v[156:159], v[216:219], v[76:79]
	v_mfma_f32_16x16x32_bf16 v[72:75], v[164:167], v[216:219], v[72:75]
	s_setprio 0
	s_setprio 1
	v_mfma_f32_16x16x32_bf16 v[116:119], v[168:171], v[184:187], v[116:119]
	v_mfma_f32_16x16x32_bf16 v[112:115], v[176:179], v[184:187], v[112:115]
	v_mfma_f32_16x16x32_bf16 v[100:103], v[168:171], v[196:199], v[100:103]
	v_mfma_f32_16x16x32_bf16 v[96:99], v[176:179], v[196:199], v[96:99]
	v_mfma_f32_16x16x32_bf16 v[84:87], v[168:171], v[204:207], v[84:87]
	v_mfma_f32_16x16x32_bf16 v[80:83], v[176:179], v[204:207], v[80:83]
	v_mfma_f32_16x16x32_bf16 v[68:71], v[168:171], v[212:215], v[68:71]
	v_mfma_f32_16x16x32_bf16 v[64:67], v[176:179], v[212:215], v[64:67]
	v_mfma_f32_16x16x32_bf16 v[116:119], v[172:175], v[188:191], v[116:119]
	v_mfma_f32_16x16x32_bf16 v[112:115], v[180:183], v[188:191], v[112:115]
	v_mfma_f32_16x16x32_bf16 v[100:103], v[172:175], v[200:203], v[100:103]
	v_mfma_f32_16x16x32_bf16 v[96:99], v[180:183], v[200:203], v[96:99]
	v_mfma_f32_16x16x32_bf16 v[84:87], v[172:175], v[208:211], v[84:87]
	v_mfma_f32_16x16x32_bf16 v[80:83], v[180:183], v[208:211], v[80:83]
	v_mfma_f32_16x16x32_bf16 v[68:71], v[172:175], v[216:219], v[68:71]
	v_mfma_f32_16x16x32_bf16 v[64:67], v[180:183], v[216:219], v[64:67]
	s_setprio 0
	s_barrier
	s_add_i32 s24, s80, s39
	v_lshl_add_u64 v[192:193], v[192:193], 0, s[16:17]
	s_mov_b32 m0, s24
	ds_read_b128 v[184:187], v150 offset:49152
	ds_read_b128 v[188:191], v150 offset:50176
	ds_read_b128 v[196:199], v150 offset:51200
	ds_read_b128 v[200:203], v150 offset:52224
	ds_read_b128 v[204:207], v150 offset:53248
	ds_read_b128 v[208:211], v150 offset:54272
	ds_read_b128 v[212:215], v150 offset:55296
	ds_read_b128 v[216:219], v150 offset:56320
	global_load_lds_dwordx4 v[192:193], off
	s_add_i32 m0, s24, 0x2000
	s_add_u32 s24, s28, 0x30080
	v_lshl_add_u64 v[192:193], v[220:221], 0, s[16:17]
	s_addc_u32 s25, s29, 0
	s_add_i32 s28, s81, s39
	global_load_lds_dwordx4 v[192:193], off
	v_lshl_add_u64 v[192:193], s[24:25], 0, v[132:133]
	s_mov_b32 m0, s28
	s_nop 0
	global_load_lds_dwordx4 v[192:193], off
	v_lshl_add_u64 v[192:193], s[24:25], 0, v[128:129]
	s_add_i32 m0, s28, 0x2000
	s_nop 0
	global_load_lds_dwordx4 v[192:193], off
	v_lshl_add_u64 v[192:193], v[222:223], 0, s[16:17]
	s_mov_b32 m0, s45
	s_nop 0
	global_load_lds_dwordx4 v[192:193], off
	s_waitcnt vmcnt(7)
	s_waitcnt lgkmcnt(0)
	s_barrier
	s_setprio 1
	s_waitcnt lgkmcnt(0)
	v_mfma_f32_16x16x32_bf16 v[60:63], v[152:155], v[184:187], v[60:63]
	v_mfma_f32_16x16x32_bf16 v[56:59], v[160:163], v[184:187], v[56:59]
	v_mfma_f32_16x16x32_bf16 v[44:47], v[152:155], v[196:199], v[44:47]
	v_mfma_f32_16x16x32_bf16 v[40:43], v[160:163], v[196:199], v[40:43]
	v_mfma_f32_16x16x32_bf16 v[28:31], v[152:155], v[204:207], v[28:31]
	v_mfma_f32_16x16x32_bf16 v[24:27], v[160:163], v[204:207], v[24:27]
	v_mfma_f32_16x16x32_bf16 v[12:15], v[152:155], v[212:215], v[12:15]
	v_mfma_f32_16x16x32_bf16 v[8:11], v[160:163], v[212:215], v[8:11]
	v_mfma_f32_16x16x32_bf16 v[60:63], v[156:159], v[188:191], v[60:63]
	v_mfma_f32_16x16x32_bf16 v[56:59], v[164:167], v[188:191], v[56:59]
	v_mfma_f32_16x16x32_bf16 v[44:47], v[156:159], v[200:203], v[44:47]
	v_mfma_f32_16x16x32_bf16 v[40:43], v[164:167], v[200:203], v[40:43]
	v_mfma_f32_16x16x32_bf16 v[28:31], v[156:159], v[208:211], v[28:31]
	v_mfma_f32_16x16x32_bf16 v[24:27], v[164:167], v[208:211], v[24:27]
	v_mfma_f32_16x16x32_bf16 v[12:15], v[156:159], v[216:219], v[12:15]
	v_mfma_f32_16x16x32_bf16 v[8:11], v[164:167], v[216:219], v[8:11]
	s_setprio 0
	s_setprio 1
	v_mfma_f32_16x16x32_bf16 v[52:55], v[168:171], v[184:187], v[52:55]
	v_mfma_f32_16x16x32_bf16 v[48:51], v[176:179], v[184:187], v[48:51]
	v_mfma_f32_16x16x32_bf16 v[36:39], v[168:171], v[196:199], v[36:39]
	v_mfma_f32_16x16x32_bf16 v[32:35], v[176:179], v[196:199], v[32:35]
	v_mfma_f32_16x16x32_bf16 v[20:23], v[168:171], v[204:207], v[20:23]
	v_mfma_f32_16x16x32_bf16 v[16:19], v[176:179], v[204:207], v[16:19]
	v_mfma_f32_16x16x32_bf16 v[4:7], v[168:171], v[212:215], v[4:7]
	v_mfma_f32_16x16x32_bf16 v[0:3], v[176:179], v[212:215], v[0:3]
	v_mfma_f32_16x16x32_bf16 v[52:55], v[172:175], v[188:191], v[52:55]
	v_mfma_f32_16x16x32_bf16 v[48:51], v[180:183], v[188:191], v[48:51]
	v_mfma_f32_16x16x32_bf16 v[36:39], v[172:175], v[200:203], v[36:39]
	v_mfma_f32_16x16x32_bf16 v[32:35], v[180:183], v[200:203], v[32:35]
	v_mfma_f32_16x16x32_bf16 v[20:23], v[172:175], v[208:211], v[20:23]
	v_mfma_f32_16x16x32_bf16 v[16:19], v[180:183], v[208:211], v[16:19]
	v_mfma_f32_16x16x32_bf16 v[4:7], v[172:175], v[216:219], v[4:7]
	v_mfma_f32_16x16x32_bf16 v[0:3], v[180:183], v[216:219], v[0:3]
	s_setprio 0
	s_barrier
	v_lshl_add_u64 v[224:225], v[224:225], 0, s[16:17]
	s_mov_b32 m0, s50
	s_nop 0
	global_load_lds_dwordx4 v[224:225], off
	s_add_i32 s79, s79, 2
	s_add_u32 s73, s73, 0x100
	s_addc_u32 s78, s78, 0
	s_cmp_gt_u32 s79, 9
	s_mov_b64 s[24:25], s[26:27]
	s_cbranch_scc0 .LBB0_923
	s_and_b64 vcc, exec, s[18:19]
	s_cbranch_vccz .LBB0_926
	s_barrier

.LBB0_947:
	ds_read_b128 v[144:147], v153
	ds_read_b128 v[158:161], v153 offset:1024
	ds_read_b128 v[162:165], v153 offset:2048
	ds_read_b128 v[166:169], v153 offset:3072
	ds_read_b128 v[170:173], v154
	ds_read_b128 v[174:177], v154 offset:1024
	ds_read_b128 v[178:181], v154 offset:2048
	ds_read_b128 v[182:185], v154 offset:3072
	s_add_u32 s36, s34, 0xfffc0080
	s_addc_u32 s37, s35, -1
	s_cmp_eq_u32 s85, 12
	s_cselect_b32 s39, s27, s37
	s_cselect_b32 s38, s81, s36
	s_cselect_b32 s37, s25, s84
	s_cselect_b32 s36, s82, s83
	v_lshl_add_u64 v[148:149], s[34:35], 0, v[136:137]
	s_add_i32 m0, s59, 0xc000
	ds_read_b128 v[186:189], v155
	ds_read_b128 v[190:193], v155 offset:1024
	ds_read_b128 v[196:199], v155 offset:2048
	ds_read_b128 v[200:203], v155 offset:3072
	ds_read_b128 v[204:207], v155 offset:4096
	ds_read_b128 v[208:211], v155 offset:5120
	ds_read_b128 v[212:215], v155 offset:6144
	ds_read_b128 v[216:219], v155 offset:7168
	global_load_lds_dwordx4 v[148:149], off
	v_lshl_add_u64 v[148:149], s[34:35], 0, v[138:139]
	s_add_i32 m0, s59, 0xe000
	s_nop 0
	global_load_lds_dwordx4 v[148:149], off
	s_waitcnt vmcnt(8)
	s_waitcnt lgkmcnt(0)
	s_barrier
	s_setprio 1
	s_waitcnt lgkmcnt(0)
	v_mfma_f32_16x16x32_bf16 v[124:127], v[144:147], v[186:189], v[124:127]
	v_mfma_f32_16x16x32_bf16 v[120:123], v[162:165], v[186:189], v[120:123]
	v_mfma_f32_16x16x32_bf16 v[108:111], v[144:147], v[196:199], v[108:111]
	v_mfma_f32_16x16x32_bf16 v[104:107], v[162:165], v[196:199], v[104:107]
	v_mfma_f32_16x16x32_bf16 v[92:95], v[144:147], v[204:207], v[92:95]
	v_mfma_f32_16x16x32_bf16 v[88:91], v[162:165], v[204:207], v[88:91]
	v_mfma_f32_16x16x32_bf16 v[76:79], v[144:147], v[212:215], v[76:79]
	v_mfma_f32_16x16x32_bf16 v[72:75], v[162:165], v[212:215], v[72:75]
	v_mfma_f32_16x16x32_bf16 v[124:127], v[158:161], v[190:193], v[124:127]
	v_mfma_f32_16x16x32_bf16 v[120:123], v[166:169], v[190:193], v[120:123]
	v_mfma_f32_16x16x32_bf16 v[108:111], v[158:161], v[200:203], v[108:111]
	v_mfma_f32_16x16x32_bf16 v[104:107], v[166:169], v[200:203], v[104:107]
	v_mfma_f32_16x16x32_bf16 v[92:95], v[158:161], v[208:211], v[92:95]
	v_mfma_f32_16x16x32_bf16 v[88:91], v[166:169], v[208:211], v[88:91]
	v_mfma_f32_16x16x32_bf16 v[76:79], v[158:161], v[216:219], v[76:79]
	v_mfma_f32_16x16x32_bf16 v[72:75], v[166:169], v[216:219], v[72:75]
	s_setprio 0
	s_setprio 1
	v_mfma_f32_16x16x32_bf16 v[116:119], v[170:173], v[186:189], v[116:119]
	v_mfma_f32_16x16x32_bf16 v[112:115], v[178:181], v[186:189], v[112:115]
	v_mfma_f32_16x16x32_bf16 v[100:103], v[170:173], v[196:199], v[100:103]
	v_mfma_f32_16x16x32_bf16 v[96:99], v[178:181], v[196:199], v[96:99]
	v_mfma_f32_16x16x32_bf16 v[84:87], v[170:173], v[204:207], v[84:87]
	v_mfma_f32_16x16x32_bf16 v[80:83], v[178:181], v[204:207], v[80:83]
	v_mfma_f32_16x16x32_bf16 v[68:71], v[170:173], v[212:215], v[68:71]
	v_mfma_f32_16x16x32_bf16 v[64:67], v[178:181], v[212:215], v[64:67]
	v_mfma_f32_16x16x32_bf16 v[116:119], v[174:177], v[190:193], v[116:119]
	v_mfma_f32_16x16x32_bf16 v[112:115], v[182:185], v[190:193], v[112:115]
	v_mfma_f32_16x16x32_bf16 v[100:103], v[174:177], v[200:203], v[100:103]
	v_mfma_f32_16x16x32_bf16 v[96:99], v[182:185], v[200:203], v[96:99]
	v_mfma_f32_16x16x32_bf16 v[84:87], v[174:177], v[208:211], v[84:87]
	v_mfma_f32_16x16x32_bf16 v[80:83], v[182:185], v[208:211], v[80:83]
	v_mfma_f32_16x16x32_bf16 v[68:71], v[174:177], v[216:219], v[68:71]
	v_mfma_f32_16x16x32_bf16 v[64:67], v[182:185], v[216:219], v[64:67]
	s_setprio 0
	s_barrier
	s_add_i32 s86, s73, s58
	v_lshl_add_u64 v[148:149], s[36:37], 0, v[130:131]
	s_mov_b32 m0, s86
	ds_read_b128 v[186:189], v155 offset:16384
	ds_read_b128 v[190:193], v155 offset:17408
	ds_read_b128 v[196:199], v155 offset:18432
	ds_read_b128 v[200:203], v155 offset:19456
	ds_read_b128 v[204:207], v155 offset:20480
	ds_read_b128 v[208:211], v155 offset:21504
	ds_read_b128 v[212:215], v155 offset:22528
	ds_read_b128 v[216:219], v155 offset:23552
	global_load_lds_dwordx4 v[148:149], off
	s_add_i32 m0, s86, 0x2000
	s_add_u32 s86, s36, 0x40000
	v_lshl_add_u64 v[220:221], s[36:37], 0, v[134:135]
	s_addc_u32 s87, s37, 0
	s_add_i32 s88, s78, s58
	global_load_lds_dwordx4 v[220:221], off
	v_lshl_add_u64 v[222:223], s[86:87], 0, v[130:131]
	s_mov_b32 m0, s88
	v_lshl_add_u64 v[224:225], s[38:39], 0, v[132:133]
	global_load_lds_dwordx4 v[222:223], off
	v_lshl_add_u64 v[222:223], s[86:87], 0, v[134:135]
	s_add_i32 m0, s88, 0x2000
	s_nop 0
	global_load_lds_dwordx4 v[222:223], off
	v_lshl_add_u64 v[222:223], s[38:39], 0, v[128:129]
	s_mov_b32 m0, s59
	s_nop 0
	global_load_lds_dwordx4 v[222:223], off
	s_waitcnt vmcnt(7)
	s_waitcnt lgkmcnt(0)
	s_barrier
	s_setprio 1
	s_waitcnt lgkmcnt(0)
	v_mfma_f32_16x16x32_bf16 v[60:63], v[144:147], v[186:189], v[60:63]
	v_mfma_f32_16x16x32_bf16 v[56:59], v[162:165], v[186:189], v[56:59]
	v_mfma_f32_16x16x32_bf16 v[44:47], v[144:147], v[196:199], v[44:47]
	v_mfma_f32_16x16x32_bf16 v[40:43], v[162:165], v[196:199], v[40:43]
	v_mfma_f32_16x16x32_bf16 v[28:31], v[144:147], v[204:207], v[28:31]
	v_mfma_f32_16x16x32_bf16 v[24:27], v[162:165], v[204:207], v[24:27]
	v_mfma_f32_16x16x32_bf16 v[12:15], v[144:147], v[212:215], v[12:15]
	v_mfma_f32_16x16x32_bf16 v[8:11], v[162:165], v[212:215], v[8:11]
	v_mfma_f32_16x16x32_bf16 v[60:63], v[158:161], v[190:193], v[60:63]
	v_mfma_f32_16x16x32_bf16 v[56:59], v[166:169], v[190:193], v[56:59]
	v_mfma_f32_16x16x32_bf16 v[44:47], v[158:161], v[200:203], v[44:47]
	v_mfma_f32_16x16x32_bf16 v[40:43], v[166:169], v[200:203], v[40:43]
	v_mfma_f32_16x16x32_bf16 v[28:31], v[158:161], v[208:211], v[28:31]
	v_mfma_f32_16x16x32_bf16 v[24:27], v[166:169], v[208:211], v[24:27]
	v_mfma_f32_16x16x32_bf16 v[12:15], v[158:161], v[216:219], v[12:15]
	v_mfma_f32_16x16x32_bf16 v[8:11], v[166:169], v[216:219], v[8:11]
	s_setprio 0
	s_setprio 1
	v_mfma_f32_16x16x32_bf16 v[52:55], v[170:173], v[186:189], v[52:55]
	v_mfma_f32_16x16x32_bf16 v[48:51], v[178:181], v[186:189], v[48:51]
	v_mfma_f32_16x16x32_bf16 v[36:39], v[170:173], v[196:199], v[36:39]
	v_mfma_f32_16x16x32_bf16 v[32:35], v[178:181], v[196:199], v[32:35]
	v_mfma_f32_16x16x32_bf16 v[20:23], v[170:173], v[204:207], v[20:23]
	v_mfma_f32_16x16x32_bf16 v[16:19], v[178:181], v[204:207], v[16:19]
	v_mfma_f32_16x16x32_bf16 v[4:7], v[170:173], v[212:215], v[4:7]
	v_mfma_f32_16x16x32_bf16 v[0:3], v[178:181], v[212:215], v[0:3]
	v_mfma_f32_16x16x32_bf16 v[52:55], v[174:177], v[190:193], v[52:55]
	v_mfma_f32_16x16x32_bf16 v[48:51], v[182:185], v[190:193], v[48:51]
	v_mfma_f32_16x16x32_bf16 v[36:39], v[174:177], v[200:203], v[36:39]
	v_mfma_f32_16x16x32_bf16 v[32:35], v[182:185], v[200:203], v[32:35]
	v_mfma_f32_16x16x32_bf16 v[20:23], v[174:177], v[208:211], v[20:23]
	v_mfma_f32_16x16x32_bf16 v[16:19], v[182:185], v[208:211], v[16:19]
	v_mfma_f32_16x16x32_bf16 v[4:7], v[174:177], v[216:219], v[4:7]
	v_mfma_f32_16x16x32_bf16 v[0:3], v[182:185], v[216:219], v[0:3]
	s_setprio 0
	s_barrier
	s_add_i32 s86, 0, 0x18000
	v_add_u32_e32 v157, s86, v151
	s_add_i32 s87, 0, 0x1c000
	ds_read_b128 v[144:147], v157
	ds_read_b128 v[158:161], v157 offset:1024
	ds_read_b128 v[162:165], v157 offset:2048
	ds_read_b128 v[166:169], v157 offset:3072
	v_add_u32_e32 v157, s87, v151
	ds_read_b128 v[170:173], v157
	ds_read_b128 v[174:177], v157 offset:1024
	ds_read_b128 v[178:181], v157 offset:2048
	ds_read_b128 v[182:185], v157 offset:3072
	s_add_u32 s38, s38, 0x40000
	s_addc_u32 s39, s39, 0
	v_lshl_add_u64 v[226:227], s[38:39], 0, v[128:129]
	ds_read_b128 v[186:189], v155 offset:32768
	ds_read_b128 v[190:193], v155 offset:33792
	ds_read_b128 v[196:199], v155 offset:34816
	ds_read_b128 v[200:203], v155 offset:35840
	ds_read_b128 v[204:207], v155 offset:36864
	ds_read_b128 v[208:211], v155 offset:37888
	ds_read_b128 v[212:215], v155 offset:38912
	ds_read_b128 v[216:219], v155 offset:39936
	s_mov_b32 m0, s60
	s_nop 0
	global_load_lds_dwordx4 v[224:225], off
	s_mov_b32 m0, s61
	s_nop 0
	global_load_lds_dwordx4 v[226:227], off
	v_lshl_add_u64 v[226:227], s[38:39], 0, v[132:133]
	s_mov_b32 m0, s62
	s_nop 0
	global_load_lds_dwordx4 v[226:227], off
	s_waitcnt vmcnt(8)
	s_waitcnt lgkmcnt(0)
	s_barrier
	s_setprio 1
	s_waitcnt lgkmcnt(0)
	v_mfma_f32_16x16x32_bf16 v[124:127], v[144:147], v[186:189], v[124:127]
	v_mfma_f32_16x16x32_bf16 v[120:123], v[162:165], v[186:189], v[120:123]
	v_mfma_f32_16x16x32_bf16 v[108:111], v[144:147], v[196:199], v[108:111]
	v_mfma_f32_16x16x32_bf16 v[104:107], v[162:165], v[196:199], v[104:107]
	v_mfma_f32_16x16x32_bf16 v[92:95], v[144:147], v[204:207], v[92:95]
	v_mfma_f32_16x16x32_bf16 v[88:91], v[162:165], v[204:207], v[88:91]
	v_mfma_f32_16x16x32_bf16 v[76:79], v[144:147], v[212:215], v[76:79]
	v_mfma_f32_16x16x32_bf16 v[72:75], v[162:165], v[212:215], v[72:75]
	v_mfma_f32_16x16x32_bf16 v[124:127], v[158:161], v[190:193], v[124:127]
	v_mfma_f32_16x16x32_bf16 v[120:123], v[166:169], v[190:193], v[120:123]
	v_mfma_f32_16x16x32_bf16 v[108:111], v[158:161], v[200:203], v[108:111]
	v_mfma_f32_16x16x32_bf16 v[104:107], v[166:169], v[200:203], v[104:107]
	v_mfma_f32_16x16x32_bf16 v[92:95], v[158:161], v[208:211], v[92:95]
	v_mfma_f32_16x16x32_bf16 v[88:91], v[166:169], v[208:211], v[88:91]
	v_mfma_f32_16x16x32_bf16 v[76:79], v[158:161], v[216:219], v[76:79]
	v_mfma_f32_16x16x32_bf16 v[72:75], v[166:169], v[216:219], v[72:75]
	s_setprio 0
	s_setprio 1
	v_mfma_f32_16x16x32_bf16 v[116:119], v[170:173], v[186:189], v[116:119]
	v_mfma_f32_16x16x32_bf16 v[112:115], v[178:181], v[186:189], v[112:115]
	v_mfma_f32_16x16x32_bf16 v[100:103], v[170:173], v[196:199], v[100:103]
	v_mfma_f32_16x16x32_bf16 v[96:99], v[178:181], v[196:199], v[96:99]
	v_mfma_f32_16x16x32_bf16 v[84:87], v[170:173], v[204:207], v[84:87]
	v_mfma_f32_16x16x32_bf16 v[80:83], v[178:181], v[204:207], v[80:83]
	v_mfma_f32_16x16x32_bf16 v[68:71], v[170:173], v[212:215], v[68:71]
	v_mfma_f32_16x16x32_bf16 v[64:67], v[178:181], v[212:215], v[64:67]
	v_mfma_f32_16x16x32_bf16 v[116:119], v[174:177], v[190:193], v[116:119]
	v_mfma_f32_16x16x32_bf16 v[112:115], v[182:185], v[190:193], v[112:115]
	v_mfma_f32_16x16x32_bf16 v[100:103], v[174:177], v[200:203], v[100:103]
	v_mfma_f32_16x16x32_bf16 v[96:99], v[182:185], v[200:203], v[96:99]
	v_mfma_f32_16x16x32_bf16 v[84:87], v[174:177], v[208:211], v[84:87]
	v_mfma_f32_16x16x32_bf16 v[80:83], v[182:185], v[208:211], v[80:83]
	v_mfma_f32_16x16x32_bf16 v[68:71], v[174:177], v[216:219], v[68:71]
	v_mfma_f32_16x16x32_bf16 v[64:67], v[182:185], v[216:219], v[64:67]
	s_setprio 0
	s_barrier
	s_add_i32 s38, s86, s58
	v_lshl_add_u64 v[148:149], v[148:149], 0, s[20:21]
	s_mov_b32 m0, s38
	ds_read_b128 v[186:189], v155 offset:49152
	ds_read_b128 v[190:193], v155 offset:50176
	ds_read_b128 v[196:199], v155 offset:51200
	ds_read_b128 v[200:203], v155 offset:52224
	ds_read_b128 v[204:207], v155 offset:53248
	ds_read_b128 v[208:211], v155 offset:54272
	ds_read_b128 v[212:215], v155 offset:55296
	ds_read_b128 v[216:219], v155 offset:56320
	global_load_lds_dwordx4 v[148:149], off
	s_add_i32 m0, s38, 0x2000
	s_add_u32 s36, s36, 0x40080
	v_lshl_add_u64 v[148:149], v[220:221], 0, s[20:21]
	s_addc_u32 s37, s37, 0
	s_add_i32 s38, s87, s58
	global_load_lds_dwordx4 v[148:149], off
	v_lshl_add_u64 v[148:149], s[36:37], 0, v[130:131]
	s_mov_b32 m0, s38
	s_nop 0
	global_load_lds_dwordx4 v[148:149], off
	v_lshl_add_u64 v[148:149], s[36:37], 0, v[134:135]
	s_add_i32 m0, s38, 0x2000
	s_nop 0
	global_load_lds_dwordx4 v[148:149], off
	v_lshl_add_u64 v[148:149], v[222:223], 0, s[20:21]
	s_mov_b32 m0, s70
	s_nop 0
	global_load_lds_dwordx4 v[148:149], off
	s_waitcnt vmcnt(7)
	s_waitcnt lgkmcnt(0)
	s_barrier
	s_setprio 1
	s_waitcnt lgkmcnt(0)
	v_mfma_f32_16x16x32_bf16 v[60:63], v[144:147], v[186:189], v[60:63]
	v_mfma_f32_16x16x32_bf16 v[56:59], v[162:165], v[186:189], v[56:59]
	v_mfma_f32_16x16x32_bf16 v[44:47], v[144:147], v[196:199], v[44:47]
	v_mfma_f32_16x16x32_bf16 v[40:43], v[162:165], v[196:199], v[40:43]
	v_mfma_f32_16x16x32_bf16 v[28:31], v[144:147], v[204:207], v[28:31]
	v_mfma_f32_16x16x32_bf16 v[24:27], v[162:165], v[204:207], v[24:27]
	v_mfma_f32_16x16x32_bf16 v[12:15], v[144:147], v[212:215], v[12:15]
	v_mfma_f32_16x16x32_bf16 v[8:11], v[162:165], v[212:215], v[8:11]
	v_mfma_f32_16x16x32_bf16 v[60:63], v[158:161], v[190:193], v[60:63]
	v_mfma_f32_16x16x32_bf16 v[56:59], v[166:169], v[190:193], v[56:59]
	v_mfma_f32_16x16x32_bf16 v[44:47], v[158:161], v[200:203], v[44:47]
	v_mfma_f32_16x16x32_bf16 v[40:43], v[166:169], v[200:203], v[40:43]
	v_mfma_f32_16x16x32_bf16 v[28:31], v[158:161], v[208:211], v[28:31]
	v_mfma_f32_16x16x32_bf16 v[24:27], v[166:169], v[208:211], v[24:27]
	v_mfma_f32_16x16x32_bf16 v[12:15], v[158:161], v[216:219], v[12:15]
	v_mfma_f32_16x16x32_bf16 v[8:11], v[166:169], v[216:219], v[8:11]
	s_setprio 0
	s_setprio 1
	v_mfma_f32_16x16x32_bf16 v[52:55], v[170:173], v[186:189], v[52:55]
	v_mfma_f32_16x16x32_bf16 v[48:51], v[178:181], v[186:189], v[48:51]
	v_mfma_f32_16x16x32_bf16 v[36:39], v[170:173], v[196:199], v[36:39]
	v_mfma_f32_16x16x32_bf16 v[32:35], v[178:181], v[196:199], v[32:35]
	v_mfma_f32_16x16x32_bf16 v[20:23], v[170:173], v[204:207], v[20:23]
	v_mfma_f32_16x16x32_bf16 v[16:19], v[178:181], v[204:207], v[16:19]
	v_mfma_f32_16x16x32_bf16 v[4:7], v[170:173], v[212:215], v[4:7]
	v_mfma_f32_16x16x32_bf16 v[0:3], v[178:181], v[212:215], v[0:3]
	v_mfma_f32_16x16x32_bf16 v[52:55], v[174:177], v[190:193], v[52:55]
	v_mfma_f32_16x16x32_bf16 v[48:51], v[182:185], v[190:193], v[48:51]
	v_mfma_f32_16x16x32_bf16 v[36:39], v[174:177], v[200:203], v[36:39]
	v_mfma_f32_16x16x32_bf16 v[32:35], v[182:185], v[200:203], v[32:35]
	v_mfma_f32_16x16x32_bf16 v[20:23], v[174:177], v[208:211], v[20:23]
	v_mfma_f32_16x16x32_bf16 v[16:19], v[182:185], v[208:211], v[16:19]
	v_mfma_f32_16x16x32_bf16 v[4:7], v[174:177], v[216:219], v[4:7]
	v_mfma_f32_16x16x32_bf16 v[0:3], v[182:185], v[216:219], v[0:3]
	s_setprio 0
	s_barrier
	v_lshl_add_u64 v[224:225], v[224:225], 0, s[20:21]
	s_mov_b32 m0, s71
	s_nop 0
	global_load_lds_dwordx4 v[224:225], off
	s_add_i32 s85, s85, 2
	s_add_u32 s34, s34, 0x100
	s_addc_u32 s35, s35, 0
	s_add_u32 s83, s83, 0x100
	s_addc_u32 s84, s84, 0
	s_cmp_gt_u32 s85, 13
	s_cbranch_scc0 .LBB0_947
	s_and_b64 vcc, exec, s[22:23]
	s_cbranch_vccz .LBB0_950
	s_barrier

.LBB0_1023:
	ds_read_b128 v[144:147], v153
	ds_read_b128 v[156:159], v153 offset:1024
	ds_read_b128 v[160:163], v153 offset:2048
	ds_read_b128 v[164:167], v153 offset:3072
	ds_read_b128 v[168:171], v154
	ds_read_b128 v[172:175], v154 offset:1024
	ds_read_b128 v[176:179], v154 offset:2048
	ds_read_b128 v[180:183], v154 offset:3072
	s_add_u32 s44, s42, 0xfffe0080
	s_addc_u32 s45, s43, -1
	s_cmp_eq_u32 s87, 4
	s_cselect_b32 s59, s35, s45
	s_cselect_b32 s58, s83, s44
	s_cselect_b32 s45, s31, s86
	s_cselect_b32 s44, s84, s85
	v_lshl_add_u64 v[148:149], s[42:43], 0, v[136:137]
	s_add_i32 m0, s41, 0xc000
	ds_read_b128 v[184:187], v155
	ds_read_b128 v[188:191], v155 offset:1024
	ds_read_b128 v[196:199], v155 offset:2048
	ds_read_b128 v[200:203], v155 offset:3072
	ds_read_b128 v[204:207], v155 offset:4096
	ds_read_b128 v[208:211], v155 offset:5120
	ds_read_b128 v[212:215], v155 offset:6144
	ds_read_b128 v[216:219], v155 offset:7168
	global_load_lds_dwordx4 v[148:149], off
	v_lshl_add_u64 v[148:149], s[42:43], 0, v[138:139]
	s_add_i32 m0, s41, 0xe000
	s_nop 0
	global_load_lds_dwordx4 v[148:149], off
	s_waitcnt vmcnt(8)
	s_waitcnt lgkmcnt(0)
	s_barrier
	s_setprio 1
	s_waitcnt lgkmcnt(0)
	v_mfma_f32_16x16x32_bf16 v[124:127], v[144:147], v[184:187], v[124:127]
	v_mfma_f32_16x16x32_bf16 v[120:123], v[160:163], v[184:187], v[120:123]
	v_mfma_f32_16x16x32_bf16 v[108:111], v[144:147], v[196:199], v[108:111]
	v_mfma_f32_16x16x32_bf16 v[104:107], v[160:163], v[196:199], v[104:107]
	v_mfma_f32_16x16x32_bf16 v[92:95], v[144:147], v[204:207], v[92:95]
	v_mfma_f32_16x16x32_bf16 v[88:91], v[160:163], v[204:207], v[88:91]
	v_mfma_f32_16x16x32_bf16 v[76:79], v[144:147], v[212:215], v[76:79]
	v_mfma_f32_16x16x32_bf16 v[72:75], v[160:163], v[212:215], v[72:75]
	v_mfma_f32_16x16x32_bf16 v[124:127], v[156:159], v[188:191], v[124:127]
	v_mfma_f32_16x16x32_bf16 v[120:123], v[164:167], v[188:191], v[120:123]
	v_mfma_f32_16x16x32_bf16 v[108:111], v[156:159], v[200:203], v[108:111]
	v_mfma_f32_16x16x32_bf16 v[104:107], v[164:167], v[200:203], v[104:107]
	v_mfma_f32_16x16x32_bf16 v[92:95], v[156:159], v[208:211], v[92:95]
	v_mfma_f32_16x16x32_bf16 v[88:91], v[164:167], v[208:211], v[88:91]
	v_mfma_f32_16x16x32_bf16 v[76:79], v[156:159], v[216:219], v[76:79]
	v_mfma_f32_16x16x32_bf16 v[72:75], v[164:167], v[216:219], v[72:75]
	s_setprio 0
	s_setprio 1
	v_mfma_f32_16x16x32_bf16 v[116:119], v[168:171], v[184:187], v[116:119]
	v_mfma_f32_16x16x32_bf16 v[112:115], v[176:179], v[184:187], v[112:115]
	v_mfma_f32_16x16x32_bf16 v[100:103], v[168:171], v[196:199], v[100:103]
	v_mfma_f32_16x16x32_bf16 v[96:99], v[176:179], v[196:199], v[96:99]
	v_mfma_f32_16x16x32_bf16 v[84:87], v[168:171], v[204:207], v[84:87]
	v_mfma_f32_16x16x32_bf16 v[80:83], v[176:179], v[204:207], v[80:83]
	v_mfma_f32_16x16x32_bf16 v[68:71], v[168:171], v[212:215], v[68:71]
	v_mfma_f32_16x16x32_bf16 v[64:67], v[176:179], v[212:215], v[64:67]
	v_mfma_f32_16x16x32_bf16 v[116:119], v[172:175], v[188:191], v[116:119]
	v_mfma_f32_16x16x32_bf16 v[112:115], v[180:183], v[188:191], v[112:115]
	v_mfma_f32_16x16x32_bf16 v[100:103], v[172:175], v[200:203], v[100:103]
	v_mfma_f32_16x16x32_bf16 v[96:99], v[180:183], v[200:203], v[96:99]
	v_mfma_f32_16x16x32_bf16 v[84:87], v[172:175], v[208:211], v[84:87]
	v_mfma_f32_16x16x32_bf16 v[80:83], v[180:183], v[208:211], v[80:83]
	v_mfma_f32_16x16x32_bf16 v[68:71], v[172:175], v[216:219], v[68:71]
	v_mfma_f32_16x16x32_bf16 v[64:67], v[180:183], v[216:219], v[64:67]
	s_setprio 0
	s_barrier
	s_add_i32 s88, s80, s62
	v_lshl_add_u64 v[148:149], s[44:45], 0, v[130:131]
	s_mov_b32 m0, s88
	ds_read_b128 v[184:187], v155 offset:16384
	ds_read_b128 v[188:191], v155 offset:17408
	ds_read_b128 v[196:199], v155 offset:18432
	ds_read_b128 v[200:203], v155 offset:19456
	ds_read_b128 v[204:207], v155 offset:20480
	ds_read_b128 v[208:211], v155 offset:21504
	ds_read_b128 v[212:215], v155 offset:22528
	ds_read_b128 v[216:219], v155 offset:23552
	global_load_lds_dwordx4 v[148:149], off
	s_add_i32 m0, s88, 0x2000
	s_add_u32 s88, s44, 0x20000
	v_lshl_add_u64 v[192:193], s[44:45], 0, v[134:135]
	s_addc_u32 s89, s45, 0
	s_add_i32 s90, s81, s62
	global_load_lds_dwordx4 v[192:193], off
	v_lshl_add_u64 v[220:221], s[88:89], 0, v[130:131]
	s_mov_b32 m0, s90
	v_lshl_add_u64 v[222:223], s[58:59], 0, v[132:133]
	global_load_lds_dwordx4 v[220:221], off
	v_lshl_add_u64 v[220:221], s[88:89], 0, v[134:135]
	s_add_i32 m0, s90, 0x2000
	s_nop 0
	global_load_lds_dwordx4 v[220:221], off
	v_lshl_add_u64 v[220:221], s[58:59], 0, v[128:129]
	s_mov_b32 m0, s41
	s_nop 0
	global_load_lds_dwordx4 v[220:221], off
	s_waitcnt vmcnt(7)
	s_waitcnt lgkmcnt(0)
	s_barrier
	s_setprio 1
	s_waitcnt lgkmcnt(0)
	v_mfma_f32_16x16x32_bf16 v[60:63], v[144:147], v[184:187], v[60:63]
	v_mfma_f32_16x16x32_bf16 v[56:59], v[160:163], v[184:187], v[56:59]
	v_mfma_f32_16x16x32_bf16 v[44:47], v[144:147], v[196:199], v[44:47]
	v_mfma_f32_16x16x32_bf16 v[40:43], v[160:163], v[196:199], v[40:43]
	v_mfma_f32_16x16x32_bf16 v[28:31], v[144:147], v[204:207], v[28:31]
	v_mfma_f32_16x16x32_bf16 v[24:27], v[160:163], v[204:207], v[24:27]
	v_mfma_f32_16x16x32_bf16 v[12:15], v[144:147], v[212:215], v[12:15]
	v_mfma_f32_16x16x32_bf16 v[8:11], v[160:163], v[212:215], v[8:11]
	v_mfma_f32_16x16x32_bf16 v[60:63], v[156:159], v[188:191], v[60:63]
	v_mfma_f32_16x16x32_bf16 v[56:59], v[164:167], v[188:191], v[56:59]
	v_mfma_f32_16x16x32_bf16 v[44:47], v[156:159], v[200:203], v[44:47]
	v_mfma_f32_16x16x32_bf16 v[40:43], v[164:167], v[200:203], v[40:43]
	v_mfma_f32_16x16x32_bf16 v[28:31], v[156:159], v[208:211], v[28:31]
	v_mfma_f32_16x16x32_bf16 v[24:27], v[164:167], v[208:211], v[24:27]
	v_mfma_f32_16x16x32_bf16 v[12:15], v[156:159], v[216:219], v[12:15]
	v_mfma_f32_16x16x32_bf16 v[8:11], v[164:167], v[216:219], v[8:11]
	s_setprio 0
	s_setprio 1
	v_mfma_f32_16x16x32_bf16 v[52:55], v[168:171], v[184:187], v[52:55]
	v_mfma_f32_16x16x32_bf16 v[48:51], v[176:179], v[184:187], v[48:51]
	v_mfma_f32_16x16x32_bf16 v[36:39], v[168:171], v[196:199], v[36:39]
	v_mfma_f32_16x16x32_bf16 v[32:35], v[176:179], v[196:199], v[32:35]
	v_mfma_f32_16x16x32_bf16 v[20:23], v[168:171], v[204:207], v[20:23]
	v_mfma_f32_16x16x32_bf16 v[16:19], v[176:179], v[204:207], v[16:19]
	v_mfma_f32_16x16x32_bf16 v[4:7], v[168:171], v[212:215], v[4:7]
	v_mfma_f32_16x16x32_bf16 v[0:3], v[176:179], v[212:215], v[0:3]
	v_mfma_f32_16x16x32_bf16 v[52:55], v[172:175], v[188:191], v[52:55]
	v_mfma_f32_16x16x32_bf16 v[48:51], v[180:183], v[188:191], v[48:51]
	v_mfma_f32_16x16x32_bf16 v[36:39], v[172:175], v[200:203], v[36:39]
	v_mfma_f32_16x16x32_bf16 v[32:35], v[180:183], v[200:203], v[32:35]
	v_mfma_f32_16x16x32_bf16 v[20:23], v[172:175], v[208:211], v[20:23]
	v_mfma_f32_16x16x32_bf16 v[16:19], v[180:183], v[208:211], v[16:19]
	v_mfma_f32_16x16x32_bf16 v[4:7], v[172:175], v[216:219], v[4:7]
	v_mfma_f32_16x16x32_bf16 v[0:3], v[180:183], v[216:219], v[0:3]
	s_setprio 0
	s_barrier
	s_add_i32 s88, 0, 0x18000
	s_add_i32 s89, 0, 0x1c000
	v_add_u32_e32 v164, s88, v151
	v_add_u32_e32 v180, s89, v151
	ds_read_b128 v[144:147], v164
	ds_read_b128 v[156:159], v164 offset:1024
	ds_read_b128 v[160:163], v164 offset:2048
	ds_read_b128 v[164:167], v164 offset:3072
	ds_read_b128 v[168:171], v180
	ds_read_b128 v[172:175], v180 offset:1024
	ds_read_b128 v[176:179], v180 offset:2048
	ds_read_b128 v[180:183], v180 offset:3072
	s_add_u32 s58, s58, 0x20000
	s_addc_u32 s59, s59, 0
	v_lshl_add_u64 v[224:225], s[58:59], 0, v[128:129]
	ds_read_b128 v[184:187], v155 offset:32768
	ds_read_b128 v[188:191], v155 offset:33792
	ds_read_b128 v[196:199], v155 offset:34816
	ds_read_b128 v[200:203], v155 offset:35840
	ds_read_b128 v[204:207], v155 offset:36864
	ds_read_b128 v[208:211], v155 offset:37888
	ds_read_b128 v[212:215], v155 offset:38912
	ds_read_b128 v[216:219], v155 offset:39936
	s_mov_b32 m0, s63
	s_nop 0
	global_load_lds_dwordx4 v[222:223], off
	s_mov_b32 m0, s70
	s_nop 0
	global_load_lds_dwordx4 v[224:225], off
	v_lshl_add_u64 v[224:225], s[58:59], 0, v[132:133]
	s_mov_b32 m0, s71
	s_nop 0
	global_load_lds_dwordx4 v[224:225], off
	s_waitcnt vmcnt(8)
	s_waitcnt lgkmcnt(0)
	s_barrier
	s_setprio 1
	s_waitcnt lgkmcnt(0)
	v_mfma_f32_16x16x32_bf16 v[124:127], v[144:147], v[184:187], v[124:127]
	v_mfma_f32_16x16x32_bf16 v[120:123], v[160:163], v[184:187], v[120:123]
	v_mfma_f32_16x16x32_bf16 v[108:111], v[144:147], v[196:199], v[108:111]
	v_mfma_f32_16x16x32_bf16 v[104:107], v[160:163], v[196:199], v[104:107]
	v_mfma_f32_16x16x32_bf16 v[92:95], v[144:147], v[204:207], v[92:95]
	v_mfma_f32_16x16x32_bf16 v[88:91], v[160:163], v[204:207], v[88:91]
	v_mfma_f32_16x16x32_bf16 v[76:79], v[144:147], v[212:215], v[76:79]
	v_mfma_f32_16x16x32_bf16 v[72:75], v[160:163], v[212:215], v[72:75]
	v_mfma_f32_16x16x32_bf16 v[124:127], v[156:159], v[188:191], v[124:127]
	v_mfma_f32_16x16x32_bf16 v[120:123], v[164:167], v[188:191], v[120:123]
	v_mfma_f32_16x16x32_bf16 v[108:111], v[156:159], v[200:203], v[108:111]
	v_mfma_f32_16x16x32_bf16 v[104:107], v[164:167], v[200:203], v[104:107]
	v_mfma_f32_16x16x32_bf16 v[92:95], v[156:159], v[208:211], v[92:95]
	v_mfma_f32_16x16x32_bf16 v[88:91], v[164:167], v[208:211], v[88:91]
	v_mfma_f32_16x16x32_bf16 v[76:79], v[156:159], v[216:219], v[76:79]
	v_mfma_f32_16x16x32_bf16 v[72:75], v[164:167], v[216:219], v[72:75]
	s_setprio 0
	s_setprio 1
	v_mfma_f32_16x16x32_bf16 v[116:119], v[168:171], v[184:187], v[116:119]
	v_mfma_f32_16x16x32_bf16 v[112:115], v[176:179], v[184:187], v[112:115]
	v_mfma_f32_16x16x32_bf16 v[100:103], v[168:171], v[196:199], v[100:103]
	v_mfma_f32_16x16x32_bf16 v[96:99], v[176:179], v[196:199], v[96:99]
	v_mfma_f32_16x16x32_bf16 v[84:87], v[168:171], v[204:207], v[84:87]
	v_mfma_f32_16x16x32_bf16 v[80:83], v[176:179], v[204:207], v[80:83]
	v_mfma_f32_16x16x32_bf16 v[68:71], v[168:171], v[212:215], v[68:71]
	v_mfma_f32_16x16x32_bf16 v[64:67], v[176:179], v[212:215], v[64:67]
	v_mfma_f32_16x16x32_bf16 v[116:119], v[172:175], v[188:191], v[116:119]
	v_mfma_f32_16x16x32_bf16 v[112:115], v[180:183], v[188:191], v[112:115]
	v_mfma_f32_16x16x32_bf16 v[100:103], v[172:175], v[200:203], v[100:103]
	v_mfma_f32_16x16x32_bf16 v[96:99], v[180:183], v[200:203], v[96:99]
	v_mfma_f32_16x16x32_bf16 v[84:87], v[172:175], v[208:211], v[84:87]
	v_mfma_f32_16x16x32_bf16 v[80:83], v[180:183], v[208:211], v[80:83]
	v_mfma_f32_16x16x32_bf16 v[68:71], v[172:175], v[216:219], v[68:71]
	v_mfma_f32_16x16x32_bf16 v[64:67], v[180:183], v[216:219], v[64:67]
	s_setprio 0
	s_barrier
	s_add_i32 s58, s88, s62
	v_lshl_add_u64 v[148:149], v[148:149], 0, s[20:21]
	s_mov_b32 m0, s58
	ds_read_b128 v[184:187], v155 offset:49152
	ds_read_b128 v[188:191], v155 offset:50176
	ds_read_b128 v[196:199], v155 offset:51200
	ds_read_b128 v[200:203], v155 offset:52224
	ds_read_b128 v[204:207], v155 offset:53248
	ds_read_b128 v[208:211], v155 offset:54272
	ds_read_b128 v[212:215], v155 offset:55296
	ds_read_b128 v[216:219], v155 offset:56320
	global_load_lds_dwordx4 v[148:149], off
	s_add_i32 m0, s58, 0x2000
	s_add_u32 s44, s44, 0x20080
	v_lshl_add_u64 v[148:149], v[192:193], 0, s[20:21]
	s_addc_u32 s45, s45, 0
	s_add_i32 s58, s89, s62
	global_load_lds_dwordx4 v[148:149], off
	v_lshl_add_u64 v[148:149], s[44:45], 0, v[130:131]
	s_mov_b32 m0, s58
	s_nop 0
	global_load_lds_dwordx4 v[148:149], off
	v_lshl_add_u64 v[148:149], s[44:45], 0, v[134:135]
	s_add_i32 m0, s58, 0x2000
	s_nop 0
	global_load_lds_dwordx4 v[148:149], off
	v_lshl_add_u64 v[148:149], v[220:221], 0, s[20:21]
	s_mov_b32 m0, s73
	s_nop 0
	global_load_lds_dwordx4 v[148:149], off
	s_waitcnt vmcnt(7)
	s_waitcnt lgkmcnt(0)
	s_barrier
	s_setprio 1
	s_waitcnt lgkmcnt(0)
	v_mfma_f32_16x16x32_bf16 v[60:63], v[144:147], v[184:187], v[60:63]
	v_mfma_f32_16x16x32_bf16 v[56:59], v[160:163], v[184:187], v[56:59]
	v_mfma_f32_16x16x32_bf16 v[44:47], v[144:147], v[196:199], v[44:47]
	v_mfma_f32_16x16x32_bf16 v[40:43], v[160:163], v[196:199], v[40:43]
	v_mfma_f32_16x16x32_bf16 v[28:31], v[144:147], v[204:207], v[28:31]
	v_mfma_f32_16x16x32_bf16 v[24:27], v[160:163], v[204:207], v[24:27]
	v_mfma_f32_16x16x32_bf16 v[12:15], v[144:147], v[212:215], v[12:15]
	v_mfma_f32_16x16x32_bf16 v[8:11], v[160:163], v[212:215], v[8:11]
	v_mfma_f32_16x16x32_bf16 v[60:63], v[156:159], v[188:191], v[60:63]
	v_mfma_f32_16x16x32_bf16 v[56:59], v[164:167], v[188:191], v[56:59]
	v_mfma_f32_16x16x32_bf16 v[44:47], v[156:159], v[200:203], v[44:47]
	v_mfma_f32_16x16x32_bf16 v[40:43], v[164:167], v[200:203], v[40:43]
	v_mfma_f32_16x16x32_bf16 v[28:31], v[156:159], v[208:211], v[28:31]
	v_mfma_f32_16x16x32_bf16 v[24:27], v[164:167], v[208:211], v[24:27]
	v_mfma_f32_16x16x32_bf16 v[12:15], v[156:159], v[216:219], v[12:15]
	v_mfma_f32_16x16x32_bf16 v[8:11], v[164:167], v[216:219], v[8:11]
	s_setprio 0
	s_setprio 1
	v_mfma_f32_16x16x32_bf16 v[52:55], v[168:171], v[184:187], v[52:55]
	v_mfma_f32_16x16x32_bf16 v[48:51], v[176:179], v[184:187], v[48:51]
	v_mfma_f32_16x16x32_bf16 v[36:39], v[168:171], v[196:199], v[36:39]
	v_mfma_f32_16x16x32_bf16 v[32:35], v[176:179], v[196:199], v[32:35]
	v_mfma_f32_16x16x32_bf16 v[20:23], v[168:171], v[204:207], v[20:23]
	v_mfma_f32_16x16x32_bf16 v[16:19], v[176:179], v[204:207], v[16:19]
	v_mfma_f32_16x16x32_bf16 v[4:7], v[168:171], v[212:215], v[4:7]
	v_mfma_f32_16x16x32_bf16 v[0:3], v[176:179], v[212:215], v[0:3]
	v_mfma_f32_16x16x32_bf16 v[52:55], v[172:175], v[188:191], v[52:55]
	v_mfma_f32_16x16x32_bf16 v[48:51], v[180:183], v[188:191], v[48:51]
	v_mfma_f32_16x16x32_bf16 v[36:39], v[172:175], v[200:203], v[36:39]
	v_mfma_f32_16x16x32_bf16 v[32:35], v[180:183], v[200:203], v[32:35]
	v_mfma_f32_16x16x32_bf16 v[20:23], v[172:175], v[208:211], v[20:23]
	v_mfma_f32_16x16x32_bf16 v[16:19], v[180:183], v[208:211], v[16:19]
	v_mfma_f32_16x16x32_bf16 v[4:7], v[172:175], v[216:219], v[4:7]
	v_mfma_f32_16x16x32_bf16 v[0:3], v[180:183], v[216:219], v[0:3]
	s_setprio 0
	s_barrier
	v_lshl_add_u64 v[222:223], v[222:223], 0, s[20:21]
	s_mov_b32 m0, s78
	s_nop 0
	global_load_lds_dwordx4 v[222:223], off
	s_add_i32 s87, s87, 2
	s_add_u32 s42, s42, 0x100
	s_addc_u32 s43, s43, 0
	s_add_u32 s85, s85, 0x100
	s_addc_u32 s86, s86, 0
	s_cmp_gt_u32 s87, 5
	s_cbranch_scc0 .LBB0_1023
	s_and_b64 vcc, exec, s[22:23]
	s_cbranch_vccz .LBB0_1026
	s_barrier

.LBB0_1421:
	ds_read_b128 v[146:149], v155
	ds_read_b128 v[160:163], v155 offset:1024
	ds_read_b128 v[164:167], v155 offset:2048
	ds_read_b128 v[168:171], v155 offset:3072
	ds_read_b128 v[172:175], v156
	ds_read_b128 v[176:179], v156 offset:1024
	ds_read_b128 v[180:183], v156 offset:2048
	ds_read_b128 v[184:187], v156 offset:3072
	s_add_u32 s40, s0, 0xfffc0080
	s_addc_u32 s41, s1, -1
	s_cmp_eq_u32 s83, 12
	s_cselect_b32 s43, s25, s41
	s_cselect_b32 s42, s27, s40
	s_cselect_b32 s41, s31, s82
	s_cselect_b32 s40, s30, s29
	v_lshl_add_u64 v[150:151], s[0:1], 0, v[138:139]
	s_add_i32 m0, s39, 0xc000
	ds_read_b128 v[188:191], v157
	ds_read_b128 v[196:199], v157 offset:1024
	ds_read_b128 v[200:203], v157 offset:2048
	ds_read_b128 v[204:207], v157 offset:3072
	ds_read_b128 v[208:211], v157 offset:4096
	ds_read_b128 v[212:215], v157 offset:5120
	ds_read_b128 v[216:219], v157 offset:6144
	ds_read_b128 v[220:223], v157 offset:7168
	global_load_lds_dwordx4 v[150:151], off
	v_lshl_add_u64 v[150:151], s[0:1], 0, v[140:141]
	s_add_i32 m0, s39, 0xe000
	s_nop 0
	global_load_lds_dwordx4 v[150:151], off
	s_waitcnt vmcnt(8)
	s_waitcnt lgkmcnt(0)
	s_barrier
	s_setprio 1
	s_waitcnt lgkmcnt(0)
	v_mfma_f32_16x16x32_bf16 v[124:127], v[146:149], v[188:191], v[124:127]
	v_mfma_f32_16x16x32_bf16 v[120:123], v[164:167], v[188:191], v[120:123]
	v_mfma_f32_16x16x32_bf16 v[108:111], v[146:149], v[200:203], v[108:111]
	v_mfma_f32_16x16x32_bf16 v[104:107], v[164:167], v[200:203], v[104:107]
	v_mfma_f32_16x16x32_bf16 v[92:95], v[146:149], v[208:211], v[92:95]
	v_mfma_f32_16x16x32_bf16 v[88:91], v[164:167], v[208:211], v[88:91]
	v_mfma_f32_16x16x32_bf16 v[76:79], v[146:149], v[216:219], v[76:79]
	v_mfma_f32_16x16x32_bf16 v[72:75], v[164:167], v[216:219], v[72:75]
	v_mfma_f32_16x16x32_bf16 v[124:127], v[160:163], v[196:199], v[124:127]
	v_mfma_f32_16x16x32_bf16 v[120:123], v[168:171], v[196:199], v[120:123]
	v_mfma_f32_16x16x32_bf16 v[108:111], v[160:163], v[204:207], v[108:111]
	v_mfma_f32_16x16x32_bf16 v[104:107], v[168:171], v[204:207], v[104:107]
	v_mfma_f32_16x16x32_bf16 v[92:95], v[160:163], v[212:215], v[92:95]
	v_mfma_f32_16x16x32_bf16 v[88:91], v[168:171], v[212:215], v[88:91]
	v_mfma_f32_16x16x32_bf16 v[76:79], v[160:163], v[220:223], v[76:79]
	v_mfma_f32_16x16x32_bf16 v[72:75], v[168:171], v[220:223], v[72:75]
	s_setprio 0
	s_setprio 1
	v_mfma_f32_16x16x32_bf16 v[116:119], v[172:175], v[188:191], v[116:119]
	v_mfma_f32_16x16x32_bf16 v[112:115], v[180:183], v[188:191], v[112:115]
	v_mfma_f32_16x16x32_bf16 v[100:103], v[172:175], v[200:203], v[100:103]
	v_mfma_f32_16x16x32_bf16 v[96:99], v[180:183], v[200:203], v[96:99]
	v_mfma_f32_16x16x32_bf16 v[84:87], v[172:175], v[208:211], v[84:87]
	v_mfma_f32_16x16x32_bf16 v[80:83], v[180:183], v[208:211], v[80:83]
	v_mfma_f32_16x16x32_bf16 v[68:71], v[172:175], v[216:219], v[68:71]
	v_mfma_f32_16x16x32_bf16 v[64:67], v[180:183], v[216:219], v[64:67]
	v_mfma_f32_16x16x32_bf16 v[116:119], v[176:179], v[196:199], v[116:119]
	v_mfma_f32_16x16x32_bf16 v[112:115], v[184:187], v[196:199], v[112:115]
	v_mfma_f32_16x16x32_bf16 v[100:103], v[176:179], v[204:207], v[100:103]
	v_mfma_f32_16x16x32_bf16 v[96:99], v[184:187], v[204:207], v[96:99]
	v_mfma_f32_16x16x32_bf16 v[84:87], v[176:179], v[212:215], v[84:87]
	v_mfma_f32_16x16x32_bf16 v[80:83], v[184:187], v[212:215], v[80:83]
	v_mfma_f32_16x16x32_bf16 v[68:71], v[176:179], v[220:223], v[68:71]
	v_mfma_f32_16x16x32_bf16 v[64:67], v[184:187], v[220:223], v[64:67]
	s_setprio 0
	s_barrier
	s_add_i32 s84, s78, s60
	v_lshl_add_u64 v[150:151], s[40:41], 0, v[132:133]
	s_mov_b32 m0, s84
	ds_read_b128 v[188:191], v157 offset:16384
	ds_read_b128 v[196:199], v157 offset:17408
	ds_read_b128 v[200:203], v157 offset:18432
	ds_read_b128 v[204:207], v157 offset:19456
	ds_read_b128 v[208:211], v157 offset:20480
	ds_read_b128 v[212:215], v157 offset:21504
	ds_read_b128 v[216:219], v157 offset:22528
	ds_read_b128 v[220:223], v157 offset:23552
	global_load_lds_dwordx4 v[150:151], off
	s_add_i32 m0, s84, 0x2000
	s_add_u32 s84, s40, 0x40000
	v_lshl_add_u64 v[192:193], s[40:41], 0, v[136:137]
	s_addc_u32 s85, s41, 0
	s_add_i32 s86, s79, s60
	global_load_lds_dwordx4 v[192:193], off
	v_lshl_add_u64 v[224:225], s[84:85], 0, v[132:133]
	s_mov_b32 m0, s86
	v_lshl_add_u64 v[226:227], s[42:43], 0, v[134:135]
	global_load_lds_dwordx4 v[224:225], off
	v_lshl_add_u64 v[224:225], s[84:85], 0, v[136:137]
	s_add_i32 m0, s86, 0x2000
	s_nop 0
	global_load_lds_dwordx4 v[224:225], off
	v_lshl_add_u64 v[224:225], s[42:43], 0, v[130:131]
	s_mov_b32 m0, s39
	s_nop 0
	global_load_lds_dwordx4 v[224:225], off
	s_waitcnt vmcnt(7)
	s_waitcnt lgkmcnt(0)
	s_barrier
	s_setprio 1
	s_waitcnt lgkmcnt(0)
	v_mfma_f32_16x16x32_bf16 v[60:63], v[146:149], v[188:191], v[60:63]
	v_mfma_f32_16x16x32_bf16 v[56:59], v[164:167], v[188:191], v[56:59]
	v_mfma_f32_16x16x32_bf16 v[44:47], v[146:149], v[200:203], v[44:47]
	v_mfma_f32_16x16x32_bf16 v[40:43], v[164:167], v[200:203], v[40:43]
	v_mfma_f32_16x16x32_bf16 v[28:31], v[146:149], v[208:211], v[28:31]
	v_mfma_f32_16x16x32_bf16 v[24:27], v[164:167], v[208:211], v[24:27]
	v_mfma_f32_16x16x32_bf16 v[12:15], v[146:149], v[216:219], v[12:15]
	v_mfma_f32_16x16x32_bf16 v[8:11], v[164:167], v[216:219], v[8:11]
	v_mfma_f32_16x16x32_bf16 v[60:63], v[160:163], v[196:199], v[60:63]
	v_mfma_f32_16x16x32_bf16 v[56:59], v[168:171], v[196:199], v[56:59]
	v_mfma_f32_16x16x32_bf16 v[44:47], v[160:163], v[204:207], v[44:47]
	v_mfma_f32_16x16x32_bf16 v[40:43], v[168:171], v[204:207], v[40:43]
	v_mfma_f32_16x16x32_bf16 v[28:31], v[160:163], v[212:215], v[28:31]
	v_mfma_f32_16x16x32_bf16 v[24:27], v[168:171], v[212:215], v[24:27]
	v_mfma_f32_16x16x32_bf16 v[12:15], v[160:163], v[220:223], v[12:15]
	v_mfma_f32_16x16x32_bf16 v[8:11], v[168:171], v[220:223], v[8:11]
	s_setprio 0
	s_setprio 1
	v_mfma_f32_16x16x32_bf16 v[52:55], v[172:175], v[188:191], v[52:55]
	v_mfma_f32_16x16x32_bf16 v[48:51], v[180:183], v[188:191], v[48:51]
	v_mfma_f32_16x16x32_bf16 v[36:39], v[172:175], v[200:203], v[36:39]
	v_mfma_f32_16x16x32_bf16 v[32:35], v[180:183], v[200:203], v[32:35]
	v_mfma_f32_16x16x32_bf16 v[20:23], v[172:175], v[208:211], v[20:23]
	v_mfma_f32_16x16x32_bf16 v[16:19], v[180:183], v[208:211], v[16:19]
	v_mfma_f32_16x16x32_bf16 v[4:7], v[172:175], v[216:219], v[4:7]
	v_mfma_f32_16x16x32_bf16 v[0:3], v[180:183], v[216:219], v[0:3]
	v_mfma_f32_16x16x32_bf16 v[52:55], v[176:179], v[196:199], v[52:55]
	v_mfma_f32_16x16x32_bf16 v[48:51], v[184:187], v[196:199], v[48:51]
	v_mfma_f32_16x16x32_bf16 v[36:39], v[176:179], v[204:207], v[36:39]
	v_mfma_f32_16x16x32_bf16 v[32:35], v[184:187], v[204:207], v[32:35]
	v_mfma_f32_16x16x32_bf16 v[20:23], v[176:179], v[212:215], v[20:23]
	v_mfma_f32_16x16x32_bf16 v[16:19], v[184:187], v[212:215], v[16:19]
	v_mfma_f32_16x16x32_bf16 v[4:7], v[176:179], v[220:223], v[4:7]
	v_mfma_f32_16x16x32_bf16 v[0:3], v[184:187], v[220:223], v[0:3]
	s_setprio 0
	s_barrier
	s_add_i32 s84, 0, 0x18000
	v_add_u32_e32 v159, s84, v153
	s_add_i32 s85, 0, 0x1c000
	ds_read_b128 v[146:149], v159
	ds_read_b128 v[160:163], v159 offset:1024
	ds_read_b128 v[164:167], v159 offset:2048
	ds_read_b128 v[168:171], v159 offset:3072
	v_add_u32_e32 v159, s85, v153
	ds_read_b128 v[172:175], v159
	ds_read_b128 v[176:179], v159 offset:1024
	ds_read_b128 v[180:183], v159 offset:2048
	ds_read_b128 v[184:187], v159 offset:3072
	s_add_u32 s42, s42, 0x40000
	s_addc_u32 s43, s43, 0
	v_lshl_add_u64 v[228:229], s[42:43], 0, v[130:131]
	ds_read_b128 v[188:191], v157 offset:32768
	ds_read_b128 v[196:199], v157 offset:33792
	ds_read_b128 v[200:203], v157 offset:34816
	ds_read_b128 v[204:207], v157 offset:35840
	ds_read_b128 v[208:211], v157 offset:36864
	ds_read_b128 v[212:215], v157 offset:37888
	ds_read_b128 v[216:219], v157 offset:38912
	ds_read_b128 v[220:223], v157 offset:39936
	s_mov_b32 m0, s61
	s_nop 0
	global_load_lds_dwordx4 v[226:227], off
	s_mov_b32 m0, s62
	s_nop 0
	global_load_lds_dwordx4 v[228:229], off
	v_lshl_add_u64 v[228:229], s[42:43], 0, v[134:135]
	s_mov_b32 m0, s63
	s_nop 0
	global_load_lds_dwordx4 v[228:229], off
	s_waitcnt vmcnt(8)
	s_waitcnt lgkmcnt(0)
	s_barrier
	s_setprio 1
	s_waitcnt lgkmcnt(0)
	v_mfma_f32_16x16x32_bf16 v[124:127], v[146:149], v[188:191], v[124:127]
	v_mfma_f32_16x16x32_bf16 v[120:123], v[164:167], v[188:191], v[120:123]
	v_mfma_f32_16x16x32_bf16 v[108:111], v[146:149], v[200:203], v[108:111]
	v_mfma_f32_16x16x32_bf16 v[104:107], v[164:167], v[200:203], v[104:107]
	v_mfma_f32_16x16x32_bf16 v[92:95], v[146:149], v[208:211], v[92:95]
	v_mfma_f32_16x16x32_bf16 v[88:91], v[164:167], v[208:211], v[88:91]
	v_mfma_f32_16x16x32_bf16 v[76:79], v[146:149], v[216:219], v[76:79]
	v_mfma_f32_16x16x32_bf16 v[72:75], v[164:167], v[216:219], v[72:75]
	v_mfma_f32_16x16x32_bf16 v[124:127], v[160:163], v[196:199], v[124:127]
	v_mfma_f32_16x16x32_bf16 v[120:123], v[168:171], v[196:199], v[120:123]
	v_mfma_f32_16x16x32_bf16 v[108:111], v[160:163], v[204:207], v[108:111]
	v_mfma_f32_16x16x32_bf16 v[104:107], v[168:171], v[204:207], v[104:107]
	v_mfma_f32_16x16x32_bf16 v[92:95], v[160:163], v[212:215], v[92:95]
	v_mfma_f32_16x16x32_bf16 v[88:91], v[168:171], v[212:215], v[88:91]
	v_mfma_f32_16x16x32_bf16 v[76:79], v[160:163], v[220:223], v[76:79]
	v_mfma_f32_16x16x32_bf16 v[72:75], v[168:171], v[220:223], v[72:75]
	s_setprio 0
	s_setprio 1
	v_mfma_f32_16x16x32_bf16 v[116:119], v[172:175], v[188:191], v[116:119]
	v_mfma_f32_16x16x32_bf16 v[112:115], v[180:183], v[188:191], v[112:115]
	v_mfma_f32_16x16x32_bf16 v[100:103], v[172:175], v[200:203], v[100:103]
	v_mfma_f32_16x16x32_bf16 v[96:99], v[180:183], v[200:203], v[96:99]
	v_mfma_f32_16x16x32_bf16 v[84:87], v[172:175], v[208:211], v[84:87]
	v_mfma_f32_16x16x32_bf16 v[80:83], v[180:183], v[208:211], v[80:83]
	v_mfma_f32_16x16x32_bf16 v[68:71], v[172:175], v[216:219], v[68:71]
	v_mfma_f32_16x16x32_bf16 v[64:67], v[180:183], v[216:219], v[64:67]
	v_mfma_f32_16x16x32_bf16 v[116:119], v[176:179], v[196:199], v[116:119]
	v_mfma_f32_16x16x32_bf16 v[112:115], v[184:187], v[196:199], v[112:115]
	v_mfma_f32_16x16x32_bf16 v[100:103], v[176:179], v[204:207], v[100:103]
	v_mfma_f32_16x16x32_bf16 v[96:99], v[184:187], v[204:207], v[96:99]
	v_mfma_f32_16x16x32_bf16 v[84:87], v[176:179], v[212:215], v[84:87]
	v_mfma_f32_16x16x32_bf16 v[80:83], v[184:187], v[212:215], v[80:83]
	v_mfma_f32_16x16x32_bf16 v[68:71], v[176:179], v[220:223], v[68:71]
	v_mfma_f32_16x16x32_bf16 v[64:67], v[184:187], v[220:223], v[64:67]
	s_setprio 0
	s_barrier
	s_add_i32 s42, s84, s60
	v_lshl_add_u64 v[150:151], v[150:151], 0, s[20:21]
	s_mov_b32 m0, s42
	ds_read_b128 v[188:191], v157 offset:49152
	ds_read_b128 v[196:199], v157 offset:50176
	ds_read_b128 v[200:203], v157 offset:51200
	ds_read_b128 v[204:207], v157 offset:52224
	ds_read_b128 v[208:211], v157 offset:53248
	ds_read_b128 v[212:215], v157 offset:54272
	ds_read_b128 v[216:219], v157 offset:55296
	ds_read_b128 v[220:223], v157 offset:56320
	global_load_lds_dwordx4 v[150:151], off
	s_add_i32 m0, s42, 0x2000
	s_add_u32 s40, s40, 0x40080
	v_lshl_add_u64 v[150:151], v[192:193], 0, s[20:21]
	s_addc_u32 s41, s41, 0
	s_add_i32 s42, s85, s60
	global_load_lds_dwordx4 v[150:151], off
	v_lshl_add_u64 v[150:151], s[40:41], 0, v[132:133]
	s_mov_b32 m0, s42
	s_nop 0
	global_load_lds_dwordx4 v[150:151], off
	v_lshl_add_u64 v[150:151], s[40:41], 0, v[136:137]
	s_add_i32 m0, s42, 0x2000
	s_nop 0
	global_load_lds_dwordx4 v[150:151], off
	v_lshl_add_u64 v[150:151], v[224:225], 0, s[20:21]
	s_mov_b32 m0, s70
	s_nop 0
	global_load_lds_dwordx4 v[150:151], off
	s_waitcnt vmcnt(7)
	s_waitcnt lgkmcnt(0)
	s_barrier
	s_setprio 1
	s_waitcnt lgkmcnt(0)
	v_mfma_f32_16x16x32_bf16 v[60:63], v[146:149], v[188:191], v[60:63]
	v_mfma_f32_16x16x32_bf16 v[56:59], v[164:167], v[188:191], v[56:59]
	v_mfma_f32_16x16x32_bf16 v[44:47], v[146:149], v[200:203], v[44:47]
	v_mfma_f32_16x16x32_bf16 v[40:43], v[164:167], v[200:203], v[40:43]
	v_mfma_f32_16x16x32_bf16 v[28:31], v[146:149], v[208:211], v[28:31]
	v_mfma_f32_16x16x32_bf16 v[24:27], v[164:167], v[208:211], v[24:27]
	v_mfma_f32_16x16x32_bf16 v[12:15], v[146:149], v[216:219], v[12:15]
	v_mfma_f32_16x16x32_bf16 v[8:11], v[164:167], v[216:219], v[8:11]
	v_mfma_f32_16x16x32_bf16 v[60:63], v[160:163], v[196:199], v[60:63]
	v_mfma_f32_16x16x32_bf16 v[56:59], v[168:171], v[196:199], v[56:59]
	v_mfma_f32_16x16x32_bf16 v[44:47], v[160:163], v[204:207], v[44:47]
	v_mfma_f32_16x16x32_bf16 v[40:43], v[168:171], v[204:207], v[40:43]
	v_mfma_f32_16x16x32_bf16 v[28:31], v[160:163], v[212:215], v[28:31]
	v_mfma_f32_16x16x32_bf16 v[24:27], v[168:171], v[212:215], v[24:27]
	v_mfma_f32_16x16x32_bf16 v[12:15], v[160:163], v[220:223], v[12:15]
	v_mfma_f32_16x16x32_bf16 v[8:11], v[168:171], v[220:223], v[8:11]
	s_setprio 0
	s_setprio 1
	v_mfma_f32_16x16x32_bf16 v[52:55], v[172:175], v[188:191], v[52:55]
	v_mfma_f32_16x16x32_bf16 v[48:51], v[180:183], v[188:191], v[48:51]
	v_mfma_f32_16x16x32_bf16 v[36:39], v[172:175], v[200:203], v[36:39]
	v_mfma_f32_16x16x32_bf16 v[32:35], v[180:183], v[200:203], v[32:35]
	v_mfma_f32_16x16x32_bf16 v[20:23], v[172:175], v[208:211], v[20:23]
	v_mfma_f32_16x16x32_bf16 v[16:19], v[180:183], v[208:211], v[16:19]
	v_mfma_f32_16x16x32_bf16 v[4:7], v[172:175], v[216:219], v[4:7]
	v_mfma_f32_16x16x32_bf16 v[0:3], v[180:183], v[216:219], v[0:3]
	v_mfma_f32_16x16x32_bf16 v[52:55], v[176:179], v[196:199], v[52:55]
	v_mfma_f32_16x16x32_bf16 v[48:51], v[184:187], v[196:199], v[48:51]
	v_mfma_f32_16x16x32_bf16 v[36:39], v[176:179], v[204:207], v[36:39]
	v_mfma_f32_16x16x32_bf16 v[32:35], v[184:187], v[204:207], v[32:35]
	v_mfma_f32_16x16x32_bf16 v[20:23], v[176:179], v[212:215], v[20:23]
	v_mfma_f32_16x16x32_bf16 v[16:19], v[184:187], v[212:215], v[16:19]
	v_mfma_f32_16x16x32_bf16 v[4:7], v[176:179], v[220:223], v[4:7]
	v_mfma_f32_16x16x32_bf16 v[0:3], v[184:187], v[220:223], v[0:3]
	s_setprio 0
	s_barrier
	v_lshl_add_u64 v[226:227], v[226:227], 0, s[20:21]
	s_mov_b32 m0, s71
	s_nop 0
	global_load_lds_dwordx4 v[226:227], off
	s_add_i32 s83, s83, 2
	s_add_u32 s0, s0, 0x100
	s_addc_u32 s1, s1, 0
	s_add_u32 s29, s29, 0x100
	s_addc_u32 s82, s82, 0
	s_cmp_gt_u32 s83, 13
	s_cbranch_scc0 .LBB0_1421
	s_and_b64 vcc, exec, s[22:23]
	s_cbranch_vccz .LBB0_1424
	s_barrier

.LBB0_1451:
	ds_read_b128 v[144:147], v159
	ds_read_b128 v[148:151], v159 offset:1024
	ds_read_b128 v[152:155], v159 offset:2048
	ds_read_b128 v[162:165], v159 offset:3072
	ds_read_b128 v[166:169], v160
	ds_read_b128 v[170:173], v160 offset:1024
	ds_read_b128 v[174:177], v160 offset:2048
	ds_read_b128 v[178:181], v160 offset:3072
	s_add_u32 s41, s58, 0xfffe0080
	s_addc_u32 s43, s59, -1
	s_cmp_eq_u32 s39, 4
	s_cselect_b32 s71, s1, s43
	s_cselect_b32 s70, s0, s41
	s_cselect_b32 s63, s45, s17
	s_cselect_b32 s62, s44, s15
	v_lshl_add_u64 v[216:217], s[58:59], 0, v[136:137]
	s_add_i32 m0, s83, 0xc000
	ds_read_b128 v[182:185], v161
	ds_read_b128 v[186:189], v161 offset:1024
	ds_read_b128 v[190:193], v161 offset:2048
	ds_read_b128 v[196:199], v161 offset:3072
	ds_read_b128 v[200:203], v161 offset:4096
	ds_read_b128 v[204:207], v161 offset:5120
	ds_read_b128 v[208:211], v161 offset:6144
	ds_read_b128 v[212:215], v161 offset:7168
	global_load_lds_dwordx4 v[216:217], off
	v_lshl_add_u64 v[216:217], s[58:59], 0, v[138:139]
	s_add_i32 m0, s83, 0xe000
	s_nop 0
	global_load_lds_dwordx4 v[216:217], off
	s_waitcnt vmcnt(8)
	s_waitcnt lgkmcnt(0)
	s_barrier
	s_setprio 1
	s_waitcnt lgkmcnt(0)
	v_mfma_f32_16x16x32_bf16 v[124:127], v[144:147], v[182:185], v[124:127]
	v_mfma_f32_16x16x32_bf16 v[120:123], v[152:155], v[182:185], v[120:123]
	v_mfma_f32_16x16x32_bf16 v[108:111], v[144:147], v[190:193], v[108:111]
	v_mfma_f32_16x16x32_bf16 v[104:107], v[152:155], v[190:193], v[104:107]
	v_mfma_f32_16x16x32_bf16 v[92:95], v[144:147], v[200:203], v[92:95]
	v_mfma_f32_16x16x32_bf16 v[88:91], v[152:155], v[200:203], v[88:91]
	v_mfma_f32_16x16x32_bf16 v[76:79], v[144:147], v[208:211], v[76:79]
	v_mfma_f32_16x16x32_bf16 v[72:75], v[152:155], v[208:211], v[72:75]
	v_mfma_f32_16x16x32_bf16 v[124:127], v[148:151], v[186:189], v[124:127]
	v_mfma_f32_16x16x32_bf16 v[120:123], v[162:165], v[186:189], v[120:123]
	v_mfma_f32_16x16x32_bf16 v[108:111], v[148:151], v[196:199], v[108:111]
	v_mfma_f32_16x16x32_bf16 v[104:107], v[162:165], v[196:199], v[104:107]
	v_mfma_f32_16x16x32_bf16 v[92:95], v[148:151], v[204:207], v[92:95]
	v_mfma_f32_16x16x32_bf16 v[88:91], v[162:165], v[204:207], v[88:91]
	v_mfma_f32_16x16x32_bf16 v[76:79], v[148:151], v[212:215], v[76:79]
	v_mfma_f32_16x16x32_bf16 v[72:75], v[162:165], v[212:215], v[72:75]
	s_setprio 0
	s_setprio 1
	v_mfma_f32_16x16x32_bf16 v[116:119], v[166:169], v[182:185], v[116:119]
	v_mfma_f32_16x16x32_bf16 v[112:115], v[174:177], v[182:185], v[112:115]
	v_mfma_f32_16x16x32_bf16 v[100:103], v[166:169], v[190:193], v[100:103]
	v_mfma_f32_16x16x32_bf16 v[96:99], v[174:177], v[190:193], v[96:99]
	v_mfma_f32_16x16x32_bf16 v[84:87], v[166:169], v[200:203], v[84:87]
	v_mfma_f32_16x16x32_bf16 v[80:83], v[174:177], v[200:203], v[80:83]
	v_mfma_f32_16x16x32_bf16 v[68:71], v[166:169], v[208:211], v[68:71]
	v_mfma_f32_16x16x32_bf16 v[64:67], v[174:177], v[208:211], v[64:67]
	v_mfma_f32_16x16x32_bf16 v[116:119], v[170:173], v[186:189], v[116:119]
	v_mfma_f32_16x16x32_bf16 v[112:115], v[178:181], v[186:189], v[112:115]
	v_mfma_f32_16x16x32_bf16 v[100:103], v[170:173], v[196:199], v[100:103]
	v_mfma_f32_16x16x32_bf16 v[96:99], v[178:181], v[196:199], v[96:99]
	v_mfma_f32_16x16x32_bf16 v[84:87], v[170:173], v[204:207], v[84:87]
	v_mfma_f32_16x16x32_bf16 v[80:83], v[178:181], v[204:207], v[80:83]
	v_mfma_f32_16x16x32_bf16 v[68:71], v[170:173], v[212:215], v[68:71]
	v_mfma_f32_16x16x32_bf16 v[64:67], v[178:181], v[212:215], v[64:67]
	s_setprio 0
	s_barrier
	s_add_i32 s41, s90, s80
	v_lshl_add_u64 v[216:217], s[62:63], 0, v[130:131]
	s_mov_b32 m0, s41
	ds_read_b128 v[182:185], v161 offset:16384
	ds_read_b128 v[186:189], v161 offset:17408
	ds_read_b128 v[190:193], v161 offset:18432
	ds_read_b128 v[196:199], v161 offset:19456
	ds_read_b128 v[200:203], v161 offset:20480
	ds_read_b128 v[204:207], v161 offset:21504
	ds_read_b128 v[208:211], v161 offset:22528
	ds_read_b128 v[212:215], v161 offset:23552
	global_load_lds_dwordx4 v[216:217], off
	s_add_i32 m0, s41, 0x2000
	s_add_u32 s94, s62, 0x20000
	v_lshl_add_u64 v[218:219], s[62:63], 0, v[134:135]
	s_addc_u32 s95, s63, 0
	s_add_i32 s41, s91, s80
	global_load_lds_dwordx4 v[218:219], off
	v_lshl_add_u64 v[220:221], s[94:95], 0, v[130:131]
	s_mov_b32 m0, s41
	v_lshl_add_u64 v[222:223], s[70:71], 0, v[132:133]
	global_load_lds_dwordx4 v[220:221], off
	v_lshl_add_u64 v[220:221], s[94:95], 0, v[134:135]
	s_add_i32 m0, s41, 0x2000
	s_nop 0
	global_load_lds_dwordx4 v[220:221], off
	v_lshl_add_u64 v[220:221], s[70:71], 0, v[128:129]
	s_mov_b32 m0, s83
	s_nop 0
	global_load_lds_dwordx4 v[220:221], off
	s_waitcnt vmcnt(7)
	s_waitcnt lgkmcnt(0)
	s_barrier
	s_setprio 1
	s_waitcnt lgkmcnt(0)
	v_mfma_f32_16x16x32_bf16 v[60:63], v[144:147], v[182:185], v[60:63]
	v_mfma_f32_16x16x32_bf16 v[56:59], v[152:155], v[182:185], v[56:59]
	v_mfma_f32_16x16x32_bf16 v[44:47], v[144:147], v[190:193], v[44:47]
	v_mfma_f32_16x16x32_bf16 v[40:43], v[152:155], v[190:193], v[40:43]
	v_mfma_f32_16x16x32_bf16 v[28:31], v[144:147], v[200:203], v[28:31]
	v_mfma_f32_16x16x32_bf16 v[24:27], v[152:155], v[200:203], v[24:27]
	v_mfma_f32_16x16x32_bf16 v[12:15], v[144:147], v[208:211], v[12:15]
	v_mfma_f32_16x16x32_bf16 v[8:11], v[152:155], v[208:211], v[8:11]
	v_mfma_f32_16x16x32_bf16 v[60:63], v[148:151], v[186:189], v[60:63]
	v_mfma_f32_16x16x32_bf16 v[56:59], v[162:165], v[186:189], v[56:59]
	v_mfma_f32_16x16x32_bf16 v[44:47], v[148:151], v[196:199], v[44:47]
	v_mfma_f32_16x16x32_bf16 v[40:43], v[162:165], v[196:199], v[40:43]
	v_mfma_f32_16x16x32_bf16 v[28:31], v[148:151], v[204:207], v[28:31]
	v_mfma_f32_16x16x32_bf16 v[24:27], v[162:165], v[204:207], v[24:27]
	v_mfma_f32_16x16x32_bf16 v[12:15], v[148:151], v[212:215], v[12:15]
	v_mfma_f32_16x16x32_bf16 v[8:11], v[162:165], v[212:215], v[8:11]
	s_setprio 0
	s_setprio 1
	v_mfma_f32_16x16x32_bf16 v[52:55], v[166:169], v[182:185], v[52:55]
	v_mfma_f32_16x16x32_bf16 v[48:51], v[174:177], v[182:185], v[48:51]
	v_mfma_f32_16x16x32_bf16 v[36:39], v[166:169], v[190:193], v[36:39]
	v_mfma_f32_16x16x32_bf16 v[32:35], v[174:177], v[190:193], v[32:35]
	v_mfma_f32_16x16x32_bf16 v[20:23], v[166:169], v[200:203], v[20:23]
	v_mfma_f32_16x16x32_bf16 v[16:19], v[174:177], v[200:203], v[16:19]
	v_mfma_f32_16x16x32_bf16 v[4:7], v[166:169], v[208:211], v[4:7]
	v_mfma_f32_16x16x32_bf16 v[0:3], v[174:177], v[208:211], v[0:3]
	v_mfma_f32_16x16x32_bf16 v[52:55], v[170:173], v[186:189], v[52:55]
	v_mfma_f32_16x16x32_bf16 v[48:51], v[178:181], v[186:189], v[48:51]
	v_mfma_f32_16x16x32_bf16 v[36:39], v[170:173], v[196:199], v[36:39]
	v_mfma_f32_16x16x32_bf16 v[32:35], v[178:181], v[196:199], v[32:35]
	v_mfma_f32_16x16x32_bf16 v[20:23], v[170:173], v[204:207], v[20:23]
	v_mfma_f32_16x16x32_bf16 v[16:19], v[178:181], v[204:207], v[16:19]
	v_mfma_f32_16x16x32_bf16 v[4:7], v[170:173], v[212:215], v[4:7]
	v_mfma_f32_16x16x32_bf16 v[0:3], v[178:181], v[212:215], v[0:3]
	s_setprio 0
	s_barrier
	s_add_i32 s41, 0, 0x18000
	s_add_i32 s43, 0, 0x1c000
	v_add_u32_e32 v162, s41, v157
	v_add_u32_e32 v178, s43, v157
	ds_read_b128 v[144:147], v162
	ds_read_b128 v[148:151], v162 offset:1024
	ds_read_b128 v[152:155], v162 offset:2048
	ds_read_b128 v[162:165], v162 offset:3072
	ds_read_b128 v[166:169], v178
	ds_read_b128 v[170:173], v178 offset:1024
	ds_read_b128 v[174:177], v178 offset:2048
	ds_read_b128 v[178:181], v178 offset:3072
	s_add_u32 s70, s70, 0x20000
	s_addc_u32 s71, s71, 0
	v_lshl_add_u64 v[224:225], s[70:71], 0, v[128:129]
	ds_read_b128 v[182:185], v161 offset:32768
	ds_read_b128 v[186:189], v161 offset:33792
	ds_read_b128 v[190:193], v161 offset:34816
	ds_read_b128 v[196:199], v161 offset:35840
	ds_read_b128 v[200:203], v161 offset:36864
	ds_read_b128 v[204:207], v161 offset:37888
	ds_read_b128 v[208:211], v161 offset:38912
	ds_read_b128 v[212:215], v161 offset:39936
	s_mov_b32 m0, s84
	s_nop 0
	global_load_lds_dwordx4 v[222:223], off
	s_mov_b32 m0, s85
	s_nop 0
	global_load_lds_dwordx4 v[224:225], off
	v_lshl_add_u64 v[224:225], s[70:71], 0, v[132:133]
	s_mov_b32 m0, s86
	s_nop 0
	global_load_lds_dwordx4 v[224:225], off
	s_waitcnt vmcnt(8)
	s_waitcnt lgkmcnt(0)
	s_barrier
	s_setprio 1
	s_waitcnt lgkmcnt(0)
	v_mfma_f32_16x16x32_bf16 v[124:127], v[144:147], v[182:185], v[124:127]
	v_mfma_f32_16x16x32_bf16 v[120:123], v[152:155], v[182:185], v[120:123]
	v_mfma_f32_16x16x32_bf16 v[108:111], v[144:147], v[190:193], v[108:111]
	v_mfma_f32_16x16x32_bf16 v[104:107], v[152:155], v[190:193], v[104:107]
	v_mfma_f32_16x16x32_bf16 v[92:95], v[144:147], v[200:203], v[92:95]
	v_mfma_f32_16x16x32_bf16 v[88:91], v[152:155], v[200:203], v[88:91]
	v_mfma_f32_16x16x32_bf16 v[76:79], v[144:147], v[208:211], v[76:79]
	v_mfma_f32_16x16x32_bf16 v[72:75], v[152:155], v[208:211], v[72:75]
	v_mfma_f32_16x16x32_bf16 v[124:127], v[148:151], v[186:189], v[124:127]
	v_mfma_f32_16x16x32_bf16 v[120:123], v[162:165], v[186:189], v[120:123]
	v_mfma_f32_16x16x32_bf16 v[108:111], v[148:151], v[196:199], v[108:111]
	v_mfma_f32_16x16x32_bf16 v[104:107], v[162:165], v[196:199], v[104:107]
	v_mfma_f32_16x16x32_bf16 v[92:95], v[148:151], v[204:207], v[92:95]
	v_mfma_f32_16x16x32_bf16 v[88:91], v[162:165], v[204:207], v[88:91]
	v_mfma_f32_16x16x32_bf16 v[76:79], v[148:151], v[212:215], v[76:79]
	v_mfma_f32_16x16x32_bf16 v[72:75], v[162:165], v[212:215], v[72:75]
	s_setprio 0
	s_setprio 1
	v_mfma_f32_16x16x32_bf16 v[116:119], v[166:169], v[182:185], v[116:119]
	v_mfma_f32_16x16x32_bf16 v[112:115], v[174:177], v[182:185], v[112:115]
	v_mfma_f32_16x16x32_bf16 v[100:103], v[166:169], v[190:193], v[100:103]
	v_mfma_f32_16x16x32_bf16 v[96:99], v[174:177], v[190:193], v[96:99]
	v_mfma_f32_16x16x32_bf16 v[84:87], v[166:169], v[200:203], v[84:87]
	v_mfma_f32_16x16x32_bf16 v[80:83], v[174:177], v[200:203], v[80:83]
	v_mfma_f32_16x16x32_bf16 v[68:71], v[166:169], v[208:211], v[68:71]
	v_mfma_f32_16x16x32_bf16 v[64:67], v[174:177], v[208:211], v[64:67]
	v_mfma_f32_16x16x32_bf16 v[116:119], v[170:173], v[186:189], v[116:119]
	v_mfma_f32_16x16x32_bf16 v[112:115], v[178:181], v[186:189], v[112:115]
	v_mfma_f32_16x16x32_bf16 v[100:103], v[170:173], v[196:199], v[100:103]
	v_mfma_f32_16x16x32_bf16 v[96:99], v[178:181], v[196:199], v[96:99]
	v_mfma_f32_16x16x32_bf16 v[84:87], v[170:173], v[204:207], v[84:87]
	v_mfma_f32_16x16x32_bf16 v[80:83], v[178:181], v[204:207], v[80:83]
	v_mfma_f32_16x16x32_bf16 v[68:71], v[170:173], v[212:215], v[68:71]
	v_mfma_f32_16x16x32_bf16 v[64:67], v[178:181], v[212:215], v[64:67]
	s_setprio 0
	s_barrier
	s_add_i32 s41, s41, s80
	v_lshl_add_u64 v[216:217], v[216:217], 0, s[26:27]
	s_mov_b32 m0, s41
	ds_read_b128 v[182:185], v161 offset:49152
	ds_read_b128 v[186:189], v161 offset:50176
	ds_read_b128 v[190:193], v161 offset:51200
	ds_read_b128 v[196:199], v161 offset:52224
	ds_read_b128 v[200:203], v161 offset:53248
	ds_read_b128 v[204:207], v161 offset:54272
	ds_read_b128 v[208:211], v161 offset:55296
	ds_read_b128 v[212:215], v161 offset:56320
	global_load_lds_dwordx4 v[216:217], off
	s_add_i32 m0, s41, 0x2000
	s_add_u32 s62, s62, 0x20080
	v_lshl_add_u64 v[216:217], v[218:219], 0, s[26:27]
	s_addc_u32 s63, s63, 0
	s_add_i32 s41, s43, s80
	global_load_lds_dwordx4 v[216:217], off
	v_lshl_add_u64 v[216:217], s[62:63], 0, v[130:131]
	s_mov_b32 m0, s41
	s_nop 0
	global_load_lds_dwordx4 v[216:217], off
	v_lshl_add_u64 v[216:217], s[62:63], 0, v[134:135]
	s_add_i32 m0, s41, 0x2000
	s_nop 0
	global_load_lds_dwordx4 v[216:217], off
	v_lshl_add_u64 v[216:217], v[220:221], 0, s[26:27]
	s_mov_b32 m0, s87
	s_nop 0
	global_load_lds_dwordx4 v[216:217], off
	s_waitcnt vmcnt(7)
	s_waitcnt lgkmcnt(0)
	s_barrier
	s_setprio 1
	s_waitcnt lgkmcnt(0)
	v_mfma_f32_16x16x32_bf16 v[60:63], v[144:147], v[182:185], v[60:63]
	v_mfma_f32_16x16x32_bf16 v[56:59], v[152:155], v[182:185], v[56:59]
	v_mfma_f32_16x16x32_bf16 v[44:47], v[144:147], v[190:193], v[44:47]
	v_mfma_f32_16x16x32_bf16 v[40:43], v[152:155], v[190:193], v[40:43]
	v_mfma_f32_16x16x32_bf16 v[28:31], v[144:147], v[200:203], v[28:31]
	v_mfma_f32_16x16x32_bf16 v[24:27], v[152:155], v[200:203], v[24:27]
	v_mfma_f32_16x16x32_bf16 v[12:15], v[144:147], v[208:211], v[12:15]
	v_mfma_f32_16x16x32_bf16 v[8:11], v[152:155], v[208:211], v[8:11]
	v_mfma_f32_16x16x32_bf16 v[60:63], v[148:151], v[186:189], v[60:63]
	v_mfma_f32_16x16x32_bf16 v[56:59], v[162:165], v[186:189], v[56:59]
	v_mfma_f32_16x16x32_bf16 v[44:47], v[148:151], v[196:199], v[44:47]
	v_mfma_f32_16x16x32_bf16 v[40:43], v[162:165], v[196:199], v[40:43]
	v_mfma_f32_16x16x32_bf16 v[28:31], v[148:151], v[204:207], v[28:31]
	v_mfma_f32_16x16x32_bf16 v[24:27], v[162:165], v[204:207], v[24:27]
	v_mfma_f32_16x16x32_bf16 v[12:15], v[148:151], v[212:215], v[12:15]
	v_mfma_f32_16x16x32_bf16 v[8:11], v[162:165], v[212:215], v[8:11]
	s_setprio 0
	s_setprio 1
	v_mfma_f32_16x16x32_bf16 v[52:55], v[166:169], v[182:185], v[52:55]
	v_mfma_f32_16x16x32_bf16 v[48:51], v[174:177], v[182:185], v[48:51]
	v_mfma_f32_16x16x32_bf16 v[36:39], v[166:169], v[190:193], v[36:39]
	v_mfma_f32_16x16x32_bf16 v[32:35], v[174:177], v[190:193], v[32:35]
	v_mfma_f32_16x16x32_bf16 v[20:23], v[166:169], v[200:203], v[20:23]
	v_mfma_f32_16x16x32_bf16 v[16:19], v[174:177], v[200:203], v[16:19]
	v_mfma_f32_16x16x32_bf16 v[4:7], v[166:169], v[208:211], v[4:7]
	v_mfma_f32_16x16x32_bf16 v[0:3], v[174:177], v[208:211], v[0:3]
	v_mfma_f32_16x16x32_bf16 v[52:55], v[170:173], v[186:189], v[52:55]
	v_mfma_f32_16x16x32_bf16 v[48:51], v[178:181], v[186:189], v[48:51]
	v_mfma_f32_16x16x32_bf16 v[36:39], v[170:173], v[196:199], v[36:39]
	v_mfma_f32_16x16x32_bf16 v[32:35], v[178:181], v[196:199], v[32:35]
	v_mfma_f32_16x16x32_bf16 v[20:23], v[170:173], v[204:207], v[20:23]
	v_mfma_f32_16x16x32_bf16 v[16:19], v[178:181], v[204:207], v[16:19]
	v_mfma_f32_16x16x32_bf16 v[4:7], v[170:173], v[212:215], v[4:7]
	v_mfma_f32_16x16x32_bf16 v[0:3], v[178:181], v[212:215], v[0:3]
	s_setprio 0
	s_barrier
	v_lshl_add_u64 v[222:223], v[222:223], 0, s[26:27]
	s_mov_b32 m0, s88
	s_nop 0
	global_load_lds_dwordx4 v[222:223], off
	s_add_i32 s39, s39, 2
	s_add_u32 s58, s58, 0x100
	s_addc_u32 s59, s59, 0
	s_add_u32 s15, s15, 0x100
	s_addc_u32 s17, s17, 0
	s_cmp_gt_u32 s39, 5
	s_cbranch_scc0 .LBB0_1451
	s_and_b64 vcc, exec, s[28:29]
	s_cbranch_vccz .LBB0_1454
	s_barrier

.LBB0_1625:
	ds_read_b128 v[144:147], v151
	ds_read_b128 v[156:159], v151 offset:1024
	ds_read_b128 v[160:163], v151 offset:2048
	ds_read_b128 v[164:167], v151 offset:3072
	ds_read_b128 v[168:171], v152
	ds_read_b128 v[172:175], v152 offset:1024
	ds_read_b128 v[176:179], v152 offset:2048
	ds_read_b128 v[180:183], v152 offset:3072
	s_add_u32 s42, s40, 0xfffc0080
	s_addc_u32 s43, s41, -1
	s_cmp_eq_u32 s87, 12
	s_cselect_b32 s45, s31, s43
	s_cselect_b32 s44, s39, s42
	s_cselect_b32 s43, s29, s86
	s_cselect_b32 s42, s84, s85
	v_lshl_add_u64 v[192:193], s[40:41], 0, v[136:137]
	s_add_i32 m0, s63, 0xc000
	ds_read_b128 v[184:187], v153
	ds_read_b128 v[188:191], v153 offset:1024
	ds_read_b128 v[196:199], v153 offset:2048
	ds_read_b128 v[200:203], v153 offset:3072
	ds_read_b128 v[204:207], v153 offset:4096
	ds_read_b128 v[208:211], v153 offset:5120
	ds_read_b128 v[212:215], v153 offset:6144
	ds_read_b128 v[216:219], v153 offset:7168
	global_load_lds_dwordx4 v[192:193], off
	v_lshl_add_u64 v[192:193], s[40:41], 0, v[138:139]
	s_add_i32 m0, s63, 0xe000
	s_nop 0
	global_load_lds_dwordx4 v[192:193], off
	s_waitcnt vmcnt(8)
	s_waitcnt lgkmcnt(0)
	s_barrier
	s_setprio 1
	s_waitcnt lgkmcnt(0)
	v_mfma_f32_16x16x32_bf16 v[124:127], v[144:147], v[184:187], v[124:127]
	v_mfma_f32_16x16x32_bf16 v[120:123], v[160:163], v[184:187], v[120:123]
	v_mfma_f32_16x16x32_bf16 v[108:111], v[144:147], v[196:199], v[108:111]
	v_mfma_f32_16x16x32_bf16 v[104:107], v[160:163], v[196:199], v[104:107]
	v_mfma_f32_16x16x32_bf16 v[92:95], v[144:147], v[204:207], v[92:95]
	v_mfma_f32_16x16x32_bf16 v[88:91], v[160:163], v[204:207], v[88:91]
	v_mfma_f32_16x16x32_bf16 v[76:79], v[144:147], v[212:215], v[76:79]
	v_mfma_f32_16x16x32_bf16 v[72:75], v[160:163], v[212:215], v[72:75]
	v_mfma_f32_16x16x32_bf16 v[124:127], v[156:159], v[188:191], v[124:127]
	v_mfma_f32_16x16x32_bf16 v[120:123], v[164:167], v[188:191], v[120:123]
	v_mfma_f32_16x16x32_bf16 v[108:111], v[156:159], v[200:203], v[108:111]
	v_mfma_f32_16x16x32_bf16 v[104:107], v[164:167], v[200:203], v[104:107]
	v_mfma_f32_16x16x32_bf16 v[92:95], v[156:159], v[208:211], v[92:95]
	v_mfma_f32_16x16x32_bf16 v[88:91], v[164:167], v[208:211], v[88:91]
	v_mfma_f32_16x16x32_bf16 v[76:79], v[156:159], v[216:219], v[76:79]
	v_mfma_f32_16x16x32_bf16 v[72:75], v[164:167], v[216:219], v[72:75]
	s_setprio 0
	s_setprio 1
	v_mfma_f32_16x16x32_bf16 v[116:119], v[168:171], v[184:187], v[116:119]
	v_mfma_f32_16x16x32_bf16 v[112:115], v[176:179], v[184:187], v[112:115]
	v_mfma_f32_16x16x32_bf16 v[100:103], v[168:171], v[196:199], v[100:103]
	v_mfma_f32_16x16x32_bf16 v[96:99], v[176:179], v[196:199], v[96:99]
	v_mfma_f32_16x16x32_bf16 v[84:87], v[168:171], v[204:207], v[84:87]
	v_mfma_f32_16x16x32_bf16 v[80:83], v[176:179], v[204:207], v[80:83]
	v_mfma_f32_16x16x32_bf16 v[68:71], v[168:171], v[212:215], v[68:71]
	v_mfma_f32_16x16x32_bf16 v[64:67], v[176:179], v[212:215], v[64:67]
	v_mfma_f32_16x16x32_bf16 v[116:119], v[172:175], v[188:191], v[116:119]
	v_mfma_f32_16x16x32_bf16 v[112:115], v[180:183], v[188:191], v[112:115]
	v_mfma_f32_16x16x32_bf16 v[100:103], v[172:175], v[200:203], v[100:103]
	v_mfma_f32_16x16x32_bf16 v[96:99], v[180:183], v[200:203], v[96:99]
	v_mfma_f32_16x16x32_bf16 v[84:87], v[172:175], v[208:211], v[84:87]
	v_mfma_f32_16x16x32_bf16 v[80:83], v[180:183], v[208:211], v[80:83]
	v_mfma_f32_16x16x32_bf16 v[68:71], v[172:175], v[216:219], v[68:71]
	v_mfma_f32_16x16x32_bf16 v[64:67], v[180:183], v[216:219], v[64:67]
	s_setprio 0
	s_barrier
	s_add_i32 s88, s81, s62
	v_lshl_add_u64 v[192:193], s[42:43], 0, v[130:131]
	s_mov_b32 m0, s88
	ds_read_b128 v[184:187], v153 offset:16384
	ds_read_b128 v[188:191], v153 offset:17408
	ds_read_b128 v[196:199], v153 offset:18432
	ds_read_b128 v[200:203], v153 offset:19456
	ds_read_b128 v[204:207], v153 offset:20480
	ds_read_b128 v[208:211], v153 offset:21504
	ds_read_b128 v[212:215], v153 offset:22528
	ds_read_b128 v[216:219], v153 offset:23552
	global_load_lds_dwordx4 v[192:193], off
	s_add_i32 m0, s88, 0x2000
	s_add_u32 s88, s42, 0x40000
	v_lshl_add_u64 v[220:221], s[42:43], 0, v[134:135]
	s_addc_u32 s89, s43, 0
	s_add_i32 s90, s82, s62
	global_load_lds_dwordx4 v[220:221], off
	v_lshl_add_u64 v[222:223], s[88:89], 0, v[130:131]
	s_mov_b32 m0, s90
	v_lshl_add_u64 v[224:225], s[44:45], 0, v[132:133]
	global_load_lds_dwordx4 v[222:223], off
	v_lshl_add_u64 v[222:223], s[88:89], 0, v[134:135]
	s_add_i32 m0, s90, 0x2000
	s_nop 0
	global_load_lds_dwordx4 v[222:223], off
	v_lshl_add_u64 v[222:223], s[44:45], 0, v[128:129]
	s_mov_b32 m0, s63
	s_nop 0
	global_load_lds_dwordx4 v[222:223], off
	s_waitcnt vmcnt(7)
	s_waitcnt lgkmcnt(0)
	s_barrier
	s_setprio 1
	s_waitcnt lgkmcnt(0)
	v_mfma_f32_16x16x32_bf16 v[60:63], v[144:147], v[184:187], v[60:63]
	v_mfma_f32_16x16x32_bf16 v[56:59], v[160:163], v[184:187], v[56:59]
	v_mfma_f32_16x16x32_bf16 v[44:47], v[144:147], v[196:199], v[44:47]
	v_mfma_f32_16x16x32_bf16 v[40:43], v[160:163], v[196:199], v[40:43]
	v_mfma_f32_16x16x32_bf16 v[28:31], v[144:147], v[204:207], v[28:31]
	v_mfma_f32_16x16x32_bf16 v[24:27], v[160:163], v[204:207], v[24:27]
	v_mfma_f32_16x16x32_bf16 v[12:15], v[144:147], v[212:215], v[12:15]
	v_mfma_f32_16x16x32_bf16 v[8:11], v[160:163], v[212:215], v[8:11]
	v_mfma_f32_16x16x32_bf16 v[60:63], v[156:159], v[188:191], v[60:63]
	v_mfma_f32_16x16x32_bf16 v[56:59], v[164:167], v[188:191], v[56:59]
	v_mfma_f32_16x16x32_bf16 v[44:47], v[156:159], v[200:203], v[44:47]
	v_mfma_f32_16x16x32_bf16 v[40:43], v[164:167], v[200:203], v[40:43]
	v_mfma_f32_16x16x32_bf16 v[28:31], v[156:159], v[208:211], v[28:31]
	v_mfma_f32_16x16x32_bf16 v[24:27], v[164:167], v[208:211], v[24:27]
	v_mfma_f32_16x16x32_bf16 v[12:15], v[156:159], v[216:219], v[12:15]
	v_mfma_f32_16x16x32_bf16 v[8:11], v[164:167], v[216:219], v[8:11]
	s_setprio 0
	s_setprio 1
	v_mfma_f32_16x16x32_bf16 v[52:55], v[168:171], v[184:187], v[52:55]
	v_mfma_f32_16x16x32_bf16 v[48:51], v[176:179], v[184:187], v[48:51]
	v_mfma_f32_16x16x32_bf16 v[36:39], v[168:171], v[196:199], v[36:39]
	v_mfma_f32_16x16x32_bf16 v[32:35], v[176:179], v[196:199], v[32:35]
	v_mfma_f32_16x16x32_bf16 v[20:23], v[168:171], v[204:207], v[20:23]
	v_mfma_f32_16x16x32_bf16 v[16:19], v[176:179], v[204:207], v[16:19]
	v_mfma_f32_16x16x32_bf16 v[4:7], v[168:171], v[212:215], v[4:7]
	v_mfma_f32_16x16x32_bf16 v[0:3], v[176:179], v[212:215], v[0:3]
	v_mfma_f32_16x16x32_bf16 v[52:55], v[172:175], v[188:191], v[52:55]
	v_mfma_f32_16x16x32_bf16 v[48:51], v[180:183], v[188:191], v[48:51]
	v_mfma_f32_16x16x32_bf16 v[36:39], v[172:175], v[200:203], v[36:39]
	v_mfma_f32_16x16x32_bf16 v[32:35], v[180:183], v[200:203], v[32:35]
	v_mfma_f32_16x16x32_bf16 v[20:23], v[172:175], v[208:211], v[20:23]
	v_mfma_f32_16x16x32_bf16 v[16:19], v[180:183], v[208:211], v[16:19]
	v_mfma_f32_16x16x32_bf16 v[4:7], v[172:175], v[216:219], v[4:7]
	v_mfma_f32_16x16x32_bf16 v[0:3], v[180:183], v[216:219], v[0:3]
	s_setprio 0
	s_barrier
	s_add_i32 s88, 0, 0x18000
	v_add_u32_e32 v155, s88, v149
	s_add_i32 s89, 0, 0x1c000
	ds_read_b128 v[144:147], v155
	ds_read_b128 v[156:159], v155 offset:1024
	ds_read_b128 v[160:163], v155 offset:2048
	ds_read_b128 v[164:167], v155 offset:3072
	v_add_u32_e32 v155, s89, v149
	ds_read_b128 v[168:171], v155
	ds_read_b128 v[172:175], v155 offset:1024
	ds_read_b128 v[176:179], v155 offset:2048
	ds_read_b128 v[180:183], v155 offset:3072
	s_add_u32 s44, s44, 0x40000
	s_addc_u32 s45, s45, 0
	v_lshl_add_u64 v[226:227], s[44:45], 0, v[128:129]
	ds_read_b128 v[184:187], v153 offset:32768
	ds_read_b128 v[188:191], v153 offset:33792
	ds_read_b128 v[196:199], v153 offset:34816
	ds_read_b128 v[200:203], v153 offset:35840
	ds_read_b128 v[204:207], v153 offset:36864
	ds_read_b128 v[208:211], v153 offset:37888
	ds_read_b128 v[212:215], v153 offset:38912
	ds_read_b128 v[216:219], v153 offset:39936
	s_mov_b32 m0, s70
	s_nop 0
	global_load_lds_dwordx4 v[224:225], off
	s_mov_b32 m0, s71
	s_nop 0
	global_load_lds_dwordx4 v[226:227], off
	v_lshl_add_u64 v[226:227], s[44:45], 0, v[132:133]
	s_mov_b32 m0, s72
	s_nop 0
	global_load_lds_dwordx4 v[226:227], off
	s_waitcnt vmcnt(8)
	s_waitcnt lgkmcnt(0)
	s_barrier
	s_setprio 1
	s_waitcnt lgkmcnt(0)
	v_mfma_f32_16x16x32_bf16 v[124:127], v[144:147], v[184:187], v[124:127]
	v_mfma_f32_16x16x32_bf16 v[120:123], v[160:163], v[184:187], v[120:123]
	v_mfma_f32_16x16x32_bf16 v[108:111], v[144:147], v[196:199], v[108:111]
	v_mfma_f32_16x16x32_bf16 v[104:107], v[160:163], v[196:199], v[104:107]
	v_mfma_f32_16x16x32_bf16 v[92:95], v[144:147], v[204:207], v[92:95]
	v_mfma_f32_16x16x32_bf16 v[88:91], v[160:163], v[204:207], v[88:91]
	v_mfma_f32_16x16x32_bf16 v[76:79], v[144:147], v[212:215], v[76:79]
	v_mfma_f32_16x16x32_bf16 v[72:75], v[160:163], v[212:215], v[72:75]
	v_mfma_f32_16x16x32_bf16 v[124:127], v[156:159], v[188:191], v[124:127]
	v_mfma_f32_16x16x32_bf16 v[120:123], v[164:167], v[188:191], v[120:123]
	v_mfma_f32_16x16x32_bf16 v[108:111], v[156:159], v[200:203], v[108:111]
	v_mfma_f32_16x16x32_bf16 v[104:107], v[164:167], v[200:203], v[104:107]
	v_mfma_f32_16x16x32_bf16 v[92:95], v[156:159], v[208:211], v[92:95]
	v_mfma_f32_16x16x32_bf16 v[88:91], v[164:167], v[208:211], v[88:91]
	v_mfma_f32_16x16x32_bf16 v[76:79], v[156:159], v[216:219], v[76:79]
	v_mfma_f32_16x16x32_bf16 v[72:75], v[164:167], v[216:219], v[72:75]
	s_setprio 0
	s_setprio 1
	v_mfma_f32_16x16x32_bf16 v[116:119], v[168:171], v[184:187], v[116:119]
	v_mfma_f32_16x16x32_bf16 v[112:115], v[176:179], v[184:187], v[112:115]
	v_mfma_f32_16x16x32_bf16 v[100:103], v[168:171], v[196:199], v[100:103]
	v_mfma_f32_16x16x32_bf16 v[96:99], v[176:179], v[196:199], v[96:99]
	v_mfma_f32_16x16x32_bf16 v[84:87], v[168:171], v[204:207], v[84:87]
	v_mfma_f32_16x16x32_bf16 v[80:83], v[176:179], v[204:207], v[80:83]
	v_mfma_f32_16x16x32_bf16 v[68:71], v[168:171], v[212:215], v[68:71]
	v_mfma_f32_16x16x32_bf16 v[64:67], v[176:179], v[212:215], v[64:67]
	v_mfma_f32_16x16x32_bf16 v[116:119], v[172:175], v[188:191], v[116:119]
	v_mfma_f32_16x16x32_bf16 v[112:115], v[180:183], v[188:191], v[112:115]
	v_mfma_f32_16x16x32_bf16 v[100:103], v[172:175], v[200:203], v[100:103]
	v_mfma_f32_16x16x32_bf16 v[96:99], v[180:183], v[200:203], v[96:99]
	v_mfma_f32_16x16x32_bf16 v[84:87], v[172:175], v[208:211], v[84:87]
	v_mfma_f32_16x16x32_bf16 v[80:83], v[180:183], v[208:211], v[80:83]
	v_mfma_f32_16x16x32_bf16 v[68:71], v[172:175], v[216:219], v[68:71]
	v_mfma_f32_16x16x32_bf16 v[64:67], v[180:183], v[216:219], v[64:67]
	s_setprio 0
	s_barrier
	s_add_i32 s44, s88, s62
	v_lshl_add_u64 v[192:193], v[192:193], 0, s[24:25]
	s_mov_b32 m0, s44
	ds_read_b128 v[184:187], v153 offset:49152
	ds_read_b128 v[188:191], v153 offset:50176
	ds_read_b128 v[196:199], v153 offset:51200
	ds_read_b128 v[200:203], v153 offset:52224
	ds_read_b128 v[204:207], v153 offset:53248
	ds_read_b128 v[208:211], v153 offset:54272
	ds_read_b128 v[212:215], v153 offset:55296
	ds_read_b128 v[216:219], v153 offset:56320
	global_load_lds_dwordx4 v[192:193], off
	s_add_i32 m0, s44, 0x2000
	s_add_u32 s42, s42, 0x40080
	v_lshl_add_u64 v[192:193], v[220:221], 0, s[24:25]
	s_addc_u32 s43, s43, 0
	s_add_i32 s44, s89, s62
	global_load_lds_dwordx4 v[192:193], off
	v_lshl_add_u64 v[192:193], s[42:43], 0, v[130:131]
	s_mov_b32 m0, s44
	s_nop 0
	global_load_lds_dwordx4 v[192:193], off
	v_lshl_add_u64 v[192:193], s[42:43], 0, v[134:135]
	s_add_i32 m0, s44, 0x2000
	s_nop 0
	global_load_lds_dwordx4 v[192:193], off
	v_lshl_add_u64 v[192:193], v[222:223], 0, s[24:25]
	s_mov_b32 m0, s78
	s_nop 0
	global_load_lds_dwordx4 v[192:193], off
	s_waitcnt vmcnt(7)
	s_waitcnt lgkmcnt(0)
	s_barrier
	s_setprio 1
	s_waitcnt lgkmcnt(0)
	v_mfma_f32_16x16x32_bf16 v[60:63], v[144:147], v[184:187], v[60:63]
	v_mfma_f32_16x16x32_bf16 v[56:59], v[160:163], v[184:187], v[56:59]
	v_mfma_f32_16x16x32_bf16 v[44:47], v[144:147], v[196:199], v[44:47]
	v_mfma_f32_16x16x32_bf16 v[40:43], v[160:163], v[196:199], v[40:43]
	v_mfma_f32_16x16x32_bf16 v[28:31], v[144:147], v[204:207], v[28:31]
	v_mfma_f32_16x16x32_bf16 v[24:27], v[160:163], v[204:207], v[24:27]
	v_mfma_f32_16x16x32_bf16 v[12:15], v[144:147], v[212:215], v[12:15]
	v_mfma_f32_16x16x32_bf16 v[8:11], v[160:163], v[212:215], v[8:11]
	v_mfma_f32_16x16x32_bf16 v[60:63], v[156:159], v[188:191], v[60:63]
	v_mfma_f32_16x16x32_bf16 v[56:59], v[164:167], v[188:191], v[56:59]
	v_mfma_f32_16x16x32_bf16 v[44:47], v[156:159], v[200:203], v[44:47]
	v_mfma_f32_16x16x32_bf16 v[40:43], v[164:167], v[200:203], v[40:43]
	v_mfma_f32_16x16x32_bf16 v[28:31], v[156:159], v[208:211], v[28:31]
	v_mfma_f32_16x16x32_bf16 v[24:27], v[164:167], v[208:211], v[24:27]
	v_mfma_f32_16x16x32_bf16 v[12:15], v[156:159], v[216:219], v[12:15]
	v_mfma_f32_16x16x32_bf16 v[8:11], v[164:167], v[216:219], v[8:11]
	s_setprio 0
	s_setprio 1
	v_mfma_f32_16x16x32_bf16 v[52:55], v[168:171], v[184:187], v[52:55]
	v_mfma_f32_16x16x32_bf16 v[48:51], v[176:179], v[184:187], v[48:51]
	v_mfma_f32_16x16x32_bf16 v[36:39], v[168:171], v[196:199], v[36:39]
	v_mfma_f32_16x16x32_bf16 v[32:35], v[176:179], v[196:199], v[32:35]
	v_mfma_f32_16x16x32_bf16 v[20:23], v[168:171], v[204:207], v[20:23]
	v_mfma_f32_16x16x32_bf16 v[16:19], v[176:179], v[204:207], v[16:19]
	v_mfma_f32_16x16x32_bf16 v[4:7], v[168:171], v[212:215], v[4:7]
	v_mfma_f32_16x16x32_bf16 v[0:3], v[176:179], v[212:215], v[0:3]
	v_mfma_f32_16x16x32_bf16 v[52:55], v[172:175], v[188:191], v[52:55]
	v_mfma_f32_16x16x32_bf16 v[48:51], v[180:183], v[188:191], v[48:51]
	v_mfma_f32_16x16x32_bf16 v[36:39], v[172:175], v[200:203], v[36:39]
	v_mfma_f32_16x16x32_bf16 v[32:35], v[180:183], v[200:203], v[32:35]
	v_mfma_f32_16x16x32_bf16 v[20:23], v[172:175], v[208:211], v[20:23]
	v_mfma_f32_16x16x32_bf16 v[16:19], v[180:183], v[208:211], v[16:19]
	v_mfma_f32_16x16x32_bf16 v[4:7], v[172:175], v[216:219], v[4:7]
	v_mfma_f32_16x16x32_bf16 v[0:3], v[180:183], v[216:219], v[0:3]
	s_setprio 0
	s_barrier
	v_lshl_add_u64 v[224:225], v[224:225], 0, s[24:25]
	s_mov_b32 m0, s79
	s_nop 0
	global_load_lds_dwordx4 v[224:225], off
	s_add_i32 s87, s87, 2
	s_add_u32 s40, s40, 0x100
	s_addc_u32 s41, s41, 0
	s_add_u32 s85, s85, 0x100
	s_addc_u32 s86, s86, 0
	s_cmp_gt_u32 s87, 13
	s_cbranch_scc0 .LBB0_1625
	s_and_b64 vcc, exec, s[26:27]
	s_cbranch_vccz .LBB0_1628
	s_barrier

.LBB0_1709:
	ds_read_b128 v[154:157], v149
	ds_read_b128 v[158:161], v149 offset:1024
	ds_read_b128 v[162:165], v149 offset:2048
	ds_read_b128 v[166:169], v149 offset:3072
	ds_read_b128 v[170:173], v150
	ds_read_b128 v[174:177], v150 offset:1024
	ds_read_b128 v[178:181], v150 offset:2048
	ds_read_b128 v[182:185], v150 offset:3072
	s_add_u32 s38, s36, 0xfffc0080
	s_addc_u32 s39, s37, -1
	s_cmp_eq_u32 s84, 12
	s_cselect_b32 s41, s27, s39
	s_cselect_b32 s40, s80, s38
	s_cselect_b32 s39, s25, s83
	s_cselect_b32 s38, s81, s82
	v_lshl_add_u64 v[144:145], s[36:37], 0, v[136:137]
	s_add_i32 m0, s35, 0xc000
	ds_read_b128 v[186:189], v151
	ds_read_b128 v[190:193], v151 offset:1024
	ds_read_b128 v[196:199], v151 offset:2048
	ds_read_b128 v[200:203], v151 offset:3072
	ds_read_b128 v[204:207], v151 offset:4096
	ds_read_b128 v[208:211], v151 offset:5120
	ds_read_b128 v[212:215], v151 offset:6144
	ds_read_b128 v[216:219], v151 offset:7168
	global_load_lds_dwordx4 v[144:145], off
	v_lshl_add_u64 v[144:145], s[36:37], 0, v[138:139]
	s_add_i32 m0, s35, 0xe000
	s_nop 0
	global_load_lds_dwordx4 v[144:145], off
	s_waitcnt vmcnt(8)
	s_waitcnt lgkmcnt(0)
	s_barrier
	s_setprio 1
	s_waitcnt lgkmcnt(0)
	v_mfma_f32_16x16x32_bf16 v[116:119], v[154:157], v[186:189], v[116:119]
	v_mfma_f32_16x16x32_bf16 v[112:115], v[162:165], v[186:189], v[112:115]
	v_mfma_f32_16x16x32_bf16 v[100:103], v[154:157], v[196:199], v[100:103]
	v_mfma_f32_16x16x32_bf16 v[96:99], v[162:165], v[196:199], v[96:99]
	v_mfma_f32_16x16x32_bf16 v[84:87], v[154:157], v[204:207], v[84:87]
	v_mfma_f32_16x16x32_bf16 v[80:83], v[162:165], v[204:207], v[80:83]
	v_mfma_f32_16x16x32_bf16 v[68:71], v[154:157], v[212:215], v[68:71]
	v_mfma_f32_16x16x32_bf16 v[64:67], v[162:165], v[212:215], v[64:67]
	v_mfma_f32_16x16x32_bf16 v[116:119], v[158:161], v[190:193], v[116:119]
	v_mfma_f32_16x16x32_bf16 v[112:115], v[166:169], v[190:193], v[112:115]
	v_mfma_f32_16x16x32_bf16 v[100:103], v[158:161], v[200:203], v[100:103]
	v_mfma_f32_16x16x32_bf16 v[96:99], v[166:169], v[200:203], v[96:99]
	v_mfma_f32_16x16x32_bf16 v[84:87], v[158:161], v[208:211], v[84:87]
	v_mfma_f32_16x16x32_bf16 v[80:83], v[166:169], v[208:211], v[80:83]
	v_mfma_f32_16x16x32_bf16 v[68:71], v[158:161], v[216:219], v[68:71]
	v_mfma_f32_16x16x32_bf16 v[64:67], v[166:169], v[216:219], v[64:67]
	s_setprio 0
	s_setprio 1
	v_mfma_f32_16x16x32_bf16 v[124:127], v[170:173], v[186:189], v[124:127]
	v_mfma_f32_16x16x32_bf16 v[120:123], v[178:181], v[186:189], v[120:123]
	v_mfma_f32_16x16x32_bf16 v[108:111], v[170:173], v[196:199], v[108:111]
	v_mfma_f32_16x16x32_bf16 v[104:107], v[178:181], v[196:199], v[104:107]
	v_mfma_f32_16x16x32_bf16 v[92:95], v[170:173], v[204:207], v[92:95]
	v_mfma_f32_16x16x32_bf16 v[88:91], v[178:181], v[204:207], v[88:91]
	v_mfma_f32_16x16x32_bf16 v[76:79], v[170:173], v[212:215], v[76:79]
	v_mfma_f32_16x16x32_bf16 v[72:75], v[178:181], v[212:215], v[72:75]
	v_mfma_f32_16x16x32_bf16 v[124:127], v[174:177], v[190:193], v[124:127]
	v_mfma_f32_16x16x32_bf16 v[120:123], v[182:185], v[190:193], v[120:123]
	v_mfma_f32_16x16x32_bf16 v[108:111], v[174:177], v[200:203], v[108:111]
	v_mfma_f32_16x16x32_bf16 v[104:107], v[182:185], v[200:203], v[104:107]
	v_mfma_f32_16x16x32_bf16 v[92:95], v[174:177], v[208:211], v[92:95]
	v_mfma_f32_16x16x32_bf16 v[88:91], v[182:185], v[208:211], v[88:91]
	v_mfma_f32_16x16x32_bf16 v[76:79], v[174:177], v[216:219], v[76:79]
	v_mfma_f32_16x16x32_bf16 v[72:75], v[182:185], v[216:219], v[72:75]
	s_setprio 0
	s_barrier
	s_add_i32 s85, s71, s56
	v_lshl_add_u64 v[144:145], s[38:39], 0, v[132:133]
	s_mov_b32 m0, s85
	ds_read_b128 v[186:189], v151 offset:16384
	ds_read_b128 v[190:193], v151 offset:17408
	ds_read_b128 v[196:199], v151 offset:18432
	ds_read_b128 v[200:203], v151 offset:19456
	ds_read_b128 v[204:207], v151 offset:20480
	ds_read_b128 v[208:211], v151 offset:21504
	ds_read_b128 v[212:215], v151 offset:22528
	ds_read_b128 v[216:219], v151 offset:23552
	global_load_lds_dwordx4 v[144:145], off
	s_add_i32 m0, s85, 0x2000
	s_add_u32 s86, s38, 0x40000
	v_lshl_add_u64 v[220:221], s[38:39], 0, v[128:129]
	s_addc_u32 s87, s39, 0
	s_add_i32 s85, s72, s56
	global_load_lds_dwordx4 v[220:221], off
	v_lshl_add_u64 v[222:223], s[86:87], 0, v[132:133]
	s_mov_b32 m0, s85
	v_lshl_add_u64 v[224:225], s[40:41], 0, v[130:131]
	global_load_lds_dwordx4 v[222:223], off
	v_lshl_add_u64 v[222:223], s[86:87], 0, v[128:129]
	s_add_i32 m0, s85, 0x2000
	s_nop 0
	global_load_lds_dwordx4 v[222:223], off
	v_lshl_add_u64 v[222:223], s[40:41], 0, v[134:135]
	s_mov_b32 m0, s35
	s_nop 0
	global_load_lds_dwordx4 v[222:223], off
	s_waitcnt vmcnt(7)
	s_waitcnt lgkmcnt(0)
	s_barrier
	s_setprio 1
	s_waitcnt lgkmcnt(0)
	v_mfma_f32_16x16x32_bf16 v[52:55], v[154:157], v[186:189], v[52:55]
	v_mfma_f32_16x16x32_bf16 v[48:51], v[162:165], v[186:189], v[48:51]
	v_mfma_f32_16x16x32_bf16 v[36:39], v[154:157], v[196:199], v[36:39]
	v_mfma_f32_16x16x32_bf16 v[32:35], v[162:165], v[196:199], v[32:35]
	v_mfma_f32_16x16x32_bf16 v[20:23], v[154:157], v[204:207], v[20:23]
	v_mfma_f32_16x16x32_bf16 v[16:19], v[162:165], v[204:207], v[16:19]
	v_mfma_f32_16x16x32_bf16 v[4:7], v[154:157], v[212:215], v[4:7]
	v_mfma_f32_16x16x32_bf16 v[0:3], v[162:165], v[212:215], v[0:3]
	v_mfma_f32_16x16x32_bf16 v[52:55], v[158:161], v[190:193], v[52:55]
	v_mfma_f32_16x16x32_bf16 v[48:51], v[166:169], v[190:193], v[48:51]
	v_mfma_f32_16x16x32_bf16 v[36:39], v[158:161], v[200:203], v[36:39]
	v_mfma_f32_16x16x32_bf16 v[32:35], v[166:169], v[200:203], v[32:35]
	v_mfma_f32_16x16x32_bf16 v[20:23], v[158:161], v[208:211], v[20:23]
	v_mfma_f32_16x16x32_bf16 v[16:19], v[166:169], v[208:211], v[16:19]
	v_mfma_f32_16x16x32_bf16 v[4:7], v[158:161], v[216:219], v[4:7]
	v_mfma_f32_16x16x32_bf16 v[0:3], v[166:169], v[216:219], v[0:3]
	s_setprio 0
	s_setprio 1
	v_mfma_f32_16x16x32_bf16 v[60:63], v[170:173], v[186:189], v[60:63]
	v_mfma_f32_16x16x32_bf16 v[56:59], v[178:181], v[186:189], v[56:59]
	v_mfma_f32_16x16x32_bf16 v[44:47], v[170:173], v[196:199], v[44:47]
	v_mfma_f32_16x16x32_bf16 v[40:43], v[178:181], v[196:199], v[40:43]
	v_mfma_f32_16x16x32_bf16 v[28:31], v[170:173], v[204:207], v[28:31]
	v_mfma_f32_16x16x32_bf16 v[24:27], v[178:181], v[204:207], v[24:27]
	v_mfma_f32_16x16x32_bf16 v[12:15], v[170:173], v[212:215], v[12:15]
	v_mfma_f32_16x16x32_bf16 v[8:11], v[178:181], v[212:215], v[8:11]
	v_mfma_f32_16x16x32_bf16 v[60:63], v[174:177], v[190:193], v[60:63]
	v_mfma_f32_16x16x32_bf16 v[56:59], v[182:185], v[190:193], v[56:59]
	v_mfma_f32_16x16x32_bf16 v[44:47], v[174:177], v[200:203], v[44:47]
	v_mfma_f32_16x16x32_bf16 v[40:43], v[182:185], v[200:203], v[40:43]
	v_mfma_f32_16x16x32_bf16 v[28:31], v[174:177], v[208:211], v[28:31]
	v_mfma_f32_16x16x32_bf16 v[24:27], v[182:185], v[208:211], v[24:27]
	v_mfma_f32_16x16x32_bf16 v[12:15], v[174:177], v[216:219], v[12:15]
	v_mfma_f32_16x16x32_bf16 v[8:11], v[182:185], v[216:219], v[8:11]
	s_setprio 0
	s_barrier
	s_add_i32 s85, 0, 0x18000
	v_add_u32_e32 v153, s85, v147
	s_add_i32 s86, 0, 0x1c000
	ds_read_b128 v[154:157], v153
	ds_read_b128 v[158:161], v153 offset:1024
	ds_read_b128 v[162:165], v153 offset:2048
	ds_read_b128 v[166:169], v153 offset:3072
	v_add_u32_e32 v153, s86, v147
	ds_read_b128 v[170:173], v153
	ds_read_b128 v[174:177], v153 offset:1024
	ds_read_b128 v[178:181], v153 offset:2048
	ds_read_b128 v[182:185], v153 offset:3072
	s_add_u32 s40, s40, 0x40000
	s_addc_u32 s41, s41, 0
	v_lshl_add_u64 v[226:227], s[40:41], 0, v[134:135]
	ds_read_b128 v[186:189], v151 offset:32768
	ds_read_b128 v[190:193], v151 offset:33792
	ds_read_b128 v[196:199], v151 offset:34816
	ds_read_b128 v[200:203], v151 offset:35840
	ds_read_b128 v[204:207], v151 offset:36864
	ds_read_b128 v[208:211], v151 offset:37888
	ds_read_b128 v[212:215], v151 offset:38912
	ds_read_b128 v[216:219], v151 offset:39936
	s_mov_b32 m0, s58
	s_nop 0
	global_load_lds_dwordx4 v[224:225], off
	s_mov_b32 m0, s59
	s_nop 0
	global_load_lds_dwordx4 v[226:227], off
	v_lshl_add_u64 v[226:227], s[40:41], 0, v[130:131]
	s_mov_b32 m0, s60
	s_nop 0
	global_load_lds_dwordx4 v[226:227], off
	s_waitcnt vmcnt(8)
	s_waitcnt lgkmcnt(0)
	s_barrier
	s_setprio 1
	s_waitcnt lgkmcnt(0)
	v_mfma_f32_16x16x32_bf16 v[116:119], v[154:157], v[186:189], v[116:119]
	v_mfma_f32_16x16x32_bf16 v[112:115], v[162:165], v[186:189], v[112:115]
	v_mfma_f32_16x16x32_bf16 v[100:103], v[154:157], v[196:199], v[100:103]
	v_mfma_f32_16x16x32_bf16 v[96:99], v[162:165], v[196:199], v[96:99]
	v_mfma_f32_16x16x32_bf16 v[84:87], v[154:157], v[204:207], v[84:87]
	v_mfma_f32_16x16x32_bf16 v[80:83], v[162:165], v[204:207], v[80:83]
	v_mfma_f32_16x16x32_bf16 v[68:71], v[154:157], v[212:215], v[68:71]
	v_mfma_f32_16x16x32_bf16 v[64:67], v[162:165], v[212:215], v[64:67]
	v_mfma_f32_16x16x32_bf16 v[116:119], v[158:161], v[190:193], v[116:119]
	v_mfma_f32_16x16x32_bf16 v[112:115], v[166:169], v[190:193], v[112:115]
	v_mfma_f32_16x16x32_bf16 v[100:103], v[158:161], v[200:203], v[100:103]
	v_mfma_f32_16x16x32_bf16 v[96:99], v[166:169], v[200:203], v[96:99]
	v_mfma_f32_16x16x32_bf16 v[84:87], v[158:161], v[208:211], v[84:87]
	v_mfma_f32_16x16x32_bf16 v[80:83], v[166:169], v[208:211], v[80:83]
	v_mfma_f32_16x16x32_bf16 v[68:71], v[158:161], v[216:219], v[68:71]
	v_mfma_f32_16x16x32_bf16 v[64:67], v[166:169], v[216:219], v[64:67]
	s_setprio 0
	s_setprio 1
	v_mfma_f32_16x16x32_bf16 v[124:127], v[170:173], v[186:189], v[124:127]
	v_mfma_f32_16x16x32_bf16 v[120:123], v[178:181], v[186:189], v[120:123]
	v_mfma_f32_16x16x32_bf16 v[108:111], v[170:173], v[196:199], v[108:111]
	v_mfma_f32_16x16x32_bf16 v[104:107], v[178:181], v[196:199], v[104:107]
	v_mfma_f32_16x16x32_bf16 v[92:95], v[170:173], v[204:207], v[92:95]
	v_mfma_f32_16x16x32_bf16 v[88:91], v[178:181], v[204:207], v[88:91]
	v_mfma_f32_16x16x32_bf16 v[76:79], v[170:173], v[212:215], v[76:79]
	v_mfma_f32_16x16x32_bf16 v[72:75], v[178:181], v[212:215], v[72:75]
	v_mfma_f32_16x16x32_bf16 v[124:127], v[174:177], v[190:193], v[124:127]
	v_mfma_f32_16x16x32_bf16 v[120:123], v[182:185], v[190:193], v[120:123]
	v_mfma_f32_16x16x32_bf16 v[108:111], v[174:177], v[200:203], v[108:111]
	v_mfma_f32_16x16x32_bf16 v[104:107], v[182:185], v[200:203], v[104:107]
	v_mfma_f32_16x16x32_bf16 v[92:95], v[174:177], v[208:211], v[92:95]
	v_mfma_f32_16x16x32_bf16 v[88:91], v[182:185], v[208:211], v[88:91]
	v_mfma_f32_16x16x32_bf16 v[76:79], v[174:177], v[216:219], v[76:79]
	v_mfma_f32_16x16x32_bf16 v[72:75], v[182:185], v[216:219], v[72:75]
	s_setprio 0
	s_barrier
	s_add_i32 s40, s85, s56
	v_lshl_add_u64 v[144:145], v[144:145], 0, s[20:21]
	s_mov_b32 m0, s40
	ds_read_b128 v[186:189], v151 offset:49152
	ds_read_b128 v[190:193], v151 offset:50176
	ds_read_b128 v[196:199], v151 offset:51200
	ds_read_b128 v[200:203], v151 offset:52224
	ds_read_b128 v[204:207], v151 offset:53248
	ds_read_b128 v[208:211], v151 offset:54272
	ds_read_b128 v[212:215], v151 offset:55296
	ds_read_b128 v[216:219], v151 offset:56320
	global_load_lds_dwordx4 v[144:145], off
	s_add_i32 m0, s40, 0x2000
	s_add_u32 s38, s38, 0x40080
	v_lshl_add_u64 v[144:145], v[220:221], 0, s[20:21]
	s_addc_u32 s39, s39, 0
	s_add_i32 s40, s86, s56
	global_load_lds_dwordx4 v[144:145], off
	v_lshl_add_u64 v[144:145], s[38:39], 0, v[132:133]
	s_mov_b32 m0, s40
	s_nop 0
	global_load_lds_dwordx4 v[144:145], off
	v_lshl_add_u64 v[144:145], s[38:39], 0, v[128:129]
	s_add_i32 m0, s40, 0x2000
	s_nop 0
	global_load_lds_dwordx4 v[144:145], off
	v_lshl_add_u64 v[144:145], v[222:223], 0, s[20:21]
	s_mov_b32 m0, s62
	s_nop 0
	global_load_lds_dwordx4 v[144:145], off
	s_waitcnt vmcnt(7)
	s_waitcnt lgkmcnt(0)
	s_barrier
	s_setprio 1
	s_waitcnt lgkmcnt(0)
	v_mfma_f32_16x16x32_bf16 v[52:55], v[154:157], v[186:189], v[52:55]
	v_mfma_f32_16x16x32_bf16 v[48:51], v[162:165], v[186:189], v[48:51]
	v_mfma_f32_16x16x32_bf16 v[36:39], v[154:157], v[196:199], v[36:39]
	v_mfma_f32_16x16x32_bf16 v[32:35], v[162:165], v[196:199], v[32:35]
	v_mfma_f32_16x16x32_bf16 v[20:23], v[154:157], v[204:207], v[20:23]
	v_mfma_f32_16x16x32_bf16 v[16:19], v[162:165], v[204:207], v[16:19]
	v_mfma_f32_16x16x32_bf16 v[4:7], v[154:157], v[212:215], v[4:7]
	v_mfma_f32_16x16x32_bf16 v[0:3], v[162:165], v[212:215], v[0:3]
	v_mfma_f32_16x16x32_bf16 v[52:55], v[158:161], v[190:193], v[52:55]
	v_mfma_f32_16x16x32_bf16 v[48:51], v[166:169], v[190:193], v[48:51]
	v_mfma_f32_16x16x32_bf16 v[36:39], v[158:161], v[200:203], v[36:39]
	v_mfma_f32_16x16x32_bf16 v[32:35], v[166:169], v[200:203], v[32:35]
	v_mfma_f32_16x16x32_bf16 v[20:23], v[158:161], v[208:211], v[20:23]
	v_mfma_f32_16x16x32_bf16 v[16:19], v[166:169], v[208:211], v[16:19]
	v_mfma_f32_16x16x32_bf16 v[4:7], v[158:161], v[216:219], v[4:7]
	v_mfma_f32_16x16x32_bf16 v[0:3], v[166:169], v[216:219], v[0:3]
	s_setprio 0
	s_setprio 1
	v_mfma_f32_16x16x32_bf16 v[60:63], v[170:173], v[186:189], v[60:63]
	v_mfma_f32_16x16x32_bf16 v[56:59], v[178:181], v[186:189], v[56:59]
	v_mfma_f32_16x16x32_bf16 v[44:47], v[170:173], v[196:199], v[44:47]
	v_mfma_f32_16x16x32_bf16 v[40:43], v[178:181], v[196:199], v[40:43]
	v_mfma_f32_16x16x32_bf16 v[28:31], v[170:173], v[204:207], v[28:31]
	v_mfma_f32_16x16x32_bf16 v[24:27], v[178:181], v[204:207], v[24:27]
	v_mfma_f32_16x16x32_bf16 v[12:15], v[170:173], v[212:215], v[12:15]
	v_mfma_f32_16x16x32_bf16 v[8:11], v[178:181], v[212:215], v[8:11]
	v_mfma_f32_16x16x32_bf16 v[60:63], v[174:177], v[190:193], v[60:63]
	v_mfma_f32_16x16x32_bf16 v[56:59], v[182:185], v[190:193], v[56:59]
	v_mfma_f32_16x16x32_bf16 v[44:47], v[174:177], v[200:203], v[44:47]
	v_mfma_f32_16x16x32_bf16 v[40:43], v[182:185], v[200:203], v[40:43]
	v_mfma_f32_16x16x32_bf16 v[28:31], v[174:177], v[208:211], v[28:31]
	v_mfma_f32_16x16x32_bf16 v[24:27], v[182:185], v[208:211], v[24:27]
	v_mfma_f32_16x16x32_bf16 v[12:15], v[174:177], v[216:219], v[12:15]
	v_mfma_f32_16x16x32_bf16 v[8:11], v[182:185], v[216:219], v[8:11]
	s_setprio 0
	s_barrier
	v_lshl_add_u64 v[224:225], v[224:225], 0, s[20:21]
	s_mov_b32 m0, s63
	s_nop 0
	global_load_lds_dwordx4 v[224:225], off
	s_add_i32 s84, s84, 2
	s_add_u32 s36, s36, 0x100
	s_addc_u32 s37, s37, 0
	s_add_u32 s82, s82, 0x100
	s_addc_u32 s83, s83, 0
	s_cmp_gt_u32 s84, 13
	s_cbranch_scc0 .LBB0_1709
	s_and_b64 vcc, exec, s[22:23]
	s_cbranch_vccz .LBB0_1712
	s_barrier

.LBB0_1791:
	ds_read_b128 v[144:147], v151
	ds_read_b128 v[156:159], v151 offset:1024
	ds_read_b128 v[160:163], v151 offset:2048
	ds_read_b128 v[164:167], v151 offset:3072
	ds_read_b128 v[168:171], v152
	ds_read_b128 v[172:175], v152 offset:1024
	ds_read_b128 v[176:179], v152 offset:2048
	ds_read_b128 v[180:183], v152 offset:3072
	s_add_u32 s38, s36, 0x100
	s_addc_u32 s39, s37, 0
	s_cmp_eq_u32 s85, 40
	s_cselect_b32 s43, s1, s39
	s_cselect_b32 s42, s0, s38
	s_cselect_b32 s41, s35, s84
	s_cselect_b32 s40, s34, s83
	v_lshl_add_u64 v[192:193], s[36:37], 0, v[136:137]
	s_add_i32 m0, s59, 0xc000
	ds_read_b128 v[184:187], v153
	ds_read_b128 v[188:191], v153 offset:1024
	ds_read_b128 v[196:199], v153 offset:2048
	ds_read_b128 v[200:203], v153 offset:3072
	ds_read_b128 v[204:207], v153 offset:4096
	ds_read_b128 v[208:211], v153 offset:5120
	ds_read_b128 v[212:215], v153 offset:6144
	ds_read_b128 v[216:219], v153 offset:7168
	global_load_lds_dwordx4 v[192:193], off
	v_lshl_add_u64 v[192:193], s[36:37], 0, v[138:139]
	s_add_i32 m0, s59, 0xe000
	s_nop 0
	global_load_lds_dwordx4 v[192:193], off
	s_waitcnt vmcnt(8)
	s_waitcnt lgkmcnt(0)
	s_barrier
	s_setprio 1
	s_waitcnt lgkmcnt(0)
	v_mfma_f32_16x16x32_bf16 v[124:127], v[144:147], v[184:187], v[124:127]
	v_mfma_f32_16x16x32_bf16 v[120:123], v[160:163], v[184:187], v[120:123]
	v_mfma_f32_16x16x32_bf16 v[108:111], v[144:147], v[196:199], v[108:111]
	v_mfma_f32_16x16x32_bf16 v[104:107], v[160:163], v[196:199], v[104:107]
	v_mfma_f32_16x16x32_bf16 v[92:95], v[144:147], v[204:207], v[92:95]
	v_mfma_f32_16x16x32_bf16 v[88:91], v[160:163], v[204:207], v[88:91]
	v_mfma_f32_16x16x32_bf16 v[76:79], v[144:147], v[212:215], v[76:79]
	v_mfma_f32_16x16x32_bf16 v[72:75], v[160:163], v[212:215], v[72:75]
	v_mfma_f32_16x16x32_bf16 v[124:127], v[156:159], v[188:191], v[124:127]
	v_mfma_f32_16x16x32_bf16 v[120:123], v[164:167], v[188:191], v[120:123]
	v_mfma_f32_16x16x32_bf16 v[108:111], v[156:159], v[200:203], v[108:111]
	v_mfma_f32_16x16x32_bf16 v[104:107], v[164:167], v[200:203], v[104:107]
	v_mfma_f32_16x16x32_bf16 v[92:95], v[156:159], v[208:211], v[92:95]
	v_mfma_f32_16x16x32_bf16 v[88:91], v[164:167], v[208:211], v[88:91]
	v_mfma_f32_16x16x32_bf16 v[76:79], v[156:159], v[216:219], v[76:79]
	v_mfma_f32_16x16x32_bf16 v[72:75], v[164:167], v[216:219], v[72:75]
	s_setprio 0
	s_setprio 1
	v_mfma_f32_16x16x32_bf16 v[116:119], v[168:171], v[184:187], v[116:119]
	v_mfma_f32_16x16x32_bf16 v[112:115], v[176:179], v[184:187], v[112:115]
	v_mfma_f32_16x16x32_bf16 v[100:103], v[168:171], v[196:199], v[100:103]
	v_mfma_f32_16x16x32_bf16 v[96:99], v[176:179], v[196:199], v[96:99]
	v_mfma_f32_16x16x32_bf16 v[84:87], v[168:171], v[204:207], v[84:87]
	v_mfma_f32_16x16x32_bf16 v[80:83], v[176:179], v[204:207], v[80:83]
	v_mfma_f32_16x16x32_bf16 v[68:71], v[168:171], v[212:215], v[68:71]
	v_mfma_f32_16x16x32_bf16 v[64:67], v[176:179], v[212:215], v[64:67]
	v_mfma_f32_16x16x32_bf16 v[116:119], v[172:175], v[188:191], v[116:119]
	v_mfma_f32_16x16x32_bf16 v[112:115], v[180:183], v[188:191], v[112:115]
	v_mfma_f32_16x16x32_bf16 v[100:103], v[172:175], v[200:203], v[100:103]
	v_mfma_f32_16x16x32_bf16 v[96:99], v[180:183], v[200:203], v[96:99]
	v_mfma_f32_16x16x32_bf16 v[84:87], v[172:175], v[208:211], v[84:87]
	v_mfma_f32_16x16x32_bf16 v[80:83], v[180:183], v[208:211], v[80:83]
	v_mfma_f32_16x16x32_bf16 v[68:71], v[172:175], v[216:219], v[68:71]
	v_mfma_f32_16x16x32_bf16 v[64:67], v[180:183], v[216:219], v[64:67]
	s_setprio 0
	s_barrier
	s_add_i32 s36, s73, s58
	v_lshl_add_u64 v[192:193], s[40:41], 0, v[130:131]
	s_mov_b32 m0, s36
	ds_read_b128 v[184:187], v153 offset:16384
	ds_read_b128 v[188:191], v153 offset:17408
	ds_read_b128 v[196:199], v153 offset:18432
	ds_read_b128 v[200:203], v153 offset:19456
	ds_read_b128 v[204:207], v153 offset:20480
	ds_read_b128 v[208:211], v153 offset:21504
	ds_read_b128 v[212:215], v153 offset:22528
	ds_read_b128 v[216:219], v153 offset:23552
	global_load_lds_dwordx4 v[192:193], off
	s_add_i32 m0, s36, 0x2000
	s_add_u32 s36, s40, 0xb0000
	v_lshl_add_u64 v[220:221], s[40:41], 0, v[134:135]
	s_addc_u32 s37, s41, 0
	s_add_i32 s86, s78, s58
	global_load_lds_dwordx4 v[220:221], off
	v_lshl_add_u64 v[222:223], s[36:37], 0, v[130:131]
	s_mov_b32 m0, s86
	v_lshl_add_u64 v[224:225], s[42:43], 0, v[132:133]
	global_load_lds_dwordx4 v[222:223], off
	v_lshl_add_u64 v[222:223], s[36:37], 0, v[134:135]
	s_add_i32 m0, s86, 0x2000
	s_nop 0
	global_load_lds_dwordx4 v[222:223], off
	v_lshl_add_u64 v[222:223], s[42:43], 0, v[128:129]
	s_mov_b32 m0, s59
	s_nop 0
	global_load_lds_dwordx4 v[222:223], off
	s_waitcnt vmcnt(7)
	s_waitcnt lgkmcnt(0)
	s_barrier
	s_setprio 1
	s_waitcnt lgkmcnt(0)
	v_mfma_f32_16x16x32_bf16 v[60:63], v[144:147], v[184:187], v[60:63]
	v_mfma_f32_16x16x32_bf16 v[56:59], v[160:163], v[184:187], v[56:59]
	v_mfma_f32_16x16x32_bf16 v[44:47], v[144:147], v[196:199], v[44:47]
	v_mfma_f32_16x16x32_bf16 v[40:43], v[160:163], v[196:199], v[40:43]
	v_mfma_f32_16x16x32_bf16 v[28:31], v[144:147], v[204:207], v[28:31]
	v_mfma_f32_16x16x32_bf16 v[24:27], v[160:163], v[204:207], v[24:27]
	v_mfma_f32_16x16x32_bf16 v[12:15], v[144:147], v[212:215], v[12:15]
	v_mfma_f32_16x16x32_bf16 v[8:11], v[160:163], v[212:215], v[8:11]
	v_mfma_f32_16x16x32_bf16 v[60:63], v[156:159], v[188:191], v[60:63]
	v_mfma_f32_16x16x32_bf16 v[56:59], v[164:167], v[188:191], v[56:59]
	v_mfma_f32_16x16x32_bf16 v[44:47], v[156:159], v[200:203], v[44:47]
	v_mfma_f32_16x16x32_bf16 v[40:43], v[164:167], v[200:203], v[40:43]
	v_mfma_f32_16x16x32_bf16 v[28:31], v[156:159], v[208:211], v[28:31]
	v_mfma_f32_16x16x32_bf16 v[24:27], v[164:167], v[208:211], v[24:27]
	v_mfma_f32_16x16x32_bf16 v[12:15], v[156:159], v[216:219], v[12:15]
	v_mfma_f32_16x16x32_bf16 v[8:11], v[164:167], v[216:219], v[8:11]
	s_setprio 0
	s_setprio 1
	v_mfma_f32_16x16x32_bf16 v[52:55], v[168:171], v[184:187], v[52:55]
	v_mfma_f32_16x16x32_bf16 v[48:51], v[176:179], v[184:187], v[48:51]
	v_mfma_f32_16x16x32_bf16 v[36:39], v[168:171], v[196:199], v[36:39]
	v_mfma_f32_16x16x32_bf16 v[32:35], v[176:179], v[196:199], v[32:35]
	v_mfma_f32_16x16x32_bf16 v[20:23], v[168:171], v[204:207], v[20:23]
	v_mfma_f32_16x16x32_bf16 v[16:19], v[176:179], v[204:207], v[16:19]
	v_mfma_f32_16x16x32_bf16 v[4:7], v[168:171], v[212:215], v[4:7]
	v_mfma_f32_16x16x32_bf16 v[0:3], v[176:179], v[212:215], v[0:3]
	v_mfma_f32_16x16x32_bf16 v[52:55], v[172:175], v[188:191], v[52:55]
	v_mfma_f32_16x16x32_bf16 v[48:51], v[180:183], v[188:191], v[48:51]
	v_mfma_f32_16x16x32_bf16 v[36:39], v[172:175], v[200:203], v[36:39]
	v_mfma_f32_16x16x32_bf16 v[32:35], v[180:183], v[200:203], v[32:35]
	v_mfma_f32_16x16x32_bf16 v[20:23], v[172:175], v[208:211], v[20:23]
	v_mfma_f32_16x16x32_bf16 v[16:19], v[180:183], v[208:211], v[16:19]
	v_mfma_f32_16x16x32_bf16 v[4:7], v[172:175], v[216:219], v[4:7]
	v_mfma_f32_16x16x32_bf16 v[0:3], v[180:183], v[216:219], v[0:3]
	s_setprio 0
	s_barrier
	s_add_i32 s86, 0, 0x18000
	v_add_u32_e32 v155, s86, v149
	s_add_i32 s87, 0, 0x1c000
	ds_read_b128 v[144:147], v155
	ds_read_b128 v[156:159], v155 offset:1024
	ds_read_b128 v[160:163], v155 offset:2048
	ds_read_b128 v[164:167], v155 offset:3072
	v_add_u32_e32 v155, s87, v149
	ds_read_b128 v[168:171], v155
	ds_read_b128 v[172:175], v155 offset:1024
	ds_read_b128 v[176:179], v155 offset:2048
	ds_read_b128 v[180:183], v155 offset:3072
	s_add_u32 s36, s42, 0xb0000
	s_addc_u32 s37, s43, 0
	v_lshl_add_u64 v[226:227], s[36:37], 0, v[128:129]
	ds_read_b128 v[184:187], v153 offset:32768
	ds_read_b128 v[188:191], v153 offset:33792
	ds_read_b128 v[196:199], v153 offset:34816
	ds_read_b128 v[200:203], v153 offset:35840
	ds_read_b128 v[204:207], v153 offset:36864
	ds_read_b128 v[208:211], v153 offset:37888
	ds_read_b128 v[212:215], v153 offset:38912
	ds_read_b128 v[216:219], v153 offset:39936
	s_mov_b32 m0, s60
	s_nop 0
	global_load_lds_dwordx4 v[224:225], off
	s_mov_b32 m0, s61
	s_nop 0
	global_load_lds_dwordx4 v[226:227], off
	v_lshl_add_u64 v[226:227], s[36:37], 0, v[132:133]
	s_mov_b32 m0, s62
	s_nop 0
	global_load_lds_dwordx4 v[226:227], off
	s_waitcnt vmcnt(8)
	s_waitcnt lgkmcnt(0)
	s_barrier
	s_setprio 1
	s_waitcnt lgkmcnt(0)
	v_mfma_f32_16x16x32_bf16 v[124:127], v[144:147], v[184:187], v[124:127]
	v_mfma_f32_16x16x32_bf16 v[120:123], v[160:163], v[184:187], v[120:123]
	v_mfma_f32_16x16x32_bf16 v[108:111], v[144:147], v[196:199], v[108:111]
	v_mfma_f32_16x16x32_bf16 v[104:107], v[160:163], v[196:199], v[104:107]
	v_mfma_f32_16x16x32_bf16 v[92:95], v[144:147], v[204:207], v[92:95]
	v_mfma_f32_16x16x32_bf16 v[88:91], v[160:163], v[204:207], v[88:91]
	v_mfma_f32_16x16x32_bf16 v[76:79], v[144:147], v[212:215], v[76:79]
	v_mfma_f32_16x16x32_bf16 v[72:75], v[160:163], v[212:215], v[72:75]
	v_mfma_f32_16x16x32_bf16 v[124:127], v[156:159], v[188:191], v[124:127]
	v_mfma_f32_16x16x32_bf16 v[120:123], v[164:167], v[188:191], v[120:123]
	v_mfma_f32_16x16x32_bf16 v[108:111], v[156:159], v[200:203], v[108:111]
	v_mfma_f32_16x16x32_bf16 v[104:107], v[164:167], v[200:203], v[104:107]
	v_mfma_f32_16x16x32_bf16 v[92:95], v[156:159], v[208:211], v[92:95]
	v_mfma_f32_16x16x32_bf16 v[88:91], v[164:167], v[208:211], v[88:91]
	v_mfma_f32_16x16x32_bf16 v[76:79], v[156:159], v[216:219], v[76:79]
	v_mfma_f32_16x16x32_bf16 v[72:75], v[164:167], v[216:219], v[72:75]
	s_setprio 0
	s_setprio 1
	v_mfma_f32_16x16x32_bf16 v[116:119], v[168:171], v[184:187], v[116:119]
	v_mfma_f32_16x16x32_bf16 v[112:115], v[176:179], v[184:187], v[112:115]
	v_mfma_f32_16x16x32_bf16 v[100:103], v[168:171], v[196:199], v[100:103]
	v_mfma_f32_16x16x32_bf16 v[96:99], v[176:179], v[196:199], v[96:99]
	v_mfma_f32_16x16x32_bf16 v[84:87], v[168:171], v[204:207], v[84:87]
	v_mfma_f32_16x16x32_bf16 v[80:83], v[176:179], v[204:207], v[80:83]
	v_mfma_f32_16x16x32_bf16 v[68:71], v[168:171], v[212:215], v[68:71]
	v_mfma_f32_16x16x32_bf16 v[64:67], v[176:179], v[212:215], v[64:67]
	v_mfma_f32_16x16x32_bf16 v[116:119], v[172:175], v[188:191], v[116:119]
	v_mfma_f32_16x16x32_bf16 v[112:115], v[180:183], v[188:191], v[112:115]
	v_mfma_f32_16x16x32_bf16 v[100:103], v[172:175], v[200:203], v[100:103]
	v_mfma_f32_16x16x32_bf16 v[96:99], v[180:183], v[200:203], v[96:99]
	v_mfma_f32_16x16x32_bf16 v[84:87], v[172:175], v[208:211], v[84:87]
	v_mfma_f32_16x16x32_bf16 v[80:83], v[180:183], v[208:211], v[80:83]
	v_mfma_f32_16x16x32_bf16 v[68:71], v[172:175], v[216:219], v[68:71]
	v_mfma_f32_16x16x32_bf16 v[64:67], v[180:183], v[216:219], v[64:67]
	s_setprio 0
	s_barrier
	s_add_i32 s36, s86, s58
	v_lshl_add_u64 v[192:193], v[192:193], 0, s[28:29]
	s_mov_b32 m0, s36
	ds_read_b128 v[184:187], v153 offset:49152
	ds_read_b128 v[188:191], v153 offset:50176
	ds_read_b128 v[196:199], v153 offset:51200
	ds_read_b128 v[200:203], v153 offset:52224
	ds_read_b128 v[204:207], v153 offset:53248
	ds_read_b128 v[208:211], v153 offset:54272
	ds_read_b128 v[212:215], v153 offset:55296
	ds_read_b128 v[216:219], v153 offset:56320
	global_load_lds_dwordx4 v[192:193], off
	s_add_i32 m0, s36, 0x2000
	s_add_u32 s36, s40, 0xb0080
	v_lshl_add_u64 v[192:193], v[220:221], 0, s[28:29]
	s_addc_u32 s37, s41, 0
	s_add_i32 s40, s87, s58
	global_load_lds_dwordx4 v[192:193], off
	v_lshl_add_u64 v[192:193], s[36:37], 0, v[130:131]
	s_mov_b32 m0, s40
	s_nop 0
	global_load_lds_dwordx4 v[192:193], off
	v_lshl_add_u64 v[192:193], s[36:37], 0, v[134:135]
	s_add_i32 m0, s40, 0x2000
	s_nop 0
	global_load_lds_dwordx4 v[192:193], off
	v_lshl_add_u64 v[192:193], v[222:223], 0, s[28:29]
	s_mov_b32 m0, s70
	s_nop 0
	global_load_lds_dwordx4 v[192:193], off
	s_waitcnt vmcnt(7)
	s_waitcnt lgkmcnt(0)
	s_barrier
	s_setprio 1
	s_waitcnt lgkmcnt(0)
	v_mfma_f32_16x16x32_bf16 v[60:63], v[144:147], v[184:187], v[60:63]
	v_mfma_f32_16x16x32_bf16 v[56:59], v[160:163], v[184:187], v[56:59]
	v_mfma_f32_16x16x32_bf16 v[44:47], v[144:147], v[196:199], v[44:47]
	v_mfma_f32_16x16x32_bf16 v[40:43], v[160:163], v[196:199], v[40:43]
	v_mfma_f32_16x16x32_bf16 v[28:31], v[144:147], v[204:207], v[28:31]
	v_mfma_f32_16x16x32_bf16 v[24:27], v[160:163], v[204:207], v[24:27]
	v_mfma_f32_16x16x32_bf16 v[12:15], v[144:147], v[212:215], v[12:15]
	v_mfma_f32_16x16x32_bf16 v[8:11], v[160:163], v[212:215], v[8:11]
	v_mfma_f32_16x16x32_bf16 v[60:63], v[156:159], v[188:191], v[60:63]
	v_mfma_f32_16x16x32_bf16 v[56:59], v[164:167], v[188:191], v[56:59]
	v_mfma_f32_16x16x32_bf16 v[44:47], v[156:159], v[200:203], v[44:47]
	v_mfma_f32_16x16x32_bf16 v[40:43], v[164:167], v[200:203], v[40:43]
	v_mfma_f32_16x16x32_bf16 v[28:31], v[156:159], v[208:211], v[28:31]
	v_mfma_f32_16x16x32_bf16 v[24:27], v[164:167], v[208:211], v[24:27]
	v_mfma_f32_16x16x32_bf16 v[12:15], v[156:159], v[216:219], v[12:15]
	v_mfma_f32_16x16x32_bf16 v[8:11], v[164:167], v[216:219], v[8:11]
	s_setprio 0
	s_setprio 1
	v_mfma_f32_16x16x32_bf16 v[52:55], v[168:171], v[184:187], v[52:55]
	v_mfma_f32_16x16x32_bf16 v[48:51], v[176:179], v[184:187], v[48:51]
	v_mfma_f32_16x16x32_bf16 v[36:39], v[168:171], v[196:199], v[36:39]
	v_mfma_f32_16x16x32_bf16 v[32:35], v[176:179], v[196:199], v[32:35]
	v_mfma_f32_16x16x32_bf16 v[20:23], v[168:171], v[204:207], v[20:23]
	v_mfma_f32_16x16x32_bf16 v[16:19], v[176:179], v[204:207], v[16:19]
	v_mfma_f32_16x16x32_bf16 v[4:7], v[168:171], v[212:215], v[4:7]
	v_mfma_f32_16x16x32_bf16 v[0:3], v[176:179], v[212:215], v[0:3]
	v_mfma_f32_16x16x32_bf16 v[52:55], v[172:175], v[188:191], v[52:55]
	v_mfma_f32_16x16x32_bf16 v[48:51], v[180:183], v[188:191], v[48:51]
	v_mfma_f32_16x16x32_bf16 v[36:39], v[172:175], v[200:203], v[36:39]
	v_mfma_f32_16x16x32_bf16 v[32:35], v[180:183], v[200:203], v[32:35]
	v_mfma_f32_16x16x32_bf16 v[20:23], v[172:175], v[208:211], v[20:23]
	v_mfma_f32_16x16x32_bf16 v[16:19], v[180:183], v[208:211], v[16:19]
	v_mfma_f32_16x16x32_bf16 v[4:7], v[172:175], v[216:219], v[4:7]
	v_mfma_f32_16x16x32_bf16 v[0:3], v[180:183], v[216:219], v[0:3]
	s_setprio 0
	s_barrier
	v_lshl_add_u64 v[224:225], v[224:225], 0, s[28:29]
	s_mov_b32 m0, s71
	s_nop 0
	global_load_lds_dwordx4 v[224:225], off
	s_add_i32 s85, s85, 2
	s_add_u32 s83, s83, 0x100
	s_addc_u32 s84, s84, 0
	s_cmp_gt_u32 s85, 41
	s_mov_b64 s[36:37], s[38:39]
	s_cbranch_scc0 .LBB0_1791
	s_and_b64 vcc, exec, s[30:31]
	s_cbranch_vccz .LBB0_1794
	s_barrier

.LBB0_2142:
	ds_read_b128 v[144:147], v151
	ds_read_b128 v[156:159], v151 offset:1024
	ds_read_b128 v[160:163], v151 offset:2048
	ds_read_b128 v[164:167], v151 offset:3072
	ds_read_b128 v[168:171], v152
	ds_read_b128 v[172:175], v152 offset:1024
	ds_read_b128 v[176:179], v152 offset:2048
	ds_read_b128 v[180:183], v152 offset:3072
	s_add_u32 s38, s36, 0x100
	s_addc_u32 s39, s37, 0
	s_cmp_eq_u32 s83, 40
	s_cselect_b32 s43, s1, s39
	s_cselect_b32 s42, s0, s38
	s_cselect_b32 s41, s35, s82
	s_cselect_b32 s40, s34, s81
	v_lshl_add_u64 v[192:193], s[36:37], 0, v[136:137]
	s_add_i32 m0, s57, 0xc000
	ds_read_b128 v[184:187], v153
	ds_read_b128 v[188:191], v153 offset:1024
	ds_read_b128 v[196:199], v153 offset:2048
	ds_read_b128 v[200:203], v153 offset:3072
	ds_read_b128 v[204:207], v153 offset:4096
	ds_read_b128 v[208:211], v153 offset:5120
	ds_read_b128 v[212:215], v153 offset:6144
	ds_read_b128 v[216:219], v153 offset:7168
	global_load_lds_dwordx4 v[192:193], off
	v_lshl_add_u64 v[192:193], s[36:37], 0, v[138:139]
	s_add_i32 m0, s57, 0xe000
	s_nop 0
	global_load_lds_dwordx4 v[192:193], off
	s_waitcnt vmcnt(8)
	s_waitcnt lgkmcnt(0)
	s_barrier
	s_setprio 1
	s_waitcnt lgkmcnt(0)
	v_mfma_f32_16x16x32_bf16 v[124:127], v[144:147], v[184:187], v[124:127]
	v_mfma_f32_16x16x32_bf16 v[120:123], v[160:163], v[184:187], v[120:123]
	v_mfma_f32_16x16x32_bf16 v[108:111], v[144:147], v[196:199], v[108:111]
	v_mfma_f32_16x16x32_bf16 v[104:107], v[160:163], v[196:199], v[104:107]
	v_mfma_f32_16x16x32_bf16 v[92:95], v[144:147], v[204:207], v[92:95]
	v_mfma_f32_16x16x32_bf16 v[88:91], v[160:163], v[204:207], v[88:91]
	v_mfma_f32_16x16x32_bf16 v[76:79], v[144:147], v[212:215], v[76:79]
	v_mfma_f32_16x16x32_bf16 v[72:75], v[160:163], v[212:215], v[72:75]
	v_mfma_f32_16x16x32_bf16 v[124:127], v[156:159], v[188:191], v[124:127]
	v_mfma_f32_16x16x32_bf16 v[120:123], v[164:167], v[188:191], v[120:123]
	v_mfma_f32_16x16x32_bf16 v[108:111], v[156:159], v[200:203], v[108:111]
	v_mfma_f32_16x16x32_bf16 v[104:107], v[164:167], v[200:203], v[104:107]
	v_mfma_f32_16x16x32_bf16 v[92:95], v[156:159], v[208:211], v[92:95]
	v_mfma_f32_16x16x32_bf16 v[88:91], v[164:167], v[208:211], v[88:91]
	v_mfma_f32_16x16x32_bf16 v[76:79], v[156:159], v[216:219], v[76:79]
	v_mfma_f32_16x16x32_bf16 v[72:75], v[164:167], v[216:219], v[72:75]
	s_setprio 0
	s_setprio 1
	v_mfma_f32_16x16x32_bf16 v[116:119], v[168:171], v[184:187], v[116:119]
	v_mfma_f32_16x16x32_bf16 v[112:115], v[176:179], v[184:187], v[112:115]
	v_mfma_f32_16x16x32_bf16 v[100:103], v[168:171], v[196:199], v[100:103]
	v_mfma_f32_16x16x32_bf16 v[96:99], v[176:179], v[196:199], v[96:99]
	v_mfma_f32_16x16x32_bf16 v[84:87], v[168:171], v[204:207], v[84:87]
	v_mfma_f32_16x16x32_bf16 v[80:83], v[176:179], v[204:207], v[80:83]
	v_mfma_f32_16x16x32_bf16 v[68:71], v[168:171], v[212:215], v[68:71]
	v_mfma_f32_16x16x32_bf16 v[64:67], v[176:179], v[212:215], v[64:67]
	v_mfma_f32_16x16x32_bf16 v[116:119], v[172:175], v[188:191], v[116:119]
	v_mfma_f32_16x16x32_bf16 v[112:115], v[180:183], v[188:191], v[112:115]
	v_mfma_f32_16x16x32_bf16 v[100:103], v[172:175], v[200:203], v[100:103]
	v_mfma_f32_16x16x32_bf16 v[96:99], v[180:183], v[200:203], v[96:99]
	v_mfma_f32_16x16x32_bf16 v[84:87], v[172:175], v[208:211], v[84:87]
	v_mfma_f32_16x16x32_bf16 v[80:83], v[180:183], v[208:211], v[80:83]
	v_mfma_f32_16x16x32_bf16 v[68:71], v[172:175], v[216:219], v[68:71]
	v_mfma_f32_16x16x32_bf16 v[64:67], v[180:183], v[216:219], v[64:67]
	s_setprio 0
	s_barrier
	s_add_i32 s36, s71, s56
	v_lshl_add_u64 v[192:193], s[40:41], 0, v[130:131]
	s_mov_b32 m0, s36
	ds_read_b128 v[184:187], v153 offset:16384
	ds_read_b128 v[188:191], v153 offset:17408
	ds_read_b128 v[196:199], v153 offset:18432
	ds_read_b128 v[200:203], v153 offset:19456
	ds_read_b128 v[204:207], v153 offset:20480
	ds_read_b128 v[208:211], v153 offset:21504
	ds_read_b128 v[212:215], v153 offset:22528
	ds_read_b128 v[216:219], v153 offset:23552
	global_load_lds_dwordx4 v[192:193], off
	s_add_i32 m0, s36, 0x2000
	s_add_u32 s36, s40, 0xb0000
	v_lshl_add_u64 v[220:221], s[40:41], 0, v[134:135]
	s_addc_u32 s37, s41, 0
	s_add_i32 s84, s72, s56
	global_load_lds_dwordx4 v[220:221], off
	v_lshl_add_u64 v[222:223], s[36:37], 0, v[130:131]
	s_mov_b32 m0, s84
	v_lshl_add_u64 v[224:225], s[42:43], 0, v[132:133]
	global_load_lds_dwordx4 v[222:223], off
	v_lshl_add_u64 v[222:223], s[36:37], 0, v[134:135]
	s_add_i32 m0, s84, 0x2000
	s_nop 0
	global_load_lds_dwordx4 v[222:223], off
	v_lshl_add_u64 v[222:223], s[42:43], 0, v[128:129]
	s_mov_b32 m0, s57
	s_nop 0
	global_load_lds_dwordx4 v[222:223], off
	s_waitcnt vmcnt(7)
	s_waitcnt lgkmcnt(0)
	s_barrier
	s_setprio 1
	s_waitcnt lgkmcnt(0)
	v_mfma_f32_16x16x32_bf16 v[60:63], v[144:147], v[184:187], v[60:63]
	v_mfma_f32_16x16x32_bf16 v[56:59], v[160:163], v[184:187], v[56:59]
	v_mfma_f32_16x16x32_bf16 v[44:47], v[144:147], v[196:199], v[44:47]
	v_mfma_f32_16x16x32_bf16 v[40:43], v[160:163], v[196:199], v[40:43]
	v_mfma_f32_16x16x32_bf16 v[28:31], v[144:147], v[204:207], v[28:31]
	v_mfma_f32_16x16x32_bf16 v[24:27], v[160:163], v[204:207], v[24:27]
	v_mfma_f32_16x16x32_bf16 v[12:15], v[144:147], v[212:215], v[12:15]
	v_mfma_f32_16x16x32_bf16 v[8:11], v[160:163], v[212:215], v[8:11]
	v_mfma_f32_16x16x32_bf16 v[60:63], v[156:159], v[188:191], v[60:63]
	v_mfma_f32_16x16x32_bf16 v[56:59], v[164:167], v[188:191], v[56:59]
	v_mfma_f32_16x16x32_bf16 v[44:47], v[156:159], v[200:203], v[44:47]
	v_mfma_f32_16x16x32_bf16 v[40:43], v[164:167], v[200:203], v[40:43]
	v_mfma_f32_16x16x32_bf16 v[28:31], v[156:159], v[208:211], v[28:31]
	v_mfma_f32_16x16x32_bf16 v[24:27], v[164:167], v[208:211], v[24:27]
	v_mfma_f32_16x16x32_bf16 v[12:15], v[156:159], v[216:219], v[12:15]
	v_mfma_f32_16x16x32_bf16 v[8:11], v[164:167], v[216:219], v[8:11]
	s_setprio 0
	s_setprio 1
	v_mfma_f32_16x16x32_bf16 v[52:55], v[168:171], v[184:187], v[52:55]
	v_mfma_f32_16x16x32_bf16 v[48:51], v[176:179], v[184:187], v[48:51]
	v_mfma_f32_16x16x32_bf16 v[36:39], v[168:171], v[196:199], v[36:39]
	v_mfma_f32_16x16x32_bf16 v[32:35], v[176:179], v[196:199], v[32:35]
	v_mfma_f32_16x16x32_bf16 v[20:23], v[168:171], v[204:207], v[20:23]
	v_mfma_f32_16x16x32_bf16 v[16:19], v[176:179], v[204:207], v[16:19]
	v_mfma_f32_16x16x32_bf16 v[4:7], v[168:171], v[212:215], v[4:7]
	v_mfma_f32_16x16x32_bf16 v[0:3], v[176:179], v[212:215], v[0:3]
	v_mfma_f32_16x16x32_bf16 v[52:55], v[172:175], v[188:191], v[52:55]
	v_mfma_f32_16x16x32_bf16 v[48:51], v[180:183], v[188:191], v[48:51]
	v_mfma_f32_16x16x32_bf16 v[36:39], v[172:175], v[200:203], v[36:39]
	v_mfma_f32_16x16x32_bf16 v[32:35], v[180:183], v[200:203], v[32:35]
	v_mfma_f32_16x16x32_bf16 v[20:23], v[172:175], v[208:211], v[20:23]
	v_mfma_f32_16x16x32_bf16 v[16:19], v[180:183], v[208:211], v[16:19]
	v_mfma_f32_16x16x32_bf16 v[4:7], v[172:175], v[216:219], v[4:7]
	v_mfma_f32_16x16x32_bf16 v[0:3], v[180:183], v[216:219], v[0:3]
	s_setprio 0
	s_barrier
	s_add_i32 s84, 0, 0x18000
	v_add_u32_e32 v155, s84, v149
	s_add_i32 s85, 0, 0x1c000
	ds_read_b128 v[144:147], v155
	ds_read_b128 v[156:159], v155 offset:1024
	ds_read_b128 v[160:163], v155 offset:2048
	ds_read_b128 v[164:167], v155 offset:3072
	v_add_u32_e32 v155, s85, v149
	ds_read_b128 v[168:171], v155
	ds_read_b128 v[172:175], v155 offset:1024
	ds_read_b128 v[176:179], v155 offset:2048
	ds_read_b128 v[180:183], v155 offset:3072
	s_add_u32 s36, s42, 0xb0000
	s_addc_u32 s37, s43, 0
	v_lshl_add_u64 v[226:227], s[36:37], 0, v[128:129]
	ds_read_b128 v[184:187], v153 offset:32768
	ds_read_b128 v[188:191], v153 offset:33792
	ds_read_b128 v[196:199], v153 offset:34816
	ds_read_b128 v[200:203], v153 offset:35840
	ds_read_b128 v[204:207], v153 offset:36864
	ds_read_b128 v[208:211], v153 offset:37888
	ds_read_b128 v[212:215], v153 offset:38912
	ds_read_b128 v[216:219], v153 offset:39936
	s_mov_b32 m0, s58
	s_nop 0
	global_load_lds_dwordx4 v[224:225], off
	s_mov_b32 m0, s59
	s_nop 0
	global_load_lds_dwordx4 v[226:227], off
	v_lshl_add_u64 v[226:227], s[36:37], 0, v[132:133]
	s_mov_b32 m0, s60
	s_nop 0
	global_load_lds_dwordx4 v[226:227], off
	s_waitcnt vmcnt(8)
	s_waitcnt lgkmcnt(0)
	s_barrier
	s_setprio 1
	s_waitcnt lgkmcnt(0)
	v_mfma_f32_16x16x32_bf16 v[124:127], v[144:147], v[184:187], v[124:127]
	v_mfma_f32_16x16x32_bf16 v[120:123], v[160:163], v[184:187], v[120:123]
	v_mfma_f32_16x16x32_bf16 v[108:111], v[144:147], v[196:199], v[108:111]
	v_mfma_f32_16x16x32_bf16 v[104:107], v[160:163], v[196:199], v[104:107]
	v_mfma_f32_16x16x32_bf16 v[92:95], v[144:147], v[204:207], v[92:95]
	v_mfma_f32_16x16x32_bf16 v[88:91], v[160:163], v[204:207], v[88:91]
	v_mfma_f32_16x16x32_bf16 v[76:79], v[144:147], v[212:215], v[76:79]
	v_mfma_f32_16x16x32_bf16 v[72:75], v[160:163], v[212:215], v[72:75]
	v_mfma_f32_16x16x32_bf16 v[124:127], v[156:159], v[188:191], v[124:127]
	v_mfma_f32_16x16x32_bf16 v[120:123], v[164:167], v[188:191], v[120:123]
	v_mfma_f32_16x16x32_bf16 v[108:111], v[156:159], v[200:203], v[108:111]
	v_mfma_f32_16x16x32_bf16 v[104:107], v[164:167], v[200:203], v[104:107]
	v_mfma_f32_16x16x32_bf16 v[92:95], v[156:159], v[208:211], v[92:95]
	v_mfma_f32_16x16x32_bf16 v[88:91], v[164:167], v[208:211], v[88:91]
	v_mfma_f32_16x16x32_bf16 v[76:79], v[156:159], v[216:219], v[76:79]
	v_mfma_f32_16x16x32_bf16 v[72:75], v[164:167], v[216:219], v[72:75]
	s_setprio 0
	s_setprio 1
	v_mfma_f32_16x16x32_bf16 v[116:119], v[168:171], v[184:187], v[116:119]
	v_mfma_f32_16x16x32_bf16 v[112:115], v[176:179], v[184:187], v[112:115]
	v_mfma_f32_16x16x32_bf16 v[100:103], v[168:171], v[196:199], v[100:103]
	v_mfma_f32_16x16x32_bf16 v[96:99], v[176:179], v[196:199], v[96:99]
	v_mfma_f32_16x16x32_bf16 v[84:87], v[168:171], v[204:207], v[84:87]
	v_mfma_f32_16x16x32_bf16 v[80:83], v[176:179], v[204:207], v[80:83]
	v_mfma_f32_16x16x32_bf16 v[68:71], v[168:171], v[212:215], v[68:71]
	v_mfma_f32_16x16x32_bf16 v[64:67], v[176:179], v[212:215], v[64:67]
	v_mfma_f32_16x16x32_bf16 v[116:119], v[172:175], v[188:191], v[116:119]
	v_mfma_f32_16x16x32_bf16 v[112:115], v[180:183], v[188:191], v[112:115]
	v_mfma_f32_16x16x32_bf16 v[100:103], v[172:175], v[200:203], v[100:103]
	v_mfma_f32_16x16x32_bf16 v[96:99], v[180:183], v[200:203], v[96:99]
	v_mfma_f32_16x16x32_bf16 v[84:87], v[172:175], v[208:211], v[84:87]
	v_mfma_f32_16x16x32_bf16 v[80:83], v[180:183], v[208:211], v[80:83]
	v_mfma_f32_16x16x32_bf16 v[68:71], v[172:175], v[216:219], v[68:71]
	v_mfma_f32_16x16x32_bf16 v[64:67], v[180:183], v[216:219], v[64:67]
	s_setprio 0
	s_barrier
	s_add_i32 s36, s84, s56
	v_lshl_add_u64 v[192:193], v[192:193], 0, s[28:29]
	s_mov_b32 m0, s36
	ds_read_b128 v[184:187], v153 offset:49152
	ds_read_b128 v[188:191], v153 offset:50176
	ds_read_b128 v[196:199], v153 offset:51200
	ds_read_b128 v[200:203], v153 offset:52224
	ds_read_b128 v[204:207], v153 offset:53248
	ds_read_b128 v[208:211], v153 offset:54272
	ds_read_b128 v[212:215], v153 offset:55296
	ds_read_b128 v[216:219], v153 offset:56320
	global_load_lds_dwordx4 v[192:193], off
	s_add_i32 m0, s36, 0x2000
	s_add_u32 s36, s40, 0xb0080
	v_lshl_add_u64 v[192:193], v[220:221], 0, s[28:29]
	s_addc_u32 s37, s41, 0
	s_add_i32 s40, s85, s56
	global_load_lds_dwordx4 v[192:193], off
	v_lshl_add_u64 v[192:193], s[36:37], 0, v[130:131]
	s_mov_b32 m0, s40
	s_nop 0
	global_load_lds_dwordx4 v[192:193], off
	v_lshl_add_u64 v[192:193], s[36:37], 0, v[134:135]
	s_add_i32 m0, s40, 0x2000
	s_nop 0
	global_load_lds_dwordx4 v[192:193], off
	v_lshl_add_u64 v[192:193], v[222:223], 0, s[28:29]
	s_mov_b32 m0, s62
	s_nop 0
	global_load_lds_dwordx4 v[192:193], off
	s_waitcnt vmcnt(7)
	s_waitcnt lgkmcnt(0)
	s_barrier
	s_setprio 1
	s_waitcnt lgkmcnt(0)
	v_mfma_f32_16x16x32_bf16 v[60:63], v[144:147], v[184:187], v[60:63]
	v_mfma_f32_16x16x32_bf16 v[56:59], v[160:163], v[184:187], v[56:59]
	v_mfma_f32_16x16x32_bf16 v[44:47], v[144:147], v[196:199], v[44:47]
	v_mfma_f32_16x16x32_bf16 v[40:43], v[160:163], v[196:199], v[40:43]
	v_mfma_f32_16x16x32_bf16 v[28:31], v[144:147], v[204:207], v[28:31]
	v_mfma_f32_16x16x32_bf16 v[24:27], v[160:163], v[204:207], v[24:27]
	v_mfma_f32_16x16x32_bf16 v[12:15], v[144:147], v[212:215], v[12:15]
	v_mfma_f32_16x16x32_bf16 v[8:11], v[160:163], v[212:215], v[8:11]
	v_mfma_f32_16x16x32_bf16 v[60:63], v[156:159], v[188:191], v[60:63]
	v_mfma_f32_16x16x32_bf16 v[56:59], v[164:167], v[188:191], v[56:59]
	v_mfma_f32_16x16x32_bf16 v[44:47], v[156:159], v[200:203], v[44:47]
	v_mfma_f32_16x16x32_bf16 v[40:43], v[164:167], v[200:203], v[40:43]
	v_mfma_f32_16x16x32_bf16 v[28:31], v[156:159], v[208:211], v[28:31]
	v_mfma_f32_16x16x32_bf16 v[24:27], v[164:167], v[208:211], v[24:27]
	v_mfma_f32_16x16x32_bf16 v[12:15], v[156:159], v[216:219], v[12:15]
	v_mfma_f32_16x16x32_bf16 v[8:11], v[164:167], v[216:219], v[8:11]
	s_setprio 0
	s_setprio 1
	v_mfma_f32_16x16x32_bf16 v[52:55], v[168:171], v[184:187], v[52:55]
	v_mfma_f32_16x16x32_bf16 v[48:51], v[176:179], v[184:187], v[48:51]
	v_mfma_f32_16x16x32_bf16 v[36:39], v[168:171], v[196:199], v[36:39]
	v_mfma_f32_16x16x32_bf16 v[32:35], v[176:179], v[196:199], v[32:35]
	v_mfma_f32_16x16x32_bf16 v[20:23], v[168:171], v[204:207], v[20:23]
	v_mfma_f32_16x16x32_bf16 v[16:19], v[176:179], v[204:207], v[16:19]
	v_mfma_f32_16x16x32_bf16 v[4:7], v[168:171], v[212:215], v[4:7]
	v_mfma_f32_16x16x32_bf16 v[0:3], v[176:179], v[212:215], v[0:3]
	v_mfma_f32_16x16x32_bf16 v[52:55], v[172:175], v[188:191], v[52:55]
	v_mfma_f32_16x16x32_bf16 v[48:51], v[180:183], v[188:191], v[48:51]
	v_mfma_f32_16x16x32_bf16 v[36:39], v[172:175], v[200:203], v[36:39]
	v_mfma_f32_16x16x32_bf16 v[32:35], v[180:183], v[200:203], v[32:35]
	v_mfma_f32_16x16x32_bf16 v[20:23], v[172:175], v[208:211], v[20:23]
	v_mfma_f32_16x16x32_bf16 v[16:19], v[180:183], v[208:211], v[16:19]
	v_mfma_f32_16x16x32_bf16 v[4:7], v[172:175], v[216:219], v[4:7]
	v_mfma_f32_16x16x32_bf16 v[0:3], v[180:183], v[216:219], v[0:3]
	s_setprio 0
	s_barrier
	v_lshl_add_u64 v[224:225], v[224:225], 0, s[28:29]
	s_mov_b32 m0, s63
	s_nop 0
	global_load_lds_dwordx4 v[224:225], off
	s_add_i32 s83, s83, 2
	s_add_u32 s81, s81, 0x100
	s_addc_u32 s82, s82, 0
	s_cmp_gt_u32 s83, 41
	s_mov_b64 s[36:37], s[38:39]
	s_cbranch_scc0 .LBB0_2142
	s_and_b64 vcc, exec, s[30:31]
	s_cbranch_vccz .LBB0_2145
	s_barrier

.LBB0_2236:
	ds_read_b128 v[152:155], v157
	ds_read_b128 v[162:165], v157 offset:1024
	ds_read_b128 v[166:169], v157 offset:2048
	ds_read_b128 v[170:173], v157 offset:3072
	ds_read_b128 v[174:177], v158
	ds_read_b128 v[178:181], v158 offset:1024
	ds_read_b128 v[182:185], v158 offset:2048
	ds_read_b128 v[186:189], v158 offset:3072
	s_add_u32 s42, s40, 0xfffc0080
	s_addc_u32 s43, s41, -1
	s_cmp_eq_u32 s88, 12
	s_cselect_b32 s45, s1, s43
	s_cselect_b32 s44, s15, s42
	s_cselect_b32 s43, s16, s87
	s_cselect_b32 s42, s31, s35
	v_lshl_add_u64 v[224:225], s[40:41], 0, v[144:145]
	s_add_i32 m0, s59, 0xc000
	ds_read_b128 v[190:193], v159
	ds_read_b128 v[196:199], v159 offset:1024
	ds_read_b128 v[200:203], v159 offset:2048
	ds_read_b128 v[204:207], v159 offset:3072
	ds_read_b128 v[208:211], v159 offset:4096
	ds_read_b128 v[212:215], v159 offset:5120
	ds_read_b128 v[216:219], v159 offset:6144
	ds_read_b128 v[220:223], v159 offset:7168
	global_load_lds_dwordx4 v[224:225], off
	v_lshl_add_u64 v[224:225], s[40:41], 0, v[146:147]
	s_add_i32 m0, s59, 0xe000
	s_nop 0
	global_load_lds_dwordx4 v[224:225], off
	s_waitcnt vmcnt(8)
	s_waitcnt lgkmcnt(0)
	s_barrier
	s_setprio 1
	s_waitcnt lgkmcnt(0)
	v_mfma_f32_16x16x32_bf16 v[124:127], v[152:155], v[190:193], v[124:127]
	v_mfma_f32_16x16x32_bf16 v[120:123], v[166:169], v[190:193], v[120:123]
	v_mfma_f32_16x16x32_bf16 v[108:111], v[152:155], v[200:203], v[108:111]
	v_mfma_f32_16x16x32_bf16 v[104:107], v[166:169], v[200:203], v[104:107]
	v_mfma_f32_16x16x32_bf16 v[92:95], v[152:155], v[208:211], v[92:95]
	v_mfma_f32_16x16x32_bf16 v[88:91], v[166:169], v[208:211], v[88:91]
	v_mfma_f32_16x16x32_bf16 v[76:79], v[152:155], v[216:219], v[76:79]
	v_mfma_f32_16x16x32_bf16 v[72:75], v[166:169], v[216:219], v[72:75]
	v_mfma_f32_16x16x32_bf16 v[124:127], v[162:165], v[196:199], v[124:127]
	v_mfma_f32_16x16x32_bf16 v[120:123], v[170:173], v[196:199], v[120:123]
	v_mfma_f32_16x16x32_bf16 v[108:111], v[162:165], v[204:207], v[108:111]
	v_mfma_f32_16x16x32_bf16 v[104:107], v[170:173], v[204:207], v[104:107]
	v_mfma_f32_16x16x32_bf16 v[92:95], v[162:165], v[212:215], v[92:95]
	v_mfma_f32_16x16x32_bf16 v[88:91], v[170:173], v[212:215], v[88:91]
	v_mfma_f32_16x16x32_bf16 v[76:79], v[162:165], v[220:223], v[76:79]
	v_mfma_f32_16x16x32_bf16 v[72:75], v[170:173], v[220:223], v[72:75]
	s_setprio 0
	s_setprio 1
	v_mfma_f32_16x16x32_bf16 v[116:119], v[174:177], v[190:193], v[116:119]
	v_mfma_f32_16x16x32_bf16 v[112:115], v[182:185], v[190:193], v[112:115]
	v_mfma_f32_16x16x32_bf16 v[100:103], v[174:177], v[200:203], v[100:103]
	v_mfma_f32_16x16x32_bf16 v[96:99], v[182:185], v[200:203], v[96:99]
	v_mfma_f32_16x16x32_bf16 v[84:87], v[174:177], v[208:211], v[84:87]
	v_mfma_f32_16x16x32_bf16 v[80:83], v[182:185], v[208:211], v[80:83]
	v_mfma_f32_16x16x32_bf16 v[68:71], v[174:177], v[216:219], v[68:71]
	v_mfma_f32_16x16x32_bf16 v[64:67], v[182:185], v[216:219], v[64:67]
	v_mfma_f32_16x16x32_bf16 v[116:119], v[178:181], v[196:199], v[116:119]
	v_mfma_f32_16x16x32_bf16 v[112:115], v[186:189], v[196:199], v[112:115]
	v_mfma_f32_16x16x32_bf16 v[100:103], v[178:181], v[204:207], v[100:103]
	v_mfma_f32_16x16x32_bf16 v[96:99], v[186:189], v[204:207], v[96:99]
	v_mfma_f32_16x16x32_bf16 v[84:87], v[178:181], v[212:215], v[84:87]
	v_mfma_f32_16x16x32_bf16 v[80:83], v[186:189], v[212:215], v[80:83]
	v_mfma_f32_16x16x32_bf16 v[68:71], v[178:181], v[220:223], v[68:71]
	v_mfma_f32_16x16x32_bf16 v[64:67], v[186:189], v[220:223], v[64:67]
	s_setprio 0
	s_barrier
	s_add_i32 s89, s78, s58
	v_lshl_add_u64 v[224:225], s[42:43], 0, v[130:131]
	s_mov_b32 m0, s89
	ds_read_b128 v[190:193], v159 offset:16384
	ds_read_b128 v[196:199], v159 offset:17408
	ds_read_b128 v[200:203], v159 offset:18432
	ds_read_b128 v[204:207], v159 offset:19456
	ds_read_b128 v[208:211], v159 offset:20480
	ds_read_b128 v[212:215], v159 offset:21504
	ds_read_b128 v[216:219], v159 offset:22528
	ds_read_b128 v[220:223], v159 offset:23552
	global_load_lds_dwordx4 v[224:225], off
	s_add_i32 m0, s89, 0x2000
	s_add_u32 s90, s42, 0x40000
	v_lshl_add_u64 v[226:227], s[42:43], 0, v[134:135]
	s_addc_u32 s91, s43, 0
	s_add_i32 s89, s79, s58
	global_load_lds_dwordx4 v[226:227], off
	v_lshl_add_u64 v[228:229], s[90:91], 0, v[130:131]
	s_mov_b32 m0, s89
	v_lshl_add_u64 v[230:231], s[44:45], 0, v[132:133]
	global_load_lds_dwordx4 v[228:229], off
	v_lshl_add_u64 v[228:229], s[90:91], 0, v[134:135]
	s_add_i32 m0, s89, 0x2000
	s_nop 0
	global_load_lds_dwordx4 v[228:229], off
	v_lshl_add_u64 v[228:229], s[44:45], 0, v[128:129]
	s_mov_b32 m0, s59
	s_nop 0
	global_load_lds_dwordx4 v[228:229], off
	s_waitcnt vmcnt(7)
	s_waitcnt lgkmcnt(0)
	s_barrier
	s_setprio 1
	s_waitcnt lgkmcnt(0)
	v_mfma_f32_16x16x32_bf16 v[60:63], v[152:155], v[190:193], v[60:63]
	v_mfma_f32_16x16x32_bf16 v[56:59], v[166:169], v[190:193], v[56:59]
	v_mfma_f32_16x16x32_bf16 v[44:47], v[152:155], v[200:203], v[44:47]
	v_mfma_f32_16x16x32_bf16 v[40:43], v[166:169], v[200:203], v[40:43]
	v_mfma_f32_16x16x32_bf16 v[28:31], v[152:155], v[208:211], v[28:31]
	v_mfma_f32_16x16x32_bf16 v[24:27], v[166:169], v[208:211], v[24:27]
	v_mfma_f32_16x16x32_bf16 v[12:15], v[152:155], v[216:219], v[12:15]
	v_mfma_f32_16x16x32_bf16 v[8:11], v[166:169], v[216:219], v[8:11]
	v_mfma_f32_16x16x32_bf16 v[60:63], v[162:165], v[196:199], v[60:63]
	v_mfma_f32_16x16x32_bf16 v[56:59], v[170:173], v[196:199], v[56:59]
	v_mfma_f32_16x16x32_bf16 v[44:47], v[162:165], v[204:207], v[44:47]
	v_mfma_f32_16x16x32_bf16 v[40:43], v[170:173], v[204:207], v[40:43]
	v_mfma_f32_16x16x32_bf16 v[28:31], v[162:165], v[212:215], v[28:31]
	v_mfma_f32_16x16x32_bf16 v[24:27], v[170:173], v[212:215], v[24:27]
	v_mfma_f32_16x16x32_bf16 v[12:15], v[162:165], v[220:223], v[12:15]
	v_mfma_f32_16x16x32_bf16 v[8:11], v[170:173], v[220:223], v[8:11]
	s_setprio 0
	s_setprio 1
	v_mfma_f32_16x16x32_bf16 v[52:55], v[174:177], v[190:193], v[52:55]
	v_mfma_f32_16x16x32_bf16 v[48:51], v[182:185], v[190:193], v[48:51]
	v_mfma_f32_16x16x32_bf16 v[36:39], v[174:177], v[200:203], v[36:39]
	v_mfma_f32_16x16x32_bf16 v[32:35], v[182:185], v[200:203], v[32:35]
	v_mfma_f32_16x16x32_bf16 v[20:23], v[174:177], v[208:211], v[20:23]
	v_mfma_f32_16x16x32_bf16 v[16:19], v[182:185], v[208:211], v[16:19]
	v_mfma_f32_16x16x32_bf16 v[4:7], v[174:177], v[216:219], v[4:7]
	v_mfma_f32_16x16x32_bf16 v[0:3], v[182:185], v[216:219], v[0:3]
	v_mfma_f32_16x16x32_bf16 v[52:55], v[178:181], v[196:199], v[52:55]
	v_mfma_f32_16x16x32_bf16 v[48:51], v[186:189], v[196:199], v[48:51]
	v_mfma_f32_16x16x32_bf16 v[36:39], v[178:181], v[204:207], v[36:39]
	v_mfma_f32_16x16x32_bf16 v[32:35], v[186:189], v[204:207], v[32:35]
	v_mfma_f32_16x16x32_bf16 v[20:23], v[178:181], v[212:215], v[20:23]
	v_mfma_f32_16x16x32_bf16 v[16:19], v[186:189], v[212:215], v[16:19]
	v_mfma_f32_16x16x32_bf16 v[4:7], v[178:181], v[220:223], v[4:7]
	v_mfma_f32_16x16x32_bf16 v[0:3], v[186:189], v[220:223], v[0:3]
	s_setprio 0
	s_barrier
	s_add_i32 s89, 0, 0x18000
	v_add_u32_e32 v136, s89, v141
	s_add_i32 s90, 0, 0x1c000
	ds_read_b128 v[152:155], v136
	ds_read_b128 v[162:165], v136 offset:1024
	ds_read_b128 v[166:169], v136 offset:2048
	ds_read_b128 v[170:173], v136 offset:3072
	v_add_u32_e32 v136, s90, v141
	ds_read_b128 v[174:177], v136
	ds_read_b128 v[178:181], v136 offset:1024
	ds_read_b128 v[182:185], v136 offset:2048
	ds_read_b128 v[186:189], v136 offset:3072
	s_add_u32 s44, s44, 0x40000
	s_addc_u32 s45, s45, 0
	v_lshl_add_u64 v[232:233], s[44:45], 0, v[128:129]
	ds_read_b128 v[190:193], v159 offset:32768
	ds_read_b128 v[196:199], v159 offset:33792
	ds_read_b128 v[200:203], v159 offset:34816
	ds_read_b128 v[204:207], v159 offset:35840
	ds_read_b128 v[208:211], v159 offset:36864
	ds_read_b128 v[212:215], v159 offset:37888
	ds_read_b128 v[216:219], v159 offset:38912
	ds_read_b128 v[220:223], v159 offset:39936
	s_mov_b32 m0, s60
	s_nop 0
	global_load_lds_dwordx4 v[230:231], off
	s_mov_b32 m0, s61
	s_nop 0
	global_load_lds_dwordx4 v[232:233], off
	v_lshl_add_u64 v[232:233], s[44:45], 0, v[132:133]
	s_mov_b32 m0, s62
	s_nop 0
	global_load_lds_dwordx4 v[232:233], off
	s_waitcnt vmcnt(8)
	s_waitcnt lgkmcnt(0)
	s_barrier
	s_setprio 1
	s_waitcnt lgkmcnt(0)
	v_mfma_f32_16x16x32_bf16 v[124:127], v[152:155], v[190:193], v[124:127]
	v_mfma_f32_16x16x32_bf16 v[120:123], v[166:169], v[190:193], v[120:123]
	v_mfma_f32_16x16x32_bf16 v[108:111], v[152:155], v[200:203], v[108:111]
	v_mfma_f32_16x16x32_bf16 v[104:107], v[166:169], v[200:203], v[104:107]
	v_mfma_f32_16x16x32_bf16 v[92:95], v[152:155], v[208:211], v[92:95]
	v_mfma_f32_16x16x32_bf16 v[88:91], v[166:169], v[208:211], v[88:91]
	v_mfma_f32_16x16x32_bf16 v[76:79], v[152:155], v[216:219], v[76:79]
	v_mfma_f32_16x16x32_bf16 v[72:75], v[166:169], v[216:219], v[72:75]
	v_mfma_f32_16x16x32_bf16 v[124:127], v[162:165], v[196:199], v[124:127]
	v_mfma_f32_16x16x32_bf16 v[120:123], v[170:173], v[196:199], v[120:123]
	v_mfma_f32_16x16x32_bf16 v[108:111], v[162:165], v[204:207], v[108:111]
	v_mfma_f32_16x16x32_bf16 v[104:107], v[170:173], v[204:207], v[104:107]
	v_mfma_f32_16x16x32_bf16 v[92:95], v[162:165], v[212:215], v[92:95]
	v_mfma_f32_16x16x32_bf16 v[88:91], v[170:173], v[212:215], v[88:91]
	v_mfma_f32_16x16x32_bf16 v[76:79], v[162:165], v[220:223], v[76:79]
	v_mfma_f32_16x16x32_bf16 v[72:75], v[170:173], v[220:223], v[72:75]
	s_setprio 0
	s_setprio 1
	v_mfma_f32_16x16x32_bf16 v[116:119], v[174:177], v[190:193], v[116:119]
	v_mfma_f32_16x16x32_bf16 v[112:115], v[182:185], v[190:193], v[112:115]
	v_mfma_f32_16x16x32_bf16 v[100:103], v[174:177], v[200:203], v[100:103]
	v_mfma_f32_16x16x32_bf16 v[96:99], v[182:185], v[200:203], v[96:99]
	v_mfma_f32_16x16x32_bf16 v[84:87], v[174:177], v[208:211], v[84:87]
	v_mfma_f32_16x16x32_bf16 v[80:83], v[182:185], v[208:211], v[80:83]
	v_mfma_f32_16x16x32_bf16 v[68:71], v[174:177], v[216:219], v[68:71]
	v_mfma_f32_16x16x32_bf16 v[64:67], v[182:185], v[216:219], v[64:67]
	v_mfma_f32_16x16x32_bf16 v[116:119], v[178:181], v[196:199], v[116:119]
	v_mfma_f32_16x16x32_bf16 v[112:115], v[186:189], v[196:199], v[112:115]
	v_mfma_f32_16x16x32_bf16 v[100:103], v[178:181], v[204:207], v[100:103]
	v_mfma_f32_16x16x32_bf16 v[96:99], v[186:189], v[204:207], v[96:99]
	v_mfma_f32_16x16x32_bf16 v[84:87], v[178:181], v[212:215], v[84:87]
	v_mfma_f32_16x16x32_bf16 v[80:83], v[186:189], v[212:215], v[80:83]
	v_mfma_f32_16x16x32_bf16 v[68:71], v[178:181], v[220:223], v[68:71]
	v_mfma_f32_16x16x32_bf16 v[64:67], v[186:189], v[220:223], v[64:67]
	s_setprio 0
	s_barrier
	s_add_i32 s44, s89, s58
	v_lshl_add_u64 v[224:225], v[224:225], 0, s[26:27]
	s_mov_b32 m0, s44
	ds_read_b128 v[190:193], v159 offset:49152
	ds_read_b128 v[196:199], v159 offset:50176
	ds_read_b128 v[200:203], v159 offset:51200
	ds_read_b128 v[204:207], v159 offset:52224
	ds_read_b128 v[208:211], v159 offset:53248
	ds_read_b128 v[212:215], v159 offset:54272
	ds_read_b128 v[216:219], v159 offset:55296
	ds_read_b128 v[220:223], v159 offset:56320
	global_load_lds_dwordx4 v[224:225], off
	s_add_i32 m0, s44, 0x2000
	s_add_u32 s42, s42, 0x40080
	v_lshl_add_u64 v[224:225], v[226:227], 0, s[26:27]
	s_addc_u32 s43, s43, 0
	s_add_i32 s44, s90, s58
	global_load_lds_dwordx4 v[224:225], off
	v_lshl_add_u64 v[224:225], s[42:43], 0, v[130:131]
	s_mov_b32 m0, s44
	s_nop 0
	global_load_lds_dwordx4 v[224:225], off
	v_lshl_add_u64 v[224:225], s[42:43], 0, v[134:135]
	s_add_i32 m0, s44, 0x2000
	s_nop 0
	global_load_lds_dwordx4 v[224:225], off
	v_lshl_add_u64 v[224:225], v[228:229], 0, s[26:27]
	s_mov_b32 m0, s71
	s_nop 0
	global_load_lds_dwordx4 v[224:225], off
	s_waitcnt vmcnt(7)
	s_waitcnt lgkmcnt(0)
	s_barrier
	s_setprio 1
	s_waitcnt lgkmcnt(0)
	v_mfma_f32_16x16x32_bf16 v[60:63], v[152:155], v[190:193], v[60:63]
	v_mfma_f32_16x16x32_bf16 v[56:59], v[166:169], v[190:193], v[56:59]
	v_mfma_f32_16x16x32_bf16 v[44:47], v[152:155], v[200:203], v[44:47]
	v_mfma_f32_16x16x32_bf16 v[40:43], v[166:169], v[200:203], v[40:43]
	v_mfma_f32_16x16x32_bf16 v[28:31], v[152:155], v[208:211], v[28:31]
	v_mfma_f32_16x16x32_bf16 v[24:27], v[166:169], v[208:211], v[24:27]
	v_mfma_f32_16x16x32_bf16 v[12:15], v[152:155], v[216:219], v[12:15]
	v_mfma_f32_16x16x32_bf16 v[8:11], v[166:169], v[216:219], v[8:11]
	v_mfma_f32_16x16x32_bf16 v[60:63], v[162:165], v[196:199], v[60:63]
	v_mfma_f32_16x16x32_bf16 v[56:59], v[170:173], v[196:199], v[56:59]
	v_mfma_f32_16x16x32_bf16 v[44:47], v[162:165], v[204:207], v[44:47]
	v_mfma_f32_16x16x32_bf16 v[40:43], v[170:173], v[204:207], v[40:43]
	v_mfma_f32_16x16x32_bf16 v[28:31], v[162:165], v[212:215], v[28:31]
	v_mfma_f32_16x16x32_bf16 v[24:27], v[170:173], v[212:215], v[24:27]
	v_mfma_f32_16x16x32_bf16 v[12:15], v[162:165], v[220:223], v[12:15]
	v_mfma_f32_16x16x32_bf16 v[8:11], v[170:173], v[220:223], v[8:11]
	s_setprio 0
	s_setprio 1
	v_mfma_f32_16x16x32_bf16 v[52:55], v[174:177], v[190:193], v[52:55]
	v_mfma_f32_16x16x32_bf16 v[48:51], v[182:185], v[190:193], v[48:51]
	v_mfma_f32_16x16x32_bf16 v[36:39], v[174:177], v[200:203], v[36:39]
	v_mfma_f32_16x16x32_bf16 v[32:35], v[182:185], v[200:203], v[32:35]
	v_mfma_f32_16x16x32_bf16 v[20:23], v[174:177], v[208:211], v[20:23]
	v_mfma_f32_16x16x32_bf16 v[16:19], v[182:185], v[208:211], v[16:19]
	v_mfma_f32_16x16x32_bf16 v[4:7], v[174:177], v[216:219], v[4:7]
	v_mfma_f32_16x16x32_bf16 v[0:3], v[182:185], v[216:219], v[0:3]
	v_mfma_f32_16x16x32_bf16 v[52:55], v[178:181], v[196:199], v[52:55]
	v_mfma_f32_16x16x32_bf16 v[48:51], v[186:189], v[196:199], v[48:51]
	v_mfma_f32_16x16x32_bf16 v[36:39], v[178:181], v[204:207], v[36:39]
	v_mfma_f32_16x16x32_bf16 v[32:35], v[186:189], v[204:207], v[32:35]
	v_mfma_f32_16x16x32_bf16 v[20:23], v[178:181], v[212:215], v[20:23]
	v_mfma_f32_16x16x32_bf16 v[16:19], v[186:189], v[212:215], v[16:19]
	v_mfma_f32_16x16x32_bf16 v[4:7], v[178:181], v[220:223], v[4:7]
	v_mfma_f32_16x16x32_bf16 v[0:3], v[186:189], v[220:223], v[0:3]
	s_setprio 0
	s_barrier
	v_lshl_add_u64 v[230:231], v[230:231], 0, s[26:27]
	s_mov_b32 m0, s72
	s_nop 0
	global_load_lds_dwordx4 v[230:231], off
	s_add_i32 s88, s88, 2
	s_add_u32 s40, s40, 0x100
	s_addc_u32 s41, s41, 0
	s_add_u32 s35, s35, 0x100
	s_addc_u32 s87, s87, 0
	s_cmp_gt_u32 s88, 13
	s_cbranch_scc0 .LBB0_2236
	s_and_b64 vcc, exec, s[28:29]
	s_cbranch_vccz .LBB0_2239
	s_barrier

.LBB0_2370:
	ds_read_b128 v[148:151], v144
	ds_read_b128 v[152:155], v144 offset:1024
	ds_read_b128 v[156:159], v144 offset:2048
	ds_read_b128 v[160:163], v144 offset:3072
	ds_read_b128 v[164:167], v145
	ds_read_b128 v[168:171], v145 offset:1024
	ds_read_b128 v[172:175], v145 offset:2048
	ds_read_b128 v[176:179], v145 offset:3072
	s_add_u32 s38, s36, 0x100
	s_addc_u32 s39, s37, 0
	s_cmp_eq_u32 s81, 4
	s_cselect_b32 s43, s31, s39
	s_cselect_b32 s42, s30, s38
	s_cselect_b32 s41, s35, s27
	s_cselect_b32 s40, s34, s17
	v_lshl_add_u64 v[192:193], s[36:37], 0, v[138:139]
	s_add_i32 m0, s55, 0xc000
	ds_read_b128 v[180:183], v146
	ds_read_b128 v[184:187], v146 offset:1024
	ds_read_b128 v[188:191], v146 offset:2048
	ds_read_b128 v[196:199], v146 offset:3072
	ds_read_b128 v[200:203], v146 offset:4096
	ds_read_b128 v[204:207], v146 offset:5120
	ds_read_b128 v[208:211], v146 offset:6144
	ds_read_b128 v[212:215], v146 offset:7168
	global_load_lds_dwordx4 v[192:193], off
	v_lshl_add_u64 v[192:193], s[36:37], 0, v[140:141]
	s_add_i32 m0, s55, 0xe000
	s_nop 0
	global_load_lds_dwordx4 v[192:193], off
	s_waitcnt vmcnt(8)
	s_waitcnt lgkmcnt(0)
	s_barrier
	s_setprio 1
	s_waitcnt lgkmcnt(0)
	v_mfma_f32_16x16x32_bf16 v[124:127], v[148:151], v[180:183], v[124:127]
	v_mfma_f32_16x16x32_bf16 v[120:123], v[156:159], v[180:183], v[120:123]
	v_mfma_f32_16x16x32_bf16 v[116:119], v[148:151], v[188:191], v[116:119]
	v_mfma_f32_16x16x32_bf16 v[112:115], v[156:159], v[188:191], v[112:115]
	v_mfma_f32_16x16x32_bf16 v[104:107], v[148:151], v[200:203], v[104:107]
	v_mfma_f32_16x16x32_bf16 v[96:99], v[156:159], v[200:203], v[96:99]
	v_mfma_f32_16x16x32_bf16 v[88:91], v[148:151], v[208:211], v[88:91]
	v_mfma_f32_16x16x32_bf16 v[80:83], v[156:159], v[208:211], v[80:83]
	v_mfma_f32_16x16x32_bf16 v[124:127], v[152:155], v[184:187], v[124:127]
	v_mfma_f32_16x16x32_bf16 v[120:123], v[160:163], v[184:187], v[120:123]
	v_mfma_f32_16x16x32_bf16 v[116:119], v[152:155], v[196:199], v[116:119]
	v_mfma_f32_16x16x32_bf16 v[112:115], v[160:163], v[196:199], v[112:115]
	v_mfma_f32_16x16x32_bf16 v[104:107], v[152:155], v[204:207], v[104:107]
	v_mfma_f32_16x16x32_bf16 v[96:99], v[160:163], v[204:207], v[96:99]
	v_mfma_f32_16x16x32_bf16 v[88:91], v[152:155], v[212:215], v[88:91]
	v_mfma_f32_16x16x32_bf16 v[80:83], v[160:163], v[212:215], v[80:83]
	s_setprio 0
	s_setprio 1
	v_mfma_f32_16x16x32_bf16 v[108:111], v[164:167], v[180:183], v[108:111]
	v_mfma_f32_16x16x32_bf16 v[100:103], v[172:175], v[180:183], v[100:103]
	v_mfma_f32_16x16x32_bf16 v[92:95], v[164:167], v[188:191], v[92:95]
	v_mfma_f32_16x16x32_bf16 v[84:87], v[172:175], v[188:191], v[84:87]
	v_mfma_f32_16x16x32_bf16 v[76:79], v[164:167], v[200:203], v[76:79]
	v_mfma_f32_16x16x32_bf16 v[72:75], v[172:175], v[200:203], v[72:75]
	v_mfma_f32_16x16x32_bf16 v[68:71], v[164:167], v[208:211], v[68:71]
	v_mfma_f32_16x16x32_bf16 v[64:67], v[172:175], v[208:211], v[64:67]
	v_mfma_f32_16x16x32_bf16 v[108:111], v[168:171], v[184:187], v[108:111]
	v_mfma_f32_16x16x32_bf16 v[100:103], v[176:179], v[184:187], v[100:103]
	v_mfma_f32_16x16x32_bf16 v[92:95], v[168:171], v[196:199], v[92:95]
	v_mfma_f32_16x16x32_bf16 v[84:87], v[176:179], v[196:199], v[84:87]
	v_mfma_f32_16x16x32_bf16 v[76:79], v[168:171], v[204:207], v[76:79]
	v_mfma_f32_16x16x32_bf16 v[72:75], v[176:179], v[204:207], v[72:75]
	v_mfma_f32_16x16x32_bf16 v[68:71], v[168:171], v[212:215], v[68:71]
	v_mfma_f32_16x16x32_bf16 v[64:67], v[176:179], v[212:215], v[64:67]
	s_setprio 0
	s_barrier
	s_add_i32 s36, s71, s54
	v_lshl_add_u64 v[192:193], s[40:41], 0, v[132:133]
	s_mov_b32 m0, s36
	ds_read_b128 v[180:183], v146 offset:16384
	ds_read_b128 v[184:187], v146 offset:17408
	ds_read_b128 v[188:191], v146 offset:18432
	ds_read_b128 v[196:199], v146 offset:19456
	ds_read_b128 v[200:203], v146 offset:20480
	ds_read_b128 v[204:207], v146 offset:21504
	ds_read_b128 v[208:211], v146 offset:22528
	ds_read_b128 v[212:215], v146 offset:23552
	global_load_lds_dwordx4 v[192:193], off
	s_add_i32 m0, s36, 0x2000
	s_add_u32 s36, s40, 0x20000
	v_lshl_add_u64 v[216:217], s[40:41], 0, v[128:129]
	s_addc_u32 s37, s41, 0
	s_add_i32 s82, s72, s54
	global_load_lds_dwordx4 v[216:217], off
	v_lshl_add_u64 v[218:219], s[36:37], 0, v[132:133]
	s_mov_b32 m0, s82
	v_lshl_add_u64 v[220:221], s[42:43], 0, v[130:131]
	global_load_lds_dwordx4 v[218:219], off
	v_lshl_add_u64 v[218:219], s[36:37], 0, v[128:129]
	s_add_i32 m0, s82, 0x2000
	s_nop 0
	global_load_lds_dwordx4 v[218:219], off
	v_lshl_add_u64 v[218:219], s[42:43], 0, v[134:135]
	s_mov_b32 m0, s55
	s_nop 0
	global_load_lds_dwordx4 v[218:219], off
	s_waitcnt vmcnt(7)
	s_waitcnt lgkmcnt(0)
	s_barrier
	s_setprio 1
	s_waitcnt lgkmcnt(0)
	v_mfma_f32_16x16x32_bf16 v[60:63], v[148:151], v[180:183], v[60:63]
	v_mfma_f32_16x16x32_bf16 v[56:59], v[156:159], v[180:183], v[56:59]
	v_mfma_f32_16x16x32_bf16 v[52:55], v[148:151], v[188:191], v[52:55]
	v_mfma_f32_16x16x32_bf16 v[48:51], v[156:159], v[188:191], v[48:51]
	v_mfma_f32_16x16x32_bf16 v[40:43], v[148:151], v[200:203], v[40:43]
	v_mfma_f32_16x16x32_bf16 v[32:35], v[156:159], v[200:203], v[32:35]
	v_mfma_f32_16x16x32_bf16 v[24:27], v[148:151], v[208:211], v[24:27]
	v_mfma_f32_16x16x32_bf16 v[16:19], v[156:159], v[208:211], v[16:19]
	v_mfma_f32_16x16x32_bf16 v[60:63], v[152:155], v[184:187], v[60:63]
	v_mfma_f32_16x16x32_bf16 v[56:59], v[160:163], v[184:187], v[56:59]
	v_mfma_f32_16x16x32_bf16 v[52:55], v[152:155], v[196:199], v[52:55]
	v_mfma_f32_16x16x32_bf16 v[48:51], v[160:163], v[196:199], v[48:51]
	v_mfma_f32_16x16x32_bf16 v[40:43], v[152:155], v[204:207], v[40:43]
	v_mfma_f32_16x16x32_bf16 v[32:35], v[160:163], v[204:207], v[32:35]
	v_mfma_f32_16x16x32_bf16 v[24:27], v[152:155], v[212:215], v[24:27]
	v_mfma_f32_16x16x32_bf16 v[16:19], v[160:163], v[212:215], v[16:19]
	s_setprio 0
	s_setprio 1
	v_mfma_f32_16x16x32_bf16 v[44:47], v[164:167], v[180:183], v[44:47]
	v_mfma_f32_16x16x32_bf16 v[36:39], v[172:175], v[180:183], v[36:39]
	v_mfma_f32_16x16x32_bf16 v[28:31], v[164:167], v[188:191], v[28:31]
	v_mfma_f32_16x16x32_bf16 v[20:23], v[172:175], v[188:191], v[20:23]
	v_mfma_f32_16x16x32_bf16 v[12:15], v[164:167], v[200:203], v[12:15]
	v_mfma_f32_16x16x32_bf16 v[8:11], v[172:175], v[200:203], v[8:11]
	v_mfma_f32_16x16x32_bf16 v[4:7], v[164:167], v[208:211], v[4:7]
	v_mfma_f32_16x16x32_bf16 v[0:3], v[172:175], v[208:211], v[0:3]
	v_mfma_f32_16x16x32_bf16 v[44:47], v[168:171], v[184:187], v[44:47]
	v_mfma_f32_16x16x32_bf16 v[36:39], v[176:179], v[184:187], v[36:39]
	v_mfma_f32_16x16x32_bf16 v[28:31], v[168:171], v[196:199], v[28:31]
	v_mfma_f32_16x16x32_bf16 v[20:23], v[176:179], v[196:199], v[20:23]
	v_mfma_f32_16x16x32_bf16 v[12:15], v[168:171], v[204:207], v[12:15]
	v_mfma_f32_16x16x32_bf16 v[8:11], v[176:179], v[204:207], v[8:11]
	v_mfma_f32_16x16x32_bf16 v[4:7], v[168:171], v[212:215], v[4:7]
	v_mfma_f32_16x16x32_bf16 v[0:3], v[176:179], v[212:215], v[0:3]
	s_setprio 0
	s_barrier
	s_add_i32 s82, 0, 0x18000
	v_add_u32_e32 v147, s82, v143
	s_add_i32 s83, 0, 0x1c000
	ds_read_b128 v[148:151], v147
	ds_read_b128 v[152:155], v147 offset:1024
	ds_read_b128 v[156:159], v147 offset:2048
	ds_read_b128 v[160:163], v147 offset:3072
	v_add_u32_e32 v147, s83, v143
	ds_read_b128 v[164:167], v147
	ds_read_b128 v[168:171], v147 offset:1024
	ds_read_b128 v[172:175], v147 offset:2048
	ds_read_b128 v[176:179], v147 offset:3072
	s_add_u32 s36, s42, 0x30000
	s_addc_u32 s37, s43, 0
	v_lshl_add_u64 v[222:223], s[36:37], 0, v[134:135]
	ds_read_b128 v[180:183], v146 offset:32768
	ds_read_b128 v[184:187], v146 offset:33792
	ds_read_b128 v[188:191], v146 offset:34816
	ds_read_b128 v[196:199], v146 offset:35840
	ds_read_b128 v[200:203], v146 offset:36864
	ds_read_b128 v[204:207], v146 offset:37888
	ds_read_b128 v[208:211], v146 offset:38912
	ds_read_b128 v[212:215], v146 offset:39936
	s_mov_b32 m0, s56
	s_nop 0
	global_load_lds_dwordx4 v[220:221], off
	s_mov_b32 m0, s57
	s_nop 0
	global_load_lds_dwordx4 v[222:223], off
	v_lshl_add_u64 v[222:223], s[36:37], 0, v[130:131]
	s_mov_b32 m0, s58
	s_nop 0
	global_load_lds_dwordx4 v[222:223], off
	s_waitcnt vmcnt(8)
	s_waitcnt lgkmcnt(0)
	s_barrier
	s_setprio 1
	s_waitcnt lgkmcnt(0)
	v_mfma_f32_16x16x32_bf16 v[124:127], v[148:151], v[180:183], v[124:127]
	v_mfma_f32_16x16x32_bf16 v[120:123], v[156:159], v[180:183], v[120:123]
	v_mfma_f32_16x16x32_bf16 v[116:119], v[148:151], v[188:191], v[116:119]
	v_mfma_f32_16x16x32_bf16 v[112:115], v[156:159], v[188:191], v[112:115]
	v_mfma_f32_16x16x32_bf16 v[104:107], v[148:151], v[200:203], v[104:107]
	v_mfma_f32_16x16x32_bf16 v[96:99], v[156:159], v[200:203], v[96:99]
	v_mfma_f32_16x16x32_bf16 v[88:91], v[148:151], v[208:211], v[88:91]
	v_mfma_f32_16x16x32_bf16 v[80:83], v[156:159], v[208:211], v[80:83]
	v_mfma_f32_16x16x32_bf16 v[124:127], v[152:155], v[184:187], v[124:127]
	v_mfma_f32_16x16x32_bf16 v[120:123], v[160:163], v[184:187], v[120:123]
	v_mfma_f32_16x16x32_bf16 v[116:119], v[152:155], v[196:199], v[116:119]
	v_mfma_f32_16x16x32_bf16 v[112:115], v[160:163], v[196:199], v[112:115]
	v_mfma_f32_16x16x32_bf16 v[104:107], v[152:155], v[204:207], v[104:107]
	v_mfma_f32_16x16x32_bf16 v[96:99], v[160:163], v[204:207], v[96:99]
	v_mfma_f32_16x16x32_bf16 v[88:91], v[152:155], v[212:215], v[88:91]
	v_mfma_f32_16x16x32_bf16 v[80:83], v[160:163], v[212:215], v[80:83]
	s_setprio 0
	s_setprio 1
	v_mfma_f32_16x16x32_bf16 v[108:111], v[164:167], v[180:183], v[108:111]
	v_mfma_f32_16x16x32_bf16 v[100:103], v[172:175], v[180:183], v[100:103]
	v_mfma_f32_16x16x32_bf16 v[92:95], v[164:167], v[188:191], v[92:95]
	v_mfma_f32_16x16x32_bf16 v[84:87], v[172:175], v[188:191], v[84:87]
	v_mfma_f32_16x16x32_bf16 v[76:79], v[164:167], v[200:203], v[76:79]
	v_mfma_f32_16x16x32_bf16 v[72:75], v[172:175], v[200:203], v[72:75]
	v_mfma_f32_16x16x32_bf16 v[68:71], v[164:167], v[208:211], v[68:71]
	v_mfma_f32_16x16x32_bf16 v[64:67], v[172:175], v[208:211], v[64:67]
	v_mfma_f32_16x16x32_bf16 v[108:111], v[168:171], v[184:187], v[108:111]
	v_mfma_f32_16x16x32_bf16 v[100:103], v[176:179], v[184:187], v[100:103]
	v_mfma_f32_16x16x32_bf16 v[92:95], v[168:171], v[196:199], v[92:95]
	v_mfma_f32_16x16x32_bf16 v[84:87], v[176:179], v[196:199], v[84:87]
	v_mfma_f32_16x16x32_bf16 v[76:79], v[168:171], v[204:207], v[76:79]
	v_mfma_f32_16x16x32_bf16 v[72:75], v[176:179], v[204:207], v[72:75]
	v_mfma_f32_16x16x32_bf16 v[68:71], v[168:171], v[212:215], v[68:71]
	v_mfma_f32_16x16x32_bf16 v[64:67], v[176:179], v[212:215], v[64:67]
	s_setprio 0
	s_barrier
	s_add_i32 s36, s82, s54
	v_lshl_add_u64 v[192:193], v[192:193], 0, s[14:15]
	s_mov_b32 m0, s36
	ds_read_b128 v[180:183], v146 offset:49152
	ds_read_b128 v[184:187], v146 offset:50176
	ds_read_b128 v[188:191], v146 offset:51200
	ds_read_b128 v[196:199], v146 offset:52224
	ds_read_b128 v[200:203], v146 offset:53248
	ds_read_b128 v[204:207], v146 offset:54272
	ds_read_b128 v[208:211], v146 offset:55296
	ds_read_b128 v[212:215], v146 offset:56320
	global_load_lds_dwordx4 v[192:193], off
	s_add_i32 m0, s36, 0x2000
	s_add_u32 s36, s40, 0x20080
	v_lshl_add_u64 v[192:193], v[216:217], 0, s[14:15]
	s_addc_u32 s37, s41, 0
	s_add_i32 s40, s83, s54
	global_load_lds_dwordx4 v[192:193], off
	v_lshl_add_u64 v[192:193], s[36:37], 0, v[132:133]
	s_mov_b32 m0, s40
	s_nop 0
	global_load_lds_dwordx4 v[192:193], off
	v_lshl_add_u64 v[192:193], s[36:37], 0, v[128:129]
	s_add_i32 m0, s40, 0x2000
	s_nop 0
	global_load_lds_dwordx4 v[192:193], off
	v_lshl_add_u64 v[192:193], v[218:219], 0, s[14:15]
	s_mov_b32 m0, s62
	s_nop 0
	global_load_lds_dwordx4 v[192:193], off
	s_waitcnt vmcnt(7)
	s_waitcnt lgkmcnt(0)
	s_barrier
	s_setprio 1
	s_waitcnt lgkmcnt(0)
	v_mfma_f32_16x16x32_bf16 v[60:63], v[148:151], v[180:183], v[60:63]
	v_mfma_f32_16x16x32_bf16 v[56:59], v[156:159], v[180:183], v[56:59]
	v_mfma_f32_16x16x32_bf16 v[52:55], v[148:151], v[188:191], v[52:55]
	v_mfma_f32_16x16x32_bf16 v[48:51], v[156:159], v[188:191], v[48:51]
	v_mfma_f32_16x16x32_bf16 v[40:43], v[148:151], v[200:203], v[40:43]
	v_mfma_f32_16x16x32_bf16 v[32:35], v[156:159], v[200:203], v[32:35]
	v_mfma_f32_16x16x32_bf16 v[24:27], v[148:151], v[208:211], v[24:27]
	v_mfma_f32_16x16x32_bf16 v[16:19], v[156:159], v[208:211], v[16:19]
	v_mfma_f32_16x16x32_bf16 v[60:63], v[152:155], v[184:187], v[60:63]
	v_mfma_f32_16x16x32_bf16 v[56:59], v[160:163], v[184:187], v[56:59]
	v_mfma_f32_16x16x32_bf16 v[52:55], v[152:155], v[196:199], v[52:55]
	v_mfma_f32_16x16x32_bf16 v[48:51], v[160:163], v[196:199], v[48:51]
	v_mfma_f32_16x16x32_bf16 v[40:43], v[152:155], v[204:207], v[40:43]
	v_mfma_f32_16x16x32_bf16 v[32:35], v[160:163], v[204:207], v[32:35]
	v_mfma_f32_16x16x32_bf16 v[24:27], v[152:155], v[212:215], v[24:27]
	v_mfma_f32_16x16x32_bf16 v[16:19], v[160:163], v[212:215], v[16:19]
	s_setprio 0
	s_setprio 1
	v_mfma_f32_16x16x32_bf16 v[44:47], v[164:167], v[180:183], v[44:47]
	v_mfma_f32_16x16x32_bf16 v[36:39], v[172:175], v[180:183], v[36:39]
	v_mfma_f32_16x16x32_bf16 v[28:31], v[164:167], v[188:191], v[28:31]
	v_mfma_f32_16x16x32_bf16 v[20:23], v[172:175], v[188:191], v[20:23]
	v_mfma_f32_16x16x32_bf16 v[12:15], v[164:167], v[200:203], v[12:15]
	v_mfma_f32_16x16x32_bf16 v[8:11], v[172:175], v[200:203], v[8:11]
	v_mfma_f32_16x16x32_bf16 v[4:7], v[164:167], v[208:211], v[4:7]
	v_mfma_f32_16x16x32_bf16 v[0:3], v[172:175], v[208:211], v[0:3]
	v_mfma_f32_16x16x32_bf16 v[44:47], v[168:171], v[184:187], v[44:47]
	v_mfma_f32_16x16x32_bf16 v[36:39], v[176:179], v[184:187], v[36:39]
	v_mfma_f32_16x16x32_bf16 v[28:31], v[168:171], v[196:199], v[28:31]
	v_mfma_f32_16x16x32_bf16 v[20:23], v[176:179], v[196:199], v[20:23]
	v_mfma_f32_16x16x32_bf16 v[12:15], v[168:171], v[204:207], v[12:15]
	v_mfma_f32_16x16x32_bf16 v[8:11], v[176:179], v[204:207], v[8:11]
	v_mfma_f32_16x16x32_bf16 v[4:7], v[168:171], v[212:215], v[4:7]
	v_mfma_f32_16x16x32_bf16 v[0:3], v[176:179], v[212:215], v[0:3]
	s_setprio 0
	s_barrier
	v_lshl_add_u64 v[220:221], v[220:221], 0, s[14:15]
	s_mov_b32 m0, s63
	s_nop 0
	global_load_lds_dwordx4 v[220:221], off
	s_add_i32 s81, s81, 2
	s_add_u32 s17, s17, 0x100
	s_addc_u32 s27, s27, 0
	s_cmp_gt_u32 s81, 5
	s_mov_b64 s[36:37], s[38:39]
	s_cbranch_scc0 .LBB0_2370
	s_and_b64 vcc, exec, s[18:19]
	s_cbranch_vccz .LBB0_2373
	s_barrier

.LBB0_2396:
	ds_read_b128 v[144:147], v153
	ds_read_b128 v[158:161], v153 offset:1024
	ds_read_b128 v[162:165], v153 offset:2048
	ds_read_b128 v[166:169], v153 offset:3072
	ds_read_b128 v[170:173], v154
	ds_read_b128 v[174:177], v154 offset:1024
	ds_read_b128 v[178:181], v154 offset:2048
	ds_read_b128 v[182:185], v154 offset:3072
	s_add_u32 s36, s34, 0xfffc0080
	s_addc_u32 s37, s35, -1
	s_cmp_eq_u32 s78, 12
	s_cselect_b32 s39, s27, s37
	s_cselect_b32 s38, s71, s36
	s_cselect_b32 s37, s25, s77
	s_cselect_b32 s36, s72, s73
	v_lshl_add_u64 v[148:149], s[34:35], 0, v[136:137]
	s_add_i32 m0, s53, 0xc000
	ds_read_b128 v[186:189], v155
	ds_read_b128 v[190:193], v155 offset:1024
	ds_read_b128 v[196:199], v155 offset:2048
	ds_read_b128 v[200:203], v155 offset:3072
	ds_read_b128 v[204:207], v155 offset:4096
	ds_read_b128 v[208:211], v155 offset:5120
	ds_read_b128 v[212:215], v155 offset:6144
	ds_read_b128 v[216:219], v155 offset:7168
	global_load_lds_dwordx4 v[148:149], off
	v_lshl_add_u64 v[148:149], s[34:35], 0, v[138:139]
	s_add_i32 m0, s53, 0xe000
	s_nop 0
	global_load_lds_dwordx4 v[148:149], off
	s_waitcnt vmcnt(8)
	s_waitcnt lgkmcnt(0)
	s_barrier
	s_setprio 1
	s_waitcnt lgkmcnt(0)
	v_mfma_f32_16x16x32_bf16 v[124:127], v[144:147], v[186:189], v[124:127]
	v_mfma_f32_16x16x32_bf16 v[120:123], v[162:165], v[186:189], v[120:123]
	v_mfma_f32_16x16x32_bf16 v[108:111], v[144:147], v[196:199], v[108:111]
	v_mfma_f32_16x16x32_bf16 v[104:107], v[162:165], v[196:199], v[104:107]
	v_mfma_f32_16x16x32_bf16 v[92:95], v[144:147], v[204:207], v[92:95]
	v_mfma_f32_16x16x32_bf16 v[88:91], v[162:165], v[204:207], v[88:91]
	v_mfma_f32_16x16x32_bf16 v[76:79], v[144:147], v[212:215], v[76:79]
	v_mfma_f32_16x16x32_bf16 v[72:75], v[162:165], v[212:215], v[72:75]
	v_mfma_f32_16x16x32_bf16 v[124:127], v[158:161], v[190:193], v[124:127]
	v_mfma_f32_16x16x32_bf16 v[120:123], v[166:169], v[190:193], v[120:123]
	v_mfma_f32_16x16x32_bf16 v[108:111], v[158:161], v[200:203], v[108:111]
	v_mfma_f32_16x16x32_bf16 v[104:107], v[166:169], v[200:203], v[104:107]
	v_mfma_f32_16x16x32_bf16 v[92:95], v[158:161], v[208:211], v[92:95]
	v_mfma_f32_16x16x32_bf16 v[88:91], v[166:169], v[208:211], v[88:91]
	v_mfma_f32_16x16x32_bf16 v[76:79], v[158:161], v[216:219], v[76:79]
	v_mfma_f32_16x16x32_bf16 v[72:75], v[166:169], v[216:219], v[72:75]
	s_setprio 0
	s_setprio 1
	v_mfma_f32_16x16x32_bf16 v[116:119], v[170:173], v[186:189], v[116:119]
	v_mfma_f32_16x16x32_bf16 v[112:115], v[178:181], v[186:189], v[112:115]
	v_mfma_f32_16x16x32_bf16 v[100:103], v[170:173], v[196:199], v[100:103]
	v_mfma_f32_16x16x32_bf16 v[96:99], v[178:181], v[196:199], v[96:99]
	v_mfma_f32_16x16x32_bf16 v[84:87], v[170:173], v[204:207], v[84:87]
	v_mfma_f32_16x16x32_bf16 v[80:83], v[178:181], v[204:207], v[80:83]
	v_mfma_f32_16x16x32_bf16 v[68:71], v[170:173], v[212:215], v[68:71]
	v_mfma_f32_16x16x32_bf16 v[64:67], v[178:181], v[212:215], v[64:67]
	v_mfma_f32_16x16x32_bf16 v[116:119], v[174:177], v[190:193], v[116:119]
	v_mfma_f32_16x16x32_bf16 v[112:115], v[182:185], v[190:193], v[112:115]
	v_mfma_f32_16x16x32_bf16 v[100:103], v[174:177], v[200:203], v[100:103]
	v_mfma_f32_16x16x32_bf16 v[96:99], v[182:185], v[200:203], v[96:99]
	v_mfma_f32_16x16x32_bf16 v[84:87], v[174:177], v[208:211], v[84:87]
	v_mfma_f32_16x16x32_bf16 v[80:83], v[182:185], v[208:211], v[80:83]
	v_mfma_f32_16x16x32_bf16 v[68:71], v[174:177], v[216:219], v[68:71]
	v_mfma_f32_16x16x32_bf16 v[64:67], v[182:185], v[216:219], v[64:67]
	s_setprio 0
	s_barrier
	s_add_i32 s79, s61, s52
	v_lshl_add_u64 v[148:149], s[36:37], 0, v[130:131]
	s_mov_b32 m0, s79
	ds_read_b128 v[186:189], v155 offset:16384
	ds_read_b128 v[190:193], v155 offset:17408
	ds_read_b128 v[196:199], v155 offset:18432
	ds_read_b128 v[200:203], v155 offset:19456
	ds_read_b128 v[204:207], v155 offset:20480
	ds_read_b128 v[208:211], v155 offset:21504
	ds_read_b128 v[212:215], v155 offset:22528
	ds_read_b128 v[216:219], v155 offset:23552
	global_load_lds_dwordx4 v[148:149], off
	s_add_i32 m0, s79, 0x2000
	s_add_u32 s80, s36, 0x40000
	v_lshl_add_u64 v[220:221], s[36:37], 0, v[134:135]
	s_addc_u32 s81, s37, 0
	s_add_i32 s79, s62, s52
	global_load_lds_dwordx4 v[220:221], off
	v_lshl_add_u64 v[222:223], s[80:81], 0, v[130:131]
	s_mov_b32 m0, s79
	v_lshl_add_u64 v[224:225], s[38:39], 0, v[132:133]
	global_load_lds_dwordx4 v[222:223], off
	v_lshl_add_u64 v[222:223], s[80:81], 0, v[134:135]
	s_add_i32 m0, s79, 0x2000
	s_nop 0
	global_load_lds_dwordx4 v[222:223], off
	v_lshl_add_u64 v[222:223], s[38:39], 0, v[128:129]
	s_mov_b32 m0, s53
	s_nop 0
	global_load_lds_dwordx4 v[222:223], off
	s_waitcnt vmcnt(7)
	s_waitcnt lgkmcnt(0)
	s_barrier
	s_setprio 1
	s_waitcnt lgkmcnt(0)
	v_mfma_f32_16x16x32_bf16 v[60:63], v[144:147], v[186:189], v[60:63]
	v_mfma_f32_16x16x32_bf16 v[56:59], v[162:165], v[186:189], v[56:59]
	v_mfma_f32_16x16x32_bf16 v[44:47], v[144:147], v[196:199], v[44:47]
	v_mfma_f32_16x16x32_bf16 v[40:43], v[162:165], v[196:199], v[40:43]
	v_mfma_f32_16x16x32_bf16 v[28:31], v[144:147], v[204:207], v[28:31]
	v_mfma_f32_16x16x32_bf16 v[24:27], v[162:165], v[204:207], v[24:27]
	v_mfma_f32_16x16x32_bf16 v[12:15], v[144:147], v[212:215], v[12:15]
	v_mfma_f32_16x16x32_bf16 v[8:11], v[162:165], v[212:215], v[8:11]
	v_mfma_f32_16x16x32_bf16 v[60:63], v[158:161], v[190:193], v[60:63]
	v_mfma_f32_16x16x32_bf16 v[56:59], v[166:169], v[190:193], v[56:59]
	v_mfma_f32_16x16x32_bf16 v[44:47], v[158:161], v[200:203], v[44:47]
	v_mfma_f32_16x16x32_bf16 v[40:43], v[166:169], v[200:203], v[40:43]
	v_mfma_f32_16x16x32_bf16 v[28:31], v[158:161], v[208:211], v[28:31]
	v_mfma_f32_16x16x32_bf16 v[24:27], v[166:169], v[208:211], v[24:27]
	v_mfma_f32_16x16x32_bf16 v[12:15], v[158:161], v[216:219], v[12:15]
	v_mfma_f32_16x16x32_bf16 v[8:11], v[166:169], v[216:219], v[8:11]
	s_setprio 0
	s_setprio 1
	v_mfma_f32_16x16x32_bf16 v[52:55], v[170:173], v[186:189], v[52:55]
	v_mfma_f32_16x16x32_bf16 v[48:51], v[178:181], v[186:189], v[48:51]
	v_mfma_f32_16x16x32_bf16 v[36:39], v[170:173], v[196:199], v[36:39]
	v_mfma_f32_16x16x32_bf16 v[32:35], v[178:181], v[196:199], v[32:35]
	v_mfma_f32_16x16x32_bf16 v[20:23], v[170:173], v[204:207], v[20:23]
	v_mfma_f32_16x16x32_bf16 v[16:19], v[178:181], v[204:207], v[16:19]
	v_mfma_f32_16x16x32_bf16 v[4:7], v[170:173], v[212:215], v[4:7]
	v_mfma_f32_16x16x32_bf16 v[0:3], v[178:181], v[212:215], v[0:3]
	v_mfma_f32_16x16x32_bf16 v[52:55], v[174:177], v[190:193], v[52:55]
	v_mfma_f32_16x16x32_bf16 v[48:51], v[182:185], v[190:193], v[48:51]
	v_mfma_f32_16x16x32_bf16 v[36:39], v[174:177], v[200:203], v[36:39]
	v_mfma_f32_16x16x32_bf16 v[32:35], v[182:185], v[200:203], v[32:35]
	v_mfma_f32_16x16x32_bf16 v[20:23], v[174:177], v[208:211], v[20:23]
	v_mfma_f32_16x16x32_bf16 v[16:19], v[182:185], v[208:211], v[16:19]
	v_mfma_f32_16x16x32_bf16 v[4:7], v[174:177], v[216:219], v[4:7]
	v_mfma_f32_16x16x32_bf16 v[0:3], v[182:185], v[216:219], v[0:3]
	s_setprio 0
	s_barrier
	s_add_i32 s79, 0, 0x18000
	v_add_u32_e32 v157, s79, v151
	s_add_i32 s80, 0, 0x1c000
	ds_read_b128 v[144:147], v157
	ds_read_b128 v[158:161], v157 offset:1024
	ds_read_b128 v[162:165], v157 offset:2048
	ds_read_b128 v[166:169], v157 offset:3072
	v_add_u32_e32 v157, s80, v151
	ds_read_b128 v[170:173], v157
	ds_read_b128 v[174:177], v157 offset:1024
	ds_read_b128 v[178:181], v157 offset:2048
	ds_read_b128 v[182:185], v157 offset:3072
	s_add_u32 s38, s38, 0x40000
	s_addc_u32 s39, s39, 0
	v_lshl_add_u64 v[226:227], s[38:39], 0, v[128:129]
	ds_read_b128 v[186:189], v155 offset:32768
	ds_read_b128 v[190:193], v155 offset:33792
	ds_read_b128 v[196:199], v155 offset:34816
	ds_read_b128 v[200:203], v155 offset:35840
	ds_read_b128 v[204:207], v155 offset:36864
	ds_read_b128 v[208:211], v155 offset:37888
	ds_read_b128 v[212:215], v155 offset:38912
	ds_read_b128 v[216:219], v155 offset:39936
	s_mov_b32 m0, s54
	s_nop 0
	global_load_lds_dwordx4 v[224:225], off
	s_mov_b32 m0, s55
	s_nop 0
	global_load_lds_dwordx4 v[226:227], off
	v_lshl_add_u64 v[226:227], s[38:39], 0, v[132:133]
	s_mov_b32 m0, s56
	s_nop 0
	global_load_lds_dwordx4 v[226:227], off
	s_waitcnt vmcnt(8)
	s_waitcnt lgkmcnt(0)
	s_barrier
	s_setprio 1
	s_waitcnt lgkmcnt(0)
	v_mfma_f32_16x16x32_bf16 v[124:127], v[144:147], v[186:189], v[124:127]
	v_mfma_f32_16x16x32_bf16 v[120:123], v[162:165], v[186:189], v[120:123]
	v_mfma_f32_16x16x32_bf16 v[108:111], v[144:147], v[196:199], v[108:111]
	v_mfma_f32_16x16x32_bf16 v[104:107], v[162:165], v[196:199], v[104:107]
	v_mfma_f32_16x16x32_bf16 v[92:95], v[144:147], v[204:207], v[92:95]
	v_mfma_f32_16x16x32_bf16 v[88:91], v[162:165], v[204:207], v[88:91]
	v_mfma_f32_16x16x32_bf16 v[76:79], v[144:147], v[212:215], v[76:79]
	v_mfma_f32_16x16x32_bf16 v[72:75], v[162:165], v[212:215], v[72:75]
	v_mfma_f32_16x16x32_bf16 v[124:127], v[158:161], v[190:193], v[124:127]
	v_mfma_f32_16x16x32_bf16 v[120:123], v[166:169], v[190:193], v[120:123]
	v_mfma_f32_16x16x32_bf16 v[108:111], v[158:161], v[200:203], v[108:111]
	v_mfma_f32_16x16x32_bf16 v[104:107], v[166:169], v[200:203], v[104:107]
	v_mfma_f32_16x16x32_bf16 v[92:95], v[158:161], v[208:211], v[92:95]
	v_mfma_f32_16x16x32_bf16 v[88:91], v[166:169], v[208:211], v[88:91]
	v_mfma_f32_16x16x32_bf16 v[76:79], v[158:161], v[216:219], v[76:79]
	v_mfma_f32_16x16x32_bf16 v[72:75], v[166:169], v[216:219], v[72:75]
	s_setprio 0
	s_setprio 1
	v_mfma_f32_16x16x32_bf16 v[116:119], v[170:173], v[186:189], v[116:119]
	v_mfma_f32_16x16x32_bf16 v[112:115], v[178:181], v[186:189], v[112:115]
	v_mfma_f32_16x16x32_bf16 v[100:103], v[170:173], v[196:199], v[100:103]
	v_mfma_f32_16x16x32_bf16 v[96:99], v[178:181], v[196:199], v[96:99]
	v_mfma_f32_16x16x32_bf16 v[84:87], v[170:173], v[204:207], v[84:87]
	v_mfma_f32_16x16x32_bf16 v[80:83], v[178:181], v[204:207], v[80:83]
	v_mfma_f32_16x16x32_bf16 v[68:71], v[170:173], v[212:215], v[68:71]
	v_mfma_f32_16x16x32_bf16 v[64:67], v[178:181], v[212:215], v[64:67]
	v_mfma_f32_16x16x32_bf16 v[116:119], v[174:177], v[190:193], v[116:119]
	v_mfma_f32_16x16x32_bf16 v[112:115], v[182:185], v[190:193], v[112:115]
	v_mfma_f32_16x16x32_bf16 v[100:103], v[174:177], v[200:203], v[100:103]
	v_mfma_f32_16x16x32_bf16 v[96:99], v[182:185], v[200:203], v[96:99]
	v_mfma_f32_16x16x32_bf16 v[84:87], v[174:177], v[208:211], v[84:87]
	v_mfma_f32_16x16x32_bf16 v[80:83], v[182:185], v[208:211], v[80:83]
	v_mfma_f32_16x16x32_bf16 v[68:71], v[174:177], v[216:219], v[68:71]
	v_mfma_f32_16x16x32_bf16 v[64:67], v[182:185], v[216:219], v[64:67]
	s_setprio 0
	s_barrier
	s_add_i32 s38, s79, s52
	v_lshl_add_u64 v[148:149], v[148:149], 0, s[20:21]
	s_mov_b32 m0, s38
	ds_read_b128 v[186:189], v155 offset:49152
	ds_read_b128 v[190:193], v155 offset:50176
	ds_read_b128 v[196:199], v155 offset:51200
	ds_read_b128 v[200:203], v155 offset:52224
	ds_read_b128 v[204:207], v155 offset:53248
	ds_read_b128 v[208:211], v155 offset:54272
	ds_read_b128 v[212:215], v155 offset:55296
	ds_read_b128 v[216:219], v155 offset:56320
	global_load_lds_dwordx4 v[148:149], off
	s_add_i32 m0, s38, 0x2000
	s_add_u32 s36, s36, 0x40080
	v_lshl_add_u64 v[148:149], v[220:221], 0, s[20:21]
	s_addc_u32 s37, s37, 0
	s_add_i32 s38, s80, s52
	global_load_lds_dwordx4 v[148:149], off
	v_lshl_add_u64 v[148:149], s[36:37], 0, v[130:131]
	s_mov_b32 m0, s38
	s_nop 0
	global_load_lds_dwordx4 v[148:149], off
	v_lshl_add_u64 v[148:149], s[36:37], 0, v[134:135]
	s_add_i32 m0, s38, 0x2000
	s_nop 0
	global_load_lds_dwordx4 v[148:149], off
	v_lshl_add_u64 v[148:149], v[222:223], 0, s[20:21]
	s_mov_b32 m0, s58
	s_nop 0
	global_load_lds_dwordx4 v[148:149], off
	s_waitcnt vmcnt(7)
	s_waitcnt lgkmcnt(0)
	s_barrier
	s_setprio 1
	s_waitcnt lgkmcnt(0)
	v_mfma_f32_16x16x32_bf16 v[60:63], v[144:147], v[186:189], v[60:63]
	v_mfma_f32_16x16x32_bf16 v[56:59], v[162:165], v[186:189], v[56:59]
	v_mfma_f32_16x16x32_bf16 v[44:47], v[144:147], v[196:199], v[44:47]
	v_mfma_f32_16x16x32_bf16 v[40:43], v[162:165], v[196:199], v[40:43]
	v_mfma_f32_16x16x32_bf16 v[28:31], v[144:147], v[204:207], v[28:31]
	v_mfma_f32_16x16x32_bf16 v[24:27], v[162:165], v[204:207], v[24:27]
	v_mfma_f32_16x16x32_bf16 v[12:15], v[144:147], v[212:215], v[12:15]
	v_mfma_f32_16x16x32_bf16 v[8:11], v[162:165], v[212:215], v[8:11]
	v_mfma_f32_16x16x32_bf16 v[60:63], v[158:161], v[190:193], v[60:63]
	v_mfma_f32_16x16x32_bf16 v[56:59], v[166:169], v[190:193], v[56:59]
	v_mfma_f32_16x16x32_bf16 v[44:47], v[158:161], v[200:203], v[44:47]
	v_mfma_f32_16x16x32_bf16 v[40:43], v[166:169], v[200:203], v[40:43]
	v_mfma_f32_16x16x32_bf16 v[28:31], v[158:161], v[208:211], v[28:31]
	v_mfma_f32_16x16x32_bf16 v[24:27], v[166:169], v[208:211], v[24:27]
	v_mfma_f32_16x16x32_bf16 v[12:15], v[158:161], v[216:219], v[12:15]
	v_mfma_f32_16x16x32_bf16 v[8:11], v[166:169], v[216:219], v[8:11]
	s_setprio 0
	s_setprio 1
	v_mfma_f32_16x16x32_bf16 v[52:55], v[170:173], v[186:189], v[52:55]
	v_mfma_f32_16x16x32_bf16 v[48:51], v[178:181], v[186:189], v[48:51]
	v_mfma_f32_16x16x32_bf16 v[36:39], v[170:173], v[196:199], v[36:39]
	v_mfma_f32_16x16x32_bf16 v[32:35], v[178:181], v[196:199], v[32:35]
	v_mfma_f32_16x16x32_bf16 v[20:23], v[170:173], v[204:207], v[20:23]
	v_mfma_f32_16x16x32_bf16 v[16:19], v[178:181], v[204:207], v[16:19]
	v_mfma_f32_16x16x32_bf16 v[4:7], v[170:173], v[212:215], v[4:7]
	v_mfma_f32_16x16x32_bf16 v[0:3], v[178:181], v[212:215], v[0:3]
	v_mfma_f32_16x16x32_bf16 v[52:55], v[174:177], v[190:193], v[52:55]
	v_mfma_f32_16x16x32_bf16 v[48:51], v[182:185], v[190:193], v[48:51]
	v_mfma_f32_16x16x32_bf16 v[36:39], v[174:177], v[200:203], v[36:39]
	v_mfma_f32_16x16x32_bf16 v[32:35], v[182:185], v[200:203], v[32:35]
	v_mfma_f32_16x16x32_bf16 v[20:23], v[174:177], v[208:211], v[20:23]
	v_mfma_f32_16x16x32_bf16 v[16:19], v[182:185], v[208:211], v[16:19]
	v_mfma_f32_16x16x32_bf16 v[4:7], v[174:177], v[216:219], v[4:7]
	v_mfma_f32_16x16x32_bf16 v[0:3], v[182:185], v[216:219], v[0:3]
	s_setprio 0
	s_barrier
	v_lshl_add_u64 v[224:225], v[224:225], 0, s[20:21]
	s_mov_b32 m0, s59
	s_nop 0
	global_load_lds_dwordx4 v[224:225], off
	s_add_i32 s78, s78, 2
	s_add_u32 s34, s34, 0x100
	s_addc_u32 s35, s35, 0
	s_add_u32 s73, s73, 0x100
	s_addc_u32 s77, s77, 0
	s_cmp_gt_u32 s78, 13
	s_cbranch_scc0 .LBB0_2396
	s_and_b64 vcc, exec, s[22:23]
	s_cbranch_vccz .LBB0_2399
	s_barrier

.LBB0_2533:
	ds_read_b128 v[152:155], v148
	ds_read_b128 v[156:159], v148 offset:1024
	ds_read_b128 v[160:163], v148 offset:2048
	ds_read_b128 v[164:167], v148 offset:3072
	ds_read_b128 v[168:171], v149
	ds_read_b128 v[172:175], v149 offset:1024
	ds_read_b128 v[176:179], v149 offset:2048
	ds_read_b128 v[180:183], v149 offset:3072
	s_add_u32 s26, s24, 0x100
	s_addc_u32 s27, s25, 0
	s_cmp_eq_u32 s62, 8
	s_cselect_b32 s31, s21, s27
	s_cselect_b32 s30, s20, s26
	s_cselect_b32 s29, s23, s61
	s_cselect_b32 s28, s22, s60
	s_mov_b32 m0, s53
	v_lshl_add_u64 v[192:193], s[24:25], 0, v[138:139]
	ds_read_b128 v[184:187], v150
	ds_read_b128 v[188:191], v150 offset:1024
	ds_read_b128 v[196:199], v150 offset:2048
	ds_read_b128 v[200:203], v150 offset:3072
	ds_read_b128 v[204:207], v150 offset:4096
	ds_read_b128 v[208:211], v150 offset:5120
	ds_read_b128 v[212:215], v150 offset:6144
	ds_read_b128 v[216:219], v150 offset:7168
	global_load_lds_dwordx4 v[192:193], off
	v_lshl_add_u64 v[192:193], s[24:25], 0, v[140:141]
	s_add_i32 m0, s40, 0xe000
	s_nop 0
	global_load_lds_dwordx4 v[192:193], off
	s_waitcnt vmcnt(8)
	s_waitcnt lgkmcnt(0)
	s_barrier
	s_setprio 1
	s_waitcnt lgkmcnt(0)
	v_mfma_f32_16x16x32_bf16 v[124:127], v[152:155], v[184:187], v[124:127]
	v_mfma_f32_16x16x32_bf16 v[120:123], v[160:163], v[184:187], v[120:123]
	v_mfma_f32_16x16x32_bf16 v[108:111], v[152:155], v[196:199], v[108:111]
	v_mfma_f32_16x16x32_bf16 v[104:107], v[160:163], v[196:199], v[104:107]
	v_mfma_f32_16x16x32_bf16 v[92:95], v[152:155], v[204:207], v[92:95]
	v_mfma_f32_16x16x32_bf16 v[88:91], v[160:163], v[204:207], v[88:91]
	v_mfma_f32_16x16x32_bf16 v[76:79], v[152:155], v[212:215], v[76:79]
	v_mfma_f32_16x16x32_bf16 v[72:75], v[160:163], v[212:215], v[72:75]
	v_mfma_f32_16x16x32_bf16 v[124:127], v[156:159], v[188:191], v[124:127]
	v_mfma_f32_16x16x32_bf16 v[120:123], v[164:167], v[188:191], v[120:123]
	v_mfma_f32_16x16x32_bf16 v[108:111], v[156:159], v[200:203], v[108:111]
	v_mfma_f32_16x16x32_bf16 v[104:107], v[164:167], v[200:203], v[104:107]
	v_mfma_f32_16x16x32_bf16 v[92:95], v[156:159], v[208:211], v[92:95]
	v_mfma_f32_16x16x32_bf16 v[88:91], v[164:167], v[208:211], v[88:91]
	v_mfma_f32_16x16x32_bf16 v[76:79], v[156:159], v[216:219], v[76:79]
	v_mfma_f32_16x16x32_bf16 v[72:75], v[164:167], v[216:219], v[72:75]
	s_setprio 0
	s_setprio 1
	v_mfma_f32_16x16x32_bf16 v[116:119], v[168:171], v[184:187], v[116:119]
	v_mfma_f32_16x16x32_bf16 v[112:115], v[176:179], v[184:187], v[112:115]
	v_mfma_f32_16x16x32_bf16 v[100:103], v[168:171], v[196:199], v[100:103]
	v_mfma_f32_16x16x32_bf16 v[96:99], v[176:179], v[196:199], v[96:99]
	v_mfma_f32_16x16x32_bf16 v[84:87], v[168:171], v[204:207], v[84:87]
	v_mfma_f32_16x16x32_bf16 v[80:83], v[176:179], v[204:207], v[80:83]
	v_mfma_f32_16x16x32_bf16 v[68:71], v[168:171], v[212:215], v[68:71]
	v_mfma_f32_16x16x32_bf16 v[64:67], v[176:179], v[212:215], v[64:67]
	v_mfma_f32_16x16x32_bf16 v[116:119], v[172:175], v[188:191], v[116:119]
	v_mfma_f32_16x16x32_bf16 v[112:115], v[180:183], v[188:191], v[112:115]
	v_mfma_f32_16x16x32_bf16 v[100:103], v[172:175], v[200:203], v[100:103]
	v_mfma_f32_16x16x32_bf16 v[96:99], v[180:183], v[200:203], v[96:99]
	v_mfma_f32_16x16x32_bf16 v[84:87], v[172:175], v[208:211], v[84:87]
	v_mfma_f32_16x16x32_bf16 v[80:83], v[180:183], v[208:211], v[80:83]
	v_mfma_f32_16x16x32_bf16 v[68:71], v[172:175], v[216:219], v[68:71]
	v_mfma_f32_16x16x32_bf16 v[64:67], v[180:183], v[216:219], v[64:67]
	s_setprio 0
	s_barrier
	s_add_i32 s24, s51, s39
	v_lshl_add_u64 v[192:193], s[28:29], 0, v[132:133]
	s_mov_b32 m0, s24
	ds_read_b128 v[184:187], v150 offset:16384
	ds_read_b128 v[188:191], v150 offset:17408
	ds_read_b128 v[196:199], v150 offset:18432
	ds_read_b128 v[200:203], v150 offset:19456
	ds_read_b128 v[204:207], v150 offset:20480
	ds_read_b128 v[208:211], v150 offset:21504
	ds_read_b128 v[212:215], v150 offset:22528
	ds_read_b128 v[216:219], v150 offset:23552
	global_load_lds_dwordx4 v[192:193], off
	s_add_i32 m0, s24, 0x2000
	s_add_u32 s24, s28, 0x30000
	v_lshl_add_u64 v[220:221], s[28:29], 0, v[128:129]
	s_addc_u32 s25, s29, 0
	s_add_i32 s63, s52, s39
	global_load_lds_dwordx4 v[220:221], off
	v_lshl_add_u64 v[222:223], s[24:25], 0, v[132:133]
	s_mov_b32 m0, s63
	v_lshl_add_u64 v[224:225], s[30:31], 0, v[130:131]
	global_load_lds_dwordx4 v[222:223], off
	v_lshl_add_u64 v[222:223], s[24:25], 0, v[128:129]
	s_add_i32 m0, s63, 0x2000
	s_nop 0
	global_load_lds_dwordx4 v[222:223], off
	v_lshl_add_u64 v[222:223], s[30:31], 0, v[134:135]
	s_mov_b32 m0, s40
	s_nop 0
	global_load_lds_dwordx4 v[222:223], off
	s_waitcnt vmcnt(7)
	s_waitcnt lgkmcnt(0)
	s_barrier
	s_setprio 1
	s_waitcnt lgkmcnt(0)
	v_mfma_f32_16x16x32_bf16 v[60:63], v[152:155], v[184:187], v[60:63]
	v_mfma_f32_16x16x32_bf16 v[56:59], v[160:163], v[184:187], v[56:59]
	v_mfma_f32_16x16x32_bf16 v[44:47], v[152:155], v[196:199], v[44:47]
	v_mfma_f32_16x16x32_bf16 v[40:43], v[160:163], v[196:199], v[40:43]
	v_mfma_f32_16x16x32_bf16 v[28:31], v[152:155], v[204:207], v[28:31]
	v_mfma_f32_16x16x32_bf16 v[24:27], v[160:163], v[204:207], v[24:27]
	v_mfma_f32_16x16x32_bf16 v[12:15], v[152:155], v[212:215], v[12:15]
	v_mfma_f32_16x16x32_bf16 v[8:11], v[160:163], v[212:215], v[8:11]
	v_mfma_f32_16x16x32_bf16 v[60:63], v[156:159], v[188:191], v[60:63]
	v_mfma_f32_16x16x32_bf16 v[56:59], v[164:167], v[188:191], v[56:59]
	v_mfma_f32_16x16x32_bf16 v[44:47], v[156:159], v[200:203], v[44:47]
	v_mfma_f32_16x16x32_bf16 v[40:43], v[164:167], v[200:203], v[40:43]
	v_mfma_f32_16x16x32_bf16 v[28:31], v[156:159], v[208:211], v[28:31]
	v_mfma_f32_16x16x32_bf16 v[24:27], v[164:167], v[208:211], v[24:27]
	v_mfma_f32_16x16x32_bf16 v[12:15], v[156:159], v[216:219], v[12:15]
	v_mfma_f32_16x16x32_bf16 v[8:11], v[164:167], v[216:219], v[8:11]
	s_setprio 0
	s_setprio 1
	v_mfma_f32_16x16x32_bf16 v[52:55], v[168:171], v[184:187], v[52:55]
	v_mfma_f32_16x16x32_bf16 v[48:51], v[176:179], v[184:187], v[48:51]
	v_mfma_f32_16x16x32_bf16 v[36:39], v[168:171], v[196:199], v[36:39]
	v_mfma_f32_16x16x32_bf16 v[32:35], v[176:179], v[196:199], v[32:35]
	v_mfma_f32_16x16x32_bf16 v[20:23], v[168:171], v[204:207], v[20:23]
	v_mfma_f32_16x16x32_bf16 v[16:19], v[176:179], v[204:207], v[16:19]
	v_mfma_f32_16x16x32_bf16 v[4:7], v[168:171], v[212:215], v[4:7]
	v_mfma_f32_16x16x32_bf16 v[0:3], v[176:179], v[212:215], v[0:3]
	v_mfma_f32_16x16x32_bf16 v[52:55], v[172:175], v[188:191], v[52:55]
	v_mfma_f32_16x16x32_bf16 v[48:51], v[180:183], v[188:191], v[48:51]
	v_mfma_f32_16x16x32_bf16 v[36:39], v[172:175], v[200:203], v[36:39]
	v_mfma_f32_16x16x32_bf16 v[32:35], v[180:183], v[200:203], v[32:35]
	v_mfma_f32_16x16x32_bf16 v[20:23], v[172:175], v[208:211], v[20:23]
	v_mfma_f32_16x16x32_bf16 v[16:19], v[180:183], v[208:211], v[16:19]
	v_mfma_f32_16x16x32_bf16 v[4:7], v[172:175], v[216:219], v[4:7]
	v_mfma_f32_16x16x32_bf16 v[0:3], v[180:183], v[216:219], v[0:3]
	s_setprio 0
	s_barrier
	s_add_i32 s63, 0, 0x18000
	v_add_u32_e32 v151, s63, v142
	s_add_i32 s70, 0, 0x1c000
	ds_read_b128 v[152:155], v151
	ds_read_b128 v[156:159], v151 offset:1024
	ds_read_b128 v[160:163], v151 offset:2048
	ds_read_b128 v[164:167], v151 offset:3072
	v_add_u32_e32 v151, s70, v142
	ds_read_b128 v[168:171], v151
	ds_read_b128 v[172:175], v151 offset:1024
	ds_read_b128 v[176:179], v151 offset:2048
	ds_read_b128 v[180:183], v151 offset:3072
	s_add_u32 s24, s30, 0x30000
	s_addc_u32 s25, s31, 0
	v_lshl_add_u64 v[226:227], s[24:25], 0, v[134:135]
	ds_read_b128 v[184:187], v150 offset:32768
	ds_read_b128 v[188:191], v150 offset:33792
	ds_read_b128 v[196:199], v150 offset:34816
	ds_read_b128 v[200:203], v150 offset:35840
	ds_read_b128 v[204:207], v150 offset:36864
	ds_read_b128 v[208:211], v150 offset:37888
	ds_read_b128 v[212:215], v150 offset:38912
	ds_read_b128 v[216:219], v150 offset:39936
	s_mov_b32 m0, s41
	s_nop 0
	global_load_lds_dwordx4 v[224:225], off
	s_mov_b32 m0, s42
	s_nop 0
	global_load_lds_dwordx4 v[226:227], off
	v_lshl_add_u64 v[226:227], s[24:25], 0, v[130:131]
	s_mov_b32 m0, s43
	s_nop 0
	global_load_lds_dwordx4 v[226:227], off
	s_waitcnt vmcnt(8)
	s_waitcnt lgkmcnt(0)
	s_barrier
	s_setprio 1
	s_waitcnt lgkmcnt(0)
	v_mfma_f32_16x16x32_bf16 v[124:127], v[152:155], v[184:187], v[124:127]
	v_mfma_f32_16x16x32_bf16 v[120:123], v[160:163], v[184:187], v[120:123]
	v_mfma_f32_16x16x32_bf16 v[108:111], v[152:155], v[196:199], v[108:111]
	v_mfma_f32_16x16x32_bf16 v[104:107], v[160:163], v[196:199], v[104:107]
	v_mfma_f32_16x16x32_bf16 v[92:95], v[152:155], v[204:207], v[92:95]
	v_mfma_f32_16x16x32_bf16 v[88:91], v[160:163], v[204:207], v[88:91]
	v_mfma_f32_16x16x32_bf16 v[76:79], v[152:155], v[212:215], v[76:79]
	v_mfma_f32_16x16x32_bf16 v[72:75], v[160:163], v[212:215], v[72:75]
	v_mfma_f32_16x16x32_bf16 v[124:127], v[156:159], v[188:191], v[124:127]
	v_mfma_f32_16x16x32_bf16 v[120:123], v[164:167], v[188:191], v[120:123]
	v_mfma_f32_16x16x32_bf16 v[108:111], v[156:159], v[200:203], v[108:111]
	v_mfma_f32_16x16x32_bf16 v[104:107], v[164:167], v[200:203], v[104:107]
	v_mfma_f32_16x16x32_bf16 v[92:95], v[156:159], v[208:211], v[92:95]
	v_mfma_f32_16x16x32_bf16 v[88:91], v[164:167], v[208:211], v[88:91]
	v_mfma_f32_16x16x32_bf16 v[76:79], v[156:159], v[216:219], v[76:79]
	v_mfma_f32_16x16x32_bf16 v[72:75], v[164:167], v[216:219], v[72:75]
	s_setprio 0
	s_setprio 1
	v_mfma_f32_16x16x32_bf16 v[116:119], v[168:171], v[184:187], v[116:119]
	v_mfma_f32_16x16x32_bf16 v[112:115], v[176:179], v[184:187], v[112:115]
	v_mfma_f32_16x16x32_bf16 v[100:103], v[168:171], v[196:199], v[100:103]
	v_mfma_f32_16x16x32_bf16 v[96:99], v[176:179], v[196:199], v[96:99]
	v_mfma_f32_16x16x32_bf16 v[84:87], v[168:171], v[204:207], v[84:87]
	v_mfma_f32_16x16x32_bf16 v[80:83], v[176:179], v[204:207], v[80:83]
	v_mfma_f32_16x16x32_bf16 v[68:71], v[168:171], v[212:215], v[68:71]
	v_mfma_f32_16x16x32_bf16 v[64:67], v[176:179], v[212:215], v[64:67]
	v_mfma_f32_16x16x32_bf16 v[116:119], v[172:175], v[188:191], v[116:119]
	v_mfma_f32_16x16x32_bf16 v[112:115], v[180:183], v[188:191], v[112:115]
	v_mfma_f32_16x16x32_bf16 v[100:103], v[172:175], v[200:203], v[100:103]
	v_mfma_f32_16x16x32_bf16 v[96:99], v[180:183], v[200:203], v[96:99]
	v_mfma_f32_16x16x32_bf16 v[84:87], v[172:175], v[208:211], v[84:87]
	v_mfma_f32_16x16x32_bf16 v[80:83], v[180:183], v[208:211], v[80:83]
	v_mfma_f32_16x16x32_bf16 v[68:71], v[172:175], v[216:219], v[68:71]
	v_mfma_f32_16x16x32_bf16 v[64:67], v[180:183], v[216:219], v[64:67]
	s_setprio 0
	s_barrier
	s_add_i32 s24, s63, s39
	v_lshl_add_u64 v[192:193], v[192:193], 0, s[16:17]
	s_mov_b32 m0, s24
	ds_read_b128 v[184:187], v150 offset:49152
	ds_read_b128 v[188:191], v150 offset:50176
	ds_read_b128 v[196:199], v150 offset:51200
	ds_read_b128 v[200:203], v150 offset:52224
	ds_read_b128 v[204:207], v150 offset:53248
	ds_read_b128 v[208:211], v150 offset:54272
	ds_read_b128 v[212:215], v150 offset:55296
	ds_read_b128 v[216:219], v150 offset:56320
	global_load_lds_dwordx4 v[192:193], off
	s_add_i32 m0, s24, 0x2000
	s_add_u32 s24, s28, 0x30080
	v_lshl_add_u64 v[192:193], v[220:221], 0, s[16:17]
	s_addc_u32 s25, s29, 0
	s_add_i32 s28, s70, s39
	global_load_lds_dwordx4 v[192:193], off
	v_lshl_add_u64 v[192:193], s[24:25], 0, v[132:133]
	s_mov_b32 m0, s28
	s_nop 0
	global_load_lds_dwordx4 v[192:193], off
	v_lshl_add_u64 v[192:193], s[24:25], 0, v[128:129]
	s_add_i32 m0, s28, 0x2000
	s_nop 0
	global_load_lds_dwordx4 v[192:193], off
	v_lshl_add_u64 v[192:193], v[222:223], 0, s[16:17]
	s_mov_b32 m0, s45
	s_nop 0
	global_load_lds_dwordx4 v[192:193], off
	s_waitcnt vmcnt(7)
	s_waitcnt lgkmcnt(0)
	s_barrier
	s_setprio 1
	s_waitcnt lgkmcnt(0)
	v_mfma_f32_16x16x32_bf16 v[60:63], v[152:155], v[184:187], v[60:63]
	v_mfma_f32_16x16x32_bf16 v[56:59], v[160:163], v[184:187], v[56:59]
	v_mfma_f32_16x16x32_bf16 v[44:47], v[152:155], v[196:199], v[44:47]
	v_mfma_f32_16x16x32_bf16 v[40:43], v[160:163], v[196:199], v[40:43]
	v_mfma_f32_16x16x32_bf16 v[28:31], v[152:155], v[204:207], v[28:31]
	v_mfma_f32_16x16x32_bf16 v[24:27], v[160:163], v[204:207], v[24:27]
	v_mfma_f32_16x16x32_bf16 v[12:15], v[152:155], v[212:215], v[12:15]
	v_mfma_f32_16x16x32_bf16 v[8:11], v[160:163], v[212:215], v[8:11]
	v_mfma_f32_16x16x32_bf16 v[60:63], v[156:159], v[188:191], v[60:63]
	v_mfma_f32_16x16x32_bf16 v[56:59], v[164:167], v[188:191], v[56:59]
	v_mfma_f32_16x16x32_bf16 v[44:47], v[156:159], v[200:203], v[44:47]
	v_mfma_f32_16x16x32_bf16 v[40:43], v[164:167], v[200:203], v[40:43]
	v_mfma_f32_16x16x32_bf16 v[28:31], v[156:159], v[208:211], v[28:31]
	v_mfma_f32_16x16x32_bf16 v[24:27], v[164:167], v[208:211], v[24:27]
	v_mfma_f32_16x16x32_bf16 v[12:15], v[156:159], v[216:219], v[12:15]
	v_mfma_f32_16x16x32_bf16 v[8:11], v[164:167], v[216:219], v[8:11]
	s_setprio 0
	s_setprio 1
	v_mfma_f32_16x16x32_bf16 v[52:55], v[168:171], v[184:187], v[52:55]
	v_mfma_f32_16x16x32_bf16 v[48:51], v[176:179], v[184:187], v[48:51]
	v_mfma_f32_16x16x32_bf16 v[36:39], v[168:171], v[196:199], v[36:39]
	v_mfma_f32_16x16x32_bf16 v[32:35], v[176:179], v[196:199], v[32:35]
	v_mfma_f32_16x16x32_bf16 v[20:23], v[168:171], v[204:207], v[20:23]
	v_mfma_f32_16x16x32_bf16 v[16:19], v[176:179], v[204:207], v[16:19]
	v_mfma_f32_16x16x32_bf16 v[4:7], v[168:171], v[212:215], v[4:7]
	v_mfma_f32_16x16x32_bf16 v[0:3], v[176:179], v[212:215], v[0:3]
	v_mfma_f32_16x16x32_bf16 v[52:55], v[172:175], v[188:191], v[52:55]
	v_mfma_f32_16x16x32_bf16 v[48:51], v[180:183], v[188:191], v[48:51]
	v_mfma_f32_16x16x32_bf16 v[36:39], v[172:175], v[200:203], v[36:39]
	v_mfma_f32_16x16x32_bf16 v[32:35], v[180:183], v[200:203], v[32:35]
	v_mfma_f32_16x16x32_bf16 v[20:23], v[172:175], v[208:211], v[20:23]
	v_mfma_f32_16x16x32_bf16 v[16:19], v[180:183], v[208:211], v[16:19]
	v_mfma_f32_16x16x32_bf16 v[4:7], v[172:175], v[216:219], v[4:7]
	v_mfma_f32_16x16x32_bf16 v[0:3], v[180:183], v[216:219], v[0:3]
	s_setprio 0
	s_barrier
	v_lshl_add_u64 v[224:225], v[224:225], 0, s[16:17]
	s_mov_b32 m0, s48
	s_nop 0
	global_load_lds_dwordx4 v[224:225], off
	s_add_i32 s62, s62, 2
	s_add_u32 s60, s60, 0x100
	s_addc_u32 s61, s61, 0
	s_cmp_gt_u32 s62, 9
	s_mov_b64 s[24:25], s[26:27]
	s_cbranch_scc0 .LBB0_2533
	s_and_b64 vcc, exec, s[18:19]
	s_cbranch_vccz .LBB0_2536
	s_barrier

.LBB0_2557:
	ds_read_b128 v[144:147], v153
	ds_read_b128 v[158:161], v153 offset:1024
	ds_read_b128 v[162:165], v153 offset:2048
	ds_read_b128 v[166:169], v153 offset:3072
	ds_read_b128 v[170:173], v154
	ds_read_b128 v[174:177], v154 offset:1024
	ds_read_b128 v[178:181], v154 offset:2048
	ds_read_b128 v[182:185], v154 offset:3072
	s_add_u32 s36, s34, 0xfffc0080
	s_addc_u32 s37, s35, -1
	s_cmp_eq_u32 s73, 12
	s_cselect_b32 s39, s27, s37
	s_cselect_b32 s38, s63, s36
	s_cselect_b32 s37, s25, s72
	s_cselect_b32 s36, s70, s71
	v_lshl_add_u64 v[148:149], s[34:35], 0, v[136:137]
	s_add_i32 m0, s51, 0xc000
	ds_read_b128 v[186:189], v155
	ds_read_b128 v[190:193], v155 offset:1024
	ds_read_b128 v[196:199], v155 offset:2048
	ds_read_b128 v[200:203], v155 offset:3072
	ds_read_b128 v[204:207], v155 offset:4096
	ds_read_b128 v[208:211], v155 offset:5120
	ds_read_b128 v[212:215], v155 offset:6144
	ds_read_b128 v[216:219], v155 offset:7168
	global_load_lds_dwordx4 v[148:149], off
	v_lshl_add_u64 v[148:149], s[34:35], 0, v[138:139]
	s_add_i32 m0, s51, 0xe000
	s_nop 0
	global_load_lds_dwordx4 v[148:149], off
	s_waitcnt vmcnt(8)
	s_waitcnt lgkmcnt(0)
	s_barrier
	s_setprio 1
	s_waitcnt lgkmcnt(0)
	v_mfma_f32_16x16x32_bf16 v[124:127], v[144:147], v[186:189], v[124:127]
	v_mfma_f32_16x16x32_bf16 v[120:123], v[162:165], v[186:189], v[120:123]
	v_mfma_f32_16x16x32_bf16 v[108:111], v[144:147], v[196:199], v[108:111]
	v_mfma_f32_16x16x32_bf16 v[104:107], v[162:165], v[196:199], v[104:107]
	v_mfma_f32_16x16x32_bf16 v[92:95], v[144:147], v[204:207], v[92:95]
	v_mfma_f32_16x16x32_bf16 v[88:91], v[162:165], v[204:207], v[88:91]
	v_mfma_f32_16x16x32_bf16 v[76:79], v[144:147], v[212:215], v[76:79]
	v_mfma_f32_16x16x32_bf16 v[72:75], v[162:165], v[212:215], v[72:75]
	v_mfma_f32_16x16x32_bf16 v[124:127], v[158:161], v[190:193], v[124:127]
	v_mfma_f32_16x16x32_bf16 v[120:123], v[166:169], v[190:193], v[120:123]
	v_mfma_f32_16x16x32_bf16 v[108:111], v[158:161], v[200:203], v[108:111]
	v_mfma_f32_16x16x32_bf16 v[104:107], v[166:169], v[200:203], v[104:107]
	v_mfma_f32_16x16x32_bf16 v[92:95], v[158:161], v[208:211], v[92:95]
	v_mfma_f32_16x16x32_bf16 v[88:91], v[166:169], v[208:211], v[88:91]
	v_mfma_f32_16x16x32_bf16 v[76:79], v[158:161], v[216:219], v[76:79]
	v_mfma_f32_16x16x32_bf16 v[72:75], v[166:169], v[216:219], v[72:75]
	s_setprio 0
	s_setprio 1
	v_mfma_f32_16x16x32_bf16 v[116:119], v[170:173], v[186:189], v[116:119]
	v_mfma_f32_16x16x32_bf16 v[112:115], v[178:181], v[186:189], v[112:115]
	v_mfma_f32_16x16x32_bf16 v[100:103], v[170:173], v[196:199], v[100:103]
	v_mfma_f32_16x16x32_bf16 v[96:99], v[178:181], v[196:199], v[96:99]
	v_mfma_f32_16x16x32_bf16 v[84:87], v[170:173], v[204:207], v[84:87]
	v_mfma_f32_16x16x32_bf16 v[80:83], v[178:181], v[204:207], v[80:83]
	v_mfma_f32_16x16x32_bf16 v[68:71], v[170:173], v[212:215], v[68:71]
	v_mfma_f32_16x16x32_bf16 v[64:67], v[178:181], v[212:215], v[64:67]
	v_mfma_f32_16x16x32_bf16 v[116:119], v[174:177], v[190:193], v[116:119]
	v_mfma_f32_16x16x32_bf16 v[112:115], v[182:185], v[190:193], v[112:115]
	v_mfma_f32_16x16x32_bf16 v[100:103], v[174:177], v[200:203], v[100:103]
	v_mfma_f32_16x16x32_bf16 v[96:99], v[182:185], v[200:203], v[96:99]
	v_mfma_f32_16x16x32_bf16 v[84:87], v[174:177], v[208:211], v[84:87]
	v_mfma_f32_16x16x32_bf16 v[80:83], v[182:185], v[208:211], v[80:83]
	v_mfma_f32_16x16x32_bf16 v[68:71], v[174:177], v[216:219], v[68:71]
	v_mfma_f32_16x16x32_bf16 v[64:67], v[182:185], v[216:219], v[64:67]
	s_setprio 0
	s_barrier
	s_add_i32 s77, s59, s49
	v_lshl_add_u64 v[148:149], s[36:37], 0, v[130:131]
	s_mov_b32 m0, s77
	ds_read_b128 v[186:189], v155 offset:16384
	ds_read_b128 v[190:193], v155 offset:17408
	ds_read_b128 v[196:199], v155 offset:18432
	ds_read_b128 v[200:203], v155 offset:19456
	ds_read_b128 v[204:207], v155 offset:20480
	ds_read_b128 v[208:211], v155 offset:21504
	ds_read_b128 v[212:215], v155 offset:22528
	ds_read_b128 v[216:219], v155 offset:23552
	global_load_lds_dwordx4 v[148:149], off
	s_add_i32 m0, s77, 0x2000
	s_add_u32 s78, s36, 0x40000
	v_lshl_add_u64 v[220:221], s[36:37], 0, v[134:135]
	s_addc_u32 s79, s37, 0
	s_add_i32 s77, s60, s49
	global_load_lds_dwordx4 v[220:221], off
	v_lshl_add_u64 v[222:223], s[78:79], 0, v[130:131]
	s_mov_b32 m0, s77
	v_lshl_add_u64 v[224:225], s[38:39], 0, v[132:133]
	global_load_lds_dwordx4 v[222:223], off
	v_lshl_add_u64 v[222:223], s[78:79], 0, v[134:135]
	s_add_i32 m0, s77, 0x2000
	s_nop 0
	global_load_lds_dwordx4 v[222:223], off
	v_lshl_add_u64 v[222:223], s[38:39], 0, v[128:129]
	s_mov_b32 m0, s51
	s_nop 0
	global_load_lds_dwordx4 v[222:223], off
	s_waitcnt vmcnt(7)
	s_waitcnt lgkmcnt(0)
	s_barrier
	s_setprio 1
	s_waitcnt lgkmcnt(0)
	v_mfma_f32_16x16x32_bf16 v[60:63], v[144:147], v[186:189], v[60:63]
	v_mfma_f32_16x16x32_bf16 v[56:59], v[162:165], v[186:189], v[56:59]
	v_mfma_f32_16x16x32_bf16 v[44:47], v[144:147], v[196:199], v[44:47]
	v_mfma_f32_16x16x32_bf16 v[40:43], v[162:165], v[196:199], v[40:43]
	v_mfma_f32_16x16x32_bf16 v[28:31], v[144:147], v[204:207], v[28:31]
	v_mfma_f32_16x16x32_bf16 v[24:27], v[162:165], v[204:207], v[24:27]
	v_mfma_f32_16x16x32_bf16 v[12:15], v[144:147], v[212:215], v[12:15]
	v_mfma_f32_16x16x32_bf16 v[8:11], v[162:165], v[212:215], v[8:11]
	v_mfma_f32_16x16x32_bf16 v[60:63], v[158:161], v[190:193], v[60:63]
	v_mfma_f32_16x16x32_bf16 v[56:59], v[166:169], v[190:193], v[56:59]
	v_mfma_f32_16x16x32_bf16 v[44:47], v[158:161], v[200:203], v[44:47]
	v_mfma_f32_16x16x32_bf16 v[40:43], v[166:169], v[200:203], v[40:43]
	v_mfma_f32_16x16x32_bf16 v[28:31], v[158:161], v[208:211], v[28:31]
	v_mfma_f32_16x16x32_bf16 v[24:27], v[166:169], v[208:211], v[24:27]
	v_mfma_f32_16x16x32_bf16 v[12:15], v[158:161], v[216:219], v[12:15]
	v_mfma_f32_16x16x32_bf16 v[8:11], v[166:169], v[216:219], v[8:11]
	s_setprio 0
	s_setprio 1
	v_mfma_f32_16x16x32_bf16 v[52:55], v[170:173], v[186:189], v[52:55]
	v_mfma_f32_16x16x32_bf16 v[48:51], v[178:181], v[186:189], v[48:51]
	v_mfma_f32_16x16x32_bf16 v[36:39], v[170:173], v[196:199], v[36:39]
	v_mfma_f32_16x16x32_bf16 v[32:35], v[178:181], v[196:199], v[32:35]
	v_mfma_f32_16x16x32_bf16 v[20:23], v[170:173], v[204:207], v[20:23]
	v_mfma_f32_16x16x32_bf16 v[16:19], v[178:181], v[204:207], v[16:19]
	v_mfma_f32_16x16x32_bf16 v[4:7], v[170:173], v[212:215], v[4:7]
	v_mfma_f32_16x16x32_bf16 v[0:3], v[178:181], v[212:215], v[0:3]
	v_mfma_f32_16x16x32_bf16 v[52:55], v[174:177], v[190:193], v[52:55]
	v_mfma_f32_16x16x32_bf16 v[48:51], v[182:185], v[190:193], v[48:51]
	v_mfma_f32_16x16x32_bf16 v[36:39], v[174:177], v[200:203], v[36:39]
	v_mfma_f32_16x16x32_bf16 v[32:35], v[182:185], v[200:203], v[32:35]
	v_mfma_f32_16x16x32_bf16 v[20:23], v[174:177], v[208:211], v[20:23]
	v_mfma_f32_16x16x32_bf16 v[16:19], v[182:185], v[208:211], v[16:19]
	v_mfma_f32_16x16x32_bf16 v[4:7], v[174:177], v[216:219], v[4:7]
	v_mfma_f32_16x16x32_bf16 v[0:3], v[182:185], v[216:219], v[0:3]
	s_setprio 0
	s_barrier
	s_add_i32 s77, 0, 0x18000
	v_add_u32_e32 v157, s77, v151
	s_add_i32 s78, 0, 0x1c000
	ds_read_b128 v[144:147], v157
	ds_read_b128 v[158:161], v157 offset:1024
	ds_read_b128 v[162:165], v157 offset:2048
	ds_read_b128 v[166:169], v157 offset:3072
	v_add_u32_e32 v157, s78, v151
	ds_read_b128 v[170:173], v157
	ds_read_b128 v[174:177], v157 offset:1024
	ds_read_b128 v[178:181], v157 offset:2048
	ds_read_b128 v[182:185], v157 offset:3072
	s_add_u32 s38, s38, 0x40000
	s_addc_u32 s39, s39, 0
	v_lshl_add_u64 v[226:227], s[38:39], 0, v[128:129]
	ds_read_b128 v[186:189], v155 offset:32768
	ds_read_b128 v[190:193], v155 offset:33792
	ds_read_b128 v[196:199], v155 offset:34816
	ds_read_b128 v[200:203], v155 offset:35840
	ds_read_b128 v[204:207], v155 offset:36864
	ds_read_b128 v[208:211], v155 offset:37888
	ds_read_b128 v[212:215], v155 offset:38912
	ds_read_b128 v[216:219], v155 offset:39936
	s_mov_b32 m0, s52
	s_nop 0
	global_load_lds_dwordx4 v[224:225], off
	s_mov_b32 m0, s53
	s_nop 0
	global_load_lds_dwordx4 v[226:227], off
	v_lshl_add_u64 v[226:227], s[38:39], 0, v[132:133]
	s_mov_b32 m0, s54
	s_nop 0
	global_load_lds_dwordx4 v[226:227], off
	s_waitcnt vmcnt(8)
	s_waitcnt lgkmcnt(0)
	s_barrier
	s_setprio 1
	s_waitcnt lgkmcnt(0)
	v_mfma_f32_16x16x32_bf16 v[124:127], v[144:147], v[186:189], v[124:127]
	v_mfma_f32_16x16x32_bf16 v[120:123], v[162:165], v[186:189], v[120:123]
	v_mfma_f32_16x16x32_bf16 v[108:111], v[144:147], v[196:199], v[108:111]
	v_mfma_f32_16x16x32_bf16 v[104:107], v[162:165], v[196:199], v[104:107]
	v_mfma_f32_16x16x32_bf16 v[92:95], v[144:147], v[204:207], v[92:95]
	v_mfma_f32_16x16x32_bf16 v[88:91], v[162:165], v[204:207], v[88:91]
	v_mfma_f32_16x16x32_bf16 v[76:79], v[144:147], v[212:215], v[76:79]
	v_mfma_f32_16x16x32_bf16 v[72:75], v[162:165], v[212:215], v[72:75]
	v_mfma_f32_16x16x32_bf16 v[124:127], v[158:161], v[190:193], v[124:127]
	v_mfma_f32_16x16x32_bf16 v[120:123], v[166:169], v[190:193], v[120:123]
	v_mfma_f32_16x16x32_bf16 v[108:111], v[158:161], v[200:203], v[108:111]
	v_mfma_f32_16x16x32_bf16 v[104:107], v[166:169], v[200:203], v[104:107]
	v_mfma_f32_16x16x32_bf16 v[92:95], v[158:161], v[208:211], v[92:95]
	v_mfma_f32_16x16x32_bf16 v[88:91], v[166:169], v[208:211], v[88:91]
	v_mfma_f32_16x16x32_bf16 v[76:79], v[158:161], v[216:219], v[76:79]
	v_mfma_f32_16x16x32_bf16 v[72:75], v[166:169], v[216:219], v[72:75]
	s_setprio 0
	s_setprio 1
	v_mfma_f32_16x16x32_bf16 v[116:119], v[170:173], v[186:189], v[116:119]
	v_mfma_f32_16x16x32_bf16 v[112:115], v[178:181], v[186:189], v[112:115]
	v_mfma_f32_16x16x32_bf16 v[100:103], v[170:173], v[196:199], v[100:103]
	v_mfma_f32_16x16x32_bf16 v[96:99], v[178:181], v[196:199], v[96:99]
	v_mfma_f32_16x16x32_bf16 v[84:87], v[170:173], v[204:207], v[84:87]
	v_mfma_f32_16x16x32_bf16 v[80:83], v[178:181], v[204:207], v[80:83]
	v_mfma_f32_16x16x32_bf16 v[68:71], v[170:173], v[212:215], v[68:71]
	v_mfma_f32_16x16x32_bf16 v[64:67], v[178:181], v[212:215], v[64:67]
	v_mfma_f32_16x16x32_bf16 v[116:119], v[174:177], v[190:193], v[116:119]
	v_mfma_f32_16x16x32_bf16 v[112:115], v[182:185], v[190:193], v[112:115]
	v_mfma_f32_16x16x32_bf16 v[100:103], v[174:177], v[200:203], v[100:103]
	v_mfma_f32_16x16x32_bf16 v[96:99], v[182:185], v[200:203], v[96:99]
	v_mfma_f32_16x16x32_bf16 v[84:87], v[174:177], v[208:211], v[84:87]
	v_mfma_f32_16x16x32_bf16 v[80:83], v[182:185], v[208:211], v[80:83]
	v_mfma_f32_16x16x32_bf16 v[68:71], v[174:177], v[216:219], v[68:71]
	v_mfma_f32_16x16x32_bf16 v[64:67], v[182:185], v[216:219], v[64:67]
	s_setprio 0
	s_barrier
	s_add_i32 s38, s77, s49
	v_lshl_add_u64 v[148:149], v[148:149], 0, s[20:21]
	s_mov_b32 m0, s38
	ds_read_b128 v[186:189], v155 offset:49152
	ds_read_b128 v[190:193], v155 offset:50176
	ds_read_b128 v[196:199], v155 offset:51200
	ds_read_b128 v[200:203], v155 offset:52224
	ds_read_b128 v[204:207], v155 offset:53248
	ds_read_b128 v[208:211], v155 offset:54272
	ds_read_b128 v[212:215], v155 offset:55296
	ds_read_b128 v[216:219], v155 offset:56320
	global_load_lds_dwordx4 v[148:149], off
	s_add_i32 m0, s38, 0x2000
	s_add_u32 s36, s36, 0x40080
	v_lshl_add_u64 v[148:149], v[220:221], 0, s[20:21]
	s_addc_u32 s37, s37, 0
	s_add_i32 s38, s78, s49
	global_load_lds_dwordx4 v[148:149], off
	v_lshl_add_u64 v[148:149], s[36:37], 0, v[130:131]
	s_mov_b32 m0, s38
	s_nop 0
	global_load_lds_dwordx4 v[148:149], off
	v_lshl_add_u64 v[148:149], s[36:37], 0, v[134:135]
	s_add_i32 m0, s38, 0x2000
	s_nop 0
	global_load_lds_dwordx4 v[148:149], off
	v_lshl_add_u64 v[148:149], v[222:223], 0, s[20:21]
	s_mov_b32 m0, s56
	s_nop 0
	global_load_lds_dwordx4 v[148:149], off
	s_waitcnt vmcnt(7)
	s_waitcnt lgkmcnt(0)
	s_barrier
	s_setprio 1
	s_waitcnt lgkmcnt(0)
	v_mfma_f32_16x16x32_bf16 v[60:63], v[144:147], v[186:189], v[60:63]
	v_mfma_f32_16x16x32_bf16 v[56:59], v[162:165], v[186:189], v[56:59]
	v_mfma_f32_16x16x32_bf16 v[44:47], v[144:147], v[196:199], v[44:47]
	v_mfma_f32_16x16x32_bf16 v[40:43], v[162:165], v[196:199], v[40:43]
	v_mfma_f32_16x16x32_bf16 v[28:31], v[144:147], v[204:207], v[28:31]
	v_mfma_f32_16x16x32_bf16 v[24:27], v[162:165], v[204:207], v[24:27]
	v_mfma_f32_16x16x32_bf16 v[12:15], v[144:147], v[212:215], v[12:15]
	v_mfma_f32_16x16x32_bf16 v[8:11], v[162:165], v[212:215], v[8:11]
	v_mfma_f32_16x16x32_bf16 v[60:63], v[158:161], v[190:193], v[60:63]
	v_mfma_f32_16x16x32_bf16 v[56:59], v[166:169], v[190:193], v[56:59]
	v_mfma_f32_16x16x32_bf16 v[44:47], v[158:161], v[200:203], v[44:47]
	v_mfma_f32_16x16x32_bf16 v[40:43], v[166:169], v[200:203], v[40:43]
	v_mfma_f32_16x16x32_bf16 v[28:31], v[158:161], v[208:211], v[28:31]
	v_mfma_f32_16x16x32_bf16 v[24:27], v[166:169], v[208:211], v[24:27]
	v_mfma_f32_16x16x32_bf16 v[12:15], v[158:161], v[216:219], v[12:15]
	v_mfma_f32_16x16x32_bf16 v[8:11], v[166:169], v[216:219], v[8:11]
	s_setprio 0
	s_setprio 1
	v_mfma_f32_16x16x32_bf16 v[52:55], v[170:173], v[186:189], v[52:55]
	v_mfma_f32_16x16x32_bf16 v[48:51], v[178:181], v[186:189], v[48:51]
	v_mfma_f32_16x16x32_bf16 v[36:39], v[170:173], v[196:199], v[36:39]
	v_mfma_f32_16x16x32_bf16 v[32:35], v[178:181], v[196:199], v[32:35]
	v_mfma_f32_16x16x32_bf16 v[20:23], v[170:173], v[204:207], v[20:23]
	v_mfma_f32_16x16x32_bf16 v[16:19], v[178:181], v[204:207], v[16:19]
	v_mfma_f32_16x16x32_bf16 v[4:7], v[170:173], v[212:215], v[4:7]
	v_mfma_f32_16x16x32_bf16 v[0:3], v[178:181], v[212:215], v[0:3]
	v_mfma_f32_16x16x32_bf16 v[52:55], v[174:177], v[190:193], v[52:55]
	v_mfma_f32_16x16x32_bf16 v[48:51], v[182:185], v[190:193], v[48:51]
	v_mfma_f32_16x16x32_bf16 v[36:39], v[174:177], v[200:203], v[36:39]
	v_mfma_f32_16x16x32_bf16 v[32:35], v[182:185], v[200:203], v[32:35]
	v_mfma_f32_16x16x32_bf16 v[20:23], v[174:177], v[208:211], v[20:23]
	v_mfma_f32_16x16x32_bf16 v[16:19], v[182:185], v[208:211], v[16:19]
	v_mfma_f32_16x16x32_bf16 v[4:7], v[174:177], v[216:219], v[4:7]
	v_mfma_f32_16x16x32_bf16 v[0:3], v[182:185], v[216:219], v[0:3]
	s_setprio 0
	s_barrier
	v_lshl_add_u64 v[224:225], v[224:225], 0, s[20:21]
	s_mov_b32 m0, s57
	s_nop 0
	global_load_lds_dwordx4 v[224:225], off
	s_add_i32 s73, s73, 2
	s_add_u32 s34, s34, 0x100
	s_addc_u32 s35, s35, 0
	s_add_u32 s71, s71, 0x100
	s_addc_u32 s72, s72, 0
	s_cmp_gt_u32 s73, 13
	s_cbranch_scc0 .LBB0_2557
	s_and_b64 vcc, exec, s[22:23]
	s_cbranch_vccz .LBB0_2560
	s_barrier

.LBB0_2633:
	ds_read_b128 v[144:147], v153
	ds_read_b128 v[156:159], v153 offset:1024
	ds_read_b128 v[160:163], v153 offset:2048
	ds_read_b128 v[164:167], v153 offset:3072
	ds_read_b128 v[168:171], v154
	ds_read_b128 v[172:175], v154 offset:1024
	ds_read_b128 v[176:179], v154 offset:2048
	ds_read_b128 v[180:183], v154 offset:3072
	s_add_u32 s42, s40, 0xfffe0080
	s_addc_u32 s43, s41, -1
	s_cmp_eq_u32 s73, 4
	s_cselect_b32 s45, s31, s43
	s_cselect_b32 s44, s63, s42
	s_cselect_b32 s43, s29, s72
	s_cselect_b32 s42, s70, s71
	v_lshl_add_u64 v[148:149], s[40:41], 0, v[136:137]
	s_add_i32 m0, s39, 0xc000
	ds_read_b128 v[184:187], v155
	ds_read_b128 v[188:191], v155 offset:1024
	ds_read_b128 v[196:199], v155 offset:2048
	ds_read_b128 v[200:203], v155 offset:3072
	ds_read_b128 v[204:207], v155 offset:4096
	ds_read_b128 v[208:211], v155 offset:5120
	ds_read_b128 v[212:215], v155 offset:6144
	ds_read_b128 v[216:219], v155 offset:7168
	global_load_lds_dwordx4 v[148:149], off
	v_lshl_add_u64 v[148:149], s[40:41], 0, v[138:139]
	s_add_i32 m0, s39, 0xe000
	s_nop 0
	global_load_lds_dwordx4 v[148:149], off
	s_waitcnt vmcnt(8)
	s_waitcnt lgkmcnt(0)
	s_barrier
	s_setprio 1
	s_waitcnt lgkmcnt(0)
	v_mfma_f32_16x16x32_bf16 v[124:127], v[144:147], v[184:187], v[124:127]
	v_mfma_f32_16x16x32_bf16 v[120:123], v[160:163], v[184:187], v[120:123]
	v_mfma_f32_16x16x32_bf16 v[108:111], v[144:147], v[196:199], v[108:111]
	v_mfma_f32_16x16x32_bf16 v[104:107], v[160:163], v[196:199], v[104:107]
	v_mfma_f32_16x16x32_bf16 v[92:95], v[144:147], v[204:207], v[92:95]
	v_mfma_f32_16x16x32_bf16 v[88:91], v[160:163], v[204:207], v[88:91]
	v_mfma_f32_16x16x32_bf16 v[76:79], v[144:147], v[212:215], v[76:79]
	v_mfma_f32_16x16x32_bf16 v[72:75], v[160:163], v[212:215], v[72:75]
	v_mfma_f32_16x16x32_bf16 v[124:127], v[156:159], v[188:191], v[124:127]
	v_mfma_f32_16x16x32_bf16 v[120:123], v[164:167], v[188:191], v[120:123]
	v_mfma_f32_16x16x32_bf16 v[108:111], v[156:159], v[200:203], v[108:111]
	v_mfma_f32_16x16x32_bf16 v[104:107], v[164:167], v[200:203], v[104:107]
	v_mfma_f32_16x16x32_bf16 v[92:95], v[156:159], v[208:211], v[92:95]
	v_mfma_f32_16x16x32_bf16 v[88:91], v[164:167], v[208:211], v[88:91]
	v_mfma_f32_16x16x32_bf16 v[76:79], v[156:159], v[216:219], v[76:79]
	v_mfma_f32_16x16x32_bf16 v[72:75], v[164:167], v[216:219], v[72:75]
	s_setprio 0
	s_setprio 1
	v_mfma_f32_16x16x32_bf16 v[116:119], v[168:171], v[184:187], v[116:119]
	v_mfma_f32_16x16x32_bf16 v[112:115], v[176:179], v[184:187], v[112:115]
	v_mfma_f32_16x16x32_bf16 v[100:103], v[168:171], v[196:199], v[100:103]
	v_mfma_f32_16x16x32_bf16 v[96:99], v[176:179], v[196:199], v[96:99]
	v_mfma_f32_16x16x32_bf16 v[84:87], v[168:171], v[204:207], v[84:87]
	v_mfma_f32_16x16x32_bf16 v[80:83], v[176:179], v[204:207], v[80:83]
	v_mfma_f32_16x16x32_bf16 v[68:71], v[168:171], v[212:215], v[68:71]
	v_mfma_f32_16x16x32_bf16 v[64:67], v[176:179], v[212:215], v[64:67]
	v_mfma_f32_16x16x32_bf16 v[116:119], v[172:175], v[188:191], v[116:119]
	v_mfma_f32_16x16x32_bf16 v[112:115], v[180:183], v[188:191], v[112:115]
	v_mfma_f32_16x16x32_bf16 v[100:103], v[172:175], v[200:203], v[100:103]
	v_mfma_f32_16x16x32_bf16 v[96:99], v[180:183], v[200:203], v[96:99]
	v_mfma_f32_16x16x32_bf16 v[84:87], v[172:175], v[208:211], v[84:87]
	v_mfma_f32_16x16x32_bf16 v[80:83], v[180:183], v[208:211], v[80:83]
	v_mfma_f32_16x16x32_bf16 v[68:71], v[172:175], v[216:219], v[68:71]
	v_mfma_f32_16x16x32_bf16 v[64:67], v[180:183], v[216:219], v[64:67]
	s_setprio 0
	s_barrier
	s_add_i32 s77, s60, s52
	v_lshl_add_u64 v[148:149], s[42:43], 0, v[130:131]
	s_mov_b32 m0, s77
	ds_read_b128 v[184:187], v155 offset:16384
	ds_read_b128 v[188:191], v155 offset:17408
	ds_read_b128 v[196:199], v155 offset:18432
	ds_read_b128 v[200:203], v155 offset:19456
	ds_read_b128 v[204:207], v155 offset:20480
	ds_read_b128 v[208:211], v155 offset:21504
	ds_read_b128 v[212:215], v155 offset:22528
	ds_read_b128 v[216:219], v155 offset:23552
	global_load_lds_dwordx4 v[148:149], off
	s_add_i32 m0, s77, 0x2000
	s_add_u32 s78, s42, 0x20000
	v_lshl_add_u64 v[192:193], s[42:43], 0, v[134:135]
	s_addc_u32 s79, s43, 0
	s_add_i32 s77, s61, s52
	global_load_lds_dwordx4 v[192:193], off
	v_lshl_add_u64 v[220:221], s[78:79], 0, v[130:131]
	s_mov_b32 m0, s77
	v_lshl_add_u64 v[222:223], s[44:45], 0, v[132:133]
	global_load_lds_dwordx4 v[220:221], off
	v_lshl_add_u64 v[220:221], s[78:79], 0, v[134:135]
	s_add_i32 m0, s77, 0x2000
	s_nop 0
	global_load_lds_dwordx4 v[220:221], off
	v_lshl_add_u64 v[220:221], s[44:45], 0, v[128:129]
	s_mov_b32 m0, s39
	s_nop 0
	global_load_lds_dwordx4 v[220:221], off
	s_waitcnt vmcnt(7)
	s_waitcnt lgkmcnt(0)
	s_barrier
	s_setprio 1
	s_waitcnt lgkmcnt(0)
	v_mfma_f32_16x16x32_bf16 v[60:63], v[144:147], v[184:187], v[60:63]
	v_mfma_f32_16x16x32_bf16 v[56:59], v[160:163], v[184:187], v[56:59]
	v_mfma_f32_16x16x32_bf16 v[44:47], v[144:147], v[196:199], v[44:47]
	v_mfma_f32_16x16x32_bf16 v[40:43], v[160:163], v[196:199], v[40:43]
	v_mfma_f32_16x16x32_bf16 v[28:31], v[144:147], v[204:207], v[28:31]
	v_mfma_f32_16x16x32_bf16 v[24:27], v[160:163], v[204:207], v[24:27]
	v_mfma_f32_16x16x32_bf16 v[12:15], v[144:147], v[212:215], v[12:15]
	v_mfma_f32_16x16x32_bf16 v[8:11], v[160:163], v[212:215], v[8:11]
	v_mfma_f32_16x16x32_bf16 v[60:63], v[156:159], v[188:191], v[60:63]
	v_mfma_f32_16x16x32_bf16 v[56:59], v[164:167], v[188:191], v[56:59]
	v_mfma_f32_16x16x32_bf16 v[44:47], v[156:159], v[200:203], v[44:47]
	v_mfma_f32_16x16x32_bf16 v[40:43], v[164:167], v[200:203], v[40:43]
	v_mfma_f32_16x16x32_bf16 v[28:31], v[156:159], v[208:211], v[28:31]
	v_mfma_f32_16x16x32_bf16 v[24:27], v[164:167], v[208:211], v[24:27]
	v_mfma_f32_16x16x32_bf16 v[12:15], v[156:159], v[216:219], v[12:15]
	v_mfma_f32_16x16x32_bf16 v[8:11], v[164:167], v[216:219], v[8:11]
	s_setprio 0
	s_setprio 1
	v_mfma_f32_16x16x32_bf16 v[52:55], v[168:171], v[184:187], v[52:55]
	v_mfma_f32_16x16x32_bf16 v[48:51], v[176:179], v[184:187], v[48:51]
	v_mfma_f32_16x16x32_bf16 v[36:39], v[168:171], v[196:199], v[36:39]
	v_mfma_f32_16x16x32_bf16 v[32:35], v[176:179], v[196:199], v[32:35]
	v_mfma_f32_16x16x32_bf16 v[20:23], v[168:171], v[204:207], v[20:23]
	v_mfma_f32_16x16x32_bf16 v[16:19], v[176:179], v[204:207], v[16:19]
	v_mfma_f32_16x16x32_bf16 v[4:7], v[168:171], v[212:215], v[4:7]
	v_mfma_f32_16x16x32_bf16 v[0:3], v[176:179], v[212:215], v[0:3]
	v_mfma_f32_16x16x32_bf16 v[52:55], v[172:175], v[188:191], v[52:55]
	v_mfma_f32_16x16x32_bf16 v[48:51], v[180:183], v[188:191], v[48:51]
	v_mfma_f32_16x16x32_bf16 v[36:39], v[172:175], v[200:203], v[36:39]
	v_mfma_f32_16x16x32_bf16 v[32:35], v[180:183], v[200:203], v[32:35]
	v_mfma_f32_16x16x32_bf16 v[20:23], v[172:175], v[208:211], v[20:23]
	v_mfma_f32_16x16x32_bf16 v[16:19], v[180:183], v[208:211], v[16:19]
	v_mfma_f32_16x16x32_bf16 v[4:7], v[172:175], v[216:219], v[4:7]
	v_mfma_f32_16x16x32_bf16 v[0:3], v[180:183], v[216:219], v[0:3]
	s_setprio 0
	s_barrier
	s_add_i32 s77, 0, 0x18000
	s_add_i32 s78, 0, 0x1c000
	v_add_u32_e32 v164, s77, v151
	v_add_u32_e32 v180, s78, v151
	ds_read_b128 v[144:147], v164
	ds_read_b128 v[156:159], v164 offset:1024
	ds_read_b128 v[160:163], v164 offset:2048
	ds_read_b128 v[164:167], v164 offset:3072
	ds_read_b128 v[168:171], v180
	ds_read_b128 v[172:175], v180 offset:1024
	ds_read_b128 v[176:179], v180 offset:2048
	ds_read_b128 v[180:183], v180 offset:3072
	s_add_u32 s44, s44, 0x20000
	s_addc_u32 s45, s45, 0
	v_lshl_add_u64 v[224:225], s[44:45], 0, v[128:129]
	ds_read_b128 v[184:187], v155 offset:32768
	ds_read_b128 v[188:191], v155 offset:33792
	ds_read_b128 v[196:199], v155 offset:34816
	ds_read_b128 v[200:203], v155 offset:35840
	ds_read_b128 v[204:207], v155 offset:36864
	ds_read_b128 v[208:211], v155 offset:37888
	ds_read_b128 v[212:215], v155 offset:38912
	ds_read_b128 v[216:219], v155 offset:39936
	s_mov_b32 m0, s53
	s_nop 0
	global_load_lds_dwordx4 v[222:223], off
	s_mov_b32 m0, s54
	s_nop 0
	global_load_lds_dwordx4 v[224:225], off
	v_lshl_add_u64 v[224:225], s[44:45], 0, v[132:133]
	s_mov_b32 m0, s55
	s_nop 0
	global_load_lds_dwordx4 v[224:225], off
	s_waitcnt vmcnt(8)
	s_waitcnt lgkmcnt(0)
	s_barrier
	s_setprio 1
	s_waitcnt lgkmcnt(0)
	v_mfma_f32_16x16x32_bf16 v[124:127], v[144:147], v[184:187], v[124:127]
	v_mfma_f32_16x16x32_bf16 v[120:123], v[160:163], v[184:187], v[120:123]
	v_mfma_f32_16x16x32_bf16 v[108:111], v[144:147], v[196:199], v[108:111]
	v_mfma_f32_16x16x32_bf16 v[104:107], v[160:163], v[196:199], v[104:107]
	v_mfma_f32_16x16x32_bf16 v[92:95], v[144:147], v[204:207], v[92:95]
	v_mfma_f32_16x16x32_bf16 v[88:91], v[160:163], v[204:207], v[88:91]
	v_mfma_f32_16x16x32_bf16 v[76:79], v[144:147], v[212:215], v[76:79]
	v_mfma_f32_16x16x32_bf16 v[72:75], v[160:163], v[212:215], v[72:75]
	v_mfma_f32_16x16x32_bf16 v[124:127], v[156:159], v[188:191], v[124:127]
	v_mfma_f32_16x16x32_bf16 v[120:123], v[164:167], v[188:191], v[120:123]
	v_mfma_f32_16x16x32_bf16 v[108:111], v[156:159], v[200:203], v[108:111]
	v_mfma_f32_16x16x32_bf16 v[104:107], v[164:167], v[200:203], v[104:107]
	v_mfma_f32_16x16x32_bf16 v[92:95], v[156:159], v[208:211], v[92:95]
	v_mfma_f32_16x16x32_bf16 v[88:91], v[164:167], v[208:211], v[88:91]
	v_mfma_f32_16x16x32_bf16 v[76:79], v[156:159], v[216:219], v[76:79]
	v_mfma_f32_16x16x32_bf16 v[72:75], v[164:167], v[216:219], v[72:75]
	s_setprio 0
	s_setprio 1
	v_mfma_f32_16x16x32_bf16 v[116:119], v[168:171], v[184:187], v[116:119]
	v_mfma_f32_16x16x32_bf16 v[112:115], v[176:179], v[184:187], v[112:115]
	v_mfma_f32_16x16x32_bf16 v[100:103], v[168:171], v[196:199], v[100:103]
	v_mfma_f32_16x16x32_bf16 v[96:99], v[176:179], v[196:199], v[96:99]
	v_mfma_f32_16x16x32_bf16 v[84:87], v[168:171], v[204:207], v[84:87]
	v_mfma_f32_16x16x32_bf16 v[80:83], v[176:179], v[204:207], v[80:83]
	v_mfma_f32_16x16x32_bf16 v[68:71], v[168:171], v[212:215], v[68:71]
	v_mfma_f32_16x16x32_bf16 v[64:67], v[176:179], v[212:215], v[64:67]
	v_mfma_f32_16x16x32_bf16 v[116:119], v[172:175], v[188:191], v[116:119]
	v_mfma_f32_16x16x32_bf16 v[112:115], v[180:183], v[188:191], v[112:115]
	v_mfma_f32_16x16x32_bf16 v[100:103], v[172:175], v[200:203], v[100:103]
	v_mfma_f32_16x16x32_bf16 v[96:99], v[180:183], v[200:203], v[96:99]
	v_mfma_f32_16x16x32_bf16 v[84:87], v[172:175], v[208:211], v[84:87]
	v_mfma_f32_16x16x32_bf16 v[80:83], v[180:183], v[208:211], v[80:83]
	v_mfma_f32_16x16x32_bf16 v[68:71], v[172:175], v[216:219], v[68:71]
	v_mfma_f32_16x16x32_bf16 v[64:67], v[180:183], v[216:219], v[64:67]
	s_setprio 0
	s_barrier
	s_add_i32 s44, s77, s52
	v_lshl_add_u64 v[148:149], v[148:149], 0, s[18:19]
	s_mov_b32 m0, s44
	ds_read_b128 v[184:187], v155 offset:49152
	ds_read_b128 v[188:191], v155 offset:50176
	ds_read_b128 v[196:199], v155 offset:51200
	ds_read_b128 v[200:203], v155 offset:52224
	ds_read_b128 v[204:207], v155 offset:53248
	ds_read_b128 v[208:211], v155 offset:54272
	ds_read_b128 v[212:215], v155 offset:55296
	ds_read_b128 v[216:219], v155 offset:56320
	global_load_lds_dwordx4 v[148:149], off
	s_add_i32 m0, s44, 0x2000
	s_add_u32 s42, s42, 0x20080
	v_lshl_add_u64 v[148:149], v[192:193], 0, s[18:19]
	s_addc_u32 s43, s43, 0
	s_add_i32 s44, s78, s52
	global_load_lds_dwordx4 v[148:149], off
	v_lshl_add_u64 v[148:149], s[42:43], 0, v[130:131]
	s_mov_b32 m0, s44
	s_nop 0
	global_load_lds_dwordx4 v[148:149], off
	v_lshl_add_u64 v[148:149], s[42:43], 0, v[134:135]
	s_add_i32 m0, s44, 0x2000
	s_nop 0
	global_load_lds_dwordx4 v[148:149], off
	v_lshl_add_u64 v[148:149], v[220:221], 0, s[18:19]
	s_mov_b32 m0, s57
	s_nop 0
	global_load_lds_dwordx4 v[148:149], off
	s_waitcnt vmcnt(7)
	s_waitcnt lgkmcnt(0)
	s_barrier
	s_setprio 1
	s_waitcnt lgkmcnt(0)
	v_mfma_f32_16x16x32_bf16 v[60:63], v[144:147], v[184:187], v[60:63]
	v_mfma_f32_16x16x32_bf16 v[56:59], v[160:163], v[184:187], v[56:59]
	v_mfma_f32_16x16x32_bf16 v[44:47], v[144:147], v[196:199], v[44:47]
	v_mfma_f32_16x16x32_bf16 v[40:43], v[160:163], v[196:199], v[40:43]
	v_mfma_f32_16x16x32_bf16 v[28:31], v[144:147], v[204:207], v[28:31]
	v_mfma_f32_16x16x32_bf16 v[24:27], v[160:163], v[204:207], v[24:27]
	v_mfma_f32_16x16x32_bf16 v[12:15], v[144:147], v[212:215], v[12:15]
	v_mfma_f32_16x16x32_bf16 v[8:11], v[160:163], v[212:215], v[8:11]
	v_mfma_f32_16x16x32_bf16 v[60:63], v[156:159], v[188:191], v[60:63]
	v_mfma_f32_16x16x32_bf16 v[56:59], v[164:167], v[188:191], v[56:59]
	v_mfma_f32_16x16x32_bf16 v[44:47], v[156:159], v[200:203], v[44:47]
	v_mfma_f32_16x16x32_bf16 v[40:43], v[164:167], v[200:203], v[40:43]
	v_mfma_f32_16x16x32_bf16 v[28:31], v[156:159], v[208:211], v[28:31]
	v_mfma_f32_16x16x32_bf16 v[24:27], v[164:167], v[208:211], v[24:27]
	v_mfma_f32_16x16x32_bf16 v[12:15], v[156:159], v[216:219], v[12:15]
	v_mfma_f32_16x16x32_bf16 v[8:11], v[164:167], v[216:219], v[8:11]
	s_setprio 0
	s_setprio 1
	v_mfma_f32_16x16x32_bf16 v[52:55], v[168:171], v[184:187], v[52:55]
	v_mfma_f32_16x16x32_bf16 v[48:51], v[176:179], v[184:187], v[48:51]
	v_mfma_f32_16x16x32_bf16 v[36:39], v[168:171], v[196:199], v[36:39]
	v_mfma_f32_16x16x32_bf16 v[32:35], v[176:179], v[196:199], v[32:35]
	v_mfma_f32_16x16x32_bf16 v[20:23], v[168:171], v[204:207], v[20:23]
	v_mfma_f32_16x16x32_bf16 v[16:19], v[176:179], v[204:207], v[16:19]
	v_mfma_f32_16x16x32_bf16 v[4:7], v[168:171], v[212:215], v[4:7]
	v_mfma_f32_16x16x32_bf16 v[0:3], v[176:179], v[212:215], v[0:3]
	v_mfma_f32_16x16x32_bf16 v[52:55], v[172:175], v[188:191], v[52:55]
	v_mfma_f32_16x16x32_bf16 v[48:51], v[180:183], v[188:191], v[48:51]
	v_mfma_f32_16x16x32_bf16 v[36:39], v[172:175], v[200:203], v[36:39]
	v_mfma_f32_16x16x32_bf16 v[32:35], v[180:183], v[200:203], v[32:35]
	v_mfma_f32_16x16x32_bf16 v[20:23], v[172:175], v[208:211], v[20:23]
	v_mfma_f32_16x16x32_bf16 v[16:19], v[180:183], v[208:211], v[16:19]
	v_mfma_f32_16x16x32_bf16 v[4:7], v[172:175], v[216:219], v[4:7]
	v_mfma_f32_16x16x32_bf16 v[0:3], v[180:183], v[216:219], v[0:3]
	s_setprio 0
	s_barrier
	v_lshl_add_u64 v[222:223], v[222:223], 0, s[18:19]
	s_mov_b32 m0, s58
	s_nop 0
	global_load_lds_dwordx4 v[222:223], off
	s_add_i32 s73, s73, 2
	s_add_u32 s40, s40, 0x100
	s_addc_u32 s41, s41, 0
	s_add_u32 s71, s71, 0x100
	s_addc_u32 s72, s72, 0
	s_cmp_gt_u32 s73, 5
	s_cbranch_scc0 .LBB0_2633
	s_and_b64 vcc, exec, s[20:21]
	s_cbranch_vccz .LBB0_2636
	s_barrier

.LBB0_2657:
	ds_read_b128 v[144:147], v153
	ds_read_b128 v[158:161], v153 offset:1024
	ds_read_b128 v[162:165], v153 offset:2048
	ds_read_b128 v[166:169], v153 offset:3072
	ds_read_b128 v[170:173], v154
	ds_read_b128 v[174:177], v154 offset:1024
	ds_read_b128 v[178:181], v154 offset:2048
	ds_read_b128 v[182:185], v154 offset:3072
	s_add_u32 s34, s30, 0xfffc0080
	s_addc_u32 s35, s31, -1
	s_cmp_eq_u32 s70, 12
	s_cselect_b32 s37, s25, s35
	s_cselect_b32 s36, s60, s34
	s_cselect_b32 s35, s23, s63
	s_cselect_b32 s34, s61, s62
	v_lshl_add_u64 v[148:149], s[30:31], 0, v[136:137]
	s_add_i32 m0, s48, 0xc000
	ds_read_b128 v[186:189], v155
	ds_read_b128 v[190:193], v155 offset:1024
	ds_read_b128 v[196:199], v155 offset:2048
	ds_read_b128 v[200:203], v155 offset:3072
	ds_read_b128 v[204:207], v155 offset:4096
	ds_read_b128 v[208:211], v155 offset:5120
	ds_read_b128 v[212:215], v155 offset:6144
	ds_read_b128 v[216:219], v155 offset:7168
	global_load_lds_dwordx4 v[148:149], off
	v_lshl_add_u64 v[148:149], s[30:31], 0, v[138:139]
	s_add_i32 m0, s48, 0xe000
	s_nop 0
	global_load_lds_dwordx4 v[148:149], off
	s_waitcnt vmcnt(8)
	s_waitcnt lgkmcnt(0)
	s_barrier
	s_setprio 1
	s_waitcnt lgkmcnt(0)
	v_mfma_f32_16x16x32_bf16 v[124:127], v[144:147], v[186:189], v[124:127]
	v_mfma_f32_16x16x32_bf16 v[120:123], v[162:165], v[186:189], v[120:123]
	v_mfma_f32_16x16x32_bf16 v[108:111], v[144:147], v[196:199], v[108:111]
	v_mfma_f32_16x16x32_bf16 v[104:107], v[162:165], v[196:199], v[104:107]
	v_mfma_f32_16x16x32_bf16 v[92:95], v[144:147], v[204:207], v[92:95]
	v_mfma_f32_16x16x32_bf16 v[88:91], v[162:165], v[204:207], v[88:91]
	v_mfma_f32_16x16x32_bf16 v[76:79], v[144:147], v[212:215], v[76:79]
	v_mfma_f32_16x16x32_bf16 v[72:75], v[162:165], v[212:215], v[72:75]
	v_mfma_f32_16x16x32_bf16 v[124:127], v[158:161], v[190:193], v[124:127]
	v_mfma_f32_16x16x32_bf16 v[120:123], v[166:169], v[190:193], v[120:123]
	v_mfma_f32_16x16x32_bf16 v[108:111], v[158:161], v[200:203], v[108:111]
	v_mfma_f32_16x16x32_bf16 v[104:107], v[166:169], v[200:203], v[104:107]
	v_mfma_f32_16x16x32_bf16 v[92:95], v[158:161], v[208:211], v[92:95]
	v_mfma_f32_16x16x32_bf16 v[88:91], v[166:169], v[208:211], v[88:91]
	v_mfma_f32_16x16x32_bf16 v[76:79], v[158:161], v[216:219], v[76:79]
	v_mfma_f32_16x16x32_bf16 v[72:75], v[166:169], v[216:219], v[72:75]
	s_setprio 0
	s_setprio 1
	v_mfma_f32_16x16x32_bf16 v[116:119], v[170:173], v[186:189], v[116:119]
	v_mfma_f32_16x16x32_bf16 v[112:115], v[178:181], v[186:189], v[112:115]
	v_mfma_f32_16x16x32_bf16 v[100:103], v[170:173], v[196:199], v[100:103]
	v_mfma_f32_16x16x32_bf16 v[96:99], v[178:181], v[196:199], v[96:99]
	v_mfma_f32_16x16x32_bf16 v[84:87], v[170:173], v[204:207], v[84:87]
	v_mfma_f32_16x16x32_bf16 v[80:83], v[178:181], v[204:207], v[80:83]
	v_mfma_f32_16x16x32_bf16 v[68:71], v[170:173], v[212:215], v[68:71]
	v_mfma_f32_16x16x32_bf16 v[64:67], v[178:181], v[212:215], v[64:67]
	v_mfma_f32_16x16x32_bf16 v[116:119], v[174:177], v[190:193], v[116:119]
	v_mfma_f32_16x16x32_bf16 v[112:115], v[182:185], v[190:193], v[112:115]
	v_mfma_f32_16x16x32_bf16 v[100:103], v[174:177], v[200:203], v[100:103]
	v_mfma_f32_16x16x32_bf16 v[96:99], v[182:185], v[200:203], v[96:99]
	v_mfma_f32_16x16x32_bf16 v[84:87], v[174:177], v[208:211], v[84:87]
	v_mfma_f32_16x16x32_bf16 v[80:83], v[182:185], v[208:211], v[80:83]
	v_mfma_f32_16x16x32_bf16 v[68:71], v[174:177], v[216:219], v[68:71]
	v_mfma_f32_16x16x32_bf16 v[64:67], v[182:185], v[216:219], v[64:67]
	s_setprio 0
	s_barrier
	s_add_i32 s71, s56, s45
	v_lshl_add_u64 v[148:149], s[34:35], 0, v[130:131]
	s_mov_b32 m0, s71
	ds_read_b128 v[186:189], v155 offset:16384
	ds_read_b128 v[190:193], v155 offset:17408
	ds_read_b128 v[196:199], v155 offset:18432
	ds_read_b128 v[200:203], v155 offset:19456
	ds_read_b128 v[204:207], v155 offset:20480
	ds_read_b128 v[208:211], v155 offset:21504
	ds_read_b128 v[212:215], v155 offset:22528
	ds_read_b128 v[216:219], v155 offset:23552
	global_load_lds_dwordx4 v[148:149], off
	s_add_i32 m0, s71, 0x2000
	s_add_u32 s72, s34, 0x40000
	v_lshl_add_u64 v[220:221], s[34:35], 0, v[134:135]
	s_addc_u32 s73, s35, 0
	s_add_i32 s71, s57, s45
	global_load_lds_dwordx4 v[220:221], off
	v_lshl_add_u64 v[222:223], s[72:73], 0, v[130:131]
	s_mov_b32 m0, s71
	v_lshl_add_u64 v[224:225], s[36:37], 0, v[132:133]
	global_load_lds_dwordx4 v[222:223], off
	v_lshl_add_u64 v[222:223], s[72:73], 0, v[134:135]
	s_add_i32 m0, s71, 0x2000
	s_nop 0
	global_load_lds_dwordx4 v[222:223], off
	v_lshl_add_u64 v[222:223], s[36:37], 0, v[128:129]
	s_mov_b32 m0, s48
	s_nop 0
	global_load_lds_dwordx4 v[222:223], off
	s_waitcnt vmcnt(7)
	s_waitcnt lgkmcnt(0)
	s_barrier
	s_setprio 1
	s_waitcnt lgkmcnt(0)
	v_mfma_f32_16x16x32_bf16 v[60:63], v[144:147], v[186:189], v[60:63]
	v_mfma_f32_16x16x32_bf16 v[56:59], v[162:165], v[186:189], v[56:59]
	v_mfma_f32_16x16x32_bf16 v[44:47], v[144:147], v[196:199], v[44:47]
	v_mfma_f32_16x16x32_bf16 v[40:43], v[162:165], v[196:199], v[40:43]
	v_mfma_f32_16x16x32_bf16 v[28:31], v[144:147], v[204:207], v[28:31]
	v_mfma_f32_16x16x32_bf16 v[24:27], v[162:165], v[204:207], v[24:27]
	v_mfma_f32_16x16x32_bf16 v[12:15], v[144:147], v[212:215], v[12:15]
	v_mfma_f32_16x16x32_bf16 v[8:11], v[162:165], v[212:215], v[8:11]
	v_mfma_f32_16x16x32_bf16 v[60:63], v[158:161], v[190:193], v[60:63]
	v_mfma_f32_16x16x32_bf16 v[56:59], v[166:169], v[190:193], v[56:59]
	v_mfma_f32_16x16x32_bf16 v[44:47], v[158:161], v[200:203], v[44:47]
	v_mfma_f32_16x16x32_bf16 v[40:43], v[166:169], v[200:203], v[40:43]
	v_mfma_f32_16x16x32_bf16 v[28:31], v[158:161], v[208:211], v[28:31]
	v_mfma_f32_16x16x32_bf16 v[24:27], v[166:169], v[208:211], v[24:27]
	v_mfma_f32_16x16x32_bf16 v[12:15], v[158:161], v[216:219], v[12:15]
	v_mfma_f32_16x16x32_bf16 v[8:11], v[166:169], v[216:219], v[8:11]
	s_setprio 0
	s_setprio 1
	v_mfma_f32_16x16x32_bf16 v[52:55], v[170:173], v[186:189], v[52:55]
	v_mfma_f32_16x16x32_bf16 v[48:51], v[178:181], v[186:189], v[48:51]
	v_mfma_f32_16x16x32_bf16 v[36:39], v[170:173], v[196:199], v[36:39]
	v_mfma_f32_16x16x32_bf16 v[32:35], v[178:181], v[196:199], v[32:35]
	v_mfma_f32_16x16x32_bf16 v[20:23], v[170:173], v[204:207], v[20:23]
	v_mfma_f32_16x16x32_bf16 v[16:19], v[178:181], v[204:207], v[16:19]
	v_mfma_f32_16x16x32_bf16 v[4:7], v[170:173], v[212:215], v[4:7]
	v_mfma_f32_16x16x32_bf16 v[0:3], v[178:181], v[212:215], v[0:3]
	v_mfma_f32_16x16x32_bf16 v[52:55], v[174:177], v[190:193], v[52:55]
	v_mfma_f32_16x16x32_bf16 v[48:51], v[182:185], v[190:193], v[48:51]
	v_mfma_f32_16x16x32_bf16 v[36:39], v[174:177], v[200:203], v[36:39]
	v_mfma_f32_16x16x32_bf16 v[32:35], v[182:185], v[200:203], v[32:35]
	v_mfma_f32_16x16x32_bf16 v[20:23], v[174:177], v[208:211], v[20:23]
	v_mfma_f32_16x16x32_bf16 v[16:19], v[182:185], v[208:211], v[16:19]
	v_mfma_f32_16x16x32_bf16 v[4:7], v[174:177], v[216:219], v[4:7]
	v_mfma_f32_16x16x32_bf16 v[0:3], v[182:185], v[216:219], v[0:3]
	s_setprio 0
	s_barrier
	s_add_i32 s71, 0, 0x18000
	v_add_u32_e32 v157, s71, v151
	s_add_i32 s72, 0, 0x1c000
	ds_read_b128 v[144:147], v157
	ds_read_b128 v[158:161], v157 offset:1024
	ds_read_b128 v[162:165], v157 offset:2048
	ds_read_b128 v[166:169], v157 offset:3072
	v_add_u32_e32 v157, s72, v151
	ds_read_b128 v[170:173], v157
	ds_read_b128 v[174:177], v157 offset:1024
	ds_read_b128 v[178:181], v157 offset:2048
	ds_read_b128 v[182:185], v157 offset:3072
	s_add_u32 s36, s36, 0x40000
	s_addc_u32 s37, s37, 0
	v_lshl_add_u64 v[226:227], s[36:37], 0, v[128:129]
	ds_read_b128 v[186:189], v155 offset:32768
	ds_read_b128 v[190:193], v155 offset:33792
	ds_read_b128 v[196:199], v155 offset:34816
	ds_read_b128 v[200:203], v155 offset:35840
	ds_read_b128 v[204:207], v155 offset:36864
	ds_read_b128 v[208:211], v155 offset:37888
	ds_read_b128 v[212:215], v155 offset:38912
	ds_read_b128 v[216:219], v155 offset:39936
	s_mov_b32 m0, s49
	s_nop 0
	global_load_lds_dwordx4 v[224:225], off
	s_mov_b32 m0, s50
	s_nop 0
	global_load_lds_dwordx4 v[226:227], off
	v_lshl_add_u64 v[226:227], s[36:37], 0, v[132:133]
	s_mov_b32 m0, s51
	s_nop 0
	global_load_lds_dwordx4 v[226:227], off
	s_waitcnt vmcnt(8)
	s_waitcnt lgkmcnt(0)
	s_barrier
	s_setprio 1
	s_waitcnt lgkmcnt(0)
	v_mfma_f32_16x16x32_bf16 v[124:127], v[144:147], v[186:189], v[124:127]
	v_mfma_f32_16x16x32_bf16 v[120:123], v[162:165], v[186:189], v[120:123]
	v_mfma_f32_16x16x32_bf16 v[108:111], v[144:147], v[196:199], v[108:111]
	v_mfma_f32_16x16x32_bf16 v[104:107], v[162:165], v[196:199], v[104:107]
	v_mfma_f32_16x16x32_bf16 v[92:95], v[144:147], v[204:207], v[92:95]
	v_mfma_f32_16x16x32_bf16 v[88:91], v[162:165], v[204:207], v[88:91]
	v_mfma_f32_16x16x32_bf16 v[76:79], v[144:147], v[212:215], v[76:79]
	v_mfma_f32_16x16x32_bf16 v[72:75], v[162:165], v[212:215], v[72:75]
	v_mfma_f32_16x16x32_bf16 v[124:127], v[158:161], v[190:193], v[124:127]
	v_mfma_f32_16x16x32_bf16 v[120:123], v[166:169], v[190:193], v[120:123]
	v_mfma_f32_16x16x32_bf16 v[108:111], v[158:161], v[200:203], v[108:111]
	v_mfma_f32_16x16x32_bf16 v[104:107], v[166:169], v[200:203], v[104:107]
	v_mfma_f32_16x16x32_bf16 v[92:95], v[158:161], v[208:211], v[92:95]
	v_mfma_f32_16x16x32_bf16 v[88:91], v[166:169], v[208:211], v[88:91]
	v_mfma_f32_16x16x32_bf16 v[76:79], v[158:161], v[216:219], v[76:79]
	v_mfma_f32_16x16x32_bf16 v[72:75], v[166:169], v[216:219], v[72:75]
	s_setprio 0
	s_setprio 1
	v_mfma_f32_16x16x32_bf16 v[116:119], v[170:173], v[186:189], v[116:119]
	v_mfma_f32_16x16x32_bf16 v[112:115], v[178:181], v[186:189], v[112:115]
	v_mfma_f32_16x16x32_bf16 v[100:103], v[170:173], v[196:199], v[100:103]
	v_mfma_f32_16x16x32_bf16 v[96:99], v[178:181], v[196:199], v[96:99]
	v_mfma_f32_16x16x32_bf16 v[84:87], v[170:173], v[204:207], v[84:87]
	v_mfma_f32_16x16x32_bf16 v[80:83], v[178:181], v[204:207], v[80:83]
	v_mfma_f32_16x16x32_bf16 v[68:71], v[170:173], v[212:215], v[68:71]
	v_mfma_f32_16x16x32_bf16 v[64:67], v[178:181], v[212:215], v[64:67]
	v_mfma_f32_16x16x32_bf16 v[116:119], v[174:177], v[190:193], v[116:119]
	v_mfma_f32_16x16x32_bf16 v[112:115], v[182:185], v[190:193], v[112:115]
	v_mfma_f32_16x16x32_bf16 v[100:103], v[174:177], v[200:203], v[100:103]
	v_mfma_f32_16x16x32_bf16 v[96:99], v[182:185], v[200:203], v[96:99]
	v_mfma_f32_16x16x32_bf16 v[84:87], v[174:177], v[208:211], v[84:87]
	v_mfma_f32_16x16x32_bf16 v[80:83], v[182:185], v[208:211], v[80:83]
	v_mfma_f32_16x16x32_bf16 v[68:71], v[174:177], v[216:219], v[68:71]
	v_mfma_f32_16x16x32_bf16 v[64:67], v[182:185], v[216:219], v[64:67]
	s_setprio 0
	s_barrier
	s_add_i32 s36, s71, s45
	v_lshl_add_u64 v[148:149], v[148:149], 0, s[18:19]
	s_mov_b32 m0, s36
	ds_read_b128 v[186:189], v155 offset:49152
	ds_read_b128 v[190:193], v155 offset:50176
	ds_read_b128 v[196:199], v155 offset:51200
	ds_read_b128 v[200:203], v155 offset:52224
	ds_read_b128 v[204:207], v155 offset:53248
	ds_read_b128 v[208:211], v155 offset:54272
	ds_read_b128 v[212:215], v155 offset:55296
	ds_read_b128 v[216:219], v155 offset:56320
	global_load_lds_dwordx4 v[148:149], off
	s_add_i32 m0, s36, 0x2000
	s_add_u32 s34, s34, 0x40080
	v_lshl_add_u64 v[148:149], v[220:221], 0, s[18:19]
	s_addc_u32 s35, s35, 0
	s_add_i32 s36, s72, s45
	global_load_lds_dwordx4 v[148:149], off
	v_lshl_add_u64 v[148:149], s[34:35], 0, v[130:131]
	s_mov_b32 m0, s36
	s_nop 0
	global_load_lds_dwordx4 v[148:149], off
	v_lshl_add_u64 v[148:149], s[34:35], 0, v[134:135]
	s_add_i32 m0, s36, 0x2000
	s_nop 0
	global_load_lds_dwordx4 v[148:149], off
	v_lshl_add_u64 v[148:149], v[222:223], 0, s[18:19]
	s_mov_b32 m0, s53
	s_nop 0
	global_load_lds_dwordx4 v[148:149], off
	s_waitcnt vmcnt(7)
	s_waitcnt lgkmcnt(0)
	s_barrier
	s_setprio 1
	s_waitcnt lgkmcnt(0)
	v_mfma_f32_16x16x32_bf16 v[60:63], v[144:147], v[186:189], v[60:63]
	v_mfma_f32_16x16x32_bf16 v[56:59], v[162:165], v[186:189], v[56:59]
	v_mfma_f32_16x16x32_bf16 v[44:47], v[144:147], v[196:199], v[44:47]
	v_mfma_f32_16x16x32_bf16 v[40:43], v[162:165], v[196:199], v[40:43]
	v_mfma_f32_16x16x32_bf16 v[28:31], v[144:147], v[204:207], v[28:31]
	v_mfma_f32_16x16x32_bf16 v[24:27], v[162:165], v[204:207], v[24:27]
	v_mfma_f32_16x16x32_bf16 v[12:15], v[144:147], v[212:215], v[12:15]
	v_mfma_f32_16x16x32_bf16 v[8:11], v[162:165], v[212:215], v[8:11]
	v_mfma_f32_16x16x32_bf16 v[60:63], v[158:161], v[190:193], v[60:63]
	v_mfma_f32_16x16x32_bf16 v[56:59], v[166:169], v[190:193], v[56:59]
	v_mfma_f32_16x16x32_bf16 v[44:47], v[158:161], v[200:203], v[44:47]
	v_mfma_f32_16x16x32_bf16 v[40:43], v[166:169], v[200:203], v[40:43]
	v_mfma_f32_16x16x32_bf16 v[28:31], v[158:161], v[208:211], v[28:31]
	v_mfma_f32_16x16x32_bf16 v[24:27], v[166:169], v[208:211], v[24:27]
	v_mfma_f32_16x16x32_bf16 v[12:15], v[158:161], v[216:219], v[12:15]
	v_mfma_f32_16x16x32_bf16 v[8:11], v[166:169], v[216:219], v[8:11]
	s_setprio 0
	s_setprio 1
	v_mfma_f32_16x16x32_bf16 v[52:55], v[170:173], v[186:189], v[52:55]
	v_mfma_f32_16x16x32_bf16 v[48:51], v[178:181], v[186:189], v[48:51]
	v_mfma_f32_16x16x32_bf16 v[36:39], v[170:173], v[196:199], v[36:39]
	v_mfma_f32_16x16x32_bf16 v[32:35], v[178:181], v[196:199], v[32:35]
	v_mfma_f32_16x16x32_bf16 v[20:23], v[170:173], v[204:207], v[20:23]
	v_mfma_f32_16x16x32_bf16 v[16:19], v[178:181], v[204:207], v[16:19]
	v_mfma_f32_16x16x32_bf16 v[4:7], v[170:173], v[212:215], v[4:7]
	v_mfma_f32_16x16x32_bf16 v[0:3], v[178:181], v[212:215], v[0:3]
	v_mfma_f32_16x16x32_bf16 v[52:55], v[174:177], v[190:193], v[52:55]
	v_mfma_f32_16x16x32_bf16 v[48:51], v[182:185], v[190:193], v[48:51]
	v_mfma_f32_16x16x32_bf16 v[36:39], v[174:177], v[200:203], v[36:39]
	v_mfma_f32_16x16x32_bf16 v[32:35], v[182:185], v[200:203], v[32:35]
	v_mfma_f32_16x16x32_bf16 v[20:23], v[174:177], v[208:211], v[20:23]
	v_mfma_f32_16x16x32_bf16 v[16:19], v[182:185], v[208:211], v[16:19]
	v_mfma_f32_16x16x32_bf16 v[4:7], v[174:177], v[216:219], v[4:7]
	v_mfma_f32_16x16x32_bf16 v[0:3], v[182:185], v[216:219], v[0:3]
	s_setprio 0
	s_barrier
	v_lshl_add_u64 v[224:225], v[224:225], 0, s[18:19]
	s_mov_b32 m0, s54
	s_nop 0
	global_load_lds_dwordx4 v[224:225], off
	s_add_i32 s70, s70, 2
	s_add_u32 s30, s30, 0x100
	s_addc_u32 s31, s31, 0
	s_add_u32 s62, s62, 0x100
	s_addc_u32 s63, s63, 0
	s_cmp_gt_u32 s70, 13
	s_cbranch_scc0 .LBB0_2657
	s_and_b64 vcc, exec, s[20:21]
	s_cbranch_vccz .LBB0_2660
	s_barrier

.LBB0_3031:
	ds_read_b128 v[146:149], v155
	ds_read_b128 v[160:163], v155 offset:1024
	ds_read_b128 v[164:167], v155 offset:2048
	ds_read_b128 v[168:171], v155 offset:3072
	ds_read_b128 v[172:175], v156
	ds_read_b128 v[176:179], v156 offset:1024
	ds_read_b128 v[180:183], v156 offset:2048
	ds_read_b128 v[184:187], v156 offset:3072
	s_add_u32 s36, s0, 0xfffc0080
	s_addc_u32 s37, s1, -1
	s_cmp_eq_u32 s60, 12
	s_cselect_b32 s39, s21, s37
	s_cselect_b32 s38, s23, s36
	s_cselect_b32 s37, s27, s59
	s_cselect_b32 s36, s26, s25
	v_lshl_add_u64 v[150:151], s[0:1], 0, v[138:139]
	s_add_i32 m0, s35, 0xc000
	ds_read_b128 v[188:191], v157
	ds_read_b128 v[196:199], v157 offset:1024
	ds_read_b128 v[200:203], v157 offset:2048
	ds_read_b128 v[204:207], v157 offset:3072
	ds_read_b128 v[208:211], v157 offset:4096
	ds_read_b128 v[212:215], v157 offset:5120
	ds_read_b128 v[216:219], v157 offset:6144
	ds_read_b128 v[220:223], v157 offset:7168
	global_load_lds_dwordx4 v[150:151], off
	v_lshl_add_u64 v[150:151], s[0:1], 0, v[140:141]
	s_add_i32 m0, s35, 0xe000
	s_nop 0
	global_load_lds_dwordx4 v[150:151], off
	s_waitcnt vmcnt(8)
	s_waitcnt lgkmcnt(0)
	s_barrier
	s_setprio 1
	s_waitcnt lgkmcnt(0)
	v_mfma_f32_16x16x32_bf16 v[124:127], v[146:149], v[188:191], v[124:127]
	v_mfma_f32_16x16x32_bf16 v[120:123], v[164:167], v[188:191], v[120:123]
	v_mfma_f32_16x16x32_bf16 v[108:111], v[146:149], v[200:203], v[108:111]
	v_mfma_f32_16x16x32_bf16 v[104:107], v[164:167], v[200:203], v[104:107]
	v_mfma_f32_16x16x32_bf16 v[92:95], v[146:149], v[208:211], v[92:95]
	v_mfma_f32_16x16x32_bf16 v[88:91], v[164:167], v[208:211], v[88:91]
	v_mfma_f32_16x16x32_bf16 v[76:79], v[146:149], v[216:219], v[76:79]
	v_mfma_f32_16x16x32_bf16 v[72:75], v[164:167], v[216:219], v[72:75]
	v_mfma_f32_16x16x32_bf16 v[124:127], v[160:163], v[196:199], v[124:127]
	v_mfma_f32_16x16x32_bf16 v[120:123], v[168:171], v[196:199], v[120:123]
	v_mfma_f32_16x16x32_bf16 v[108:111], v[160:163], v[204:207], v[108:111]
	v_mfma_f32_16x16x32_bf16 v[104:107], v[168:171], v[204:207], v[104:107]
	v_mfma_f32_16x16x32_bf16 v[92:95], v[160:163], v[212:215], v[92:95]
	v_mfma_f32_16x16x32_bf16 v[88:91], v[168:171], v[212:215], v[88:91]
	v_mfma_f32_16x16x32_bf16 v[76:79], v[160:163], v[220:223], v[76:79]
	v_mfma_f32_16x16x32_bf16 v[72:75], v[168:171], v[220:223], v[72:75]
	s_setprio 0
	s_setprio 1
	v_mfma_f32_16x16x32_bf16 v[116:119], v[172:175], v[188:191], v[116:119]
	v_mfma_f32_16x16x32_bf16 v[112:115], v[180:183], v[188:191], v[112:115]
	v_mfma_f32_16x16x32_bf16 v[100:103], v[172:175], v[200:203], v[100:103]
	v_mfma_f32_16x16x32_bf16 v[96:99], v[180:183], v[200:203], v[96:99]
	v_mfma_f32_16x16x32_bf16 v[84:87], v[172:175], v[208:211], v[84:87]
	v_mfma_f32_16x16x32_bf16 v[80:83], v[180:183], v[208:211], v[80:83]
	v_mfma_f32_16x16x32_bf16 v[68:71], v[172:175], v[216:219], v[68:71]
	v_mfma_f32_16x16x32_bf16 v[64:67], v[180:183], v[216:219], v[64:67]
	v_mfma_f32_16x16x32_bf16 v[116:119], v[176:179], v[196:199], v[116:119]
	v_mfma_f32_16x16x32_bf16 v[112:115], v[184:187], v[196:199], v[112:115]
	v_mfma_f32_16x16x32_bf16 v[100:103], v[176:179], v[204:207], v[100:103]
	v_mfma_f32_16x16x32_bf16 v[96:99], v[184:187], v[204:207], v[96:99]
	v_mfma_f32_16x16x32_bf16 v[84:87], v[176:179], v[212:215], v[84:87]
	v_mfma_f32_16x16x32_bf16 v[80:83], v[184:187], v[212:215], v[80:83]
	v_mfma_f32_16x16x32_bf16 v[68:71], v[176:179], v[220:223], v[68:71]
	v_mfma_f32_16x16x32_bf16 v[64:67], v[184:187], v[220:223], v[64:67]
	s_setprio 0
	s_barrier
	s_add_i32 s61, s55, s44
	v_lshl_add_u64 v[150:151], s[36:37], 0, v[130:131]
	s_mov_b32 m0, s61
	ds_read_b128 v[188:191], v157 offset:16384
	ds_read_b128 v[196:199], v157 offset:17408
	ds_read_b128 v[200:203], v157 offset:18432
	ds_read_b128 v[204:207], v157 offset:19456
	ds_read_b128 v[208:211], v157 offset:20480
	ds_read_b128 v[212:215], v157 offset:21504
	ds_read_b128 v[216:219], v157 offset:22528
	ds_read_b128 v[220:223], v157 offset:23552
	global_load_lds_dwordx4 v[150:151], off
	s_add_i32 m0, s61, 0x2000
	s_add_u32 s62, s36, 0x40000
	v_lshl_add_u64 v[192:193], s[36:37], 0, v[134:135]
	s_addc_u32 s63, s37, 0
	s_add_i32 s61, s56, s44
	global_load_lds_dwordx4 v[192:193], off
	v_lshl_add_u64 v[224:225], s[62:63], 0, v[130:131]
	s_mov_b32 m0, s61
	v_lshl_add_u64 v[226:227], s[38:39], 0, v[132:133]
	global_load_lds_dwordx4 v[224:225], off
	v_lshl_add_u64 v[224:225], s[62:63], 0, v[134:135]
	s_add_i32 m0, s61, 0x2000
	s_nop 0
	global_load_lds_dwordx4 v[224:225], off
	v_lshl_add_u64 v[224:225], s[38:39], 0, v[128:129]
	s_mov_b32 m0, s35
	s_nop 0
	global_load_lds_dwordx4 v[224:225], off
	s_waitcnt vmcnt(7)
	s_waitcnt lgkmcnt(0)
	s_barrier
	s_setprio 1
	s_waitcnt lgkmcnt(0)
	v_mfma_f32_16x16x32_bf16 v[60:63], v[146:149], v[188:191], v[60:63]
	v_mfma_f32_16x16x32_bf16 v[56:59], v[164:167], v[188:191], v[56:59]
	v_mfma_f32_16x16x32_bf16 v[44:47], v[146:149], v[200:203], v[44:47]
	v_mfma_f32_16x16x32_bf16 v[40:43], v[164:167], v[200:203], v[40:43]
	v_mfma_f32_16x16x32_bf16 v[28:31], v[146:149], v[208:211], v[28:31]
	v_mfma_f32_16x16x32_bf16 v[24:27], v[164:167], v[208:211], v[24:27]
	v_mfma_f32_16x16x32_bf16 v[12:15], v[146:149], v[216:219], v[12:15]
	v_mfma_f32_16x16x32_bf16 v[8:11], v[164:167], v[216:219], v[8:11]
	v_mfma_f32_16x16x32_bf16 v[60:63], v[160:163], v[196:199], v[60:63]
	v_mfma_f32_16x16x32_bf16 v[56:59], v[168:171], v[196:199], v[56:59]
	v_mfma_f32_16x16x32_bf16 v[44:47], v[160:163], v[204:207], v[44:47]
	v_mfma_f32_16x16x32_bf16 v[40:43], v[168:171], v[204:207], v[40:43]
	v_mfma_f32_16x16x32_bf16 v[28:31], v[160:163], v[212:215], v[28:31]
	v_mfma_f32_16x16x32_bf16 v[24:27], v[168:171], v[212:215], v[24:27]
	v_mfma_f32_16x16x32_bf16 v[12:15], v[160:163], v[220:223], v[12:15]
	v_mfma_f32_16x16x32_bf16 v[8:11], v[168:171], v[220:223], v[8:11]
	s_setprio 0
	s_setprio 1
	v_mfma_f32_16x16x32_bf16 v[52:55], v[172:175], v[188:191], v[52:55]
	v_mfma_f32_16x16x32_bf16 v[48:51], v[180:183], v[188:191], v[48:51]
	v_mfma_f32_16x16x32_bf16 v[36:39], v[172:175], v[200:203], v[36:39]
	v_mfma_f32_16x16x32_bf16 v[32:35], v[180:183], v[200:203], v[32:35]
	v_mfma_f32_16x16x32_bf16 v[20:23], v[172:175], v[208:211], v[20:23]
	v_mfma_f32_16x16x32_bf16 v[16:19], v[180:183], v[208:211], v[16:19]
	v_mfma_f32_16x16x32_bf16 v[4:7], v[172:175], v[216:219], v[4:7]
	v_mfma_f32_16x16x32_bf16 v[0:3], v[180:183], v[216:219], v[0:3]
	v_mfma_f32_16x16x32_bf16 v[52:55], v[176:179], v[196:199], v[52:55]
	v_mfma_f32_16x16x32_bf16 v[48:51], v[184:187], v[196:199], v[48:51]
	v_mfma_f32_16x16x32_bf16 v[36:39], v[176:179], v[204:207], v[36:39]
	v_mfma_f32_16x16x32_bf16 v[32:35], v[184:187], v[204:207], v[32:35]
	v_mfma_f32_16x16x32_bf16 v[20:23], v[176:179], v[212:215], v[20:23]
	v_mfma_f32_16x16x32_bf16 v[16:19], v[184:187], v[212:215], v[16:19]
	v_mfma_f32_16x16x32_bf16 v[4:7], v[176:179], v[220:223], v[4:7]
	v_mfma_f32_16x16x32_bf16 v[0:3], v[184:187], v[220:223], v[0:3]
	s_setprio 0
	s_barrier
	s_add_i32 s61, 0, 0x18000
	v_add_u32_e32 v159, s61, v153
	s_add_i32 s62, 0, 0x1c000
	ds_read_b128 v[146:149], v159
	ds_read_b128 v[160:163], v159 offset:1024
	ds_read_b128 v[164:167], v159 offset:2048
	ds_read_b128 v[168:171], v159 offset:3072
	v_add_u32_e32 v159, s62, v153
	ds_read_b128 v[172:175], v159
	ds_read_b128 v[176:179], v159 offset:1024
	ds_read_b128 v[180:183], v159 offset:2048
	ds_read_b128 v[184:187], v159 offset:3072
	s_add_u32 s38, s38, 0x40000
	s_addc_u32 s39, s39, 0
	v_lshl_add_u64 v[228:229], s[38:39], 0, v[128:129]
	ds_read_b128 v[188:191], v157 offset:32768
	ds_read_b128 v[196:199], v157 offset:33792
	ds_read_b128 v[200:203], v157 offset:34816
	ds_read_b128 v[204:207], v157 offset:35840
	ds_read_b128 v[208:211], v157 offset:36864
	ds_read_b128 v[212:215], v157 offset:37888
	ds_read_b128 v[216:219], v157 offset:38912
	ds_read_b128 v[220:223], v157 offset:39936
	s_mov_b32 m0, s45
	s_nop 0
	global_load_lds_dwordx4 v[226:227], off
	s_mov_b32 m0, s48
	s_nop 0
	global_load_lds_dwordx4 v[228:229], off
	v_lshl_add_u64 v[228:229], s[38:39], 0, v[132:133]
	s_mov_b32 m0, s49
	s_nop 0
	global_load_lds_dwordx4 v[228:229], off
	s_waitcnt vmcnt(8)
	s_waitcnt lgkmcnt(0)
	s_barrier
	s_setprio 1
	s_waitcnt lgkmcnt(0)
	v_mfma_f32_16x16x32_bf16 v[124:127], v[146:149], v[188:191], v[124:127]
	v_mfma_f32_16x16x32_bf16 v[120:123], v[164:167], v[188:191], v[120:123]
	v_mfma_f32_16x16x32_bf16 v[108:111], v[146:149], v[200:203], v[108:111]
	v_mfma_f32_16x16x32_bf16 v[104:107], v[164:167], v[200:203], v[104:107]
	v_mfma_f32_16x16x32_bf16 v[92:95], v[146:149], v[208:211], v[92:95]
	v_mfma_f32_16x16x32_bf16 v[88:91], v[164:167], v[208:211], v[88:91]
	v_mfma_f32_16x16x32_bf16 v[76:79], v[146:149], v[216:219], v[76:79]
	v_mfma_f32_16x16x32_bf16 v[72:75], v[164:167], v[216:219], v[72:75]
	v_mfma_f32_16x16x32_bf16 v[124:127], v[160:163], v[196:199], v[124:127]
	v_mfma_f32_16x16x32_bf16 v[120:123], v[168:171], v[196:199], v[120:123]
	v_mfma_f32_16x16x32_bf16 v[108:111], v[160:163], v[204:207], v[108:111]
	v_mfma_f32_16x16x32_bf16 v[104:107], v[168:171], v[204:207], v[104:107]
	v_mfma_f32_16x16x32_bf16 v[92:95], v[160:163], v[212:215], v[92:95]
	v_mfma_f32_16x16x32_bf16 v[88:91], v[168:171], v[212:215], v[88:91]
	v_mfma_f32_16x16x32_bf16 v[76:79], v[160:163], v[220:223], v[76:79]
	v_mfma_f32_16x16x32_bf16 v[72:75], v[168:171], v[220:223], v[72:75]
	s_setprio 0
	s_setprio 1
	v_mfma_f32_16x16x32_bf16 v[116:119], v[172:175], v[188:191], v[116:119]
	v_mfma_f32_16x16x32_bf16 v[112:115], v[180:183], v[188:191], v[112:115]
	v_mfma_f32_16x16x32_bf16 v[100:103], v[172:175], v[200:203], v[100:103]
	v_mfma_f32_16x16x32_bf16 v[96:99], v[180:183], v[200:203], v[96:99]
	v_mfma_f32_16x16x32_bf16 v[84:87], v[172:175], v[208:211], v[84:87]
	v_mfma_f32_16x16x32_bf16 v[80:83], v[180:183], v[208:211], v[80:83]
	v_mfma_f32_16x16x32_bf16 v[68:71], v[172:175], v[216:219], v[68:71]
	v_mfma_f32_16x16x32_bf16 v[64:67], v[180:183], v[216:219], v[64:67]
	v_mfma_f32_16x16x32_bf16 v[116:119], v[176:179], v[196:199], v[116:119]
	v_mfma_f32_16x16x32_bf16 v[112:115], v[184:187], v[196:199], v[112:115]
	v_mfma_f32_16x16x32_bf16 v[100:103], v[176:179], v[204:207], v[100:103]
	v_mfma_f32_16x16x32_bf16 v[96:99], v[184:187], v[204:207], v[96:99]
	v_mfma_f32_16x16x32_bf16 v[84:87], v[176:179], v[212:215], v[84:87]
	v_mfma_f32_16x16x32_bf16 v[80:83], v[184:187], v[212:215], v[80:83]
	v_mfma_f32_16x16x32_bf16 v[68:71], v[176:179], v[220:223], v[68:71]
	v_mfma_f32_16x16x32_bf16 v[64:67], v[184:187], v[220:223], v[64:67]
	s_setprio 0
	s_barrier
	s_add_i32 s38, s61, s44
	v_lshl_add_u64 v[150:151], v[150:151], 0, s[16:17]
	s_mov_b32 m0, s38
	ds_read_b128 v[188:191], v157 offset:49152
	ds_read_b128 v[196:199], v157 offset:50176
	ds_read_b128 v[200:203], v157 offset:51200
	ds_read_b128 v[204:207], v157 offset:52224
	ds_read_b128 v[208:211], v157 offset:53248
	ds_read_b128 v[212:215], v157 offset:54272
	ds_read_b128 v[216:219], v157 offset:55296
	ds_read_b128 v[220:223], v157 offset:56320
	global_load_lds_dwordx4 v[150:151], off
	s_add_i32 m0, s38, 0x2000
	s_add_u32 s36, s36, 0x40080
	v_lshl_add_u64 v[150:151], v[192:193], 0, s[16:17]
	s_addc_u32 s37, s37, 0
	s_add_i32 s38, s62, s44
	global_load_lds_dwordx4 v[150:151], off
	v_lshl_add_u64 v[150:151], s[36:37], 0, v[130:131]
	s_mov_b32 m0, s38
	s_nop 0
	global_load_lds_dwordx4 v[150:151], off
	v_lshl_add_u64 v[150:151], s[36:37], 0, v[134:135]
	s_add_i32 m0, s38, 0x2000
	s_nop 0
	global_load_lds_dwordx4 v[150:151], off
	v_lshl_add_u64 v[150:151], v[224:225], 0, s[16:17]
	s_mov_b32 m0, s50
	s_nop 0
	global_load_lds_dwordx4 v[150:151], off
	s_waitcnt vmcnt(7)
	s_waitcnt lgkmcnt(0)
	s_barrier
	s_setprio 1
	s_waitcnt lgkmcnt(0)
	v_mfma_f32_16x16x32_bf16 v[60:63], v[146:149], v[188:191], v[60:63]
	v_mfma_f32_16x16x32_bf16 v[56:59], v[164:167], v[188:191], v[56:59]
	v_mfma_f32_16x16x32_bf16 v[44:47], v[146:149], v[200:203], v[44:47]
	v_mfma_f32_16x16x32_bf16 v[40:43], v[164:167], v[200:203], v[40:43]
	v_mfma_f32_16x16x32_bf16 v[28:31], v[146:149], v[208:211], v[28:31]
	v_mfma_f32_16x16x32_bf16 v[24:27], v[164:167], v[208:211], v[24:27]
	v_mfma_f32_16x16x32_bf16 v[12:15], v[146:149], v[216:219], v[12:15]
	v_mfma_f32_16x16x32_bf16 v[8:11], v[164:167], v[216:219], v[8:11]
	v_mfma_f32_16x16x32_bf16 v[60:63], v[160:163], v[196:199], v[60:63]
	v_mfma_f32_16x16x32_bf16 v[56:59], v[168:171], v[196:199], v[56:59]
	v_mfma_f32_16x16x32_bf16 v[44:47], v[160:163], v[204:207], v[44:47]
	v_mfma_f32_16x16x32_bf16 v[40:43], v[168:171], v[204:207], v[40:43]
	v_mfma_f32_16x16x32_bf16 v[28:31], v[160:163], v[212:215], v[28:31]
	v_mfma_f32_16x16x32_bf16 v[24:27], v[168:171], v[212:215], v[24:27]
	v_mfma_f32_16x16x32_bf16 v[12:15], v[160:163], v[220:223], v[12:15]
	v_mfma_f32_16x16x32_bf16 v[8:11], v[168:171], v[220:223], v[8:11]
	s_setprio 0
	s_setprio 1
	v_mfma_f32_16x16x32_bf16 v[52:55], v[172:175], v[188:191], v[52:55]
	v_mfma_f32_16x16x32_bf16 v[48:51], v[180:183], v[188:191], v[48:51]
	v_mfma_f32_16x16x32_bf16 v[36:39], v[172:175], v[200:203], v[36:39]
	v_mfma_f32_16x16x32_bf16 v[32:35], v[180:183], v[200:203], v[32:35]
	v_mfma_f32_16x16x32_bf16 v[20:23], v[172:175], v[208:211], v[20:23]
	v_mfma_f32_16x16x32_bf16 v[16:19], v[180:183], v[208:211], v[16:19]
	v_mfma_f32_16x16x32_bf16 v[4:7], v[172:175], v[216:219], v[4:7]
	v_mfma_f32_16x16x32_bf16 v[0:3], v[180:183], v[216:219], v[0:3]
	v_mfma_f32_16x16x32_bf16 v[52:55], v[176:179], v[196:199], v[52:55]
	v_mfma_f32_16x16x32_bf16 v[48:51], v[184:187], v[196:199], v[48:51]
	v_mfma_f32_16x16x32_bf16 v[36:39], v[176:179], v[204:207], v[36:39]
	v_mfma_f32_16x16x32_bf16 v[32:35], v[184:187], v[204:207], v[32:35]
	v_mfma_f32_16x16x32_bf16 v[20:23], v[176:179], v[212:215], v[20:23]
	v_mfma_f32_16x16x32_bf16 v[16:19], v[184:187], v[212:215], v[16:19]
	v_mfma_f32_16x16x32_bf16 v[4:7], v[176:179], v[220:223], v[4:7]
	v_mfma_f32_16x16x32_bf16 v[0:3], v[184:187], v[220:223], v[0:3]
	s_setprio 0
	s_barrier
	v_lshl_add_u64 v[226:227], v[226:227], 0, s[16:17]
	s_mov_b32 m0, s51
	s_nop 0
	global_load_lds_dwordx4 v[226:227], off
	s_add_i32 s60, s60, 2
	s_add_u32 s0, s0, 0x100
	s_addc_u32 s1, s1, 0
	s_add_u32 s25, s25, 0x100
	s_addc_u32 s59, s59, 0
	s_cmp_gt_u32 s60, 13
	s_cbranch_scc0 .LBB0_3031
	s_and_b64 vcc, exec, s[18:19]
	s_cbranch_vccz .LBB0_3034
	s_barrier

.LBB0_3061:
	ds_read_b128 v[144:147], v159
	ds_read_b128 v[148:151], v159 offset:1024
	ds_read_b128 v[152:155], v159 offset:2048
	ds_read_b128 v[162:165], v159 offset:3072
	ds_read_b128 v[166:169], v160
	ds_read_b128 v[170:173], v160 offset:1024
	ds_read_b128 v[174:177], v160 offset:2048
	ds_read_b128 v[178:181], v160 offset:3072
	s_add_u32 s37, s42, 0xfffe0080
	s_addc_u32 s39, s43, -1
	s_cmp_eq_u32 s35, 4
	s_cselect_b32 s51, s1, s39
	s_cselect_b32 s50, s0, s37
	s_cselect_b32 s49, s41, s13
	s_cselect_b32 s48, s40, s11
	v_lshl_add_u64 v[216:217], s[42:43], 0, v[136:137]
	s_add_i32 m0, s60, 0xc000
	ds_read_b128 v[182:185], v161
	ds_read_b128 v[186:189], v161 offset:1024
	ds_read_b128 v[190:193], v161 offset:2048
	ds_read_b128 v[196:199], v161 offset:3072
	ds_read_b128 v[200:203], v161 offset:4096
	ds_read_b128 v[204:207], v161 offset:5120
	ds_read_b128 v[208:211], v161 offset:6144
	ds_read_b128 v[212:215], v161 offset:7168
	global_load_lds_dwordx4 v[216:217], off
	v_lshl_add_u64 v[216:217], s[42:43], 0, v[138:139]
	s_add_i32 m0, s60, 0xe000
	s_nop 0
	global_load_lds_dwordx4 v[216:217], off
	s_waitcnt vmcnt(8)
	s_waitcnt lgkmcnt(0)
	s_barrier
	s_setprio 1
	s_waitcnt lgkmcnt(0)
	v_mfma_f32_16x16x32_bf16 v[124:127], v[144:147], v[182:185], v[124:127]
	v_mfma_f32_16x16x32_bf16 v[120:123], v[152:155], v[182:185], v[120:123]
	v_mfma_f32_16x16x32_bf16 v[108:111], v[144:147], v[190:193], v[108:111]
	v_mfma_f32_16x16x32_bf16 v[104:107], v[152:155], v[190:193], v[104:107]
	v_mfma_f32_16x16x32_bf16 v[92:95], v[144:147], v[200:203], v[92:95]
	v_mfma_f32_16x16x32_bf16 v[88:91], v[152:155], v[200:203], v[88:91]
	v_mfma_f32_16x16x32_bf16 v[76:79], v[144:147], v[208:211], v[76:79]
	v_mfma_f32_16x16x32_bf16 v[72:75], v[152:155], v[208:211], v[72:75]
	v_mfma_f32_16x16x32_bf16 v[124:127], v[148:151], v[186:189], v[124:127]
	v_mfma_f32_16x16x32_bf16 v[120:123], v[162:165], v[186:189], v[120:123]
	v_mfma_f32_16x16x32_bf16 v[108:111], v[148:151], v[196:199], v[108:111]
	v_mfma_f32_16x16x32_bf16 v[104:107], v[162:165], v[196:199], v[104:107]
	v_mfma_f32_16x16x32_bf16 v[92:95], v[148:151], v[204:207], v[92:95]
	v_mfma_f32_16x16x32_bf16 v[88:91], v[162:165], v[204:207], v[88:91]
	v_mfma_f32_16x16x32_bf16 v[76:79], v[148:151], v[212:215], v[76:79]
	v_mfma_f32_16x16x32_bf16 v[72:75], v[162:165], v[212:215], v[72:75]
	s_setprio 0
	s_setprio 1
	v_mfma_f32_16x16x32_bf16 v[116:119], v[166:169], v[182:185], v[116:119]
	v_mfma_f32_16x16x32_bf16 v[112:115], v[174:177], v[182:185], v[112:115]
	v_mfma_f32_16x16x32_bf16 v[100:103], v[166:169], v[190:193], v[100:103]
	v_mfma_f32_16x16x32_bf16 v[96:99], v[174:177], v[190:193], v[96:99]
	v_mfma_f32_16x16x32_bf16 v[84:87], v[166:169], v[200:203], v[84:87]
	v_mfma_f32_16x16x32_bf16 v[80:83], v[174:177], v[200:203], v[80:83]
	v_mfma_f32_16x16x32_bf16 v[68:71], v[166:169], v[208:211], v[68:71]
	v_mfma_f32_16x16x32_bf16 v[64:67], v[174:177], v[208:211], v[64:67]
	v_mfma_f32_16x16x32_bf16 v[116:119], v[170:173], v[186:189], v[116:119]
	v_mfma_f32_16x16x32_bf16 v[112:115], v[178:181], v[186:189], v[112:115]
	v_mfma_f32_16x16x32_bf16 v[100:103], v[170:173], v[196:199], v[100:103]
	v_mfma_f32_16x16x32_bf16 v[96:99], v[178:181], v[196:199], v[96:99]
	v_mfma_f32_16x16x32_bf16 v[84:87], v[170:173], v[204:207], v[84:87]
	v_mfma_f32_16x16x32_bf16 v[80:83], v[178:181], v[204:207], v[80:83]
	v_mfma_f32_16x16x32_bf16 v[68:71], v[170:173], v[212:215], v[68:71]
	v_mfma_f32_16x16x32_bf16 v[64:67], v[178:181], v[212:215], v[64:67]
	s_setprio 0
	s_barrier
	s_add_i32 s37, s73, s57
	v_lshl_add_u64 v[216:217], s[48:49], 0, v[130:131]
	s_mov_b32 m0, s37
	ds_read_b128 v[182:185], v161 offset:16384
	ds_read_b128 v[186:189], v161 offset:17408
	ds_read_b128 v[190:193], v161 offset:18432
	ds_read_b128 v[196:199], v161 offset:19456
	ds_read_b128 v[200:203], v161 offset:20480
	ds_read_b128 v[204:207], v161 offset:21504
	ds_read_b128 v[208:211], v161 offset:22528
	ds_read_b128 v[212:215], v161 offset:23552
	global_load_lds_dwordx4 v[216:217], off
	s_add_i32 m0, s37, 0x2000
	s_add_u32 s80, s48, 0x20000
	v_lshl_add_u64 v[218:219], s[48:49], 0, v[134:135]
	s_addc_u32 s81, s49, 0
	s_add_i32 s37, s77, s57
	global_load_lds_dwordx4 v[218:219], off
	v_lshl_add_u64 v[220:221], s[80:81], 0, v[130:131]
	s_mov_b32 m0, s37
	v_lshl_add_u64 v[222:223], s[50:51], 0, v[132:133]
	global_load_lds_dwordx4 v[220:221], off
	v_lshl_add_u64 v[220:221], s[80:81], 0, v[134:135]
	s_add_i32 m0, s37, 0x2000
	s_nop 0
	global_load_lds_dwordx4 v[220:221], off
	v_lshl_add_u64 v[220:221], s[50:51], 0, v[128:129]
	s_mov_b32 m0, s60
	s_nop 0
	global_load_lds_dwordx4 v[220:221], off
	s_waitcnt vmcnt(7)
	s_waitcnt lgkmcnt(0)
	s_barrier
	s_setprio 1
	s_waitcnt lgkmcnt(0)
	v_mfma_f32_16x16x32_bf16 v[60:63], v[144:147], v[182:185], v[60:63]
	v_mfma_f32_16x16x32_bf16 v[56:59], v[152:155], v[182:185], v[56:59]
	v_mfma_f32_16x16x32_bf16 v[44:47], v[144:147], v[190:193], v[44:47]
	v_mfma_f32_16x16x32_bf16 v[40:43], v[152:155], v[190:193], v[40:43]
	v_mfma_f32_16x16x32_bf16 v[28:31], v[144:147], v[200:203], v[28:31]
	v_mfma_f32_16x16x32_bf16 v[24:27], v[152:155], v[200:203], v[24:27]
	v_mfma_f32_16x16x32_bf16 v[12:15], v[144:147], v[208:211], v[12:15]
	v_mfma_f32_16x16x32_bf16 v[8:11], v[152:155], v[208:211], v[8:11]
	v_mfma_f32_16x16x32_bf16 v[60:63], v[148:151], v[186:189], v[60:63]
	v_mfma_f32_16x16x32_bf16 v[56:59], v[162:165], v[186:189], v[56:59]
	v_mfma_f32_16x16x32_bf16 v[44:47], v[148:151], v[196:199], v[44:47]
	v_mfma_f32_16x16x32_bf16 v[40:43], v[162:165], v[196:199], v[40:43]
	v_mfma_f32_16x16x32_bf16 v[28:31], v[148:151], v[204:207], v[28:31]
	v_mfma_f32_16x16x32_bf16 v[24:27], v[162:165], v[204:207], v[24:27]
	v_mfma_f32_16x16x32_bf16 v[12:15], v[148:151], v[212:215], v[12:15]
	v_mfma_f32_16x16x32_bf16 v[8:11], v[162:165], v[212:215], v[8:11]
	s_setprio 0
	s_setprio 1
	v_mfma_f32_16x16x32_bf16 v[52:55], v[166:169], v[182:185], v[52:55]
	v_mfma_f32_16x16x32_bf16 v[48:51], v[174:177], v[182:185], v[48:51]
	v_mfma_f32_16x16x32_bf16 v[36:39], v[166:169], v[190:193], v[36:39]
	v_mfma_f32_16x16x32_bf16 v[32:35], v[174:177], v[190:193], v[32:35]
	v_mfma_f32_16x16x32_bf16 v[20:23], v[166:169], v[200:203], v[20:23]
	v_mfma_f32_16x16x32_bf16 v[16:19], v[174:177], v[200:203], v[16:19]
	v_mfma_f32_16x16x32_bf16 v[4:7], v[166:169], v[208:211], v[4:7]
	v_mfma_f32_16x16x32_bf16 v[0:3], v[174:177], v[208:211], v[0:3]
	v_mfma_f32_16x16x32_bf16 v[52:55], v[170:173], v[186:189], v[52:55]
	v_mfma_f32_16x16x32_bf16 v[48:51], v[178:181], v[186:189], v[48:51]
	v_mfma_f32_16x16x32_bf16 v[36:39], v[170:173], v[196:199], v[36:39]
	v_mfma_f32_16x16x32_bf16 v[32:35], v[178:181], v[196:199], v[32:35]
	v_mfma_f32_16x16x32_bf16 v[20:23], v[170:173], v[204:207], v[20:23]
	v_mfma_f32_16x16x32_bf16 v[16:19], v[178:181], v[204:207], v[16:19]
	v_mfma_f32_16x16x32_bf16 v[4:7], v[170:173], v[212:215], v[4:7]
	v_mfma_f32_16x16x32_bf16 v[0:3], v[178:181], v[212:215], v[0:3]
	s_setprio 0
	s_barrier
	s_add_i32 s37, 0, 0x18000
	s_add_i32 s39, 0, 0x1c000
	v_add_u32_e32 v162, s37, v157
	v_add_u32_e32 v178, s39, v157
	ds_read_b128 v[144:147], v162
	ds_read_b128 v[148:151], v162 offset:1024
	ds_read_b128 v[152:155], v162 offset:2048
	ds_read_b128 v[162:165], v162 offset:3072
	ds_read_b128 v[166:169], v178
	ds_read_b128 v[170:173], v178 offset:1024
	ds_read_b128 v[174:177], v178 offset:2048
	ds_read_b128 v[178:181], v178 offset:3072
	s_add_u32 s50, s50, 0x20000
	s_addc_u32 s51, s51, 0
	v_lshl_add_u64 v[224:225], s[50:51], 0, v[128:129]
	ds_read_b128 v[182:185], v161 offset:32768
	ds_read_b128 v[186:189], v161 offset:33792
	ds_read_b128 v[190:193], v161 offset:34816
	ds_read_b128 v[196:199], v161 offset:35840
	ds_read_b128 v[200:203], v161 offset:36864
	ds_read_b128 v[204:207], v161 offset:37888
	ds_read_b128 v[208:211], v161 offset:38912
	ds_read_b128 v[212:215], v161 offset:39936
	s_mov_b32 m0, s61
	s_nop 0
	global_load_lds_dwordx4 v[222:223], off
	s_mov_b32 m0, s62
	s_nop 0
	global_load_lds_dwordx4 v[224:225], off
	v_lshl_add_u64 v[224:225], s[50:51], 0, v[132:133]
	s_mov_b32 m0, s63
	s_nop 0
	global_load_lds_dwordx4 v[224:225], off
	s_waitcnt vmcnt(8)
	s_waitcnt lgkmcnt(0)
	s_barrier
	s_setprio 1
	s_waitcnt lgkmcnt(0)
	v_mfma_f32_16x16x32_bf16 v[124:127], v[144:147], v[182:185], v[124:127]
	v_mfma_f32_16x16x32_bf16 v[120:123], v[152:155], v[182:185], v[120:123]
	v_mfma_f32_16x16x32_bf16 v[108:111], v[144:147], v[190:193], v[108:111]
	v_mfma_f32_16x16x32_bf16 v[104:107], v[152:155], v[190:193], v[104:107]
	v_mfma_f32_16x16x32_bf16 v[92:95], v[144:147], v[200:203], v[92:95]
	v_mfma_f32_16x16x32_bf16 v[88:91], v[152:155], v[200:203], v[88:91]
	v_mfma_f32_16x16x32_bf16 v[76:79], v[144:147], v[208:211], v[76:79]
	v_mfma_f32_16x16x32_bf16 v[72:75], v[152:155], v[208:211], v[72:75]
	v_mfma_f32_16x16x32_bf16 v[124:127], v[148:151], v[186:189], v[124:127]
	v_mfma_f32_16x16x32_bf16 v[120:123], v[162:165], v[186:189], v[120:123]
	v_mfma_f32_16x16x32_bf16 v[108:111], v[148:151], v[196:199], v[108:111]
	v_mfma_f32_16x16x32_bf16 v[104:107], v[162:165], v[196:199], v[104:107]
	v_mfma_f32_16x16x32_bf16 v[92:95], v[148:151], v[204:207], v[92:95]
	v_mfma_f32_16x16x32_bf16 v[88:91], v[162:165], v[204:207], v[88:91]
	v_mfma_f32_16x16x32_bf16 v[76:79], v[148:151], v[212:215], v[76:79]
	v_mfma_f32_16x16x32_bf16 v[72:75], v[162:165], v[212:215], v[72:75]
	s_setprio 0
	s_setprio 1
	v_mfma_f32_16x16x32_bf16 v[116:119], v[166:169], v[182:185], v[116:119]
	v_mfma_f32_16x16x32_bf16 v[112:115], v[174:177], v[182:185], v[112:115]
	v_mfma_f32_16x16x32_bf16 v[100:103], v[166:169], v[190:193], v[100:103]
	v_mfma_f32_16x16x32_bf16 v[96:99], v[174:177], v[190:193], v[96:99]
	v_mfma_f32_16x16x32_bf16 v[84:87], v[166:169], v[200:203], v[84:87]
	v_mfma_f32_16x16x32_bf16 v[80:83], v[174:177], v[200:203], v[80:83]
	v_mfma_f32_16x16x32_bf16 v[68:71], v[166:169], v[208:211], v[68:71]
	v_mfma_f32_16x16x32_bf16 v[64:67], v[174:177], v[208:211], v[64:67]
	v_mfma_f32_16x16x32_bf16 v[116:119], v[170:173], v[186:189], v[116:119]
	v_mfma_f32_16x16x32_bf16 v[112:115], v[178:181], v[186:189], v[112:115]
	v_mfma_f32_16x16x32_bf16 v[100:103], v[170:173], v[196:199], v[100:103]
	v_mfma_f32_16x16x32_bf16 v[96:99], v[178:181], v[196:199], v[96:99]
	v_mfma_f32_16x16x32_bf16 v[84:87], v[170:173], v[204:207], v[84:87]
	v_mfma_f32_16x16x32_bf16 v[80:83], v[178:181], v[204:207], v[80:83]
	v_mfma_f32_16x16x32_bf16 v[68:71], v[170:173], v[212:215], v[68:71]
	v_mfma_f32_16x16x32_bf16 v[64:67], v[178:181], v[212:215], v[64:67]
	s_setprio 0
	s_barrier
	s_add_i32 s37, s37, s57
	v_lshl_add_u64 v[216:217], v[216:217], 0, s[22:23]
	s_mov_b32 m0, s37
	ds_read_b128 v[182:185], v161 offset:49152
	ds_read_b128 v[186:189], v161 offset:50176
	ds_read_b128 v[190:193], v161 offset:51200
	ds_read_b128 v[196:199], v161 offset:52224
	ds_read_b128 v[200:203], v161 offset:53248
	ds_read_b128 v[204:207], v161 offset:54272
	ds_read_b128 v[208:211], v161 offset:55296
	ds_read_b128 v[212:215], v161 offset:56320
	global_load_lds_dwordx4 v[216:217], off
	s_add_i32 m0, s37, 0x2000
	s_add_u32 s48, s48, 0x20080
	v_lshl_add_u64 v[216:217], v[218:219], 0, s[22:23]
	s_addc_u32 s49, s49, 0
	s_add_i32 s37, s39, s57
	global_load_lds_dwordx4 v[216:217], off
	v_lshl_add_u64 v[216:217], s[48:49], 0, v[130:131]
	s_mov_b32 m0, s37
	s_nop 0
	global_load_lds_dwordx4 v[216:217], off
	v_lshl_add_u64 v[216:217], s[48:49], 0, v[134:135]
	s_add_i32 m0, s37, 0x2000
	s_nop 0
	global_load_lds_dwordx4 v[216:217], off
	v_lshl_add_u64 v[216:217], v[220:221], 0, s[22:23]
	s_mov_b32 m0, s70
	s_nop 0
	global_load_lds_dwordx4 v[216:217], off
	s_waitcnt vmcnt(7)
	s_waitcnt lgkmcnt(0)
	s_barrier
	s_setprio 1
	s_waitcnt lgkmcnt(0)
	v_mfma_f32_16x16x32_bf16 v[60:63], v[144:147], v[182:185], v[60:63]
	v_mfma_f32_16x16x32_bf16 v[56:59], v[152:155], v[182:185], v[56:59]
	v_mfma_f32_16x16x32_bf16 v[44:47], v[144:147], v[190:193], v[44:47]
	v_mfma_f32_16x16x32_bf16 v[40:43], v[152:155], v[190:193], v[40:43]
	v_mfma_f32_16x16x32_bf16 v[28:31], v[144:147], v[200:203], v[28:31]
	v_mfma_f32_16x16x32_bf16 v[24:27], v[152:155], v[200:203], v[24:27]
	v_mfma_f32_16x16x32_bf16 v[12:15], v[144:147], v[208:211], v[12:15]
	v_mfma_f32_16x16x32_bf16 v[8:11], v[152:155], v[208:211], v[8:11]
	v_mfma_f32_16x16x32_bf16 v[60:63], v[148:151], v[186:189], v[60:63]
	v_mfma_f32_16x16x32_bf16 v[56:59], v[162:165], v[186:189], v[56:59]
	v_mfma_f32_16x16x32_bf16 v[44:47], v[148:151], v[196:199], v[44:47]
	v_mfma_f32_16x16x32_bf16 v[40:43], v[162:165], v[196:199], v[40:43]
	v_mfma_f32_16x16x32_bf16 v[28:31], v[148:151], v[204:207], v[28:31]
	v_mfma_f32_16x16x32_bf16 v[24:27], v[162:165], v[204:207], v[24:27]
	v_mfma_f32_16x16x32_bf16 v[12:15], v[148:151], v[212:215], v[12:15]
	v_mfma_f32_16x16x32_bf16 v[8:11], v[162:165], v[212:215], v[8:11]
	s_setprio 0
	s_setprio 1
	v_mfma_f32_16x16x32_bf16 v[52:55], v[166:169], v[182:185], v[52:55]
	v_mfma_f32_16x16x32_bf16 v[48:51], v[174:177], v[182:185], v[48:51]
	v_mfma_f32_16x16x32_bf16 v[36:39], v[166:169], v[190:193], v[36:39]
	v_mfma_f32_16x16x32_bf16 v[32:35], v[174:177], v[190:193], v[32:35]
	v_mfma_f32_16x16x32_bf16 v[20:23], v[166:169], v[200:203], v[20:23]
	v_mfma_f32_16x16x32_bf16 v[16:19], v[174:177], v[200:203], v[16:19]
	v_mfma_f32_16x16x32_bf16 v[4:7], v[166:169], v[208:211], v[4:7]
	v_mfma_f32_16x16x32_bf16 v[0:3], v[174:177], v[208:211], v[0:3]
	v_mfma_f32_16x16x32_bf16 v[52:55], v[170:173], v[186:189], v[52:55]
	v_mfma_f32_16x16x32_bf16 v[48:51], v[178:181], v[186:189], v[48:51]
	v_mfma_f32_16x16x32_bf16 v[36:39], v[170:173], v[196:199], v[36:39]
	v_mfma_f32_16x16x32_bf16 v[32:35], v[178:181], v[196:199], v[32:35]
	v_mfma_f32_16x16x32_bf16 v[20:23], v[170:173], v[204:207], v[20:23]
	v_mfma_f32_16x16x32_bf16 v[16:19], v[178:181], v[204:207], v[16:19]
	v_mfma_f32_16x16x32_bf16 v[4:7], v[170:173], v[212:215], v[4:7]
	v_mfma_f32_16x16x32_bf16 v[0:3], v[178:181], v[212:215], v[0:3]
	s_setprio 0
	s_barrier
	v_lshl_add_u64 v[222:223], v[222:223], 0, s[22:23]
	s_mov_b32 m0, s71
	s_nop 0
	global_load_lds_dwordx4 v[222:223], off
	s_add_i32 s35, s35, 2
	s_add_u32 s42, s42, 0x100
	s_addc_u32 s43, s43, 0
	s_add_u32 s11, s11, 0x100
	s_addc_u32 s13, s13, 0
	s_cmp_gt_u32 s35, 5
	s_cbranch_scc0 .LBB0_3061
	s_and_b64 vcc, exec, s[24:25]
	s_cbranch_vccz .LBB0_3064
	s_barrier

.LBB0_3235:
	ds_read_b128 v[144:147], v151
	ds_read_b128 v[156:159], v151 offset:1024
	ds_read_b128 v[160:163], v151 offset:2048
	ds_read_b128 v[164:167], v151 offset:3072
	ds_read_b128 v[168:171], v152
	ds_read_b128 v[172:175], v152 offset:1024
	ds_read_b128 v[176:179], v152 offset:2048
	ds_read_b128 v[180:183], v152 offset:3072
	s_add_u32 s38, s36, 0xfffc0080
	s_addc_u32 s39, s37, -1
	s_cmp_eq_u32 s70, 12
	s_cselect_b32 s41, s27, s39
	s_cselect_b32 s40, s35, s38
	s_cselect_b32 s39, s25, s63
	s_cselect_b32 s38, s61, s62
	v_lshl_add_u64 v[192:193], s[36:37], 0, v[136:137]
	s_add_i32 m0, s50, 0xc000
	ds_read_b128 v[184:187], v153
	ds_read_b128 v[188:191], v153 offset:1024
	ds_read_b128 v[196:199], v153 offset:2048
	ds_read_b128 v[200:203], v153 offset:3072
	ds_read_b128 v[204:207], v153 offset:4096
	ds_read_b128 v[208:211], v153 offset:5120
	ds_read_b128 v[212:215], v153 offset:6144
	ds_read_b128 v[216:219], v153 offset:7168
	global_load_lds_dwordx4 v[192:193], off
	v_lshl_add_u64 v[192:193], s[36:37], 0, v[138:139]
	s_add_i32 m0, s50, 0xe000
	s_nop 0
	global_load_lds_dwordx4 v[192:193], off
	s_waitcnt vmcnt(8)
	s_waitcnt lgkmcnt(0)
	s_barrier
	s_setprio 1
	s_waitcnt lgkmcnt(0)
	v_mfma_f32_16x16x32_bf16 v[124:127], v[144:147], v[184:187], v[124:127]
	v_mfma_f32_16x16x32_bf16 v[120:123], v[160:163], v[184:187], v[120:123]
	v_mfma_f32_16x16x32_bf16 v[108:111], v[144:147], v[196:199], v[108:111]
	v_mfma_f32_16x16x32_bf16 v[104:107], v[160:163], v[196:199], v[104:107]
	v_mfma_f32_16x16x32_bf16 v[92:95], v[144:147], v[204:207], v[92:95]
	v_mfma_f32_16x16x32_bf16 v[88:91], v[160:163], v[204:207], v[88:91]
	v_mfma_f32_16x16x32_bf16 v[76:79], v[144:147], v[212:215], v[76:79]
	v_mfma_f32_16x16x32_bf16 v[72:75], v[160:163], v[212:215], v[72:75]
	v_mfma_f32_16x16x32_bf16 v[124:127], v[156:159], v[188:191], v[124:127]
	v_mfma_f32_16x16x32_bf16 v[120:123], v[164:167], v[188:191], v[120:123]
	v_mfma_f32_16x16x32_bf16 v[108:111], v[156:159], v[200:203], v[108:111]
	v_mfma_f32_16x16x32_bf16 v[104:107], v[164:167], v[200:203], v[104:107]
	v_mfma_f32_16x16x32_bf16 v[92:95], v[156:159], v[208:211], v[92:95]
	v_mfma_f32_16x16x32_bf16 v[88:91], v[164:167], v[208:211], v[88:91]
	v_mfma_f32_16x16x32_bf16 v[76:79], v[156:159], v[216:219], v[76:79]
	v_mfma_f32_16x16x32_bf16 v[72:75], v[164:167], v[216:219], v[72:75]
	s_setprio 0
	s_setprio 1
	v_mfma_f32_16x16x32_bf16 v[116:119], v[168:171], v[184:187], v[116:119]
	v_mfma_f32_16x16x32_bf16 v[112:115], v[176:179], v[184:187], v[112:115]
	v_mfma_f32_16x16x32_bf16 v[100:103], v[168:171], v[196:199], v[100:103]
	v_mfma_f32_16x16x32_bf16 v[96:99], v[176:179], v[196:199], v[96:99]
	v_mfma_f32_16x16x32_bf16 v[84:87], v[168:171], v[204:207], v[84:87]
	v_mfma_f32_16x16x32_bf16 v[80:83], v[176:179], v[204:207], v[80:83]
	v_mfma_f32_16x16x32_bf16 v[68:71], v[168:171], v[212:215], v[68:71]
	v_mfma_f32_16x16x32_bf16 v[64:67], v[176:179], v[212:215], v[64:67]
	v_mfma_f32_16x16x32_bf16 v[116:119], v[172:175], v[188:191], v[116:119]
	v_mfma_f32_16x16x32_bf16 v[112:115], v[180:183], v[188:191], v[112:115]
	v_mfma_f32_16x16x32_bf16 v[100:103], v[172:175], v[200:203], v[100:103]
	v_mfma_f32_16x16x32_bf16 v[96:99], v[180:183], v[200:203], v[96:99]
	v_mfma_f32_16x16x32_bf16 v[84:87], v[172:175], v[208:211], v[84:87]
	v_mfma_f32_16x16x32_bf16 v[80:83], v[180:183], v[208:211], v[80:83]
	v_mfma_f32_16x16x32_bf16 v[68:71], v[172:175], v[216:219], v[68:71]
	v_mfma_f32_16x16x32_bf16 v[64:67], v[180:183], v[216:219], v[64:67]
	s_setprio 0
	s_barrier
	s_add_i32 s71, s58, s49
	v_lshl_add_u64 v[192:193], s[38:39], 0, v[130:131]
	s_mov_b32 m0, s71
	ds_read_b128 v[184:187], v153 offset:16384
	ds_read_b128 v[188:191], v153 offset:17408
	ds_read_b128 v[196:199], v153 offset:18432
	ds_read_b128 v[200:203], v153 offset:19456
	ds_read_b128 v[204:207], v153 offset:20480
	ds_read_b128 v[208:211], v153 offset:21504
	ds_read_b128 v[212:215], v153 offset:22528
	ds_read_b128 v[216:219], v153 offset:23552
	global_load_lds_dwordx4 v[192:193], off
	s_add_i32 m0, s71, 0x2000
	s_add_u32 s72, s38, 0x40000
	v_lshl_add_u64 v[220:221], s[38:39], 0, v[134:135]
	s_addc_u32 s73, s39, 0
	s_add_i32 s71, s59, s49
	global_load_lds_dwordx4 v[220:221], off
	v_lshl_add_u64 v[222:223], s[72:73], 0, v[130:131]
	s_mov_b32 m0, s71
	v_lshl_add_u64 v[224:225], s[40:41], 0, v[132:133]
	global_load_lds_dwordx4 v[222:223], off
	v_lshl_add_u64 v[222:223], s[72:73], 0, v[134:135]
	s_add_i32 m0, s71, 0x2000
	s_nop 0
	global_load_lds_dwordx4 v[222:223], off
	v_lshl_add_u64 v[222:223], s[40:41], 0, v[128:129]
	s_mov_b32 m0, s50
	s_nop 0
	global_load_lds_dwordx4 v[222:223], off
	s_waitcnt vmcnt(7)
	s_waitcnt lgkmcnt(0)
	s_barrier
	s_setprio 1
	s_waitcnt lgkmcnt(0)
	v_mfma_f32_16x16x32_bf16 v[60:63], v[144:147], v[184:187], v[60:63]
	v_mfma_f32_16x16x32_bf16 v[56:59], v[160:163], v[184:187], v[56:59]
	v_mfma_f32_16x16x32_bf16 v[44:47], v[144:147], v[196:199], v[44:47]
	v_mfma_f32_16x16x32_bf16 v[40:43], v[160:163], v[196:199], v[40:43]
	v_mfma_f32_16x16x32_bf16 v[28:31], v[144:147], v[204:207], v[28:31]
	v_mfma_f32_16x16x32_bf16 v[24:27], v[160:163], v[204:207], v[24:27]
	v_mfma_f32_16x16x32_bf16 v[12:15], v[144:147], v[212:215], v[12:15]
	v_mfma_f32_16x16x32_bf16 v[8:11], v[160:163], v[212:215], v[8:11]
	v_mfma_f32_16x16x32_bf16 v[60:63], v[156:159], v[188:191], v[60:63]
	v_mfma_f32_16x16x32_bf16 v[56:59], v[164:167], v[188:191], v[56:59]
	v_mfma_f32_16x16x32_bf16 v[44:47], v[156:159], v[200:203], v[44:47]
	v_mfma_f32_16x16x32_bf16 v[40:43], v[164:167], v[200:203], v[40:43]
	v_mfma_f32_16x16x32_bf16 v[28:31], v[156:159], v[208:211], v[28:31]
	v_mfma_f32_16x16x32_bf16 v[24:27], v[164:167], v[208:211], v[24:27]
	v_mfma_f32_16x16x32_bf16 v[12:15], v[156:159], v[216:219], v[12:15]
	v_mfma_f32_16x16x32_bf16 v[8:11], v[164:167], v[216:219], v[8:11]
	s_setprio 0
	s_setprio 1
	v_mfma_f32_16x16x32_bf16 v[52:55], v[168:171], v[184:187], v[52:55]
	v_mfma_f32_16x16x32_bf16 v[48:51], v[176:179], v[184:187], v[48:51]
	v_mfma_f32_16x16x32_bf16 v[36:39], v[168:171], v[196:199], v[36:39]
	v_mfma_f32_16x16x32_bf16 v[32:35], v[176:179], v[196:199], v[32:35]
	v_mfma_f32_16x16x32_bf16 v[20:23], v[168:171], v[204:207], v[20:23]
	v_mfma_f32_16x16x32_bf16 v[16:19], v[176:179], v[204:207], v[16:19]
	v_mfma_f32_16x16x32_bf16 v[4:7], v[168:171], v[212:215], v[4:7]
	v_mfma_f32_16x16x32_bf16 v[0:3], v[176:179], v[212:215], v[0:3]
	v_mfma_f32_16x16x32_bf16 v[52:55], v[172:175], v[188:191], v[52:55]
	v_mfma_f32_16x16x32_bf16 v[48:51], v[180:183], v[188:191], v[48:51]
	v_mfma_f32_16x16x32_bf16 v[36:39], v[172:175], v[200:203], v[36:39]
	v_mfma_f32_16x16x32_bf16 v[32:35], v[180:183], v[200:203], v[32:35]
	v_mfma_f32_16x16x32_bf16 v[20:23], v[172:175], v[208:211], v[20:23]
	v_mfma_f32_16x16x32_bf16 v[16:19], v[180:183], v[208:211], v[16:19]
	v_mfma_f32_16x16x32_bf16 v[4:7], v[172:175], v[216:219], v[4:7]
	v_mfma_f32_16x16x32_bf16 v[0:3], v[180:183], v[216:219], v[0:3]
	s_setprio 0
	s_barrier
	s_add_i32 s71, 0, 0x18000
	v_add_u32_e32 v155, s71, v149
	s_add_i32 s72, 0, 0x1c000
	ds_read_b128 v[144:147], v155
	ds_read_b128 v[156:159], v155 offset:1024
	ds_read_b128 v[160:163], v155 offset:2048
	ds_read_b128 v[164:167], v155 offset:3072
	v_add_u32_e32 v155, s72, v149
	ds_read_b128 v[168:171], v155
	ds_read_b128 v[172:175], v155 offset:1024
	ds_read_b128 v[176:179], v155 offset:2048
	ds_read_b128 v[180:183], v155 offset:3072
	s_add_u32 s40, s40, 0x40000
	s_addc_u32 s41, s41, 0
	v_lshl_add_u64 v[226:227], s[40:41], 0, v[128:129]
	ds_read_b128 v[184:187], v153 offset:32768
	ds_read_b128 v[188:191], v153 offset:33792
	ds_read_b128 v[196:199], v153 offset:34816
	ds_read_b128 v[200:203], v153 offset:35840
	ds_read_b128 v[204:207], v153 offset:36864
	ds_read_b128 v[208:211], v153 offset:37888
	ds_read_b128 v[212:215], v153 offset:38912
	ds_read_b128 v[216:219], v153 offset:39936
	s_mov_b32 m0, s51
	s_nop 0
	global_load_lds_dwordx4 v[224:225], off
	s_mov_b32 m0, s52
	s_nop 0
	global_load_lds_dwordx4 v[226:227], off
	v_lshl_add_u64 v[226:227], s[40:41], 0, v[132:133]
	s_mov_b32 m0, s53
	s_nop 0
	global_load_lds_dwordx4 v[226:227], off
	s_waitcnt vmcnt(8)
	s_waitcnt lgkmcnt(0)
	s_barrier
	s_setprio 1
	s_waitcnt lgkmcnt(0)
	v_mfma_f32_16x16x32_bf16 v[124:127], v[144:147], v[184:187], v[124:127]
	v_mfma_f32_16x16x32_bf16 v[120:123], v[160:163], v[184:187], v[120:123]
	v_mfma_f32_16x16x32_bf16 v[108:111], v[144:147], v[196:199], v[108:111]
	v_mfma_f32_16x16x32_bf16 v[104:107], v[160:163], v[196:199], v[104:107]
	v_mfma_f32_16x16x32_bf16 v[92:95], v[144:147], v[204:207], v[92:95]
	v_mfma_f32_16x16x32_bf16 v[88:91], v[160:163], v[204:207], v[88:91]
	v_mfma_f32_16x16x32_bf16 v[76:79], v[144:147], v[212:215], v[76:79]
	v_mfma_f32_16x16x32_bf16 v[72:75], v[160:163], v[212:215], v[72:75]
	v_mfma_f32_16x16x32_bf16 v[124:127], v[156:159], v[188:191], v[124:127]
	v_mfma_f32_16x16x32_bf16 v[120:123], v[164:167], v[188:191], v[120:123]
	v_mfma_f32_16x16x32_bf16 v[108:111], v[156:159], v[200:203], v[108:111]
	v_mfma_f32_16x16x32_bf16 v[104:107], v[164:167], v[200:203], v[104:107]
	v_mfma_f32_16x16x32_bf16 v[92:95], v[156:159], v[208:211], v[92:95]
	v_mfma_f32_16x16x32_bf16 v[88:91], v[164:167], v[208:211], v[88:91]
	v_mfma_f32_16x16x32_bf16 v[76:79], v[156:159], v[216:219], v[76:79]
	v_mfma_f32_16x16x32_bf16 v[72:75], v[164:167], v[216:219], v[72:75]
	s_setprio 0
	s_setprio 1
	v_mfma_f32_16x16x32_bf16 v[116:119], v[168:171], v[184:187], v[116:119]
	v_mfma_f32_16x16x32_bf16 v[112:115], v[176:179], v[184:187], v[112:115]
	v_mfma_f32_16x16x32_bf16 v[100:103], v[168:171], v[196:199], v[100:103]
	v_mfma_f32_16x16x32_bf16 v[96:99], v[176:179], v[196:199], v[96:99]
	v_mfma_f32_16x16x32_bf16 v[84:87], v[168:171], v[204:207], v[84:87]
	v_mfma_f32_16x16x32_bf16 v[80:83], v[176:179], v[204:207], v[80:83]
	v_mfma_f32_16x16x32_bf16 v[68:71], v[168:171], v[212:215], v[68:71]
	v_mfma_f32_16x16x32_bf16 v[64:67], v[176:179], v[212:215], v[64:67]
	v_mfma_f32_16x16x32_bf16 v[116:119], v[172:175], v[188:191], v[116:119]
	v_mfma_f32_16x16x32_bf16 v[112:115], v[180:183], v[188:191], v[112:115]
	v_mfma_f32_16x16x32_bf16 v[100:103], v[172:175], v[200:203], v[100:103]
	v_mfma_f32_16x16x32_bf16 v[96:99], v[180:183], v[200:203], v[96:99]
	v_mfma_f32_16x16x32_bf16 v[84:87], v[172:175], v[208:211], v[84:87]
	v_mfma_f32_16x16x32_bf16 v[80:83], v[180:183], v[208:211], v[80:83]
	v_mfma_f32_16x16x32_bf16 v[68:71], v[172:175], v[216:219], v[68:71]
	v_mfma_f32_16x16x32_bf16 v[64:67], v[180:183], v[216:219], v[64:67]
	s_setprio 0
	s_barrier
	s_add_i32 s40, s71, s49
	v_lshl_add_u64 v[192:193], v[192:193], 0, s[20:21]
	s_mov_b32 m0, s40
	ds_read_b128 v[184:187], v153 offset:49152
	ds_read_b128 v[188:191], v153 offset:50176
	ds_read_b128 v[196:199], v153 offset:51200
	ds_read_b128 v[200:203], v153 offset:52224
	ds_read_b128 v[204:207], v153 offset:53248
	ds_read_b128 v[208:211], v153 offset:54272
	ds_read_b128 v[212:215], v153 offset:55296
	ds_read_b128 v[216:219], v153 offset:56320
	global_load_lds_dwordx4 v[192:193], off
	s_add_i32 m0, s40, 0x2000
	s_add_u32 s38, s38, 0x40080
	v_lshl_add_u64 v[192:193], v[220:221], 0, s[20:21]
	s_addc_u32 s39, s39, 0
	s_add_i32 s40, s72, s49
	global_load_lds_dwordx4 v[192:193], off
	v_lshl_add_u64 v[192:193], s[38:39], 0, v[130:131]
	s_mov_b32 m0, s40
	s_nop 0
	global_load_lds_dwordx4 v[192:193], off
	v_lshl_add_u64 v[192:193], s[38:39], 0, v[134:135]
	s_add_i32 m0, s40, 0x2000
	s_nop 0
	global_load_lds_dwordx4 v[192:193], off
	v_lshl_add_u64 v[192:193], v[222:223], 0, s[20:21]
	s_mov_b32 m0, s55
	s_nop 0
	global_load_lds_dwordx4 v[192:193], off
	s_waitcnt vmcnt(7)
	s_waitcnt lgkmcnt(0)
	s_barrier
	s_setprio 1
	s_waitcnt lgkmcnt(0)
	v_mfma_f32_16x16x32_bf16 v[60:63], v[144:147], v[184:187], v[60:63]
	v_mfma_f32_16x16x32_bf16 v[56:59], v[160:163], v[184:187], v[56:59]
	v_mfma_f32_16x16x32_bf16 v[44:47], v[144:147], v[196:199], v[44:47]
	v_mfma_f32_16x16x32_bf16 v[40:43], v[160:163], v[196:199], v[40:43]
	v_mfma_f32_16x16x32_bf16 v[28:31], v[144:147], v[204:207], v[28:31]
	v_mfma_f32_16x16x32_bf16 v[24:27], v[160:163], v[204:207], v[24:27]
	v_mfma_f32_16x16x32_bf16 v[12:15], v[144:147], v[212:215], v[12:15]
	v_mfma_f32_16x16x32_bf16 v[8:11], v[160:163], v[212:215], v[8:11]
	v_mfma_f32_16x16x32_bf16 v[60:63], v[156:159], v[188:191], v[60:63]
	v_mfma_f32_16x16x32_bf16 v[56:59], v[164:167], v[188:191], v[56:59]
	v_mfma_f32_16x16x32_bf16 v[44:47], v[156:159], v[200:203], v[44:47]
	v_mfma_f32_16x16x32_bf16 v[40:43], v[164:167], v[200:203], v[40:43]
	v_mfma_f32_16x16x32_bf16 v[28:31], v[156:159], v[208:211], v[28:31]
	v_mfma_f32_16x16x32_bf16 v[24:27], v[164:167], v[208:211], v[24:27]
	v_mfma_f32_16x16x32_bf16 v[12:15], v[156:159], v[216:219], v[12:15]
	v_mfma_f32_16x16x32_bf16 v[8:11], v[164:167], v[216:219], v[8:11]
	s_setprio 0
	s_setprio 1
	v_mfma_f32_16x16x32_bf16 v[52:55], v[168:171], v[184:187], v[52:55]
	v_mfma_f32_16x16x32_bf16 v[48:51], v[176:179], v[184:187], v[48:51]
	v_mfma_f32_16x16x32_bf16 v[36:39], v[168:171], v[196:199], v[36:39]
	v_mfma_f32_16x16x32_bf16 v[32:35], v[176:179], v[196:199], v[32:35]
	v_mfma_f32_16x16x32_bf16 v[20:23], v[168:171], v[204:207], v[20:23]
	v_mfma_f32_16x16x32_bf16 v[16:19], v[176:179], v[204:207], v[16:19]
	v_mfma_f32_16x16x32_bf16 v[4:7], v[168:171], v[212:215], v[4:7]
	v_mfma_f32_16x16x32_bf16 v[0:3], v[176:179], v[212:215], v[0:3]
	v_mfma_f32_16x16x32_bf16 v[52:55], v[172:175], v[188:191], v[52:55]
	v_mfma_f32_16x16x32_bf16 v[48:51], v[180:183], v[188:191], v[48:51]
	v_mfma_f32_16x16x32_bf16 v[36:39], v[172:175], v[200:203], v[36:39]
	v_mfma_f32_16x16x32_bf16 v[32:35], v[180:183], v[200:203], v[32:35]
	v_mfma_f32_16x16x32_bf16 v[20:23], v[172:175], v[208:211], v[20:23]
	v_mfma_f32_16x16x32_bf16 v[16:19], v[180:183], v[208:211], v[16:19]
	v_mfma_f32_16x16x32_bf16 v[4:7], v[172:175], v[216:219], v[4:7]
	v_mfma_f32_16x16x32_bf16 v[0:3], v[180:183], v[216:219], v[0:3]
	s_setprio 0
	s_barrier
	v_lshl_add_u64 v[224:225], v[224:225], 0, s[20:21]
	s_mov_b32 m0, s56
	s_nop 0
	global_load_lds_dwordx4 v[224:225], off
	s_add_i32 s70, s70, 2
	s_add_u32 s36, s36, 0x100
	s_addc_u32 s37, s37, 0
	s_add_u32 s62, s62, 0x100
	s_addc_u32 s63, s63, 0
	s_cmp_gt_u32 s70, 13
	s_cbranch_scc0 .LBB0_3235
	s_and_b64 vcc, exec, s[22:23]
	s_cbranch_vccz .LBB0_3238
	s_barrier

.LBB0_3319:
	ds_read_b128 v[154:157], v149
	ds_read_b128 v[158:161], v149 offset:1024
	ds_read_b128 v[162:165], v149 offset:2048
	ds_read_b128 v[166:169], v149 offset:3072
	ds_read_b128 v[170:173], v150
	ds_read_b128 v[174:177], v150 offset:1024
	ds_read_b128 v[178:181], v150 offset:2048
	ds_read_b128 v[182:185], v150 offset:3072
	s_add_u32 s28, s26, 0xfffc0080
	s_addc_u32 s29, s27, -1
	s_cmp_eq_u32 s59, 12
	s_cselect_b32 s31, s19, s29
	s_cselect_b32 s30, s55, s28
	s_cselect_b32 s29, s17, s58
	s_cselect_b32 s28, s56, s57
	v_lshl_add_u64 v[144:145], s[26:27], 0, v[136:137]
	s_add_i32 m0, s25, 0xc000
	ds_read_b128 v[186:189], v151
	ds_read_b128 v[190:193], v151 offset:1024
	ds_read_b128 v[196:199], v151 offset:2048
	ds_read_b128 v[200:203], v151 offset:3072
	ds_read_b128 v[204:207], v151 offset:4096
	ds_read_b128 v[208:211], v151 offset:5120
	ds_read_b128 v[212:215], v151 offset:6144
	ds_read_b128 v[216:219], v151 offset:7168
	global_load_lds_dwordx4 v[144:145], off
	v_lshl_add_u64 v[144:145], s[26:27], 0, v[138:139]
	s_add_i32 m0, s25, 0xe000
	s_nop 0
	global_load_lds_dwordx4 v[144:145], off
	s_waitcnt vmcnt(8)
	s_waitcnt lgkmcnt(0)
	s_barrier
	s_setprio 1
	s_waitcnt lgkmcnt(0)
	v_mfma_f32_16x16x32_bf16 v[116:119], v[154:157], v[186:189], v[116:119]
	v_mfma_f32_16x16x32_bf16 v[112:115], v[162:165], v[186:189], v[112:115]
	v_mfma_f32_16x16x32_bf16 v[100:103], v[154:157], v[196:199], v[100:103]
	v_mfma_f32_16x16x32_bf16 v[96:99], v[162:165], v[196:199], v[96:99]
	v_mfma_f32_16x16x32_bf16 v[84:87], v[154:157], v[204:207], v[84:87]
	v_mfma_f32_16x16x32_bf16 v[80:83], v[162:165], v[204:207], v[80:83]
	v_mfma_f32_16x16x32_bf16 v[68:71], v[154:157], v[212:215], v[68:71]
	v_mfma_f32_16x16x32_bf16 v[64:67], v[162:165], v[212:215], v[64:67]
	v_mfma_f32_16x16x32_bf16 v[116:119], v[158:161], v[190:193], v[116:119]
	v_mfma_f32_16x16x32_bf16 v[112:115], v[166:169], v[190:193], v[112:115]
	v_mfma_f32_16x16x32_bf16 v[100:103], v[158:161], v[200:203], v[100:103]
	v_mfma_f32_16x16x32_bf16 v[96:99], v[166:169], v[200:203], v[96:99]
	v_mfma_f32_16x16x32_bf16 v[84:87], v[158:161], v[208:211], v[84:87]
	v_mfma_f32_16x16x32_bf16 v[80:83], v[166:169], v[208:211], v[80:83]
	v_mfma_f32_16x16x32_bf16 v[68:71], v[158:161], v[216:219], v[68:71]
	v_mfma_f32_16x16x32_bf16 v[64:67], v[166:169], v[216:219], v[64:67]
	s_setprio 0
	s_setprio 1
	v_mfma_f32_16x16x32_bf16 v[124:127], v[170:173], v[186:189], v[124:127]
	v_mfma_f32_16x16x32_bf16 v[120:123], v[178:181], v[186:189], v[120:123]
	v_mfma_f32_16x16x32_bf16 v[108:111], v[170:173], v[196:199], v[108:111]
	v_mfma_f32_16x16x32_bf16 v[104:107], v[178:181], v[196:199], v[104:107]
	v_mfma_f32_16x16x32_bf16 v[92:95], v[170:173], v[204:207], v[92:95]
	v_mfma_f32_16x16x32_bf16 v[88:91], v[178:181], v[204:207], v[88:91]
	v_mfma_f32_16x16x32_bf16 v[76:79], v[170:173], v[212:215], v[76:79]
	v_mfma_f32_16x16x32_bf16 v[72:75], v[178:181], v[212:215], v[72:75]
	v_mfma_f32_16x16x32_bf16 v[124:127], v[174:177], v[190:193], v[124:127]
	v_mfma_f32_16x16x32_bf16 v[120:123], v[182:185], v[190:193], v[120:123]
	v_mfma_f32_16x16x32_bf16 v[108:111], v[174:177], v[200:203], v[108:111]
	v_mfma_f32_16x16x32_bf16 v[104:107], v[182:185], v[200:203], v[104:107]
	v_mfma_f32_16x16x32_bf16 v[92:95], v[174:177], v[208:211], v[92:95]
	v_mfma_f32_16x16x32_bf16 v[88:91], v[182:185], v[208:211], v[88:91]
	v_mfma_f32_16x16x32_bf16 v[76:79], v[174:177], v[216:219], v[76:79]
	v_mfma_f32_16x16x32_bf16 v[72:75], v[182:185], v[216:219], v[72:75]
	s_setprio 0
	s_barrier
	s_add_i32 s60, s50, s39
	v_lshl_add_u64 v[144:145], s[28:29], 0, v[132:133]
	s_mov_b32 m0, s60
	ds_read_b128 v[186:189], v151 offset:16384
	ds_read_b128 v[190:193], v151 offset:17408
	ds_read_b128 v[196:199], v151 offset:18432
	ds_read_b128 v[200:203], v151 offset:19456
	ds_read_b128 v[204:207], v151 offset:20480
	ds_read_b128 v[208:211], v151 offset:21504
	ds_read_b128 v[212:215], v151 offset:22528
	ds_read_b128 v[216:219], v151 offset:23552
	global_load_lds_dwordx4 v[144:145], off
	s_add_i32 m0, s60, 0x2000
	s_add_u32 s60, s28, 0x40000
	v_lshl_add_u64 v[220:221], s[28:29], 0, v[128:129]
	s_addc_u32 s61, s29, 0
	s_add_i32 s62, s51, s39
	global_load_lds_dwordx4 v[220:221], off
	v_lshl_add_u64 v[222:223], s[60:61], 0, v[132:133]
	s_mov_b32 m0, s62
	v_lshl_add_u64 v[224:225], s[30:31], 0, v[130:131]
	global_load_lds_dwordx4 v[222:223], off
	v_lshl_add_u64 v[222:223], s[60:61], 0, v[128:129]
	s_add_i32 m0, s62, 0x2000
	s_nop 0
	global_load_lds_dwordx4 v[222:223], off
	v_lshl_add_u64 v[222:223], s[30:31], 0, v[134:135]
	s_mov_b32 m0, s25
	s_nop 0
	global_load_lds_dwordx4 v[222:223], off
	s_waitcnt vmcnt(7)
	s_waitcnt lgkmcnt(0)
	s_barrier
	s_setprio 1
	s_waitcnt lgkmcnt(0)
	v_mfma_f32_16x16x32_bf16 v[52:55], v[154:157], v[186:189], v[52:55]
	v_mfma_f32_16x16x32_bf16 v[48:51], v[162:165], v[186:189], v[48:51]
	v_mfma_f32_16x16x32_bf16 v[36:39], v[154:157], v[196:199], v[36:39]
	v_mfma_f32_16x16x32_bf16 v[32:35], v[162:165], v[196:199], v[32:35]
	v_mfma_f32_16x16x32_bf16 v[20:23], v[154:157], v[204:207], v[20:23]
	v_mfma_f32_16x16x32_bf16 v[16:19], v[162:165], v[204:207], v[16:19]
	v_mfma_f32_16x16x32_bf16 v[4:7], v[154:157], v[212:215], v[4:7]
	v_mfma_f32_16x16x32_bf16 v[0:3], v[162:165], v[212:215], v[0:3]
	v_mfma_f32_16x16x32_bf16 v[52:55], v[158:161], v[190:193], v[52:55]
	v_mfma_f32_16x16x32_bf16 v[48:51], v[166:169], v[190:193], v[48:51]
	v_mfma_f32_16x16x32_bf16 v[36:39], v[158:161], v[200:203], v[36:39]
	v_mfma_f32_16x16x32_bf16 v[32:35], v[166:169], v[200:203], v[32:35]
	v_mfma_f32_16x16x32_bf16 v[20:23], v[158:161], v[208:211], v[20:23]
	v_mfma_f32_16x16x32_bf16 v[16:19], v[166:169], v[208:211], v[16:19]
	v_mfma_f32_16x16x32_bf16 v[4:7], v[158:161], v[216:219], v[4:7]
	v_mfma_f32_16x16x32_bf16 v[0:3], v[166:169], v[216:219], v[0:3]
	s_setprio 0
	s_setprio 1
	v_mfma_f32_16x16x32_bf16 v[60:63], v[170:173], v[186:189], v[60:63]
	v_mfma_f32_16x16x32_bf16 v[56:59], v[178:181], v[186:189], v[56:59]
	v_mfma_f32_16x16x32_bf16 v[44:47], v[170:173], v[196:199], v[44:47]
	v_mfma_f32_16x16x32_bf16 v[40:43], v[178:181], v[196:199], v[40:43]
	v_mfma_f32_16x16x32_bf16 v[28:31], v[170:173], v[204:207], v[28:31]
	v_mfma_f32_16x16x32_bf16 v[24:27], v[178:181], v[204:207], v[24:27]
	v_mfma_f32_16x16x32_bf16 v[12:15], v[170:173], v[212:215], v[12:15]
	v_mfma_f32_16x16x32_bf16 v[8:11], v[178:181], v[212:215], v[8:11]
	v_mfma_f32_16x16x32_bf16 v[60:63], v[174:177], v[190:193], v[60:63]
	v_mfma_f32_16x16x32_bf16 v[56:59], v[182:185], v[190:193], v[56:59]
	v_mfma_f32_16x16x32_bf16 v[44:47], v[174:177], v[200:203], v[44:47]
	v_mfma_f32_16x16x32_bf16 v[40:43], v[182:185], v[200:203], v[40:43]
	v_mfma_f32_16x16x32_bf16 v[28:31], v[174:177], v[208:211], v[28:31]
	v_mfma_f32_16x16x32_bf16 v[24:27], v[182:185], v[208:211], v[24:27]
	v_mfma_f32_16x16x32_bf16 v[12:15], v[174:177], v[216:219], v[12:15]
	v_mfma_f32_16x16x32_bf16 v[8:11], v[182:185], v[216:219], v[8:11]
	s_setprio 0
	s_barrier
	s_add_i32 s60, 0, 0x18000
	v_add_u32_e32 v153, s60, v147
	s_add_i32 s61, 0, 0x1c000
	ds_read_b128 v[154:157], v153
	ds_read_b128 v[158:161], v153 offset:1024
	ds_read_b128 v[162:165], v153 offset:2048
	ds_read_b128 v[166:169], v153 offset:3072
	v_add_u32_e32 v153, s61, v147
	ds_read_b128 v[170:173], v153
	ds_read_b128 v[174:177], v153 offset:1024
	ds_read_b128 v[178:181], v153 offset:2048
	ds_read_b128 v[182:185], v153 offset:3072
	s_add_u32 s30, s30, 0x40000
	s_addc_u32 s31, s31, 0
	v_lshl_add_u64 v[226:227], s[30:31], 0, v[134:135]
	ds_read_b128 v[186:189], v151 offset:32768
	ds_read_b128 v[190:193], v151 offset:33792
	ds_read_b128 v[196:199], v151 offset:34816
	ds_read_b128 v[200:203], v151 offset:35840
	ds_read_b128 v[204:207], v151 offset:36864
	ds_read_b128 v[208:211], v151 offset:37888
	ds_read_b128 v[212:215], v151 offset:38912
	ds_read_b128 v[216:219], v151 offset:39936
	s_mov_b32 m0, s41
	s_nop 0
	global_load_lds_dwordx4 v[224:225], off
	s_mov_b32 m0, s42
	s_nop 0
	global_load_lds_dwordx4 v[226:227], off
	v_lshl_add_u64 v[226:227], s[30:31], 0, v[130:131]
	s_mov_b32 m0, s43
	s_nop 0
	global_load_lds_dwordx4 v[226:227], off
	s_waitcnt vmcnt(8)
	s_waitcnt lgkmcnt(0)
	s_barrier
	s_setprio 1
	s_waitcnt lgkmcnt(0)
	v_mfma_f32_16x16x32_bf16 v[116:119], v[154:157], v[186:189], v[116:119]
	v_mfma_f32_16x16x32_bf16 v[112:115], v[162:165], v[186:189], v[112:115]
	v_mfma_f32_16x16x32_bf16 v[100:103], v[154:157], v[196:199], v[100:103]
	v_mfma_f32_16x16x32_bf16 v[96:99], v[162:165], v[196:199], v[96:99]
	v_mfma_f32_16x16x32_bf16 v[84:87], v[154:157], v[204:207], v[84:87]
	v_mfma_f32_16x16x32_bf16 v[80:83], v[162:165], v[204:207], v[80:83]
	v_mfma_f32_16x16x32_bf16 v[68:71], v[154:157], v[212:215], v[68:71]
	v_mfma_f32_16x16x32_bf16 v[64:67], v[162:165], v[212:215], v[64:67]
	v_mfma_f32_16x16x32_bf16 v[116:119], v[158:161], v[190:193], v[116:119]
	v_mfma_f32_16x16x32_bf16 v[112:115], v[166:169], v[190:193], v[112:115]
	v_mfma_f32_16x16x32_bf16 v[100:103], v[158:161], v[200:203], v[100:103]
	v_mfma_f32_16x16x32_bf16 v[96:99], v[166:169], v[200:203], v[96:99]
	v_mfma_f32_16x16x32_bf16 v[84:87], v[158:161], v[208:211], v[84:87]
	v_mfma_f32_16x16x32_bf16 v[80:83], v[166:169], v[208:211], v[80:83]
	v_mfma_f32_16x16x32_bf16 v[68:71], v[158:161], v[216:219], v[68:71]
	v_mfma_f32_16x16x32_bf16 v[64:67], v[166:169], v[216:219], v[64:67]
	s_setprio 0
	s_setprio 1
	v_mfma_f32_16x16x32_bf16 v[124:127], v[170:173], v[186:189], v[124:127]
	v_mfma_f32_16x16x32_bf16 v[120:123], v[178:181], v[186:189], v[120:123]
	v_mfma_f32_16x16x32_bf16 v[108:111], v[170:173], v[196:199], v[108:111]
	v_mfma_f32_16x16x32_bf16 v[104:107], v[178:181], v[196:199], v[104:107]
	v_mfma_f32_16x16x32_bf16 v[92:95], v[170:173], v[204:207], v[92:95]
	v_mfma_f32_16x16x32_bf16 v[88:91], v[178:181], v[204:207], v[88:91]
	v_mfma_f32_16x16x32_bf16 v[76:79], v[170:173], v[212:215], v[76:79]
	v_mfma_f32_16x16x32_bf16 v[72:75], v[178:181], v[212:215], v[72:75]
	v_mfma_f32_16x16x32_bf16 v[124:127], v[174:177], v[190:193], v[124:127]
	v_mfma_f32_16x16x32_bf16 v[120:123], v[182:185], v[190:193], v[120:123]
	v_mfma_f32_16x16x32_bf16 v[108:111], v[174:177], v[200:203], v[108:111]
	v_mfma_f32_16x16x32_bf16 v[104:107], v[182:185], v[200:203], v[104:107]
	v_mfma_f32_16x16x32_bf16 v[92:95], v[174:177], v[208:211], v[92:95]
	v_mfma_f32_16x16x32_bf16 v[88:91], v[182:185], v[208:211], v[88:91]
	v_mfma_f32_16x16x32_bf16 v[76:79], v[174:177], v[216:219], v[76:79]
	v_mfma_f32_16x16x32_bf16 v[72:75], v[182:185], v[216:219], v[72:75]
	s_setprio 0
	s_barrier
	s_add_i32 s30, s60, s39
	v_lshl_add_u64 v[144:145], v[144:145], 0, s[12:13]
	s_mov_b32 m0, s30
	ds_read_b128 v[186:189], v151 offset:49152
	ds_read_b128 v[190:193], v151 offset:50176
	ds_read_b128 v[196:199], v151 offset:51200
	ds_read_b128 v[200:203], v151 offset:52224
	ds_read_b128 v[204:207], v151 offset:53248
	ds_read_b128 v[208:211], v151 offset:54272
	ds_read_b128 v[212:215], v151 offset:55296
	ds_read_b128 v[216:219], v151 offset:56320
	global_load_lds_dwordx4 v[144:145], off
	s_add_i32 m0, s30, 0x2000
	s_add_u32 s28, s28, 0x40080
	v_lshl_add_u64 v[144:145], v[220:221], 0, s[12:13]
	s_addc_u32 s29, s29, 0
	s_add_i32 s30, s61, s39
	global_load_lds_dwordx4 v[144:145], off
	v_lshl_add_u64 v[144:145], s[28:29], 0, v[132:133]
	s_mov_b32 m0, s30
	s_nop 0
	global_load_lds_dwordx4 v[144:145], off
	v_lshl_add_u64 v[144:145], s[28:29], 0, v[128:129]
	s_add_i32 m0, s30, 0x2000
	s_nop 0
	global_load_lds_dwordx4 v[144:145], off
	v_lshl_add_u64 v[144:145], v[222:223], 0, s[12:13]
	s_mov_b32 m0, s45
	s_nop 0
	global_load_lds_dwordx4 v[144:145], off
	s_waitcnt vmcnt(7)
	s_waitcnt lgkmcnt(0)
	s_barrier
	s_setprio 1
	s_waitcnt lgkmcnt(0)
	v_mfma_f32_16x16x32_bf16 v[52:55], v[154:157], v[186:189], v[52:55]
	v_mfma_f32_16x16x32_bf16 v[48:51], v[162:165], v[186:189], v[48:51]
	v_mfma_f32_16x16x32_bf16 v[36:39], v[154:157], v[196:199], v[36:39]
	v_mfma_f32_16x16x32_bf16 v[32:35], v[162:165], v[196:199], v[32:35]
	v_mfma_f32_16x16x32_bf16 v[20:23], v[154:157], v[204:207], v[20:23]
	v_mfma_f32_16x16x32_bf16 v[16:19], v[162:165], v[204:207], v[16:19]
	v_mfma_f32_16x16x32_bf16 v[4:7], v[154:157], v[212:215], v[4:7]
	v_mfma_f32_16x16x32_bf16 v[0:3], v[162:165], v[212:215], v[0:3]
	v_mfma_f32_16x16x32_bf16 v[52:55], v[158:161], v[190:193], v[52:55]
	v_mfma_f32_16x16x32_bf16 v[48:51], v[166:169], v[190:193], v[48:51]
	v_mfma_f32_16x16x32_bf16 v[36:39], v[158:161], v[200:203], v[36:39]
	v_mfma_f32_16x16x32_bf16 v[32:35], v[166:169], v[200:203], v[32:35]
	v_mfma_f32_16x16x32_bf16 v[20:23], v[158:161], v[208:211], v[20:23]
	v_mfma_f32_16x16x32_bf16 v[16:19], v[166:169], v[208:211], v[16:19]
	v_mfma_f32_16x16x32_bf16 v[4:7], v[158:161], v[216:219], v[4:7]
	v_mfma_f32_16x16x32_bf16 v[0:3], v[166:169], v[216:219], v[0:3]
	s_setprio 0
	s_setprio 1
	v_mfma_f32_16x16x32_bf16 v[60:63], v[170:173], v[186:189], v[60:63]
	v_mfma_f32_16x16x32_bf16 v[56:59], v[178:181], v[186:189], v[56:59]
	v_mfma_f32_16x16x32_bf16 v[44:47], v[170:173], v[196:199], v[44:47]
	v_mfma_f32_16x16x32_bf16 v[40:43], v[178:181], v[196:199], v[40:43]
	v_mfma_f32_16x16x32_bf16 v[28:31], v[170:173], v[204:207], v[28:31]
	v_mfma_f32_16x16x32_bf16 v[24:27], v[178:181], v[204:207], v[24:27]
	v_mfma_f32_16x16x32_bf16 v[12:15], v[170:173], v[212:215], v[12:15]
	v_mfma_f32_16x16x32_bf16 v[8:11], v[178:181], v[212:215], v[8:11]
	v_mfma_f32_16x16x32_bf16 v[60:63], v[174:177], v[190:193], v[60:63]
	v_mfma_f32_16x16x32_bf16 v[56:59], v[182:185], v[190:193], v[56:59]
	v_mfma_f32_16x16x32_bf16 v[44:47], v[174:177], v[200:203], v[44:47]
	v_mfma_f32_16x16x32_bf16 v[40:43], v[182:185], v[200:203], v[40:43]
	v_mfma_f32_16x16x32_bf16 v[28:31], v[174:177], v[208:211], v[28:31]
	v_mfma_f32_16x16x32_bf16 v[24:27], v[182:185], v[208:211], v[24:27]
	v_mfma_f32_16x16x32_bf16 v[12:15], v[174:177], v[216:219], v[12:15]
	v_mfma_f32_16x16x32_bf16 v[8:11], v[182:185], v[216:219], v[8:11]
	s_setprio 0
	s_barrier
	v_lshl_add_u64 v[224:225], v[224:225], 0, s[12:13]
	s_mov_b32 m0, s48
	s_nop 0
	global_load_lds_dwordx4 v[224:225], off
	s_add_i32 s59, s59, 2
	s_add_u32 s26, s26, 0x100
	s_addc_u32 s27, s27, 0
	s_add_u32 s57, s57, 0x100
	s_addc_u32 s58, s58, 0
	s_cmp_gt_u32 s59, 13
	s_cbranch_scc0 .LBB0_3319
	s_and_b64 vcc, exec, s[14:15]
	s_cbranch_vccz .LBB0_3322
	s_barrier

.LBB0_3401:
	ds_read_b128 v[144:147], v151
	ds_read_b128 v[156:159], v151 offset:1024
	ds_read_b128 v[160:163], v151 offset:2048
	ds_read_b128 v[164:167], v151 offset:3072
	ds_read_b128 v[168:171], v152
	ds_read_b128 v[172:175], v152 offset:1024
	ds_read_b128 v[176:179], v152 offset:2048
	ds_read_b128 v[180:183], v152 offset:3072
	s_add_u32 s24, s22, 0x100
	s_addc_u32 s25, s23, 0
	s_cmp_eq_u32 s56, 40
	s_cselect_b32 s29, s1, s25
	s_cselect_b32 s28, s0, s24
	s_cselect_b32 s27, s21, s55
	s_cselect_b32 s26, s20, s54
	v_lshl_add_u64 v[192:193], s[22:23], 0, v[136:137]
	s_add_i32 m0, s38, 0xc000
	ds_read_b128 v[184:187], v153
	ds_read_b128 v[188:191], v153 offset:1024
	ds_read_b128 v[196:199], v153 offset:2048
	ds_read_b128 v[200:203], v153 offset:3072
	ds_read_b128 v[204:207], v153 offset:4096
	ds_read_b128 v[208:211], v153 offset:5120
	ds_read_b128 v[212:215], v153 offset:6144
	ds_read_b128 v[216:219], v153 offset:7168
	global_load_lds_dwordx4 v[192:193], off
	v_lshl_add_u64 v[192:193], s[22:23], 0, v[138:139]
	s_add_i32 m0, s38, 0xe000
	s_nop 0
	global_load_lds_dwordx4 v[192:193], off
	s_waitcnt vmcnt(8)
	s_waitcnt lgkmcnt(0)
	s_barrier
	s_setprio 1
	s_waitcnt lgkmcnt(0)
	v_mfma_f32_16x16x32_bf16 v[124:127], v[144:147], v[184:187], v[124:127]
	v_mfma_f32_16x16x32_bf16 v[120:123], v[160:163], v[184:187], v[120:123]
	v_mfma_f32_16x16x32_bf16 v[108:111], v[144:147], v[196:199], v[108:111]
	v_mfma_f32_16x16x32_bf16 v[104:107], v[160:163], v[196:199], v[104:107]
	v_mfma_f32_16x16x32_bf16 v[92:95], v[144:147], v[204:207], v[92:95]
	v_mfma_f32_16x16x32_bf16 v[88:91], v[160:163], v[204:207], v[88:91]
	v_mfma_f32_16x16x32_bf16 v[76:79], v[144:147], v[212:215], v[76:79]
	v_mfma_f32_16x16x32_bf16 v[72:75], v[160:163], v[212:215], v[72:75]
	v_mfma_f32_16x16x32_bf16 v[124:127], v[156:159], v[188:191], v[124:127]
	v_mfma_f32_16x16x32_bf16 v[120:123], v[164:167], v[188:191], v[120:123]
	v_mfma_f32_16x16x32_bf16 v[108:111], v[156:159], v[200:203], v[108:111]
	v_mfma_f32_16x16x32_bf16 v[104:107], v[164:167], v[200:203], v[104:107]
	v_mfma_f32_16x16x32_bf16 v[92:95], v[156:159], v[208:211], v[92:95]
	v_mfma_f32_16x16x32_bf16 v[88:91], v[164:167], v[208:211], v[88:91]
	v_mfma_f32_16x16x32_bf16 v[76:79], v[156:159], v[216:219], v[76:79]
	v_mfma_f32_16x16x32_bf16 v[72:75], v[164:167], v[216:219], v[72:75]
	s_setprio 0
	s_setprio 1
	v_mfma_f32_16x16x32_bf16 v[116:119], v[168:171], v[184:187], v[116:119]
	v_mfma_f32_16x16x32_bf16 v[112:115], v[176:179], v[184:187], v[112:115]
	v_mfma_f32_16x16x32_bf16 v[100:103], v[168:171], v[196:199], v[100:103]
	v_mfma_f32_16x16x32_bf16 v[96:99], v[176:179], v[196:199], v[96:99]
	v_mfma_f32_16x16x32_bf16 v[84:87], v[168:171], v[204:207], v[84:87]
	v_mfma_f32_16x16x32_bf16 v[80:83], v[176:179], v[204:207], v[80:83]
	v_mfma_f32_16x16x32_bf16 v[68:71], v[168:171], v[212:215], v[68:71]
	v_mfma_f32_16x16x32_bf16 v[64:67], v[176:179], v[212:215], v[64:67]
	v_mfma_f32_16x16x32_bf16 v[116:119], v[172:175], v[188:191], v[116:119]
	v_mfma_f32_16x16x32_bf16 v[112:115], v[180:183], v[188:191], v[112:115]
	v_mfma_f32_16x16x32_bf16 v[100:103], v[172:175], v[200:203], v[100:103]
	v_mfma_f32_16x16x32_bf16 v[96:99], v[180:183], v[200:203], v[96:99]
	v_mfma_f32_16x16x32_bf16 v[84:87], v[172:175], v[208:211], v[84:87]
	v_mfma_f32_16x16x32_bf16 v[80:83], v[180:183], v[208:211], v[80:83]
	v_mfma_f32_16x16x32_bf16 v[68:71], v[172:175], v[216:219], v[68:71]
	v_mfma_f32_16x16x32_bf16 v[64:67], v[180:183], v[216:219], v[64:67]
	s_setprio 0
	s_barrier
	s_add_i32 s22, s48, s37
	v_lshl_add_u64 v[192:193], s[26:27], 0, v[130:131]
	s_mov_b32 m0, s22
	ds_read_b128 v[184:187], v153 offset:16384
	ds_read_b128 v[188:191], v153 offset:17408
	ds_read_b128 v[196:199], v153 offset:18432
	ds_read_b128 v[200:203], v153 offset:19456
	ds_read_b128 v[204:207], v153 offset:20480
	ds_read_b128 v[208:211], v153 offset:21504
	ds_read_b128 v[212:215], v153 offset:22528
	ds_read_b128 v[216:219], v153 offset:23552
	global_load_lds_dwordx4 v[192:193], off
	s_add_i32 m0, s22, 0x2000
	s_add_u32 s22, s26, 0xb0000
	v_lshl_add_u64 v[220:221], s[26:27], 0, v[134:135]
	s_addc_u32 s23, s27, 0
	s_add_i32 s57, s49, s37
	global_load_lds_dwordx4 v[220:221], off
	v_lshl_add_u64 v[222:223], s[22:23], 0, v[130:131]
	s_mov_b32 m0, s57
	v_lshl_add_u64 v[224:225], s[28:29], 0, v[132:133]
	global_load_lds_dwordx4 v[222:223], off
	v_lshl_add_u64 v[222:223], s[22:23], 0, v[134:135]
	s_add_i32 m0, s57, 0x2000
	s_nop 0
	global_load_lds_dwordx4 v[222:223], off
	v_lshl_add_u64 v[222:223], s[28:29], 0, v[128:129]
	s_mov_b32 m0, s38
	s_nop 0
	global_load_lds_dwordx4 v[222:223], off
	s_waitcnt vmcnt(7)
	s_waitcnt lgkmcnt(0)
	s_barrier
	s_setprio 1
	s_waitcnt lgkmcnt(0)
	v_mfma_f32_16x16x32_bf16 v[60:63], v[144:147], v[184:187], v[60:63]
	v_mfma_f32_16x16x32_bf16 v[56:59], v[160:163], v[184:187], v[56:59]
	v_mfma_f32_16x16x32_bf16 v[44:47], v[144:147], v[196:199], v[44:47]
	v_mfma_f32_16x16x32_bf16 v[40:43], v[160:163], v[196:199], v[40:43]
	v_mfma_f32_16x16x32_bf16 v[28:31], v[144:147], v[204:207], v[28:31]
	v_mfma_f32_16x16x32_bf16 v[24:27], v[160:163], v[204:207], v[24:27]
	v_mfma_f32_16x16x32_bf16 v[12:15], v[144:147], v[212:215], v[12:15]
	v_mfma_f32_16x16x32_bf16 v[8:11], v[160:163], v[212:215], v[8:11]
	v_mfma_f32_16x16x32_bf16 v[60:63], v[156:159], v[188:191], v[60:63]
	v_mfma_f32_16x16x32_bf16 v[56:59], v[164:167], v[188:191], v[56:59]
	v_mfma_f32_16x16x32_bf16 v[44:47], v[156:159], v[200:203], v[44:47]
	v_mfma_f32_16x16x32_bf16 v[40:43], v[164:167], v[200:203], v[40:43]
	v_mfma_f32_16x16x32_bf16 v[28:31], v[156:159], v[208:211], v[28:31]
	v_mfma_f32_16x16x32_bf16 v[24:27], v[164:167], v[208:211], v[24:27]
	v_mfma_f32_16x16x32_bf16 v[12:15], v[156:159], v[216:219], v[12:15]
	v_mfma_f32_16x16x32_bf16 v[8:11], v[164:167], v[216:219], v[8:11]
	s_setprio 0
	s_setprio 1
	v_mfma_f32_16x16x32_bf16 v[52:55], v[168:171], v[184:187], v[52:55]
	v_mfma_f32_16x16x32_bf16 v[48:51], v[176:179], v[184:187], v[48:51]
	v_mfma_f32_16x16x32_bf16 v[36:39], v[168:171], v[196:199], v[36:39]
	v_mfma_f32_16x16x32_bf16 v[32:35], v[176:179], v[196:199], v[32:35]
	v_mfma_f32_16x16x32_bf16 v[20:23], v[168:171], v[204:207], v[20:23]
	v_mfma_f32_16x16x32_bf16 v[16:19], v[176:179], v[204:207], v[16:19]
	v_mfma_f32_16x16x32_bf16 v[4:7], v[168:171], v[212:215], v[4:7]
	v_mfma_f32_16x16x32_bf16 v[0:3], v[176:179], v[212:215], v[0:3]
	v_mfma_f32_16x16x32_bf16 v[52:55], v[172:175], v[188:191], v[52:55]
	v_mfma_f32_16x16x32_bf16 v[48:51], v[180:183], v[188:191], v[48:51]
	v_mfma_f32_16x16x32_bf16 v[36:39], v[172:175], v[200:203], v[36:39]
	v_mfma_f32_16x16x32_bf16 v[32:35], v[180:183], v[200:203], v[32:35]
	v_mfma_f32_16x16x32_bf16 v[20:23], v[172:175], v[208:211], v[20:23]
	v_mfma_f32_16x16x32_bf16 v[16:19], v[180:183], v[208:211], v[16:19]
	v_mfma_f32_16x16x32_bf16 v[4:7], v[172:175], v[216:219], v[4:7]
	v_mfma_f32_16x16x32_bf16 v[0:3], v[180:183], v[216:219], v[0:3]
	s_setprio 0
	s_barrier
	s_add_i32 s57, 0, 0x18000
	v_add_u32_e32 v155, s57, v149
	s_add_i32 s58, 0, 0x1c000
	ds_read_b128 v[144:147], v155
	ds_read_b128 v[156:159], v155 offset:1024
	ds_read_b128 v[160:163], v155 offset:2048
	ds_read_b128 v[164:167], v155 offset:3072
	v_add_u32_e32 v155, s58, v149
	ds_read_b128 v[168:171], v155
	ds_read_b128 v[172:175], v155 offset:1024
	ds_read_b128 v[176:179], v155 offset:2048
	ds_read_b128 v[180:183], v155 offset:3072
	s_add_u32 s22, s28, 0xb0000
	s_addc_u32 s23, s29, 0
	v_lshl_add_u64 v[226:227], s[22:23], 0, v[128:129]
	ds_read_b128 v[184:187], v153 offset:32768
	ds_read_b128 v[188:191], v153 offset:33792
	ds_read_b128 v[196:199], v153 offset:34816
	ds_read_b128 v[200:203], v153 offset:35840
	ds_read_b128 v[204:207], v153 offset:36864
	ds_read_b128 v[208:211], v153 offset:37888
	ds_read_b128 v[212:215], v153 offset:38912
	ds_read_b128 v[216:219], v153 offset:39936
	s_mov_b32 m0, s39
	s_nop 0
	global_load_lds_dwordx4 v[224:225], off
	s_mov_b32 m0, s40
	s_nop 0
	global_load_lds_dwordx4 v[226:227], off
	v_lshl_add_u64 v[226:227], s[22:23], 0, v[132:133]
	s_mov_b32 m0, s41
	s_nop 0
	global_load_lds_dwordx4 v[226:227], off
	s_waitcnt vmcnt(8)
	s_waitcnt lgkmcnt(0)
	s_barrier
	s_setprio 1
	s_waitcnt lgkmcnt(0)
	v_mfma_f32_16x16x32_bf16 v[124:127], v[144:147], v[184:187], v[124:127]
	v_mfma_f32_16x16x32_bf16 v[120:123], v[160:163], v[184:187], v[120:123]
	v_mfma_f32_16x16x32_bf16 v[108:111], v[144:147], v[196:199], v[108:111]
	v_mfma_f32_16x16x32_bf16 v[104:107], v[160:163], v[196:199], v[104:107]
	v_mfma_f32_16x16x32_bf16 v[92:95], v[144:147], v[204:207], v[92:95]
	v_mfma_f32_16x16x32_bf16 v[88:91], v[160:163], v[204:207], v[88:91]
	v_mfma_f32_16x16x32_bf16 v[76:79], v[144:147], v[212:215], v[76:79]
	v_mfma_f32_16x16x32_bf16 v[72:75], v[160:163], v[212:215], v[72:75]
	v_mfma_f32_16x16x32_bf16 v[124:127], v[156:159], v[188:191], v[124:127]
	v_mfma_f32_16x16x32_bf16 v[120:123], v[164:167], v[188:191], v[120:123]
	v_mfma_f32_16x16x32_bf16 v[108:111], v[156:159], v[200:203], v[108:111]
	v_mfma_f32_16x16x32_bf16 v[104:107], v[164:167], v[200:203], v[104:107]
	v_mfma_f32_16x16x32_bf16 v[92:95], v[156:159], v[208:211], v[92:95]
	v_mfma_f32_16x16x32_bf16 v[88:91], v[164:167], v[208:211], v[88:91]
	v_mfma_f32_16x16x32_bf16 v[76:79], v[156:159], v[216:219], v[76:79]
	v_mfma_f32_16x16x32_bf16 v[72:75], v[164:167], v[216:219], v[72:75]
	s_setprio 0
	s_setprio 1
	v_mfma_f32_16x16x32_bf16 v[116:119], v[168:171], v[184:187], v[116:119]
	v_mfma_f32_16x16x32_bf16 v[112:115], v[176:179], v[184:187], v[112:115]
	v_mfma_f32_16x16x32_bf16 v[100:103], v[168:171], v[196:199], v[100:103]
	v_mfma_f32_16x16x32_bf16 v[96:99], v[176:179], v[196:199], v[96:99]
	v_mfma_f32_16x16x32_bf16 v[84:87], v[168:171], v[204:207], v[84:87]
	v_mfma_f32_16x16x32_bf16 v[80:83], v[176:179], v[204:207], v[80:83]
	v_mfma_f32_16x16x32_bf16 v[68:71], v[168:171], v[212:215], v[68:71]
	v_mfma_f32_16x16x32_bf16 v[64:67], v[176:179], v[212:215], v[64:67]
	v_mfma_f32_16x16x32_bf16 v[116:119], v[172:175], v[188:191], v[116:119]
	v_mfma_f32_16x16x32_bf16 v[112:115], v[180:183], v[188:191], v[112:115]
	v_mfma_f32_16x16x32_bf16 v[100:103], v[172:175], v[200:203], v[100:103]
	v_mfma_f32_16x16x32_bf16 v[96:99], v[180:183], v[200:203], v[96:99]
	v_mfma_f32_16x16x32_bf16 v[84:87], v[172:175], v[208:211], v[84:87]
	v_mfma_f32_16x16x32_bf16 v[80:83], v[180:183], v[208:211], v[80:83]
	v_mfma_f32_16x16x32_bf16 v[68:71], v[172:175], v[216:219], v[68:71]
	v_mfma_f32_16x16x32_bf16 v[64:67], v[180:183], v[216:219], v[64:67]
	s_setprio 0
	s_barrier
	s_add_i32 s22, s57, s37
	v_lshl_add_u64 v[192:193], v[192:193], 0, s[16:17]
	s_mov_b32 m0, s22
	ds_read_b128 v[184:187], v153 offset:49152
	ds_read_b128 v[188:191], v153 offset:50176
	ds_read_b128 v[196:199], v153 offset:51200
	ds_read_b128 v[200:203], v153 offset:52224
	ds_read_b128 v[204:207], v153 offset:53248
	ds_read_b128 v[208:211], v153 offset:54272
	ds_read_b128 v[212:215], v153 offset:55296
	ds_read_b128 v[216:219], v153 offset:56320
	global_load_lds_dwordx4 v[192:193], off
	s_add_i32 m0, s22, 0x2000
	s_add_u32 s22, s26, 0xb0080
	v_lshl_add_u64 v[192:193], v[220:221], 0, s[16:17]
	s_addc_u32 s23, s27, 0
	s_add_i32 s26, s58, s37
	global_load_lds_dwordx4 v[192:193], off
	v_lshl_add_u64 v[192:193], s[22:23], 0, v[130:131]
	s_mov_b32 m0, s26
	s_nop 0
	global_load_lds_dwordx4 v[192:193], off
	v_lshl_add_u64 v[192:193], s[22:23], 0, v[134:135]
	s_add_i32 m0, s26, 0x2000
	s_nop 0
	global_load_lds_dwordx4 v[192:193], off
	v_lshl_add_u64 v[192:193], v[222:223], 0, s[16:17]
	s_mov_b32 m0, s43
	s_nop 0
	global_load_lds_dwordx4 v[192:193], off
	s_waitcnt vmcnt(7)
	s_waitcnt lgkmcnt(0)
	s_barrier
	s_setprio 1
	s_waitcnt lgkmcnt(0)
	v_mfma_f32_16x16x32_bf16 v[60:63], v[144:147], v[184:187], v[60:63]
	v_mfma_f32_16x16x32_bf16 v[56:59], v[160:163], v[184:187], v[56:59]
	v_mfma_f32_16x16x32_bf16 v[44:47], v[144:147], v[196:199], v[44:47]
	v_mfma_f32_16x16x32_bf16 v[40:43], v[160:163], v[196:199], v[40:43]
	v_mfma_f32_16x16x32_bf16 v[28:31], v[144:147], v[204:207], v[28:31]
	v_mfma_f32_16x16x32_bf16 v[24:27], v[160:163], v[204:207], v[24:27]
	v_mfma_f32_16x16x32_bf16 v[12:15], v[144:147], v[212:215], v[12:15]
	v_mfma_f32_16x16x32_bf16 v[8:11], v[160:163], v[212:215], v[8:11]
	v_mfma_f32_16x16x32_bf16 v[60:63], v[156:159], v[188:191], v[60:63]
	v_mfma_f32_16x16x32_bf16 v[56:59], v[164:167], v[188:191], v[56:59]
	v_mfma_f32_16x16x32_bf16 v[44:47], v[156:159], v[200:203], v[44:47]
	v_mfma_f32_16x16x32_bf16 v[40:43], v[164:167], v[200:203], v[40:43]
	v_mfma_f32_16x16x32_bf16 v[28:31], v[156:159], v[208:211], v[28:31]
	v_mfma_f32_16x16x32_bf16 v[24:27], v[164:167], v[208:211], v[24:27]
	v_mfma_f32_16x16x32_bf16 v[12:15], v[156:159], v[216:219], v[12:15]
	v_mfma_f32_16x16x32_bf16 v[8:11], v[164:167], v[216:219], v[8:11]
	s_setprio 0
	s_setprio 1
	v_mfma_f32_16x16x32_bf16 v[52:55], v[168:171], v[184:187], v[52:55]
	v_mfma_f32_16x16x32_bf16 v[48:51], v[176:179], v[184:187], v[48:51]
	v_mfma_f32_16x16x32_bf16 v[36:39], v[168:171], v[196:199], v[36:39]
	v_mfma_f32_16x16x32_bf16 v[32:35], v[176:179], v[196:199], v[32:35]
	v_mfma_f32_16x16x32_bf16 v[20:23], v[168:171], v[204:207], v[20:23]
	v_mfma_f32_16x16x32_bf16 v[16:19], v[176:179], v[204:207], v[16:19]
	v_mfma_f32_16x16x32_bf16 v[4:7], v[168:171], v[212:215], v[4:7]
	v_mfma_f32_16x16x32_bf16 v[0:3], v[176:179], v[212:215], v[0:3]
	v_mfma_f32_16x16x32_bf16 v[52:55], v[172:175], v[188:191], v[52:55]
	v_mfma_f32_16x16x32_bf16 v[48:51], v[180:183], v[188:191], v[48:51]
	v_mfma_f32_16x16x32_bf16 v[36:39], v[172:175], v[200:203], v[36:39]
	v_mfma_f32_16x16x32_bf16 v[32:35], v[180:183], v[200:203], v[32:35]
	v_mfma_f32_16x16x32_bf16 v[20:23], v[172:175], v[208:211], v[20:23]
	v_mfma_f32_16x16x32_bf16 v[16:19], v[180:183], v[208:211], v[16:19]
	v_mfma_f32_16x16x32_bf16 v[4:7], v[172:175], v[216:219], v[4:7]
	v_mfma_f32_16x16x32_bf16 v[0:3], v[180:183], v[216:219], v[0:3]
	s_setprio 0
	s_barrier
	v_lshl_add_u64 v[224:225], v[224:225], 0, s[16:17]
	s_mov_b32 m0, s44
	s_nop 0
	global_load_lds_dwordx4 v[224:225], off
	s_add_i32 s56, s56, 2
	s_add_u32 s54, s54, 0x100
	s_addc_u32 s55, s55, 0
	s_cmp_gt_u32 s56, 41
	s_mov_b64 s[22:23], s[24:25]
	s_cbranch_scc0 .LBB0_3401
	s_and_b64 vcc, exec, s[18:19]
	s_cbranch_vccz .LBB0_3404
	s_barrier
